# K-loops: half of the LDS-DMA pieces issued between the first MFMAs (hides DMA issue cost), early redundant vmcnt(0) before the K-loops removed
# speedup vs baseline: 1.0202x; 1.0102x over previous
; DEV int tid_() { int t = threadIdx.x; asm volatile("" : "+v"(t)); return t; }
; DEV int bid_() { int t = blockIdx.x; asm volatile("" : "+s"(t)); return t; }
; DEV int gdim_() { int t = gridDim.x; asm volatile("" : "+s"(t)); return t; }
; #define P (*launderP(lp))
; template <class FragT, class AccT>
; DEV void gemm_core_t(const char* __restrict__ A, size_t lda_bytes, const char* __restrict__ Bt, size_t ldb_bytes, int kbytes,
;                      int m0, int n0, int Sshift, int dl, char* smem, AccT (&acc)[4][4]) {
;   const int tid = tid_(), lane = tid & 63, wid = tid >> 6, wm = wid >> 1, wn = wid & 1;
;   const int l15 = lane & 15, q = lane >> 4;
;   const int srow = lane >> 3, schunk = (lane & 7) ^ (lane >> 3);
;   const char* ap[4];
;   const char* bp[4];
; #pragma unroll
;   for (int u = 0; u < 4; ++u) {
;     int r = (wid * 4 + u) * 8 + srow;
;     int ar = rowmap(m0 + r, Sshift, dl);
;     ap[u] = A + (size_t)ar * lda_bytes + schunk * 16;
;     bp[u] = Bt + (size_t)(n0 + r) * ldb_bytes + schunk * 16;
;   }
; #pragma unroll
;   for (int i = 0; i < 4; ++i)
; #pragma unroll
;     for (int j = 0; j < 4; ++j) acc[i][j] = AccT{0, 0, 0, 0};
;   const int nk = kbytes >> 7;
;   __syncthreads();
; #pragma unroll
;   for (int u = 0; u < 4; ++u) {
;     __builtin_amdgcn_global_load_lds((const unsigned*)ap[u], (unsigned*)(smem + (wid * 4 + u) * 1024 + lane * 16), 16, 0, 0);
;     __builtin_amdgcn_global_load_lds((const unsigned*)bp[u], (unsigned*)(smem + 16384 + (wid * 4 + u) * 1024 + lane * 16), 16, 0, 0);
;   }
;   const unsigned sbase = (unsigned)(unsigned long)((__attribute__((address_space(3))) char*)smem);
;   const unsigned sq0 = (unsigned)((q ^ (l15 & 7)) << 4);
;   const unsigned a0 = sbase + (unsigned)((wm * 64 + l15) * 128) + sq0;
;   const unsigned b0 = sbase + 16384u + (unsigned)((wn * 32 + l15) * 128) + sq0;
;   asm volatile("s_waitcnt vmcnt(0)" ::: "memory");
;   __syncthreads();
; __device__ __forceinline__ void phase_gemm2(PREF P, char* smem) {
;     ...
;   for (int t = bid_(); t < 64 * 16; t += gdim_()) {
;     int mt, nt;
;     tile_map(t, 2, mt, nt);
;     const int m0 = mt * 128, n0 = nt * 128;
;     f32x4 acc[4][4];
;     gemm_core(P.ret, 2048, P.WretT, 2048, 2048, m0, n0, 13, 0, smem, acc);
.LBB0_399:
	s_ashr_i32 s0, s14, 3
	s_lshr_b32 s1, s0, 28
	s_add_i32 s1, s0, s1
	s_and_b32 s4, s1, -16
	v_mov_b32_e32 v22, v188
	s_sub_i32 s0, s0, s4
	s_lshl_b32 s4, s14, 1
	ds_read2_b64 v[0:3], v92 offset0:21 offset1:40
	s_and_b32 s4, s4, 14
	v_ashrrev_i32_e32 v24, 6, v22
	s_ashr_i32 s5, s0, 3
	s_lshl_b32 s1, s1, 6
	s_lshl_b32 s0, s0, 7
	v_bfe_u32 v25, v22, 3, 3
	v_lshlrev_b32_e32 v26, 5, v24
	s_add_i32 s4, s5, s4
	s_and_b32 s17, s1, 0xfffffc00
	s_and_b32 s18, s0, 0x380
	v_or_b32_e32 v20, v26, v25
	s_or_b32 s15, s18, s17
	s_lshl_b32 s0, s4, 7
	v_or_b32_e32 v14, 8, v20
	v_or_b32_e32 v18, 16, v20
	v_or_b32_e32 v27, 24, v20
	v_bitop3_b32 v4, v25, v22, 7 bitop3:0x78
	v_add_u32_e32 v8, s15, v20
	v_add_u32_e32 v10, s0, v20
	v_add_u32_e32 v12, s15, v14
	v_add_u32_e32 v16, s15, v18
	v_add_u32_e32 v20, s15, v27
	v_lshlrev_b32_e32 v180, 4, v4
	v_ashrrev_i32_e32 v9, 31, v8
	v_ashrrev_i32_e32 v13, 31, v12
	v_ashrrev_i32_e32 v17, 31, v16
	v_ashrrev_i32_e32 v21, 31, v20
	s_waitcnt lgkmcnt(0)
	v_lshl_add_u64 v[4:5], v[2:3], 0, v[180:181]
	v_lshlrev_b64 v[8:9], 12, v[8:9]
	v_lshlrev_b64 v[12:13], 12, v[12:13]
	v_lshlrev_b64 v[16:17], 12, v[16:17]
	v_lshlrev_b64 v[20:21], 12, v[20:21]
	v_lshl_add_u64 v[8:9], v[4:5], 0, v[8:9]
	v_lshl_add_u64 v[12:13], v[4:5], 0, v[12:13]
	v_add_u32_e32 v14, s0, v14
	v_lshl_add_u64 v[16:17], v[4:5], 0, v[16:17]
	v_add_u32_e32 v18, s0, v18
	v_lshl_add_u64 v[4:5], v[4:5], 0, v[20:21]
	v_add_u32_e32 v20, s0, v27
	v_ashrrev_i32_e32 v11, 31, v10
	v_ashrrev_i32_e32 v15, 31, v14
	v_ashrrev_i32_e32 v19, 31, v18
	v_ashrrev_i32_e32 v21, 31, v20
	v_lshl_add_u64 v[6:7], v[0:1], 0, v[180:181]
	v_lshlrev_b64 v[10:11], 12, v[10:11]
	v_lshlrev_b64 v[14:15], 12, v[14:15]
	v_lshlrev_b64 v[18:19], 12, v[18:19]
	v_lshlrev_b64 v[20:21], 12, v[20:21]
	v_and_b32_e32 v23, 63, v22
	v_lshl_add_u64 v[10:11], v[6:7], 0, v[10:11]
	v_lshl_add_u64 v[14:15], v[6:7], 0, v[14:15]
	v_lshl_add_u64 v[18:19], v[6:7], 0, v[18:19]
	v_lshl_add_u64 v[6:7], v[6:7], 0, v[20:21]
	v_lshlrev_b32_e32 v21, 12, v24
	v_lshl_or_b32 v80, v23, 4, v21
	s_nop 0
	v_readfirstlane_b32 s1, v80
	s_mov_b32 m0, s1
	s_barrier
	global_load_lds_dwordx4 v[8:9], off
	v_add_u32_e32 v8, 0x4000, v80
	v_and_b32_e32 v20, 15, v22
	v_readfirstlane_b32 s1, v8
	v_or_b32_e32 v8, 0x400, v80
	s_mov_b32 m0, s1
	v_readfirstlane_b32 s1, v8
	v_add_u32_e32 v8, 0x4400, v80
	global_load_lds_dwordx4 v[10:11], off
	s_mov_b32 m0, s1
	v_readfirstlane_b32 s1, v8
	v_or_b32_e32 v8, 0x800, v80
	global_load_lds_dwordx4 v[12:13], off
	s_mov_b32 m0, s1
	v_readfirstlane_b32 s1, v8
	v_add_u32_e32 v8, 0x4800, v80
	global_load_lds_dwordx4 v[14:15], off
	s_mov_b32 m0, s1
	v_readfirstlane_b32 s1, v8
	v_or_b32_e32 v8, 0xc00, v80
	global_load_lds_dwordx4 v[16:17], off
	s_mov_b32 m0, s1
	v_readfirstlane_b32 s1, v8
	global_load_lds_dwordx4 v[18:19], off
	s_mov_b32 m0, s1
	s_lshl_b32 s4, s5, 7
	global_load_lds_dwordx4 v[4:5], off
	v_add_u32_e32 v4, 0x4c00, v80
	v_lshrrev_b32_e32 v5, 1, v22
	v_readfirstlane_b32 s1, v4
	s_mov_b32 m0, s1
	v_lshlrev_b32_e32 v4, 4, v22
	global_load_lds_dwordx4 v[6:7], off
	s_mov_b32 s1, 0x1ffffc0
	v_bitop3_b32 v4, v23, s31, v4 bitop3:0x48
	v_and_or_b32 v5, v5, s1, v20
	v_and_or_b32 v6, v26, 32, v20
	s_lshl_b32 s1, s14, 8
	v_lshl_or_b32 v6, v6, 7, v4
	s_and_b32 s1, s1, 0x700
	v_lshlrev_b32_e32 v5, 7, v5
	v_or_b32_e32 v82, 0x4000, v6
	v_bitop3_b32 v83, v6, 64, v219 bitop3:0x36
	v_or_b32_e32 v6, 24, v25
	s_add_i32 s1, s4, s1
	v_or_b32_e32 v81, v4, v5
	v_bitop3_b32 v84, v4, 64, v5 bitop3:0x36
	v_or_b32_e32 v4, s1, v6
	v_add_u32_e32 v4, v4, v26
	v_ashrrev_i32_e32 v5, 31, v4
	s_mov_b64 s[36:37], 0x80
	v_lshlrev_b64 v[4:5], 12, v[4:5]
	v_lshl_add_u64 v[0:1], v[0:1], 0, s[36:37]
	v_or_b32_e32 v4, v4, v180
	v_lshl_add_u64 v[64:65], v[0:1], 0, v[4:5]
	v_or_b32_e32 v4, s17, v6
	v_or_b32_e32 v4, s18, v4
	v_add_u32_e32 v4, v4, v26
	v_ashrrev_i32_e32 v5, 31, v4
	v_lshlrev_b64 v[4:5], 12, v[4:5]
	v_lshl_add_u64 v[2:3], v[2:3], 0, s[36:37]
	v_or_b32_e32 v4, v4, v180
	v_or_b32_e32 v6, 16, v25
	v_lshl_add_u64 v[66:67], v[2:3], 0, v[4:5]
	v_or_b32_e32 v4, s1, v6
	v_add_u32_e32 v4, v4, v26
	v_ashrrev_i32_e32 v5, 31, v4
	v_lshlrev_b64 v[4:5], 12, v[4:5]
	v_or_b32_e32 v4, v4, v180
	v_lshl_add_u64 v[68:69], v[0:1], 0, v[4:5]
	v_or_b32_e32 v4, s17, v6
	v_or_b32_e32 v4, s18, v4
	v_add_u32_e32 v4, v4, v26
	v_ashrrev_i32_e32 v5, 31, v4
	v_lshlrev_b64 v[4:5], 12, v[4:5]
	v_or_b32_e32 v4, v4, v180
	v_or_b32_e32 v6, 8, v25
	v_lshl_add_u64 v[70:71], v[2:3], 0, v[4:5]
	v_or_b32_e32 v4, s1, v6
	v_add_u32_e32 v4, v4, v26
	v_ashrrev_i32_e32 v5, 31, v4
	v_lshlrev_b64 v[4:5], 12, v[4:5]
	v_or_b32_e32 v4, v4, v180
	v_lshl_add_u64 v[72:73], v[0:1], 0, v[4:5]
	v_or_b32_e32 v4, s17, v6
	v_or_b32_e32 v4, s18, v4
	v_add_u32_e32 v4, v4, v26
	v_ashrrev_i32_e32 v5, 31, v4
	v_lshlrev_b64 v[4:5], 12, v[4:5]
	v_or_b32_e32 v4, v4, v180
	v_lshl_add_u64 v[74:75], v[2:3], 0, v[4:5]
	v_or_b32_e32 v4, s1, v25
	v_add_u32_e32 v4, v4, v26
	v_ashrrev_i32_e32 v5, 31, v4
	v_lshlrev_b64 v[4:5], 12, v[4:5]
	v_or_b32_e32 v4, v4, v180
	v_lshl_add_u64 v[76:77], v[0:1], 0, v[4:5]
	v_or_b32_e32 v0, s17, v25
	v_or_b32_e32 v0, s18, v0
	v_add_u32_e32 v0, v0, v26
	v_ashrrev_i32_e32 v1, 31, v0
	v_lshlrev_b64 v[0:1], 12, v[0:1]
	v_or_b32_e32 v0, v0, v180
	v_lshl_add_u64 v[78:79], v[2:3], 0, v[0:1]
	v_mov_b32_e32 v0, 0
	s_mov_b64 s[4:5], 0
	s_mov_b32 s6, 0x8000
	v_mov_b32_e32 v1, v0
	v_mov_b32_e32 v2, v0
	v_mov_b32_e32 v3, v0
	v_mov_b32_e32 v4, v0
	v_mov_b32_e32 v5, v0
	v_mov_b32_e32 v6, v0
	v_mov_b32_e32 v7, v0
	v_mov_b32_e32 v8, v0
	v_mov_b32_e32 v9, v0
	v_mov_b32_e32 v10, v0
	v_mov_b32_e32 v11, v0
	v_mov_b32_e32 v12, v0
	v_mov_b32_e32 v13, v0
	v_mov_b32_e32 v14, v0
; DEV f32x4 mma_step(bf16x8 a, bf16x8 b, f32x4 c) { return MFMA(a, b, c); }
; template <class FragT, class AccT>
; DEV void gemm_core_t(const char* __restrict__ A, size_t lda_bytes, const char* __restrict__ Bt, size_t ldb_bytes, int kbytes,
;                      int m0, int n0, int Sshift, int dl, char* smem, AccT (&acc)[4][4]) {
;     ...
;   for (int kt = 0; kt < nk; ++kt) {
;     const unsigned so = (unsigned)(kt & 1) * 32768u;
;     char* nxt = smem + ((kt + 1) & 1) * 32768;
;     if (kt + 1 < nk) {
; #pragma unroll
;       for (int u = 0; u < 4; ++u) {
;         __builtin_amdgcn_global_load_lds((const unsigned*)(ap[u] + (size_t)(kt + 1) * 128), (unsigned*)(nxt + (wid * 4 + u) * 1024 + lane * 16), 16, 0, 0);
;         __builtin_amdgcn_global_load_lds((const unsigned*)(bp[u] + (size_t)(kt + 1) * 128), (unsigned*)(nxt + 16384 + (wid * 4 + u) * 1024 + lane * 16), 16, 0, 0);
;       }
;     }
;     FragT xa[2][4], wb[2][4];
;     asm volatile(
;         "ds_read_b128 %0, %16\n\t"
;         "ds_read_b128 %1, %16 offset:2048\n\t"
;         "ds_read_b128 %2, %16 offset:4096\n\t"
;         "ds_read_b128 %3, %16 offset:6144\n\t"
;         "ds_read_b128 %4, %18\n\t"
;         "ds_read_b128 %5, %18 offset:2048\n\t"
;         "ds_read_b128 %6, %18 offset:8192\n\t"
;         "ds_read_b128 %7, %18 offset:10240\n\t"
;         "ds_read_b128 %8, %17\n\t"
;         "ds_read_b128 %9, %17 offset:2048\n\t"
;         "ds_read_b128 %10, %17 offset:4096\n\t"
;         "ds_read_b128 %11, %17 offset:6144\n\t"
;         "ds_read_b128 %12, %19\n\t"
;         "ds_read_b128 %13, %19 offset:2048\n\t"
;         "ds_read_b128 %14, %19 offset:8192\n\t"
;         "ds_read_b128 %15, %19 offset:10240\n\t"
;         "s_waitcnt lgkmcnt(8)"
;         : "=&v"(xa[0][0]), "=&v"(xa[0][1]), "=&v"(xa[0][2]), "=&v"(xa[0][3]), "=&v"(wb[0][0]), "=&v"(wb[0][1]), "=&v"(wb[0][2]),
;           "=&v"(wb[0][3]), "=&v"(xa[1][0]), "=&v"(xa[1][1]), "=&v"(xa[1][2]), "=&v"(xa[1][3]), "=&v"(wb[1][0]), "=&v"(wb[1][1]),
;           "=&v"(wb[1][2]), "=&v"(wb[1][3])
;         : "v"(a0 + so), "v"((a0 ^ 64u) + so), "v"(b0 + so), "v"((b0 ^ 64u) + so)
;         : "memory");
;     __builtin_amdgcn_s_setprio(1);
; #pragma unroll
;     for (int i = 0; i < 4; ++i)
; #pragma unroll
;       for (int j = 0; j < 4; ++j) acc[i][j] = mma_step(wb[0][j], xa[0][i], acc[i][j]);
;     asm volatile("s_waitcnt lgkmcnt(0)"
	v_mov_b32_e32 v15, v0
	v_mov_b32_e32 v16, v0
	v_mov_b32_e32 v17, v0
	v_mov_b32_e32 v18, v0
	v_mov_b32_e32 v19, v0
	v_mov_b32_e32 v20, v0
	v_mov_b32_e32 v21, v0
	v_mov_b32_e32 v22, v0
	v_mov_b32_e32 v23, v0
	v_mov_b32_e32 v24, v0
	v_mov_b32_e32 v25, v0
	v_mov_b32_e32 v26, v0
	v_mov_b32_e32 v27, v0
	v_mov_b32_e32 v28, v0
	v_mov_b32_e32 v29, v0
	v_mov_b32_e32 v30, v0
	v_mov_b32_e32 v31, v0
	v_mov_b32_e32 v32, v0
	v_mov_b32_e32 v33, v0
	v_mov_b32_e32 v34, v0
	v_mov_b32_e32 v35, v0
	v_mov_b32_e32 v36, v0
	v_mov_b32_e32 v37, v0
	v_mov_b32_e32 v38, v0
	v_mov_b32_e32 v39, v0
	v_mov_b32_e32 v40, v0
	v_mov_b32_e32 v41, v0
	v_mov_b32_e32 v42, v0
	v_mov_b32_e32 v43, v0
	v_mov_b32_e32 v44, v0
	v_mov_b32_e32 v45, v0
	v_mov_b32_e32 v46, v0
	v_mov_b32_e32 v47, v0
	v_mov_b32_e32 v48, v0
	v_mov_b32_e32 v49, v0
	v_mov_b32_e32 v50, v0
	v_mov_b32_e32 v51, v0
	v_mov_b32_e32 v52, v0
	v_mov_b32_e32 v53, v0
	v_mov_b32_e32 v54, v0
	v_mov_b32_e32 v55, v0
	v_mov_b32_e32 v56, v0
	v_mov_b32_e32 v57, v0
	v_mov_b32_e32 v58, v0
	v_mov_b32_e32 v59, v0
	v_mov_b32_e32 v60, v0
	v_mov_b32_e32 v61, v0
	v_mov_b32_e32 v62, v0
	v_mov_b32_e32 v63, v0
	v_readfirstlane_b32 s64, v78
	v_readfirstlane_b32 s65, v79
	v_readfirstlane_b32 s66, v76
	v_readfirstlane_b32 s67, v77
	v_readfirstlane_b32 s62, v80
	s_sub_u32 s64, s64, 0x80000000
	s_subb_u32 s65, s65, 0
	s_sub_u32 s66, s66, 0x80000000
	s_subb_u32 s67, s67, 0
	v_subrev_u32_e32 v78, s64, v78
	v_subrev_u32_e32 v76, s66, v76
	v_subrev_u32_e32 v74, s64, v74
	v_subrev_u32_e32 v72, s66, v72
	v_subrev_u32_e32 v70, s64, v70
	v_subrev_u32_e32 v68, s66, v68
	v_subrev_u32_e32 v66, s64, v66
	v_subrev_u32_e32 v64, s66, v64
	s_waitcnt vmcnt(0) lgkmcnt(0)
	s_barrier
.LBB0_400:
	s_add_i32 s16, s6, 0xffff8000
	s_and_b32 s16, s16, 0x8000
	v_add_u32_e32 v85, s16, v81
	v_add_u32_e32 v90, s16, v84
	v_or_b32_e32 v91, s16, v82
	v_or_b32_e32 v95, s16, v83
	s_and_b32 s16, s6, 0x8000
	s_add_i32 s16, s16, s62
	s_mov_b32 m0, s16
	ds_read_b128 v[86:89], v85
	global_load_lds_dwordx4 v78, s[64:65]
	ds_read_b128 v[96:99], v85 offset:2048
	s_add_i32 m0, s16, 0x4000
	ds_read_b128 v[100:103], v85 offset:4096
	global_load_lds_dwordx4 v76, s[66:67]
	ds_read_b128 v[104:107], v85 offset:6144
	s_add_i32 m0, s16, 0x400
	ds_read_b128 v[108:111], v91
	global_load_lds_dwordx4 v74, s[64:65]
	ds_read_b128 v[112:115], v91 offset:2048
	s_add_i32 m0, s16, 0x4400
	ds_read_b128 v[116:119], v91 offset:8192
	global_load_lds_dwordx4 v72, s[66:67]
	ds_read_b128 v[120:123], v91 offset:10240
	ds_read_b128 v[124:127], v90
	ds_read_b128 v[128:131], v90 offset:2048
	ds_read_b128 v[132:135], v90 offset:4096
	ds_read_b128 v[136:139], v90 offset:6144
	ds_read_b128 v[140:143], v95
	ds_read_b128 v[144:147], v95 offset:2048
	ds_read_b128 v[148:151], v95 offset:8192
	ds_read_b128 v[152:155], v95 offset:10240
	s_waitcnt lgkmcnt(8)
	s_setprio 1
	v_mfma_f32_16x16x32_bf16 v[60:63], v[108:111], v[86:89], v[60:63]
	v_mfma_f32_16x16x32_bf16 v[56:59], v[112:115], v[86:89], v[56:59]
	s_add_i32 m0, s16, 0x800
	v_mfma_f32_16x16x32_bf16 v[52:55], v[116:119], v[86:89], v[52:55]
	global_load_lds_dwordx4 v70, s[64:65]
	v_mfma_f32_16x16x32_bf16 v[48:51], v[120:123], v[86:89], v[48:51]
	v_mfma_f32_16x16x32_bf16 v[44:47], v[108:111], v[96:99], v[44:47]
	v_mfma_f32_16x16x32_bf16 v[40:43], v[112:115], v[96:99], v[40:43]
	s_add_i32 m0, s16, 0x4800
	v_mfma_f32_16x16x32_bf16 v[36:39], v[116:119], v[96:99], v[36:39]
	global_load_lds_dwordx4 v68, s[66:67]
	v_mfma_f32_16x16x32_bf16 v[32:35], v[120:123], v[96:99], v[32:35]
	v_mfma_f32_16x16x32_bf16 v[28:31], v[108:111], v[100:103], v[28:31]
	v_mfma_f32_16x16x32_bf16 v[24:27], v[112:115], v[100:103], v[24:27]
	s_add_i32 m0, s16, 0xc00
	v_mfma_f32_16x16x32_bf16 v[20:23], v[116:119], v[100:103], v[20:23]
	global_load_lds_dwordx4 v66, s[64:65]
	v_mfma_f32_16x16x32_bf16 v[16:19], v[120:123], v[100:103], v[16:19]
	v_mfma_f32_16x16x32_bf16 v[12:15], v[108:111], v[104:107], v[12:15]
	v_mfma_f32_16x16x32_bf16 v[8:11], v[112:115], v[104:107], v[8:11]
	s_add_i32 m0, s16, 0x4c00
	v_mfma_f32_16x16x32_bf16 v[4:7], v[116:119], v[104:107], v[4:7]
	global_load_lds_dwordx4 v64, s[66:67]
	v_mfma_f32_16x16x32_bf16 v[0:3], v[120:123], v[104:107], v[0:3]
	s_waitcnt lgkmcnt(0)
	s_nop 0
	v_mfma_f32_16x16x32_bf16 v[60:63], v[140:143], v[124:127], v[60:63]
	v_mfma_f32_16x16x32_bf16 v[56:59], v[144:147], v[124:127], v[56:59]
	v_mfma_f32_16x16x32_bf16 v[52:55], v[148:151], v[124:127], v[52:55]
	v_mfma_f32_16x16x32_bf16 v[48:51], v[152:155], v[124:127], v[48:51]
	v_mfma_f32_16x16x32_bf16 v[44:47], v[140:143], v[128:131], v[44:47]
	v_mfma_f32_16x16x32_bf16 v[40:43], v[144:147], v[128:131], v[40:43]
	v_mfma_f32_16x16x32_bf16 v[36:39], v[148:151], v[128:131], v[36:39]
	v_mfma_f32_16x16x32_bf16 v[32:35], v[152:155], v[128:131], v[32:35]
	v_mfma_f32_16x16x32_bf16 v[28:31], v[140:143], v[132:135], v[28:31]
	v_mfma_f32_16x16x32_bf16 v[24:27], v[144:147], v[132:135], v[24:27]
	v_mfma_f32_16x16x32_bf16 v[20:23], v[148:151], v[132:135], v[20:23]
	v_mfma_f32_16x16x32_bf16 v[16:19], v[152:155], v[132:135], v[16:19]
	v_mfma_f32_16x16x32_bf16 v[12:15], v[140:143], v[136:139], v[12:15]
	v_mfma_f32_16x16x32_bf16 v[8:11], v[144:147], v[136:139], v[8:11]
	v_mfma_f32_16x16x32_bf16 v[4:7], v[148:151], v[136:139], v[4:7]
	v_mfma_f32_16x16x32_bf16 v[0:3], v[152:155], v[136:139], v[0:3]
	s_setprio 0
	s_waitcnt vmcnt(0)
	s_add_u32 s4, s4, 0x80
	s_addc_u32 s5, s5, 0
	s_add_u32 s64, s64, 0x80
	s_addc_u32 s65, s65, 0
	s_add_u32 s66, s66, 0x80
	s_addc_u32 s67, s67, 0
	s_add_i32 s6, s6, 0x8000
	s_cmpk_lg_i32 s4, 0xf80
	s_waitcnt vmcnt(0) lgkmcnt(0)
	s_barrier
	s_cbranch_scc1 .LBB0_400
; DEV f32x4 mma_step(bf16x8 a, bf16x8 b, f32x4 c) { return MFMA(a, b, c); }
; DEV i32x4 mma_step(i32x4 a, i32x4 b, i32x4 c) { return __builtin_amdgcn_mfma_i32_16x16x64_i8(a, b, c, 0, 0, 0); }
; #define P (*launderP(lp))
; template <class FragT, class AccT>
; DEV void gemm_core_t(const char* __restrict__ A, size_t lda_bytes, const char* __restrict__ Bt, size_t ldb_bytes, int kbytes,
;                      int m0, int n0, int Sshift, int dl, char* smem, AccT (&acc)[4][4]) {
;     ...
;     for (int i = 0; i < 4; ++i)
; #pragma unroll
;       for (int j = 0; j < 4; ++j) acc[i][j] = mma_step(wb[0][j], xa[0][i], acc[i][j]);
;     asm volatile("s_waitcnt lgkmcnt(0)"
;                  : "+v"(xa[1][0]), "+v"(xa[1][1]), "+v"(xa[1][2]), "+v"(xa[1][3]), "+v"(wb[1][0]), "+v"(wb[1][1]), "+v"(wb[1][2]),
;                    "+v"(wb[1][3]), "+v"(acc[0][0]), "+v"(acc[0][1]), "+v"(acc[0][2]), "+v"(acc[0][3]), "+v"(acc[1][0]),
;                    "+v"(acc[1][1]), "+v"(acc[1][2]), "+v"(acc[1][3]), "+v"(acc[2][0]), "+v"(acc[2][1]), "+v"(acc[2][2]),
;                    "+v"(acc[2][3]), "+v"(acc[3][0]), "+v"(acc[3][1]), "+v"(acc[3][2]), "+v"(acc[3][3])
;                  :
;                  : "memory");
; #pragma unroll
;     for (int i = 0; i < 4; ++i)
; #pragma unroll
;       for (int j = 0; j < 4; ++j) acc[i][j] = mma_step(wb[1][j], xa[1][i], acc[i][j]);
; __device__ __forceinline__ void phase_gemm2(PREF P, char* smem) {
;     ...
; #pragma unroll
;     for (int i = 0; i < 4; ++i)
; #pragma unroll
;       for (int j = 0; j < 4; ++j) {
;         const int row = m0 + wm * 64 + i * 16 + l15, col = n0 + (j & 1) * 16 + wn * 32 + (j >> 1) * 64 + q * 4;
;         const unsigned g = *(const unsigned*)((const u8*)P.GA + (size_t)row * 2048 + col);
;         f32x4 v;
;         v[0] = (float)(g & 255u) * (1.f / 255.f) * acc[i][j][0]; v[1] = (float)((g >> 8) & 255u) * (1.f / 255.f) * acc[i][j][1];
;         v[2] = (float)((g >> 16) & 255u) * (1.f / 255.f) * acc[i][j][2]; v[3] = (float)(g >> 24) * (1.f / 255.f) * acc[i][j][3];
;         store_nat(P.merged, 2048, row, col, v);
;       }
	v_add_u32_e32 v95, 0x8000, v81
	v_add_u32_e32 v132, 0x8000, v84
	v_or_b32_e32 v133, 0x8000, v82
	v_or_b32_e32 v134, 0x8000, v83
	ds_read_b128 v[64:67], v95
	ds_read_b128 v[68:71], v95 offset:2048
	ds_read_b128 v[72:75], v95 offset:4096
	ds_read_b128 v[76:79], v95 offset:6144
	ds_read_b128 v[80:83], v133
	ds_read_b128 v[84:87], v133 offset:2048
	ds_read_b128 v[88:91], v133 offset:8192
	ds_read_b128 v[96:99], v133 offset:10240
	ds_read_b128 v[100:103], v132
	ds_read_b128 v[104:107], v132 offset:2048
	ds_read_b128 v[108:111], v132 offset:4096
	ds_read_b128 v[112:115], v132 offset:6144
	ds_read_b128 v[116:119], v134
	ds_read_b128 v[120:123], v134 offset:2048
	ds_read_b128 v[124:127], v134 offset:8192
	ds_read_b128 v[128:131], v134 offset:10240
	s_waitcnt lgkmcnt(8)
	s_mov_b32 s16, 0x8000
	s_setprio 1
	v_mfma_f32_16x16x32_bf16 v[60:63], v[80:83], v[64:67], v[60:63]
	v_mfma_f32_16x16x32_bf16 v[56:59], v[84:87], v[64:67], v[56:59]
	v_mfma_f32_16x16x32_bf16 v[52:55], v[88:91], v[64:67], v[52:55]
	v_mfma_f32_16x16x32_bf16 v[48:51], v[96:99], v[64:67], v[48:51]
	v_mfma_f32_16x16x32_bf16 v[44:47], v[80:83], v[68:71], v[44:47]
	v_mfma_f32_16x16x32_bf16 v[40:43], v[84:87], v[68:71], v[40:43]
	v_mfma_f32_16x16x32_bf16 v[36:39], v[88:91], v[68:71], v[36:39]
	v_mfma_f32_16x16x32_bf16 v[32:35], v[96:99], v[68:71], v[32:35]
	v_mfma_f32_16x16x32_bf16 v[28:31], v[80:83], v[72:75], v[28:31]
	v_mfma_f32_16x16x32_bf16 v[24:27], v[84:87], v[72:75], v[24:27]
	v_mfma_f32_16x16x32_bf16 v[20:23], v[88:91], v[72:75], v[20:23]
	v_mfma_f32_16x16x32_bf16 v[16:19], v[96:99], v[72:75], v[16:19]
	v_mfma_f32_16x16x32_bf16 v[12:15], v[80:83], v[76:79], v[12:15]
	v_mfma_f32_16x16x32_bf16 v[8:11], v[84:87], v[76:79], v[8:11]
	v_mfma_f32_16x16x32_bf16 v[4:7], v[88:91], v[76:79], v[4:7]
	v_mfma_f32_16x16x32_bf16 v[0:3], v[96:99], v[76:79], v[0:3]
	s_waitcnt lgkmcnt(0)
	s_nop 0
	v_mfma_f32_16x16x32_bf16 v[60:63], v[116:119], v[100:103], v[60:63]
	v_mfma_f32_16x16x32_bf16 v[70:73], v[120:123], v[100:103], v[56:59]
	v_mfma_f32_16x16x32_bf16 v[52:55], v[124:127], v[100:103], v[52:55]
	v_mfma_f32_16x16x32_bf16 v[48:51], v[128:131], v[100:103], v[48:51]
	v_mfma_f32_16x16x32_bf16 v[44:47], v[116:119], v[104:107], v[44:47]
	v_mfma_f32_16x16x32_bf16 v[40:43], v[120:123], v[104:107], v[40:43]
	v_mfma_f32_16x16x32_bf16 v[36:39], v[124:127], v[104:107], v[36:39]
	v_mfma_f32_16x16x32_bf16 v[32:35], v[128:131], v[104:107], v[32:35]
	v_mfma_f32_16x16x32_bf16 v[28:31], v[116:119], v[108:111], v[28:31]
	v_mfma_f32_16x16x32_bf16 v[24:27], v[120:123], v[108:111], v[24:27]
	v_mfma_f32_16x16x32_bf16 v[20:23], v[124:127], v[108:111], v[20:23]
	v_mfma_f32_16x16x32_bf16 v[16:19], v[128:131], v[108:111], v[16:19]
	v_mfma_f32_16x16x32_bf16 v[12:15], v[116:119], v[112:115], v[12:15]
	v_mfma_f32_16x16x32_bf16 v[8:11], v[120:123], v[112:115], v[8:11]
	v_mfma_f32_16x16x32_bf16 v[4:7], v[124:127], v[112:115], v[4:7]
	v_mfma_f32_16x16x32_bf16 v[0:3], v[128:131], v[112:115], v[0:3]
	s_setprio 0
	s_waitcnt vmcnt(0)
	s_barrier
	ds_read_b64 v[66:67], v92 offset:296
	ds_read_b64 v[74:75], v92 offset:336
	v_add_u32_e32 v56, s15, v93
	v_ashrrev_i32_e32 v57, 31, v56
	v_or_b32_e32 v64, s0, v94
	v_lshlrev_b64 v[68:69], 11, v[56:57]
	s_waitcnt lgkmcnt(1)
	v_lshl_add_u64 v[66:67], v[66:67], 0, v[68:69]
	v_ashrrev_i32_e32 v65, 31, v64
	v_lshl_add_u64 v[66:67], v[66:67], 0, v[64:65]
	v_lshlrev_b64 v[58:59], 12, v[56:57]
	flat_load_dword v57, v[66:67]
	s_mov_b32 s4, 0x3b808081
	s_add_i32 s18, s18, s17
	s_waitcnt vmcnt(0) lgkmcnt(0)
	v_cvt_f32_ubyte1_e32 v67, v57
	v_cvt_f32_ubyte0_e32 v66, v57
	v_pk_mul_f32 v[66:67], v[66:67], s[4:5] op_sel_hi:[1,0]
	s_nop 0
	v_pk_mul_f32 v[60:61], v[60:61], v[66:67]
	v_cvt_f32_ubyte3_e32 v67, v57
	v_cvt_f32_ubyte2_e32 v66, v57
	v_pk_mul_f32 v[66:67], v[66:67], s[4:5] op_sel_hi:[1,0]
	v_cvt_pk_bf16_f32 v60, v60, v61
	v_pk_mul_f32 v[62:63], v[62:63], v[66:67]
	v_lshlrev_b64 v[66:67], 1, v[64:65]
	v_cvt_pk_bf16_f32 v61, v62, v63
	v_lshl_add_u64 v[62:63], v[74:75], 0, v[58:59]
	v_lshl_add_u64 v[62:63], v[62:63], 0, v[66:67]
	flat_store_dwordx2 v[62:63], v[60:61]
	ds_read_b64 v[60:61], v92 offset:296
	ds_read_b64 v[62:63], v92 offset:336
	s_waitcnt lgkmcnt(0)
	v_lshl_add_u64 v[60:61], v[60:61], 0, v[68:69]
	v_lshl_add_u64 v[60:61], v[60:61], 0, v[64:65]
	flat_load_dword v57, v[60:61] offset:16
	v_lshl_add_u64 v[62:63], v[62:63], 0, v[58:59]
	v_lshl_add_u64 v[62:63], v[62:63], 0, v[66:67]
	s_waitcnt vmcnt(0) lgkmcnt(0)
	v_cvt_f32_ubyte1_e32 v61, v57
	v_cvt_f32_ubyte0_e32 v60, v57
	v_pk_mul_f32 v[60:61], v[60:61], s[4:5] op_sel_hi:[1,0]
	s_nop 0
	v_pk_mul_f32 v[60:61], v[70:71], v[60:61]
	v_cvt_f32_ubyte3_e32 v71, v57
	v_cvt_f32_ubyte2_e32 v70, v57
	v_pk_mul_f32 v[70:71], v[70:71], s[4:5] op_sel_hi:[1,0]
	v_cvt_pk_bf16_f32 v60, v60, v61
	v_pk_mul_f32 v[70:71], v[72:73], v[70:71]
	s_nop 0
	v_cvt_pk_bf16_f32 v61, v70, v71
	flat_store_dwordx2 v[62:63], v[60:61] offset:32
	ds_read_b64 v[60:61], v92 offset:296
	ds_read_b64 v[62:63], v92 offset:336
	s_waitcnt lgkmcnt(0)
	v_lshl_add_u64 v[60:61], v[60:61], 0, v[68:69]
	v_lshl_add_u64 v[60:61], v[60:61], 0, v[64:65]
	flat_load_dword v57, v[60:61] offset:64
	s_waitcnt vmcnt(0) lgkmcnt(0)
	v_cvt_f32_ubyte1_e32 v61, v57
	v_cvt_f32_ubyte0_e32 v60, v57
	v_pk_mul_f32 v[60:61], v[60:61], s[4:5] op_sel_hi:[1,0]
	s_nop 0
	v_pk_mul_f32 v[52:53], v[52:53], v[60:61]
	v_cvt_f32_ubyte3_e32 v61, v57
	v_cvt_f32_ubyte2_e32 v60, v57
	v_pk_mul_f32 v[60:61], v[60:61], s[4:5] op_sel_hi:[1,0]
	v_cvt_pk_bf16_f32 v52, v52, v53
	v_pk_mul_f32 v[54:55], v[54:55], v[60:61]
	s_nop 0
	v_cvt_pk_bf16_f32 v53, v54, v55
	v_lshl_add_u64 v[54:55], v[62:63], 0, v[58:59]
	v_lshl_add_u64 v[54:55], v[54:55], 0, v[66:67]
	flat_store_dwordx2 v[54:55], v[52:53] offset:128
	ds_read_b64 v[52:53], v92 offset:296
	ds_read_b64 v[54:55], v92 offset:336
	s_waitcnt lgkmcnt(0)
; #define P (*launderP(lp))
; __device__ __forceinline__ void phase_gemm2(PREF P, char* smem) {
;     ...
; #pragma unroll
;     for (int i = 0; i < 4; ++i)
; #pragma unroll
;       for (int j = 0; j < 4; ++j) {
;         const int row = m0 + wm * 64 + i * 16 + l15, col = n0 + (j & 1) * 16 + wn * 32 + (j >> 1) * 64 + q * 4;
;         const unsigned g = *(const unsigned*)((const u8*)P.GA + (size_t)row * 2048 + col);
;         f32x4 v;
;         v[0] = (float)(g & 255u) * (1.f / 255.f) * acc[i][j][0]; v[1] = (float)((g >> 8) & 255u) * (1.f / 255.f) * acc[i][j][1];
;         v[2] = (float)((g >> 16) & 255u) * (1.f / 255.f) * acc[i][j][2]; v[3] = (float)(g >> 24) * (1.f / 255.f) * acc[i][j][3];
;         store_nat(P.merged, 2048, row, col, v);
;       }
	v_lshl_add_u64 v[52:53], v[52:53], 0, v[68:69]
	v_lshl_add_u64 v[52:53], v[52:53], 0, v[64:65]
	flat_load_dword v57, v[52:53] offset:80
	s_waitcnt vmcnt(0) lgkmcnt(0)
	v_cvt_f32_ubyte1_e32 v53, v57
	v_cvt_f32_ubyte0_e32 v52, v57
	v_pk_mul_f32 v[52:53], v[52:53], s[4:5] op_sel_hi:[1,0]
	s_nop 0
	v_pk_mul_f32 v[48:49], v[48:49], v[52:53]
	v_cvt_f32_ubyte3_e32 v53, v57
	v_cvt_f32_ubyte2_e32 v52, v57
	v_pk_mul_f32 v[52:53], v[52:53], s[4:5] op_sel_hi:[1,0]
	v_cvt_pk_bf16_f32 v48, v48, v49
	v_pk_mul_f32 v[50:51], v[50:51], v[52:53]
	s_nop 0
	v_cvt_pk_bf16_f32 v49, v50, v51
	v_lshl_add_u64 v[50:51], v[54:55], 0, v[58:59]
	v_lshl_add_u64 v[50:51], v[50:51], 0, v[66:67]
	flat_store_dwordx2 v[50:51], v[48:49] offset:160
	ds_read_b64 v[50:51], v92 offset:296
	ds_read_b64 v[52:53], v92 offset:336
	v_or_b32_e32 v48, 16, v56
	v_ashrrev_i32_e32 v49, 31, v48
	v_lshlrev_b64 v[72:73], 11, v[48:49]
	s_waitcnt lgkmcnt(0)
	v_lshl_add_u64 v[50:51], v[50:51], 0, v[72:73]
	v_lshl_add_u64 v[50:51], v[50:51], 0, v[64:65]
	flat_load_dword v54, v[50:51]
	v_lshlrev_b64 v[48:49], 12, v[48:49]
	s_waitcnt vmcnt(0) lgkmcnt(0)
	v_cvt_f32_ubyte1_e32 v51, v54
	v_cvt_f32_ubyte0_e32 v50, v54
	v_pk_mul_f32 v[50:51], v[50:51], s[4:5] op_sel_hi:[1,0]
	s_nop 0
	v_pk_mul_f32 v[44:45], v[44:45], v[50:51]
	v_cvt_f32_ubyte3_e32 v51, v54
	v_cvt_f32_ubyte2_e32 v50, v54
	v_pk_mul_f32 v[50:51], v[50:51], s[4:5] op_sel_hi:[1,0]
	v_cvt_pk_bf16_f32 v44, v44, v45
	v_pk_mul_f32 v[46:47], v[46:47], v[50:51]
	s_nop 0
	v_cvt_pk_bf16_f32 v45, v46, v47
	v_lshl_add_u64 v[46:47], v[52:53], 0, v[48:49]
	v_lshl_add_u64 v[46:47], v[46:47], 0, v[66:67]
	flat_store_dwordx2 v[46:47], v[44:45]
	ds_read_b64 v[44:45], v92 offset:296
	ds_read_b64 v[46:47], v92 offset:336
	s_waitcnt lgkmcnt(0)
	v_lshl_add_u64 v[44:45], v[44:45], 0, v[72:73]
	v_lshl_add_u64 v[44:45], v[44:45], 0, v[64:65]
	flat_load_dword v50, v[44:45] offset:16
	s_waitcnt vmcnt(0) lgkmcnt(0)
	v_cvt_f32_ubyte1_e32 v45, v50
	v_cvt_f32_ubyte0_e32 v44, v50
	v_pk_mul_f32 v[44:45], v[44:45], s[4:5] op_sel_hi:[1,0]
	s_nop 0
	v_pk_mul_f32 v[40:41], v[40:41], v[44:45]
	v_cvt_f32_ubyte3_e32 v45, v50
	v_cvt_f32_ubyte2_e32 v44, v50
	v_pk_mul_f32 v[44:45], v[44:45], s[4:5] op_sel_hi:[1,0]
	v_cvt_pk_bf16_f32 v40, v40, v41
	v_pk_mul_f32 v[42:43], v[42:43], v[44:45]
	s_nop 0
	v_cvt_pk_bf16_f32 v41, v42, v43
	v_lshl_add_u64 v[42:43], v[46:47], 0, v[48:49]
	v_lshl_add_u64 v[42:43], v[42:43], 0, v[66:67]
	flat_store_dwordx2 v[42:43], v[40:41] offset:32
	ds_read_b64 v[40:41], v92 offset:296
	ds_read_b64 v[42:43], v92 offset:336
	s_waitcnt lgkmcnt(0)
	v_lshl_add_u64 v[40:41], v[40:41], 0, v[72:73]
	v_lshl_add_u64 v[40:41], v[40:41], 0, v[64:65]
	flat_load_dword v44, v[40:41] offset:64
	s_waitcnt vmcnt(0) lgkmcnt(0)
	v_cvt_f32_ubyte1_e32 v41, v44
	v_cvt_f32_ubyte0_e32 v40, v44
	v_pk_mul_f32 v[40:41], v[40:41], s[4:5] op_sel_hi:[1,0]
	s_nop 0
	v_pk_mul_f32 v[36:37], v[36:37], v[40:41]
	v_cvt_f32_ubyte3_e32 v41, v44
	v_cvt_f32_ubyte2_e32 v40, v44
	v_pk_mul_f32 v[40:41], v[40:41], s[4:5] op_sel_hi:[1,0]
	v_cvt_pk_bf16_f32 v36, v36, v37
	v_pk_mul_f32 v[38:39], v[38:39], v[40:41]
	s_nop 0
	v_cvt_pk_bf16_f32 v37, v38, v39
	v_lshl_add_u64 v[38:39], v[42:43], 0, v[48:49]
	v_lshl_add_u64 v[38:39], v[38:39], 0, v[66:67]
	flat_store_dwordx2 v[38:39], v[36:37] offset:128
	ds_read_b64 v[36:37], v92 offset:296
	ds_read_b64 v[38:39], v92 offset:336
	s_waitcnt lgkmcnt(0)
	v_lshl_add_u64 v[36:37], v[36:37], 0, v[72:73]
	v_lshl_add_u64 v[36:37], v[36:37], 0, v[64:65]
	flat_load_dword v40, v[36:37] offset:80
	s_waitcnt vmcnt(0) lgkmcnt(0)
	v_cvt_f32_ubyte1_e32 v37, v40
	v_cvt_f32_ubyte0_e32 v36, v40
	v_pk_mul_f32 v[36:37], v[36:37], s[4:5] op_sel_hi:[1,0]
	s_nop 0
	v_pk_mul_f32 v[32:33], v[32:33], v[36:37]
	v_cvt_f32_ubyte3_e32 v37, v40
	v_cvt_f32_ubyte2_e32 v36, v40
	v_pk_mul_f32 v[36:37], v[36:37], s[4:5] op_sel_hi:[1,0]
	v_cvt_pk_bf16_f32 v32, v32, v33
	v_pk_mul_f32 v[34:35], v[34:35], v[36:37]
	s_nop 0
	v_cvt_pk_bf16_f32 v33, v34, v35
	v_lshl_add_u64 v[34:35], v[38:39], 0, v[48:49]
	v_lshl_add_u64 v[34:35], v[34:35], 0, v[66:67]
	flat_store_dwordx2 v[34:35], v[32:33] offset:160
	ds_read_b64 v[34:35], v92 offset:296
	ds_read_b64 v[36:37], v92 offset:336
	v_or_b32_e32 v32, 32, v56
	v_ashrrev_i32_e32 v33, 31, v32
	v_lshlrev_b64 v[74:75], 11, v[32:33]
	s_waitcnt lgkmcnt(0)
	v_lshl_add_u64 v[34:35], v[34:35], 0, v[74:75]
	v_lshl_add_u64 v[34:35], v[34:35], 0, v[64:65]
	flat_load_dword v38, v[34:35]
	v_lshlrev_b64 v[32:33], 12, v[32:33]
	s_waitcnt vmcnt(0) lgkmcnt(0)
	v_cvt_f32_ubyte1_e32 v35, v38
	v_cvt_f32_ubyte0_e32 v34, v38
	v_pk_mul_f32 v[34:35], v[34:35], s[4:5] op_sel_hi:[1,0]
	s_nop 0
	v_pk_mul_f32 v[28:29], v[28:29], v[34:35]
	v_cvt_f32_ubyte3_e32 v35, v38
	v_cvt_f32_ubyte2_e32 v34, v38
	v_pk_mul_f32 v[34:35], v[34:35], s[4:5] op_sel_hi:[1,0]
	v_cvt_pk_bf16_f32 v28, v28, v29
	v_pk_mul_f32 v[30:31], v[30:31], v[34:35]
	s_nop 0
	v_cvt_pk_bf16_f32 v29, v30, v31
	v_lshl_add_u64 v[30:31], v[36:37], 0, v[32:33]
	v_lshl_add_u64 v[30:31], v[30:31], 0, v[66:67]
	flat_store_dwordx2 v[30:31], v[28:29]
	ds_read_b64 v[28:29], v92 offset:296
	ds_read_b64 v[30:31], v92 offset:336
	s_waitcnt lgkmcnt(0)
	v_lshl_add_u64 v[28:29], v[28:29], 0, v[74:75]
	v_lshl_add_u64 v[28:29], v[28:29], 0, v[64:65]
	flat_load_dword v34, v[28:29] offset:16
	s_waitcnt vmcnt(0) lgkmcnt(0)
; #define P (*launderP(lp))
; __device__ __forceinline__ void phase_gemm2(PREF P, char* smem) {
;     ...
; #pragma unroll
;     for (int i = 0; i < 4; ++i)
; #pragma unroll
;       for (int j = 0; j < 4; ++j) {
;         const int row = m0 + wm * 64 + i * 16 + l15, col = n0 + (j & 1) * 16 + wn * 32 + (j >> 1) * 64 + q * 4;
;         const unsigned g = *(const unsigned*)((const u8*)P.GA + (size_t)row * 2048 + col);
;         f32x4 v;
;         v[0] = (float)(g & 255u) * (1.f / 255.f) * acc[i][j][0]; v[1] = (float)((g >> 8) & 255u) * (1.f / 255.f) * acc[i][j][1];
;         v[2] = (float)((g >> 16) & 255u) * (1.f / 255.f) * acc[i][j][2]; v[3] = (float)(g >> 24) * (1.f / 255.f) * acc[i][j][3];
;         store_nat(P.merged, 2048, row, col, v);
;       }
	v_cvt_f32_ubyte1_e32 v29, v34
	v_cvt_f32_ubyte0_e32 v28, v34
	v_pk_mul_f32 v[28:29], v[28:29], s[4:5] op_sel_hi:[1,0]
	s_nop 0
	v_pk_mul_f32 v[24:25], v[24:25], v[28:29]
	v_cvt_f32_ubyte3_e32 v29, v34
	v_cvt_f32_ubyte2_e32 v28, v34
	v_pk_mul_f32 v[28:29], v[28:29], s[4:5] op_sel_hi:[1,0]
	v_cvt_pk_bf16_f32 v24, v24, v25
	v_pk_mul_f32 v[26:27], v[26:27], v[28:29]
	s_nop 0
	v_cvt_pk_bf16_f32 v25, v26, v27
	v_lshl_add_u64 v[26:27], v[30:31], 0, v[32:33]
	v_lshl_add_u64 v[26:27], v[26:27], 0, v[66:67]
	flat_store_dwordx2 v[26:27], v[24:25] offset:32
	ds_read_b64 v[24:25], v92 offset:296
	ds_read_b64 v[26:27], v92 offset:336
	s_waitcnt lgkmcnt(0)
	v_lshl_add_u64 v[24:25], v[24:25], 0, v[74:75]
	v_lshl_add_u64 v[24:25], v[24:25], 0, v[64:65]
	flat_load_dword v28, v[24:25] offset:64
	s_waitcnt vmcnt(0) lgkmcnt(0)
	v_cvt_f32_ubyte1_e32 v25, v28
	v_cvt_f32_ubyte0_e32 v24, v28
	v_pk_mul_f32 v[24:25], v[24:25], s[4:5] op_sel_hi:[1,0]
	s_nop 0
	v_pk_mul_f32 v[20:21], v[20:21], v[24:25]
	v_cvt_f32_ubyte3_e32 v25, v28
	v_cvt_f32_ubyte2_e32 v24, v28
	v_pk_mul_f32 v[24:25], v[24:25], s[4:5] op_sel_hi:[1,0]
	v_cvt_pk_bf16_f32 v20, v20, v21
	v_pk_mul_f32 v[22:23], v[22:23], v[24:25]
	s_nop 0
	v_cvt_pk_bf16_f32 v21, v22, v23
	v_lshl_add_u64 v[22:23], v[26:27], 0, v[32:33]
	v_lshl_add_u64 v[22:23], v[22:23], 0, v[66:67]
	flat_store_dwordx2 v[22:23], v[20:21] offset:128
	ds_read_b64 v[20:21], v92 offset:296
	ds_read_b64 v[22:23], v92 offset:336
	s_waitcnt lgkmcnt(0)
	v_lshl_add_u64 v[20:21], v[20:21], 0, v[74:75]
	v_lshl_add_u64 v[20:21], v[20:21], 0, v[64:65]
	flat_load_dword v24, v[20:21] offset:80
	s_waitcnt vmcnt(0) lgkmcnt(0)
	v_cvt_f32_ubyte1_e32 v21, v24
	v_cvt_f32_ubyte0_e32 v20, v24
	v_pk_mul_f32 v[20:21], v[20:21], s[4:5] op_sel_hi:[1,0]
	s_nop 0
	v_pk_mul_f32 v[16:17], v[16:17], v[20:21]
	v_cvt_f32_ubyte3_e32 v21, v24
	v_cvt_f32_ubyte2_e32 v20, v24
	v_pk_mul_f32 v[20:21], v[20:21], s[4:5] op_sel_hi:[1,0]
	v_cvt_pk_bf16_f32 v16, v16, v17
	v_pk_mul_f32 v[18:19], v[18:19], v[20:21]
	v_mov_b32_e32 v24, v188
	v_cvt_pk_bf16_f32 v17, v18, v19
	v_lshl_add_u64 v[18:19], v[22:23], 0, v[32:33]
	v_lshl_add_u64 v[18:19], v[18:19], 0, v[66:67]
	flat_store_dwordx2 v[18:19], v[16:17] offset:160
	ds_read_b64 v[18:19], v92 offset:296
	ds_read_b64 v[20:21], v92 offset:336
	v_or_b32_e32 v16, 48, v56
	v_ashrrev_i32_e32 v17, 31, v16
	v_lshlrev_b64 v[70:71], 11, v[16:17]
	s_waitcnt lgkmcnt(0)
	v_lshl_add_u64 v[18:19], v[18:19], 0, v[70:71]
	v_lshl_add_u64 v[18:19], v[18:19], 0, v[64:65]
	flat_load_dword v22, v[18:19]
	v_lshlrev_b64 v[16:17], 12, v[16:17]
	s_waitcnt vmcnt(0) lgkmcnt(0)
	v_cvt_f32_ubyte1_e32 v19, v22
	v_cvt_f32_ubyte0_e32 v18, v22
	v_pk_mul_f32 v[18:19], v[18:19], s[4:5] op_sel_hi:[1,0]
	s_nop 0
	v_pk_mul_f32 v[12:13], v[12:13], v[18:19]
	v_cvt_f32_ubyte3_e32 v19, v22
	v_cvt_f32_ubyte2_e32 v18, v22
	v_pk_mul_f32 v[18:19], v[18:19], s[4:5] op_sel_hi:[1,0]
	v_cvt_pk_bf16_f32 v12, v12, v13
	v_pk_mul_f32 v[14:15], v[14:15], v[18:19]
	s_nop 0
	v_cvt_pk_bf16_f32 v13, v14, v15
	v_lshl_add_u64 v[14:15], v[20:21], 0, v[16:17]
	v_lshl_add_u64 v[14:15], v[14:15], 0, v[66:67]
	flat_store_dwordx2 v[14:15], v[12:13]
	ds_read_b64 v[12:13], v92 offset:296
	ds_read_b64 v[14:15], v92 offset:336
	s_waitcnt lgkmcnt(0)
	v_lshl_add_u64 v[12:13], v[12:13], 0, v[70:71]
	v_lshl_add_u64 v[12:13], v[12:13], 0, v[64:65]
	flat_load_dword v18, v[12:13] offset:16
	s_waitcnt vmcnt(0) lgkmcnt(0)
	v_cvt_f32_ubyte1_e32 v13, v18
	v_cvt_f32_ubyte0_e32 v12, v18
	v_pk_mul_f32 v[12:13], v[12:13], s[4:5] op_sel_hi:[1,0]
	s_nop 0
	v_pk_mul_f32 v[8:9], v[8:9], v[12:13]
	v_cvt_f32_ubyte3_e32 v13, v18
	v_cvt_f32_ubyte2_e32 v12, v18
	v_pk_mul_f32 v[12:13], v[12:13], s[4:5] op_sel_hi:[1,0]
	v_cvt_pk_bf16_f32 v8, v8, v9
	v_pk_mul_f32 v[10:11], v[10:11], v[12:13]
	s_nop 0
	v_cvt_pk_bf16_f32 v9, v10, v11
	v_lshl_add_u64 v[10:11], v[14:15], 0, v[16:17]
	v_lshl_add_u64 v[10:11], v[10:11], 0, v[66:67]
	flat_store_dwordx2 v[10:11], v[8:9] offset:32
	ds_read_b64 v[8:9], v92 offset:296
	ds_read_b64 v[10:11], v92 offset:336
	s_waitcnt lgkmcnt(0)
	v_lshl_add_u64 v[8:9], v[8:9], 0, v[70:71]
	v_lshl_add_u64 v[8:9], v[8:9], 0, v[64:65]
	flat_load_dword v12, v[8:9] offset:64
	s_waitcnt vmcnt(0) lgkmcnt(0)
	v_cvt_f32_ubyte1_e32 v9, v12
	v_cvt_f32_ubyte0_e32 v8, v12
	v_pk_mul_f32 v[8:9], v[8:9], s[4:5] op_sel_hi:[1,0]
	s_nop 0
	v_pk_mul_f32 v[4:5], v[4:5], v[8:9]
	v_cvt_f32_ubyte3_e32 v9, v12
	v_cvt_f32_ubyte2_e32 v8, v12
	v_pk_mul_f32 v[8:9], v[8:9], s[4:5] op_sel_hi:[1,0]
	v_cvt_pk_bf16_f32 v4, v4, v5
	v_pk_mul_f32 v[6:7], v[6:7], v[8:9]
	s_nop 0
	v_cvt_pk_bf16_f32 v5, v6, v7
	v_lshl_add_u64 v[6:7], v[10:11], 0, v[16:17]
	v_lshl_add_u64 v[6:7], v[6:7], 0, v[66:67]
	flat_store_dwordx2 v[6:7], v[4:5] offset:128
	ds_read_b64 v[4:5], v92 offset:296
	ds_read_b64 v[6:7], v92 offset:336
	s_waitcnt lgkmcnt(0)
	v_lshl_add_u64 v[4:5], v[4:5], 0, v[70:71]
	v_lshl_add_u64 v[4:5], v[4:5], 0, v[64:65]
	flat_load_dword v8, v[4:5] offset:80
	s_waitcnt vmcnt(0) lgkmcnt(0)
	v_cvt_f32_ubyte1_e32 v5, v8
	v_cvt_f32_ubyte0_e32 v4, v8
	v_pk_mul_f32 v[4:5], v[4:5], s[4:5] op_sel_hi:[1,0]
	s_nop 0
	v_pk_mul_f32 v[0:1], v[0:1], v[4:5]
	v_cvt_f32_ubyte3_e32 v5, v8
	v_cvt_f32_ubyte2_e32 v4, v8
	v_pk_mul_f32 v[4:5], v[4:5], s[4:5] op_sel_hi:[1,0]
	v_cvt_pk_bf16_f32 v0, v0, v1
	v_pk_mul_f32 v[2:3], v[2:3], v[4:5]
	s_nop 0
	v_cvt_pk_bf16_f32 v1, v2, v3
	v_lshl_add_u64 v[2:3], v[6:7], 0, v[16:17]
	v_lshl_add_u64 v[2:3], v[2:3], 0, v[66:67]
	flat_store_dwordx2 v[2:3], v[0:1] offset:160
	ds_read_b64 v[0:1], v92 offset:328
	ds_read_b64 v[2:3], v92 offset:176
	s_waitcnt lgkmcnt(0)
; DEV int tid_() { int t = threadIdx.x; asm volatile("" : "+v"(t)); return t; }
; #define P (*launderP(lp))
; template <class FragT, class AccT>
; DEV void gemm_core_t(const char* __restrict__ A, size_t lda_bytes, const char* __restrict__ Bt, size_t ldb_bytes, int kbytes,
;                      int m0, int n0, int Sshift, int dl, char* smem, AccT (&acc)[4][4]) {
;   const int tid = tid_(), lane = tid & 63, wid = tid >> 6, wm = wid >> 1, wn = wid & 1;
;   const int l15 = lane & 15, q = lane >> 4;
;   const int srow = lane >> 3, schunk = (lane & 7) ^ (lane >> 3);
;   const char* ap[4];
;   const char* bp[4];
; #pragma unroll
;   for (int u = 0; u < 4; ++u) {
;     int r = (wid * 4 + u) * 8 + srow;
;     int ar = rowmap(m0 + r, Sshift, dl);
;     ap[u] = A + (size_t)ar * lda_bytes + schunk * 16;
;     bp[u] = Bt + (size_t)(n0 + r) * ldb_bytes + schunk * 16;
;   }
; #pragma unroll
;   for (int i = 0; i < 4; ++i)
; #pragma unroll
;     for (int j = 0; j < 4; ++j) acc[i][j] = AccT{0, 0, 0, 0};
;   const int nk = kbytes >> 7;
;   __syncthreads();
; #pragma unroll
;   for (int u = 0; u < 4; ++u) {
;     __builtin_amdgcn_global_load_lds((const unsigned*)ap[u], (unsigned*)(smem + (wid * 4 + u) * 1024 + lane * 16), 16, 0, 0);
;     __builtin_amdgcn_global_load_lds((const unsigned*)bp[u], (unsigned*)(smem + 16384 + (wid * 4 + u) * 1024 + lane * 16), 16, 0, 0);
;   }
;   const unsigned sbase = (unsigned)(unsigned long)((__attribute__((address_space(3))) char*)smem);
;   const unsigned sq0 = (unsigned)((q ^ (l15 & 7)) << 4);
;   const unsigned a0 = sbase + (unsigned)((wm * 64 + l15) * 128) + sq0;
;   const unsigned b0 = sbase + 16384u + (unsigned)((wn * 32 + l15) * 128) + sq0;
;   asm volatile("s_waitcnt vmcnt(0)" ::: "memory");
;   __syncthreads();
; __device__ __forceinline__ void phase_gemm2(PREF P, char* smem) {
;     ...
;     gemm_core(P.att, 1024, P.WattT, 1024, 1024, m0, n0, 13, 0, smem, acc);
	v_ashrrev_i32_e32 v26, 6, v24
	v_bfe_u32 v6, v24, 3, 3
	v_lshlrev_b32_e32 v7, 5, v26
	v_or_b32_e32 v22, v7, v6
	v_or_b32_e32 v16, 8, v22
	v_or_b32_e32 v20, 16, v22
	v_or_b32_e32 v27, 24, v22
	v_bitop3_b32 v4, v6, v24, 7 bitop3:0x78
	v_add_u32_e32 v10, s15, v22
	v_add_u32_e32 v12, s0, v22
	v_add_u32_e32 v14, s15, v16
	v_add_u32_e32 v18, s15, v20
	v_add_u32_e32 v22, s15, v27
	v_lshlrev_b32_e32 v180, 4, v4
	v_ashrrev_i32_e32 v11, 31, v10
	v_ashrrev_i32_e32 v15, 31, v14
	v_ashrrev_i32_e32 v19, 31, v18
	v_ashrrev_i32_e32 v23, 31, v22
	v_lshl_add_u64 v[4:5], v[0:1], 0, v[180:181]
	v_lshlrev_b64 v[10:11], 11, v[10:11]
	v_lshlrev_b64 v[14:15], 11, v[14:15]
	v_lshlrev_b64 v[18:19], 11, v[18:19]
	v_lshlrev_b64 v[22:23], 11, v[22:23]
	v_lshl_add_u64 v[10:11], v[4:5], 0, v[10:11]
	v_lshl_add_u64 v[14:15], v[4:5], 0, v[14:15]
	v_add_u32_e32 v16, s0, v16
	v_lshl_add_u64 v[18:19], v[4:5], 0, v[18:19]
	v_add_u32_e32 v20, s0, v20
	v_lshl_add_u64 v[4:5], v[4:5], 0, v[22:23]
	v_add_u32_e32 v22, s0, v27
	v_ashrrev_i32_e32 v13, 31, v12
	v_ashrrev_i32_e32 v17, 31, v16
	v_ashrrev_i32_e32 v21, 31, v20
	v_ashrrev_i32_e32 v23, 31, v22
	v_lshl_add_u64 v[8:9], v[2:3], 0, v[180:181]
	v_lshlrev_b64 v[12:13], 11, v[12:13]
	v_lshlrev_b64 v[16:17], 11, v[16:17]
	v_lshlrev_b64 v[20:21], 11, v[20:21]
	v_lshlrev_b64 v[22:23], 11, v[22:23]
	v_and_b32_e32 v25, 63, v24
	v_lshl_add_u64 v[12:13], v[8:9], 0, v[12:13]
	v_lshl_add_u64 v[16:17], v[8:9], 0, v[16:17]
	v_lshl_add_u64 v[20:21], v[8:9], 0, v[20:21]
	v_lshl_add_u64 v[8:9], v[8:9], 0, v[22:23]
	v_lshlrev_b32_e32 v23, 12, v26
	v_lshl_or_b32 v95, v25, 4, v23
	s_barrier
	v_readfirstlane_b32 s4, v95
	s_mov_b32 m0, s4
	s_nop 0
	global_load_lds_dwordx4 v[10:11], off
	v_add_u32_e32 v10, 0x4000, v95
	v_and_b32_e32 v22, 15, v24
	v_readfirstlane_b32 s4, v10
	v_or_b32_e32 v10, 0x400, v95
	s_mov_b32 m0, s4
	v_readfirstlane_b32 s4, v10
	v_add_u32_e32 v10, 0x4400, v95
	global_load_lds_dwordx4 v[12:13], off
	s_mov_b32 m0, s4
	v_readfirstlane_b32 s4, v10
	v_or_b32_e32 v10, 0x800, v95
	global_load_lds_dwordx4 v[14:15], off
	s_mov_b32 m0, s4
	v_readfirstlane_b32 s4, v10
	v_add_u32_e32 v10, 0x4800, v95
	global_load_lds_dwordx4 v[16:17], off
	s_mov_b32 m0, s4
	v_readfirstlane_b32 s4, v10
	v_or_b32_e32 v10, 0xc00, v95
	global_load_lds_dwordx4 v[18:19], off
	s_mov_b32 m0, s4
	v_readfirstlane_b32 s4, v10
	global_load_lds_dwordx4 v[20:21], off
	s_mov_b32 m0, s4
	s_nop 0
	global_load_lds_dwordx4 v[4:5], off
	v_add_u32_e32 v4, 0x4c00, v95
	v_lshrrev_b32_e32 v5, 1, v24
	v_readfirstlane_b32 s4, v4
	s_mov_b32 m0, s4
	v_lshlrev_b32_e32 v4, 4, v24
	global_load_lds_dwordx4 v[8:9], off
	v_bitop3_b32 v4, v25, s31, v4 bitop3:0x48
	s_mov_b32 s4, 0x1ffffc0
	v_and_or_b32 v8, v7, 32, v22
	v_and_or_b32 v5, v5, s4, v22
	v_lshl_or_b32 v8, v8, 7, v4
	v_lshlrev_b32_e32 v5, 7, v5
	v_or_b32_e32 v97, 0x4000, v8
	v_bitop3_b32 v98, v8, 64, v219 bitop3:0x36
	v_or_b32_e32 v8, 24, v6
	v_or_b32_e32 v96, v4, v5
	v_bitop3_b32 v99, v4, 64, v5 bitop3:0x36
	v_add3_u32 v4, s1, v8, v7
	v_ashrrev_i32_e32 v5, 31, v4
	s_mov_b64 s[4:5], 0x80
	v_lshlrev_b64 v[4:5], 11, v[4:5]
	v_lshl_add_u64 v[2:3], v[2:3], 0, s[4:5]
	v_or_b32_e32 v4, v4, v180
	v_lshl_add_u64 v[76:77], v[2:3], 0, v[4:5]
	v_add3_u32 v4, s18, v8, v7
	v_ashrrev_i32_e32 v5, 31, v4
	v_lshlrev_b64 v[4:5], 11, v[4:5]
	v_lshl_add_u64 v[0:1], v[0:1], 0, s[4:5]
	v_or_b32_e32 v4, v4, v180
	v_or_b32_e32 v8, 16, v6
	v_lshl_add_u64 v[78:79], v[0:1], 0, v[4:5]
	v_add3_u32 v4, s1, v8, v7
	v_ashrrev_i32_e32 v5, 31, v4
	v_lshlrev_b64 v[4:5], 11, v[4:5]
	v_or_b32_e32 v4, v4, v180
	v_lshl_add_u64 v[80:81], v[2:3], 0, v[4:5]
	v_add3_u32 v4, s18, v8, v7
	v_ashrrev_i32_e32 v5, 31, v4
	v_lshlrev_b64 v[4:5], 11, v[4:5]
	v_or_b32_e32 v4, v4, v180
	v_or_b32_e32 v8, 8, v6
	v_lshl_add_u64 v[82:83], v[0:1], 0, v[4:5]
	v_add3_u32 v4, s1, v8, v7
	v_ashrrev_i32_e32 v5, 31, v4
	v_lshlrev_b64 v[4:5], 11, v[4:5]
	v_or_b32_e32 v4, v4, v180
	v_lshl_add_u64 v[84:85], v[2:3], 0, v[4:5]
	v_add3_u32 v4, s18, v8, v7
	v_ashrrev_i32_e32 v5, 31, v4
	v_lshlrev_b64 v[4:5], 11, v[4:5]
	v_or_b32_e32 v4, v4, v180
	v_lshl_add_u64 v[86:87], v[0:1], 0, v[4:5]
	v_add3_u32 v4, s1, v6, v7
	v_ashrrev_i32_e32 v5, 31, v4
	v_lshlrev_b64 v[4:5], 11, v[4:5]
	v_or_b32_e32 v4, v4, v180
	v_lshl_add_u64 v[88:89], v[2:3], 0, v[4:5]
	v_add3_u32 v2, s18, v6, v7
	v_ashrrev_i32_e32 v3, 31, v2
	v_lshlrev_b64 v[2:3], 11, v[2:3]
	v_or_b32_e32 v2, v2, v180
	v_lshl_add_u64 v[90:91], v[0:1], 0, v[2:3]
	v_mov_b32_e32 v0, 0
	s_mov_b64 s[4:5], 0
	v_mov_b32_e32 v1, v0
	v_mov_b32_e32 v2, v0
	v_mov_b32_e32 v3, v0
	v_mov_b32_e32 v4, v0
	v_mov_b32_e32 v5, v0
	v_mov_b32_e32 v6, v0
	v_mov_b32_e32 v7, v0
	v_mov_b32_e32 v8, v0
	v_mov_b32_e32 v9, v0
	v_mov_b32_e32 v10, v0
	v_mov_b32_e32 v11, v0
	v_mov_b32_e32 v12, v0
	v_mov_b32_e32 v13, v0
	v_mov_b32_e32 v14, v0
	v_mov_b32_e32 v15, v0
	v_mov_b32_e32 v16, v0
	v_mov_b32_e32 v17, v0
	v_mov_b32_e32 v18, v0
	v_mov_b32_e32 v19, v0
	v_mov_b32_e32 v20, v0
	v_mov_b32_e32 v21, v0
	v_mov_b32_e32 v22, v0
	v_mov_b32_e32 v23, v0
	v_mov_b32_e32 v24, v0
	v_mov_b32_e32 v25, v0
	v_mov_b32_e32 v26, v0
	v_mov_b32_e32 v27, v0
	v_mov_b32_e32 v28, v0
	v_mov_b32_e32 v29, v0
	v_mov_b32_e32 v30, v0
	v_mov_b32_e32 v31, v0
	v_mov_b32_e32 v32, v0
	v_mov_b32_e32 v33, v0
	v_mov_b32_e32 v34, v0
	v_mov_b32_e32 v35, v0
	v_mov_b32_e32 v36, v0
	v_mov_b32_e32 v37, v0
	v_mov_b32_e32 v38, v0
	v_mov_b32_e32 v39, v0
	v_mov_b32_e32 v40, v0
	v_mov_b32_e32 v41, v0
	v_mov_b32_e32 v42, v0
	v_mov_b32_e32 v43, v0
	v_mov_b32_e32 v44, v0
	v_mov_b32_e32 v45, v0
	v_mov_b32_e32 v46, v0
	v_mov_b32_e32 v47, v0
	v_mov_b32_e32 v48, v0
	v_mov_b32_e32 v49, v0
	v_mov_b32_e32 v50, v0
	v_mov_b32_e32 v51, v0
	v_mov_b32_e32 v52, v0
	v_mov_b32_e32 v53, v0
	v_mov_b32_e32 v54, v0
	v_mov_b32_e32 v55, v0
	v_mov_b32_e32 v56, v0
	v_mov_b32_e32 v57, v0
	v_mov_b32_e32 v58, v0
	v_mov_b32_e32 v59, v0
	v_mov_b32_e32 v60, v0
	v_mov_b32_e32 v61, v0
	v_mov_b32_e32 v62, v0
	v_mov_b32_e32 v63, v0
	v_readfirstlane_b32 s64, v90
	v_readfirstlane_b32 s65, v91
	v_readfirstlane_b32 s66, v88
	v_readfirstlane_b32 s67, v89
	v_readfirstlane_b32 s62, v95
	s_sub_u32 s64, s64, 0x80000000
	s_subb_u32 s65, s65, 0
	s_sub_u32 s66, s66, 0x80000000
	s_subb_u32 s67, s67, 0
	v_subrev_u32_e32 v90, s64, v90
	v_subrev_u32_e32 v88, s66, v88
	v_subrev_u32_e32 v86, s64, v86
	v_subrev_u32_e32 v84, s66, v84
	v_subrev_u32_e32 v82, s64, v82
	v_subrev_u32_e32 v80, s66, v80
	v_subrev_u32_e32 v78, s64, v78
	v_subrev_u32_e32 v76, s66, v76
	s_waitcnt vmcnt(0) lgkmcnt(0)
	s_barrier
; DEV f32x4 mma_step(bf16x8 a, bf16x8 b, f32x4 c) { return MFMA(a, b, c); }
; template <class FragT, class AccT>
; DEV void gemm_core_t(const char* __restrict__ A, size_t lda_bytes, const char* __restrict__ Bt, size_t ldb_bytes, int kbytes,
;                      int m0, int n0, int Sshift, int dl, char* smem, AccT (&acc)[4][4]) {
;     ...
;   for (int kt = 0; kt < nk; ++kt) {
;     const unsigned so = (unsigned)(kt & 1) * 32768u;
;     char* nxt = smem + ((kt + 1) & 1) * 32768;
;     if (kt + 1 < nk) {
; #pragma unroll
;       for (int u = 0; u < 4; ++u) {
;         __builtin_amdgcn_global_load_lds((const unsigned*)(ap[u] + (size_t)(kt + 1) * 128), (unsigned*)(nxt + (wid * 4 + u) * 1024 + lane * 16), 16, 0, 0);
;         __builtin_amdgcn_global_load_lds((const unsigned*)(bp[u] + (size_t)(kt + 1) * 128), (unsigned*)(nxt + 16384 + (wid * 4 + u) * 1024 + lane * 16), 16, 0, 0);
;       }
;     }
;     FragT xa[2][4], wb[2][4];
;     asm volatile(
;         "ds_read_b128 %0, %16\n\t"
;         "ds_read_b128 %1, %16 offset:2048\n\t"
;         "ds_read_b128 %2, %16 offset:4096\n\t"
;         "ds_read_b128 %3, %16 offset:6144\n\t"
;         "ds_read_b128 %4, %18\n\t"
;         "ds_read_b128 %5, %18 offset:2048\n\t"
;         "ds_read_b128 %6, %18 offset:8192\n\t"
;         "ds_read_b128 %7, %18 offset:10240\n\t"
;         "ds_read_b128 %8, %17\n\t"
;         "ds_read_b128 %9, %17 offset:2048\n\t"
;         "ds_read_b128 %10, %17 offset:4096\n\t"
;         "ds_read_b128 %11, %17 offset:6144\n\t"
;         "ds_read_b128 %12, %19\n\t"
;         "ds_read_b128 %13, %19 offset:2048\n\t"
;         "ds_read_b128 %14, %19 offset:8192\n\t"
;         "ds_read_b128 %15, %19 offset:10240\n\t"
;         "s_waitcnt lgkmcnt(8)"
;         : "=&v"(xa[0][0]), "=&v"(xa[0][1]), "=&v"(xa[0][2]), "=&v"(xa[0][3]), "=&v"(wb[0][0]), "=&v"(wb[0][1]), "=&v"(wb[0][2]),
;           "=&v"(wb[0][3]), "=&v"(xa[1][0]), "=&v"(xa[1][1]), "=&v"(xa[1][2]), "=&v"(xa[1][3]), "=&v"(wb[1][0]), "=&v"(wb[1][1]),
;           "=&v"(wb[1][2]), "=&v"(wb[1][3])
;         : "v"(a0 + so), "v"((a0 ^ 64u) + so), "v"(b0 + so), "v"((b0 ^ 64u) + so)
;         : "memory");
;     __builtin_amdgcn_s_setprio(1);
; #pragma unroll
;     for (int i = 0; i < 4; ++i)
; #pragma unroll
;       for (int j = 0; j < 4; ++j) acc[i][j] = mma_step(wb[0][j], xa[0][i], acc[i][j]);
;     asm volatile("s_waitcnt lgkmcnt(0)"
.LBB0_402:
	s_add_i32 s1, s16, 0xffff8000
	s_and_b32 s1, s1, 0x8000
	v_add_u32_e32 v164, s1, v96
	v_add_u32_e32 v165, s1, v99
	v_or_b32_e32 v166, s1, v97
	v_or_b32_e32 v167, s1, v98
	s_and_b32 s1, s16, 0x8000
	s_add_i32 s1, s1, s62
	s_mov_b32 m0, s1
	ds_read_b128 v[100:103], v164
	global_load_lds_dwordx4 v90, s[64:65]
	ds_read_b128 v[104:107], v164 offset:2048
	s_add_i32 m0, s1, 0x4000
	ds_read_b128 v[108:111], v164 offset:4096
	global_load_lds_dwordx4 v88, s[66:67]
	ds_read_b128 v[112:115], v164 offset:6144
	s_add_i32 m0, s1, 0x400
	ds_read_b128 v[116:119], v166
	global_load_lds_dwordx4 v86, s[64:65]
	ds_read_b128 v[120:123], v166 offset:2048
	s_add_i32 m0, s1, 0x4400
	ds_read_b128 v[124:127], v166 offset:8192
	global_load_lds_dwordx4 v84, s[66:67]
	ds_read_b128 v[128:131], v166 offset:10240
	ds_read_b128 v[132:135], v165
	ds_read_b128 v[136:139], v165 offset:2048
	ds_read_b128 v[140:143], v165 offset:4096
	ds_read_b128 v[144:147], v165 offset:6144
	ds_read_b128 v[148:151], v167
	ds_read_b128 v[152:155], v167 offset:2048
	ds_read_b128 v[156:159], v167 offset:8192
	ds_read_b128 v[160:163], v167 offset:10240
	s_waitcnt lgkmcnt(8)
	s_setprio 1
	v_mfma_f32_16x16x32_bf16 v[60:63], v[116:119], v[100:103], v[60:63]
	v_mfma_f32_16x16x32_bf16 v[56:59], v[120:123], v[100:103], v[56:59]
	s_add_i32 m0, s1, 0x800
	v_mfma_f32_16x16x32_bf16 v[52:55], v[124:127], v[100:103], v[52:55]
	global_load_lds_dwordx4 v82, s[64:65]
	v_mfma_f32_16x16x32_bf16 v[48:51], v[128:131], v[100:103], v[48:51]
	v_mfma_f32_16x16x32_bf16 v[44:47], v[116:119], v[104:107], v[44:47]
	v_mfma_f32_16x16x32_bf16 v[40:43], v[120:123], v[104:107], v[40:43]
	s_add_i32 m0, s1, 0x4800
	v_mfma_f32_16x16x32_bf16 v[36:39], v[124:127], v[104:107], v[36:39]
	global_load_lds_dwordx4 v80, s[66:67]
	v_mfma_f32_16x16x32_bf16 v[32:35], v[128:131], v[104:107], v[32:35]
	v_mfma_f32_16x16x32_bf16 v[28:31], v[116:119], v[108:111], v[28:31]
	v_mfma_f32_16x16x32_bf16 v[24:27], v[120:123], v[108:111], v[24:27]
	s_add_i32 m0, s1, 0xc00
	v_mfma_f32_16x16x32_bf16 v[20:23], v[124:127], v[108:111], v[20:23]
	global_load_lds_dwordx4 v78, s[64:65]
	v_mfma_f32_16x16x32_bf16 v[16:19], v[128:131], v[108:111], v[16:19]
	v_mfma_f32_16x16x32_bf16 v[12:15], v[116:119], v[112:115], v[12:15]
	v_mfma_f32_16x16x32_bf16 v[8:11], v[120:123], v[112:115], v[8:11]
	s_add_i32 m0, s1, 0x4c00
	v_mfma_f32_16x16x32_bf16 v[4:7], v[124:127], v[112:115], v[4:7]
	global_load_lds_dwordx4 v76, s[66:67]
	v_mfma_f32_16x16x32_bf16 v[0:3], v[128:131], v[112:115], v[0:3]
	s_waitcnt lgkmcnt(0)
	s_nop 0
	v_mfma_f32_16x16x32_bf16 v[60:63], v[148:151], v[132:135], v[60:63]
	v_mfma_f32_16x16x32_bf16 v[56:59], v[152:155], v[132:135], v[56:59]
	v_mfma_f32_16x16x32_bf16 v[52:55], v[156:159], v[132:135], v[52:55]
	v_mfma_f32_16x16x32_bf16 v[48:51], v[160:163], v[132:135], v[48:51]
	v_mfma_f32_16x16x32_bf16 v[44:47], v[148:151], v[136:139], v[44:47]
	v_mfma_f32_16x16x32_bf16 v[40:43], v[152:155], v[136:139], v[40:43]
	v_mfma_f32_16x16x32_bf16 v[36:39], v[156:159], v[136:139], v[36:39]
	v_mfma_f32_16x16x32_bf16 v[32:35], v[160:163], v[136:139], v[32:35]
	v_mfma_f32_16x16x32_bf16 v[28:31], v[148:151], v[140:143], v[28:31]
	v_mfma_f32_16x16x32_bf16 v[24:27], v[152:155], v[140:143], v[24:27]
	v_mfma_f32_16x16x32_bf16 v[20:23], v[156:159], v[140:143], v[20:23]
	v_mfma_f32_16x16x32_bf16 v[16:19], v[160:163], v[140:143], v[16:19]
	v_mfma_f32_16x16x32_bf16 v[12:15], v[148:151], v[144:147], v[12:15]
	v_mfma_f32_16x16x32_bf16 v[8:11], v[152:155], v[144:147], v[8:11]
	v_mfma_f32_16x16x32_bf16 v[4:7], v[156:159], v[144:147], v[4:7]
	v_mfma_f32_16x16x32_bf16 v[0:3], v[160:163], v[144:147], v[0:3]
	s_setprio 0
	s_waitcnt vmcnt(0)
	s_add_u32 s4, s4, 0x80
	s_addc_u32 s5, s5, 0
	s_add_u32 s64, s64, 0x80
	s_addc_u32 s65, s65, 0
	s_add_u32 s66, s66, 0x80
	s_addc_u32 s67, s67, 0
	s_add_i32 s16, s16, 0x8000
	s_cmpk_lg_i32 s4, 0x780
	s_waitcnt vmcnt(0) lgkmcnt(0)
	s_barrier
	s_cbranch_scc1 .LBB0_402
	v_add_u32_e32 v95, 0x8000, v96
	v_add_u32_e32 v144, 0x8000, v99
	v_or_b32_e32 v145, 0x8000, v97
	v_or_b32_e32 v146, 0x8000, v98
	ds_read_b128 v[76:79], v95
	ds_read_b128 v[80:83], v95 offset:2048
	ds_read_b128 v[84:87], v95 offset:4096
	ds_read_b128 v[88:91], v95 offset:6144
	ds_read_b128 v[96:99], v145
	ds_read_b128 v[100:103], v145 offset:2048
	ds_read_b128 v[104:107], v145 offset:8192
	ds_read_b128 v[108:111], v145 offset:10240
	ds_read_b128 v[112:115], v144
	ds_read_b128 v[116:119], v144 offset:2048
	ds_read_b128 v[120:123], v144 offset:4096
	ds_read_b128 v[124:127], v144 offset:6144
	ds_read_b128 v[128:131], v146
	ds_read_b128 v[132:135], v146 offset:2048
	ds_read_b128 v[136:139], v146 offset:8192
	ds_read_b128 v[140:143], v146 offset:10240
	s_waitcnt lgkmcnt(8)
	s_setprio 1
	v_mfma_f32_16x16x32_bf16 v[60:63], v[96:99], v[76:79], v[60:63]
	v_mfma_f32_16x16x32_bf16 v[56:59], v[100:103], v[76:79], v[56:59]
	v_mfma_f32_16x16x32_bf16 v[52:55], v[104:107], v[76:79], v[52:55]
	v_mfma_f32_16x16x32_bf16 v[48:51], v[108:111], v[76:79], v[48:51]
	v_mfma_f32_16x16x32_bf16 v[44:47], v[96:99], v[80:83], v[44:47]
	v_mfma_f32_16x16x32_bf16 v[40:43], v[100:103], v[80:83], v[40:43]
	v_mfma_f32_16x16x32_bf16 v[36:39], v[104:107], v[80:83], v[36:39]
	v_mfma_f32_16x16x32_bf16 v[32:35], v[108:111], v[80:83], v[32:35]
	v_mfma_f32_16x16x32_bf16 v[28:31], v[96:99], v[84:87], v[28:31]
	v_mfma_f32_16x16x32_bf16 v[24:27], v[100:103], v[84:87], v[24:27]
	v_mfma_f32_16x16x32_bf16 v[20:23], v[104:107], v[84:87], v[20:23]
	v_mfma_f32_16x16x32_bf16 v[16:19], v[108:111], v[84:87], v[16:19]
	v_mfma_f32_16x16x32_bf16 v[12:15], v[96:99], v[88:91], v[12:15]
	v_mfma_f32_16x16x32_bf16 v[8:11], v[100:103], v[88:91], v[8:11]
	v_mfma_f32_16x16x32_bf16 v[4:7], v[104:107], v[88:91], v[4:7]
	v_mfma_f32_16x16x32_bf16 v[0:3], v[108:111], v[88:91], v[0:3]
	s_waitcnt lgkmcnt(0)
	s_nop 0
	v_mfma_f32_16x16x32_bf16 v[60:63], v[128:131], v[112:115], v[60:63]
	v_mfma_f32_16x16x32_bf16 v[76:79], v[132:135], v[112:115], v[56:59]
	v_mfma_f32_16x16x32_bf16 v[80:83], v[136:139], v[112:115], v[52:55]
	v_mfma_f32_16x16x32_bf16 v[52:55], v[140:143], v[112:115], v[48:51]
	v_mfma_f32_16x16x32_bf16 v[48:51], v[128:131], v[116:119], v[44:47]
	v_mfma_f32_16x16x32_bf16 v[44:47], v[132:135], v[116:119], v[40:43]
	v_mfma_f32_16x16x32_bf16 v[40:43], v[136:139], v[116:119], v[36:39]
	v_mfma_f32_16x16x32_bf16 v[36:39], v[140:143], v[116:119], v[32:35]
	v_mfma_f32_16x16x32_bf16 v[32:35], v[128:131], v[120:123], v[28:31]
	v_mfma_f32_16x16x32_bf16 v[28:31], v[132:135], v[120:123], v[24:27]
	v_mfma_f32_16x16x32_bf16 v[24:27], v[136:139], v[120:123], v[20:23]
	v_mfma_f32_16x16x32_bf16 v[20:23], v[140:143], v[120:123], v[16:19]
	v_mfma_f32_16x16x32_bf16 v[16:19], v[128:131], v[124:127], v[12:15]
	v_mfma_f32_16x16x32_bf16 v[12:15], v[132:135], v[124:127], v[8:11]
	v_mfma_f32_16x16x32_bf16 v[8:11], v[136:139], v[124:127], v[4:7]
	v_mfma_f32_16x16x32_bf16 v[4:7], v[140:143], v[124:127], v[0:3]
	s_setprio 0
	s_waitcnt vmcnt(0)
	s_barrier
; DEV float bflo(unsigned u) { return __uint_as_float(u << 16); }
; DEV float bfhi(unsigned u) { return __uint_as_float(u & 0xffff0000u); }
; #define P (*launderP(lp))
; __device__ __forceinline__ void phase_gemm2(PREF P, char* smem) {
;     ...
; #pragma unroll
;     for (int i = 0; i < 4; ++i)
; #pragma unroll
;       for (int j = 0; j < 4; ++j) {
;         const int row = m0 + wm * 64 + i * 16 + l15, col = n0 + (j & 1) * 16 + wn * 32 + (j >> 1) * 64 + q * 4;
;         const unsigned g = *(const unsigned*)((const u8*)P.GB + (size_t)row * 2048 + col);
;         uint2 pr = *(const uint2*)(P.merged + (size_t)row * 2048 + col);
;         f32x4 v;
;         v[0] = bflo(pr.x) + (float)(g & 255u) * (1.f / 255.f) * acc[i][j][0];
;         v[1] = bfhi(pr.x) + (float)((g >> 8) & 255u) * (1.f / 255.f) * acc[i][j][1];
;         v[2] = bflo(pr.y) + (float)((g >> 16) & 255u) * (1.f / 255.f) * acc[i][j][2];
;         v[3] = bfhi(pr.y) + (float)(g >> 24) * (1.f / 255.f) * acc[i][j][3];
;         acc[i][j] = v;
;       }
	s_nop 0
	ds_read2_b64 v[0:3], v92 offset0:38 offset1:42
	s_mov_b32 s4, 0x3b808081
	s_mov_b32 s1, 0xfffffc0
	s_waitcnt lgkmcnt(0)
	v_lshl_add_u64 v[56:57], v[0:1], 0, v[68:69]
	v_lshl_add_u64 v[58:59], v[68:69], 1, v[2:3]
	v_lshl_add_u64 v[84:85], v[56:57], 0, v[64:65]
	flat_load_dword v88, v[84:85]
	v_lshl_add_u64 v[86:87], v[58:59], 0, v[66:67]
	flat_load_dwordx2 v[58:59], v[86:87]
	s_waitcnt vmcnt(0) lgkmcnt(0)
	v_cvt_f32_ubyte1_e32 v69, v88
	v_cvt_f32_ubyte0_e32 v68, v88
	v_lshlrev_b32_e32 v56, 16, v58
	v_and_b32_e32 v57, 0xffff0000, v58
	v_pk_mul_f32 v[68:69], v[68:69], s[4:5] op_sel_hi:[1,0]
	v_lshlrev_b32_e32 v58, 16, v59
	v_pk_fma_f32 v[56:57], v[60:61], v[68:69], v[56:57]
	v_cvt_f32_ubyte3_e32 v61, v88
	v_cvt_f32_ubyte2_e32 v60, v88
	v_and_b32_e32 v59, 0xffff0000, v59
	v_pk_mul_f32 v[60:61], v[60:61], s[4:5] op_sel_hi:[1,0]
	s_nop 0
	v_pk_fma_f32 v[58:59], v[62:63], v[60:61], v[58:59]
	flat_load_dword v88, v[84:85] offset:16
	flat_load_dwordx2 v[62:63], v[86:87] offset:32
	s_waitcnt vmcnt(0) lgkmcnt(0)
	v_cvt_f32_ubyte1_e32 v69, v88
	v_cvt_f32_ubyte0_e32 v68, v88
	v_lshlrev_b32_e32 v60, 16, v62
	v_and_b32_e32 v61, 0xffff0000, v62
	v_pk_mul_f32 v[68:69], v[68:69], s[4:5] op_sel_hi:[1,0]
	v_lshlrev_b32_e32 v62, 16, v63
	v_pk_fma_f32 v[60:61], v[76:77], v[68:69], v[60:61]
	v_cvt_f32_ubyte3_e32 v69, v88
	v_cvt_f32_ubyte2_e32 v68, v88
	flat_load_dword v88, v[84:85] offset:64
	flat_load_dwordx2 v[76:77], v[86:87] offset:128
	v_and_b32_e32 v63, 0xffff0000, v63
	v_pk_mul_f32 v[68:69], v[68:69], s[4:5] op_sel_hi:[1,0]
	s_nop 0
	v_pk_fma_f32 v[62:63], v[78:79], v[68:69], v[62:63]
	s_waitcnt vmcnt(0) lgkmcnt(0)
	v_cvt_f32_ubyte1_e32 v79, v88
	v_cvt_f32_ubyte0_e32 v78, v88
	v_lshlrev_b32_e32 v68, 16, v76
	v_and_b32_e32 v69, 0xffff0000, v76
	v_pk_mul_f32 v[78:79], v[78:79], s[4:5] op_sel_hi:[1,0]
	v_lshlrev_b32_e32 v76, 16, v77
	v_pk_fma_f32 v[68:69], v[80:81], v[78:79], v[68:69]
	v_cvt_f32_ubyte3_e32 v79, v88
	v_cvt_f32_ubyte2_e32 v78, v88
	v_and_b32_e32 v77, 0xffff0000, v77
	v_pk_mul_f32 v[78:79], v[78:79], s[4:5] op_sel_hi:[1,0]
	s_nop 0
	v_pk_fma_f32 v[76:77], v[82:83], v[78:79], v[76:77]
	flat_load_dword v84, v[84:85] offset:80
	s_nop 0
	flat_load_dwordx2 v[78:79], v[86:87] offset:160
	s_waitcnt vmcnt(0) lgkmcnt(0)
	v_cvt_f32_ubyte1_e32 v83, v84
	v_cvt_f32_ubyte0_e32 v82, v84
	v_lshlrev_b32_e32 v80, 16, v78
	v_and_b32_e32 v81, 0xffff0000, v78
	v_pk_mul_f32 v[82:83], v[82:83], s[4:5] op_sel_hi:[1,0]
	v_lshlrev_b32_e32 v78, 16, v79
	v_pk_fma_f32 v[52:53], v[52:53], v[82:83], v[80:81]
	v_cvt_f32_ubyte3_e32 v81, v84
	v_cvt_f32_ubyte2_e32 v80, v84
	v_and_b32_e32 v79, 0xffff0000, v79
	v_pk_mul_f32 v[80:81], v[80:81], s[4:5] op_sel_hi:[1,0]
	v_cvt_pk_bf16_f32 v52, v52, v53
	v_pk_fma_f32 v[54:55], v[54:55], v[80:81], v[78:79]
	v_lshl_add_u64 v[78:79], v[0:1], 0, v[72:73]
	v_lshl_add_u64 v[72:73], v[72:73], 1, v[2:3]
	v_lshl_add_u64 v[78:79], v[78:79], 0, v[64:65]
	flat_load_dword v86, v[78:79]
	v_lshl_add_u64 v[72:73], v[72:73], 0, v[66:67]
	flat_load_dwordx2 v[80:81], v[72:73]
	v_cvt_pk_bf16_f32 v53, v54, v55
	s_waitcnt vmcnt(0) lgkmcnt(0)
	v_cvt_f32_ubyte1_e32 v85, v86
	v_cvt_f32_ubyte0_e32 v84, v86
	v_lshlrev_b32_e32 v82, 16, v80
	v_and_b32_e32 v83, 0xffff0000, v80
	v_pk_mul_f32 v[84:85], v[84:85], s[4:5] op_sel_hi:[1,0]
	v_lshlrev_b32_e32 v80, 16, v81
	v_pk_fma_f32 v[48:49], v[48:49], v[84:85], v[82:83]
	v_cvt_f32_ubyte3_e32 v83, v86
	v_cvt_f32_ubyte2_e32 v82, v86
	v_and_b32_e32 v81, 0xffff0000, v81
	v_pk_mul_f32 v[82:83], v[82:83], s[4:5] op_sel_hi:[1,0]
	s_nop 0
	v_pk_fma_f32 v[50:51], v[50:51], v[82:83], v[80:81]
	flat_load_dword v86, v[78:79] offset:16
	flat_load_dwordx2 v[80:81], v[72:73] offset:32
	s_waitcnt vmcnt(0) lgkmcnt(0)
	v_cvt_f32_ubyte1_e32 v85, v86
	v_cvt_f32_ubyte0_e32 v84, v86
	v_lshlrev_b32_e32 v82, 16, v80
	v_and_b32_e32 v83, 0xffff0000, v80
	v_pk_mul_f32 v[84:85], v[84:85], s[4:5] op_sel_hi:[1,0]
	v_lshlrev_b32_e32 v80, 16, v81
	v_pk_fma_f32 v[44:45], v[44:45], v[84:85], v[82:83]
	v_cvt_f32_ubyte3_e32 v83, v86
	v_cvt_f32_ubyte2_e32 v82, v86
	v_and_b32_e32 v81, 0xffff0000, v81
	v_pk_mul_f32 v[82:83], v[82:83], s[4:5] op_sel_hi:[1,0]
	v_cvt_pk_bf16_f32 v44, v44, v45
	v_pk_fma_f32 v[46:47], v[46:47], v[82:83], v[80:81]
	flat_load_dword v86, v[78:79] offset:64
	flat_load_dwordx2 v[80:81], v[72:73] offset:128
	v_cvt_pk_bf16_f32 v45, v46, v47
	s_waitcnt vmcnt(0) lgkmcnt(0)
	v_cvt_f32_ubyte1_e32 v85, v86
	v_cvt_f32_ubyte0_e32 v84, v86
	v_lshlrev_b32_e32 v82, 16, v80
	v_and_b32_e32 v83, 0xffff0000, v80
	v_pk_mul_f32 v[84:85], v[84:85], s[4:5] op_sel_hi:[1,0]
	v_lshlrev_b32_e32 v80, 16, v81
	v_pk_fma_f32 v[40:41], v[40:41], v[84:85], v[82:83]
	v_cvt_f32_ubyte3_e32 v83, v86
	v_cvt_f32_ubyte2_e32 v82, v86
	v_and_b32_e32 v81, 0xffff0000, v81
	v_pk_mul_f32 v[82:83], v[82:83], s[4:5] op_sel_hi:[1,0]
	s_nop 0
	v_pk_fma_f32 v[42:43], v[42:43], v[82:83], v[80:81]
	flat_load_dword v82, v[78:79] offset:80
	s_nop 0
	flat_load_dwordx2 v[72:73], v[72:73] offset:160
	s_waitcnt vmcnt(0) lgkmcnt(0)
	v_cvt_f32_ubyte1_e32 v81, v82
	v_cvt_f32_ubyte0_e32 v80, v82
	v_lshlrev_b32_e32 v78, 16, v72
	v_and_b32_e32 v79, 0xffff0000, v72
	v_pk_mul_f32 v[80:81], v[80:81], s[4:5] op_sel_hi:[1,0]
	v_lshlrev_b32_e32 v72, 16, v73
	v_pk_fma_f32 v[36:37], v[36:37], v[80:81], v[78:79]
	v_cvt_f32_ubyte3_e32 v79, v82
	v_cvt_f32_ubyte2_e32 v78, v82
	v_and_b32_e32 v73, 0xffff0000, v73
	v_pk_mul_f32 v[78:79], v[78:79], s[4:5] op_sel_hi:[1,0]
	v_cvt_pk_bf16_f32 v36, v36, v37
	v_pk_fma_f32 v[38:39], v[38:39], v[78:79], v[72:73]
	v_lshl_add_u64 v[72:73], v[0:1], 0, v[74:75]
	v_lshl_add_u64 v[78:79], v[74:75], 1, v[2:3]
	v_lshl_add_u64 v[74:75], v[72:73], 0, v[64:65]
	flat_load_dword v84, v[74:75]
	v_lshl_add_u64 v[72:73], v[78:79], 0, v[66:67]
	flat_load_dwordx2 v[78:79], v[72:73]
	v_lshl_add_u64 v[0:1], v[0:1], 0, v[70:71]
	v_lshl_add_u64 v[70:71], v[70:71], 1, v[2:3]
	v_cvt_pk_bf16_f32 v37, v38, v39
	s_waitcnt vmcnt(0) lgkmcnt(0)
; DEV int tid_() { int t = threadIdx.x; asm volatile("" : "+v"(t)); return t; }
; DEV float bflo(unsigned u) { return __uint_as_float(u << 16); }
; DEV float bfhi(unsigned u) { return __uint_as_float(u & 0xffff0000u); }
; #define P (*launderP(lp))
; DEV void stage_tile_bf16(char* smem, const f32x4 (&v)[4][4], u16* buf, int ld, int m0, int col0) {
;   const int tid = tid_(), lane = tid & 63, wid = tid >> 6, wm = wid >> 1, wn = wid & 1, l15 = lane & 15, q = lane >> 4;
; #pragma unroll
;   for (int i = 0; i < 4; ++i)
; #pragma unroll
;     for (int j = 0; j < 4; ++j) {
;       const int rl = wm * 64 + i * 16 + l15, cl = (j & 1) * 16 + wn * 32 + (j >> 1) * 64 + q * 4;
;       u32x2 o; o.x = pack2(v[i][j][0], v[i][j][1]); o.y = pack2(v[i][j][2], v[i][j][3]);
;       *(u32x2*)(smem + rl * 272 + cl * 2) = o;
;     }
;   __syncthreads();
; __device__ __forceinline__ void phase_gemm2(PREF P, char* smem) {
;     ...
; #pragma unroll
;     for (int i = 0; i < 4; ++i)
; #pragma unroll
;       for (int j = 0; j < 4; ++j) {
;         const int row = m0 + wm * 64 + i * 16 + l15, col = n0 + (j & 1) * 16 + wn * 32 + (j >> 1) * 64 + q * 4;
;         const unsigned g = *(const unsigned*)((const u8*)P.GB + (size_t)row * 2048 + col);
;         uint2 pr = *(const uint2*)(P.merged + (size_t)row * 2048 + col);
;         f32x4 v;
;         v[0] = bflo(pr.x) + (float)(g & 255u) * (1.f / 255.f) * acc[i][j][0];
;         v[1] = bfhi(pr.x) + (float)((g >> 8) & 255u) * (1.f / 255.f) * acc[i][j][1];
;         v[2] = bflo(pr.y) + (float)((g >> 16) & 255u) * (1.f / 255.f) * acc[i][j][2];
;         v[3] = bfhi(pr.y) + (float)(g >> 24) * (1.f / 255.f) * acc[i][j][3];
;         acc[i][j] = v;
;       }
	v_cvt_f32_ubyte1_e32 v83, v84
	v_cvt_f32_ubyte0_e32 v82, v84
	v_lshlrev_b32_e32 v80, 16, v78
	v_and_b32_e32 v81, 0xffff0000, v78
	v_pk_mul_f32 v[82:83], v[82:83], s[4:5] op_sel_hi:[1,0]
	v_lshlrev_b32_e32 v78, 16, v79
	v_pk_fma_f32 v[32:33], v[32:33], v[82:83], v[80:81]
	v_cvt_f32_ubyte3_e32 v81, v84
	v_cvt_f32_ubyte2_e32 v80, v84
	v_and_b32_e32 v79, 0xffff0000, v79
	v_pk_mul_f32 v[80:81], v[80:81], s[4:5] op_sel_hi:[1,0]
	s_nop 0
	v_pk_fma_f32 v[34:35], v[34:35], v[80:81], v[78:79]
	flat_load_dword v84, v[74:75] offset:16
	flat_load_dwordx2 v[78:79], v[72:73] offset:32
	s_waitcnt vmcnt(0) lgkmcnt(0)
	v_cvt_f32_ubyte1_e32 v83, v84
	v_cvt_f32_ubyte0_e32 v82, v84
	v_lshlrev_b32_e32 v80, 16, v78
	v_and_b32_e32 v81, 0xffff0000, v78
	v_pk_mul_f32 v[82:83], v[82:83], s[4:5] op_sel_hi:[1,0]
	v_lshlrev_b32_e32 v78, 16, v79
	v_pk_fma_f32 v[28:29], v[28:29], v[82:83], v[80:81]
	v_cvt_f32_ubyte3_e32 v81, v84
	v_cvt_f32_ubyte2_e32 v80, v84
	v_and_b32_e32 v79, 0xffff0000, v79
	v_pk_mul_f32 v[80:81], v[80:81], s[4:5] op_sel_hi:[1,0]
	v_cvt_pk_bf16_f32 v28, v28, v29
	v_pk_fma_f32 v[30:31], v[30:31], v[80:81], v[78:79]
	flat_load_dword v84, v[74:75] offset:64
	flat_load_dwordx2 v[78:79], v[72:73] offset:128
	v_cvt_pk_bf16_f32 v29, v30, v31
	s_waitcnt vmcnt(0) lgkmcnt(0)
	v_cvt_f32_ubyte1_e32 v83, v84
	v_cvt_f32_ubyte0_e32 v82, v84
	v_lshlrev_b32_e32 v80, 16, v78
	v_and_b32_e32 v81, 0xffff0000, v78
	v_pk_mul_f32 v[82:83], v[82:83], s[4:5] op_sel_hi:[1,0]
	v_lshlrev_b32_e32 v78, 16, v79
	v_pk_fma_f32 v[24:25], v[24:25], v[82:83], v[80:81]
	v_cvt_f32_ubyte3_e32 v81, v84
	v_cvt_f32_ubyte2_e32 v80, v84
	v_and_b32_e32 v79, 0xffff0000, v79
	v_pk_mul_f32 v[80:81], v[80:81], s[4:5] op_sel_hi:[1,0]
	s_nop 0
	v_pk_fma_f32 v[26:27], v[26:27], v[80:81], v[78:79]
	flat_load_dword v80, v[74:75] offset:80
	s_nop 0
	flat_load_dwordx2 v[72:73], v[72:73] offset:160
	s_waitcnt vmcnt(0) lgkmcnt(0)
	v_cvt_f32_ubyte1_e32 v79, v80
	v_cvt_f32_ubyte0_e32 v78, v80
	v_lshlrev_b32_e32 v74, 16, v72
	v_and_b32_e32 v75, 0xffff0000, v72
	v_pk_mul_f32 v[78:79], v[78:79], s[4:5] op_sel_hi:[1,0]
	v_lshlrev_b32_e32 v72, 16, v73
	v_pk_fma_f32 v[20:21], v[20:21], v[78:79], v[74:75]
	v_cvt_f32_ubyte3_e32 v75, v80
	v_cvt_f32_ubyte2_e32 v74, v80
	v_and_b32_e32 v73, 0xffff0000, v73
	v_pk_mul_f32 v[74:75], v[74:75], s[4:5] op_sel_hi:[1,0]
	v_cvt_pk_bf16_f32 v20, v20, v21
	v_pk_fma_f32 v[22:23], v[22:23], v[74:75], v[72:73]
	v_lshl_add_u64 v[72:73], v[0:1], 0, v[64:65]
	flat_load_dword v74, v[72:73]
	v_lshl_add_u64 v[64:65], v[70:71], 0, v[66:67]
	flat_load_dwordx2 v[66:67], v[64:65]
	v_cvt_pk_bf16_f32 v21, v22, v23
	s_waitcnt vmcnt(0) lgkmcnt(0)
	v_cvt_f32_ubyte1_e32 v71, v74
	v_cvt_f32_ubyte0_e32 v70, v74
	v_lshlrev_b32_e32 v0, 16, v66
	v_and_b32_e32 v1, 0xffff0000, v66
	v_pk_mul_f32 v[70:71], v[70:71], s[4:5] op_sel_hi:[1,0]
	v_cvt_f32_ubyte2_e32 v66, v74
	v_pk_fma_f32 v[0:1], v[16:17], v[70:71], v[0:1]
	v_lshlrev_b32_e32 v16, 16, v67
	v_and_b32_e32 v17, 0xffff0000, v67
	v_cvt_f32_ubyte3_e32 v67, v74
	v_pk_mul_f32 v[66:67], v[66:67], s[4:5] op_sel_hi:[1,0]
	v_cvt_pk_bf16_f32 v0, v0, v1
	v_pk_fma_f32 v[16:17], v[18:19], v[66:67], v[16:17]
	flat_load_dword v74, v[72:73] offset:16
	flat_load_dwordx2 v[18:19], v[64:65] offset:32
	v_cvt_pk_bf16_f32 v1, v16, v17
	s_waitcnt vmcnt(0) lgkmcnt(0)
	v_cvt_f32_ubyte1_e32 v71, v74
	v_cvt_f32_ubyte0_e32 v70, v74
	v_lshlrev_b32_e32 v66, 16, v18
	v_and_b32_e32 v67, 0xffff0000, v18
	v_pk_mul_f32 v[70:71], v[70:71], s[4:5] op_sel_hi:[1,0]
	v_lshlrev_b32_e32 v18, 16, v19
	v_pk_fma_f32 v[12:13], v[12:13], v[70:71], v[66:67]
	v_cvt_f32_ubyte3_e32 v67, v74
	v_cvt_f32_ubyte2_e32 v66, v74
	v_and_b32_e32 v19, 0xffff0000, v19
	v_pk_mul_f32 v[66:67], v[66:67], s[4:5] op_sel_hi:[1,0]
	v_cvt_pk_bf16_f32 v12, v12, v13
	v_pk_fma_f32 v[14:15], v[14:15], v[66:67], v[18:19]
	flat_load_dword v74, v[72:73] offset:64
	flat_load_dwordx2 v[18:19], v[64:65] offset:128
	v_cvt_pk_bf16_f32 v13, v14, v15
	s_waitcnt vmcnt(0) lgkmcnt(0)
	v_cvt_f32_ubyte1_e32 v71, v74
	v_cvt_f32_ubyte0_e32 v70, v74
	v_lshlrev_b32_e32 v66, 16, v18
	v_and_b32_e32 v67, 0xffff0000, v18
	v_pk_mul_f32 v[70:71], v[70:71], s[4:5] op_sel_hi:[1,0]
	v_lshlrev_b32_e32 v18, 16, v19
	v_pk_fma_f32 v[8:9], v[8:9], v[70:71], v[66:67]
	v_cvt_f32_ubyte3_e32 v67, v74
	v_cvt_f32_ubyte2_e32 v66, v74
	v_and_b32_e32 v19, 0xffff0000, v19
	v_pk_mul_f32 v[66:67], v[66:67], s[4:5] op_sel_hi:[1,0]
	s_nop 0
	v_pk_fma_f32 v[10:11], v[10:11], v[66:67], v[18:19]
	flat_load_dword v70, v[72:73] offset:80
	flat_load_dwordx2 v[18:19], v[64:65] offset:160
	s_waitcnt vmcnt(0) lgkmcnt(0)
	v_cvt_f32_ubyte1_e32 v67, v70
	v_cvt_f32_ubyte0_e32 v66, v70
	v_lshlrev_b32_e32 v64, 16, v18
	v_and_b32_e32 v65, 0xffff0000, v18
	v_pk_mul_f32 v[66:67], v[66:67], s[4:5] op_sel_hi:[1,0]
	v_lshlrev_b32_e32 v18, 16, v19
	v_pk_fma_f32 v[4:5], v[4:5], v[66:67], v[64:65]
	v_cvt_f32_ubyte3_e32 v65, v70
	v_cvt_f32_ubyte2_e32 v64, v70
	v_and_b32_e32 v19, 0xffff0000, v19
	v_pk_mul_f32 v[64:65], v[64:65], s[4:5] op_sel_hi:[1,0]
	v_cvt_pk_bf16_f32 v4, v4, v5
	v_pk_fma_f32 v[6:7], v[6:7], v[64:65], v[18:19]
	v_mov_b32_e32 v64, v188
	v_cvt_pk_bf16_f32 v18, v56, v57
	v_and_b32_e32 v65, 15, v64
	v_lshrrev_b32_e32 v66, 1, v64
	v_and_b32_e32 v56, 64, v64
	v_and_or_b32 v67, v66, s1, v65
	v_and_or_b32 v56, v66, 24, v56
	v_cvt_pk_bf16_f32 v19, v58, v59
	v_mad_u64_u32 v[56:57], s[4:5], v67, s11, v[56:57]
	v_cvt_pk_bf16_f32 v58, v60, v61
	v_cvt_pk_bf16_f32 v59, v62, v63
	ds_write2_b64 v56, v[18:19], v[58:59] offset1:4
	v_cvt_pk_bf16_f32 v18, v68, v69
	v_cvt_pk_bf16_f32 v19, v76, v77
	ds_write2_b64 v56, v[18:19], v[52:53] offset0:16 offset1:20
	v_cvt_pk_bf16_f32 v18, v48, v49
	v_cvt_pk_bf16_f32 v19, v50, v51
	v_add_u32_e32 v46, 0x1000, v56
	v_add_u32_e32 v14, 0x3000, v56
	ds_write2_b64 v46, v[18:19], v[44:45] offset0:32 offset1:36
	v_cvt_pk_bf16_f32 v18, v40, v41
	v_cvt_pk_bf16_f32 v19, v42, v43
	ds_write2_b64 v14, v[0:1], v[12:13] offset0:96 offset1:100
	v_cvt_pk_bf16_f32 v0, v8, v9
	v_cvt_pk_bf16_f32 v1, v10, v11
	v_cvt_pk_bf16_f32 v5, v6, v7
	s_ashr_i32 s1, s0, 31
	ds_write2_b64 v46, v[18:19], v[36:37] offset0:48 offset1:52
	v_cvt_pk_bf16_f32 v18, v32, v33
	v_cvt_pk_bf16_f32 v19, v34, v35
	v_add_u32_e32 v30, 0x2000, v56
	ds_write2_b64 v14, v[0:1], v[4:5] offset0:112 offset1:116
	v_lshlrev_b32_e32 v180, 4, v65
	v_lshl_add_u64 v[0:1], s[0:1], 1, v[2:3]
	v_ashrrev_i32_e32 v6, 4, v64
	ds_write2_b64 v30, v[18:19], v[28:29] offset0:64 offset1:68
	v_cvt_pk_bf16_f32 v18, v24, v25
	v_cvt_pk_bf16_f32 v19, v26, v27
	v_lshl_add_u64 v[4:5], v[0:1], 0, v[180:181]
	v_mad_u64_u32 v[0:1], s[0:1], v6, s11, v[180:181]
	ds_write2_b64 v30, v[18:19], v[20:21] offset0:80 offset1:84
	s_waitcnt lgkmcnt(0)
	s_barrier
; DEV void stage_tile_bf16(char* smem, const f32x4 (&v)[4][4], u16* buf, int ld, int m0, int col0) {
;     ...
; #pragma unroll
;   for (int k = 0; k < 8; ++k) {
;     const int chunk = tid + 256 * k, rl = chunk >> 4, c16 = chunk & 15;
;     u32x4 d = *(const u32x4*)(smem + rl * 272 + c16 * 16);
;     *(u32x4*)(buf + (size_t)(m0 + rl) * ld + col0 + c16 * 8) = d;
;   }
	ds_read_b128 v[0:3], v0
	v_add_u32_e32 v6, s15, v6
	v_ashrrev_i32_e32 v7, 31, v6
	v_lshlrev_b64 v[6:7], 12, v[6:7]
	v_lshl_add_u64 v[6:7], v[4:5], 0, v[6:7]
	s_waitcnt lgkmcnt(0)
	flat_store_dwordx4 v[6:7], v[0:3]
	s_nop 1
	v_add_u32_e32 v0, 0x100, v64
	v_ashrrev_i32_e32 v6, 4, v0
	v_mad_u64_u32 v[0:1], s[0:1], v6, s11, v[180:181]
	ds_read_b128 v[0:3], v0
	v_add_u32_e32 v6, s15, v6
	v_ashrrev_i32_e32 v7, 31, v6
	v_lshlrev_b64 v[6:7], 12, v[6:7]
	v_lshl_add_u64 v[6:7], v[4:5], 0, v[6:7]
	s_waitcnt lgkmcnt(0)
	flat_store_dwordx4 v[6:7], v[0:3]
	s_nop 1
	v_add_u32_e32 v0, 0x200, v64
	v_ashrrev_i32_e32 v6, 4, v0
	v_mad_u64_u32 v[0:1], s[0:1], v6, s11, v[180:181]
	ds_read_b128 v[0:3], v0
	v_add_u32_e32 v6, s15, v6
	v_ashrrev_i32_e32 v7, 31, v6
	v_lshlrev_b64 v[6:7], 12, v[6:7]
	v_lshl_add_u64 v[6:7], v[4:5], 0, v[6:7]
	s_waitcnt lgkmcnt(0)
	flat_store_dwordx4 v[6:7], v[0:3]
	s_nop 1
	v_add_u32_e32 v0, 0x300, v64
	v_ashrrev_i32_e32 v6, 4, v0
	v_mad_u64_u32 v[0:1], s[0:1], v6, s11, v[180:181]
	ds_read_b128 v[0:3], v0
	v_add_u32_e32 v6, s15, v6
	v_ashrrev_i32_e32 v7, 31, v6
	v_lshlrev_b64 v[6:7], 12, v[6:7]
	v_lshl_add_u64 v[6:7], v[4:5], 0, v[6:7]
	s_waitcnt lgkmcnt(0)
	flat_store_dwordx4 v[6:7], v[0:3]
	s_nop 1
	v_add_u32_e32 v0, 0x400, v64
	v_ashrrev_i32_e32 v6, 4, v0
	v_mad_u64_u32 v[0:1], s[0:1], v6, s11, v[180:181]
	ds_read_b128 v[0:3], v0
	v_add_u32_e32 v6, s15, v6
	v_ashrrev_i32_e32 v7, 31, v6
	v_lshlrev_b64 v[6:7], 12, v[6:7]
	v_lshl_add_u64 v[6:7], v[4:5], 0, v[6:7]
	s_waitcnt lgkmcnt(0)
	flat_store_dwordx4 v[6:7], v[0:3]
	s_nop 1
	v_add_u32_e32 v0, 0x500, v64
	v_ashrrev_i32_e32 v6, 4, v0
	v_mad_u64_u32 v[0:1], s[0:1], v6, s11, v[180:181]
	ds_read_b128 v[0:3], v0
	v_add_u32_e32 v6, s15, v6
	v_ashrrev_i32_e32 v7, 31, v6
	v_lshlrev_b64 v[6:7], 12, v[6:7]
	v_lshl_add_u64 v[6:7], v[4:5], 0, v[6:7]
	s_waitcnt lgkmcnt(0)
	flat_store_dwordx4 v[6:7], v[0:3]
	s_nop 1
	v_add_u32_e32 v0, 0x600, v64
	v_ashrrev_i32_e32 v6, 4, v0
	v_mad_u64_u32 v[0:1], s[0:1], v6, s11, v[180:181]
	ds_read_b128 v[0:3], v0
	v_add_u32_e32 v6, s15, v6
	v_ashrrev_i32_e32 v7, 31, v6
	v_lshlrev_b64 v[6:7], 12, v[6:7]
	v_lshl_add_u64 v[6:7], v[4:5], 0, v[6:7]
	s_waitcnt lgkmcnt(0)
	flat_store_dwordx4 v[6:7], v[0:3]
	s_nop 1
	v_add_u32_e32 v0, 0x700, v64
	v_ashrrev_i32_e32 v6, 4, v0
	v_mad_u64_u32 v[0:1], s[0:1], v6, s11, v[180:181]
	ds_read_b128 v[0:3], v0
	v_add_u32_e32 v6, s15, v6
	v_ashrrev_i32_e32 v7, 31, v6
	v_lshlrev_b64 v[6:7], 12, v[6:7]
	v_lshl_add_u64 v[4:5], v[4:5], 0, v[6:7]
	v_readlane_b32 s0, v251, 6
	s_waitcnt lgkmcnt(0)
	flat_store_dwordx4 v[4:5], v[0:3]
	s_add_i32 s14, s0, s14
	s_cmpk_lt_i32 s14, 0x400
	v_readlane_b32 s1, v251, 7
	s_cbranch_scc1 .LBB0_399

; DEV int tid_() { int t = threadIdx.x; asm volatile("" : "+v"(t)); return t; }
; DEV int bid_() { int t = blockIdx.x; asm volatile("" : "+s"(t)); return t; }
; DEV int gdim_() { int t = gridDim.x; asm volatile("" : "+s"(t)); return t; }
; #define P (*launderP(lp))
; template <class FragT, class AccT>
; DEV void gemm_core_t(const char* __restrict__ A, size_t lda_bytes, const char* __restrict__ Bt, size_t ldb_bytes, int kbytes,
;                      int m0, int n0, int Sshift, int dl, char* smem, AccT (&acc)[4][4]) {
;   const int tid = tid_(), lane = tid & 63, wid = tid >> 6, wm = wid >> 1, wn = wid & 1;
;   const int l15 = lane & 15, q = lane >> 4;
;   const int srow = lane >> 3, schunk = (lane & 7) ^ (lane >> 3);
;   const char* ap[4];
;   const char* bp[4];
; #pragma unroll
;   for (int u = 0; u < 4; ++u) {
;     int r = (wid * 4 + u) * 8 + srow;
;     int ar = rowmap(m0 + r, Sshift, dl);
;     ap[u] = A + (size_t)ar * lda_bytes + schunk * 16;
;     bp[u] = Bt + (size_t)(n0 + r) * ldb_bytes + schunk * 16;
;   }
; #pragma unroll
;   for (int i = 0; i < 4; ++i)
; #pragma unroll
;     for (int j = 0; j < 4; ++j) acc[i][j] = AccT{0, 0, 0, 0};
;   const int nk = kbytes >> 7;
;   __syncthreads();
; #pragma unroll
;   for (int u = 0; u < 4; ++u) {
;     __builtin_amdgcn_global_load_lds((const unsigned*)ap[u], (unsigned*)(smem + (wid * 4 + u) * 1024 + lane * 16), 16, 0, 0);
;     __builtin_amdgcn_global_load_lds((const unsigned*)bp[u], (unsigned*)(smem + 16384 + (wid * 4 + u) * 1024 + lane * 16), 16, 0, 0);
;   }
;   const unsigned sbase = (unsigned)(unsigned long)((__attribute__((address_space(3))) char*)smem);
;   const unsigned sq0 = (unsigned)((q ^ (l15 & 7)) << 4);
;   const unsigned a0 = sbase + (unsigned)((wm * 64 + l15) * 128) + sq0;
;   const unsigned b0 = sbase + 16384u + (unsigned)((wn * 32 + l15) * 128) + sq0;
;   asm volatile("s_waitcnt vmcnt(0)" ::: "memory");
;   __syncthreads();
; __device__ __forceinline__ void phase_gemm3(PREF P, int slab, char* smem) {
;     ...
;   for (int t = bid_(); t < 64 * 16; t += gdim_()) {
;     int mt, nt;
;     tile_map(t, 2, mt, nt);
;     const int m0 = mt * 128, n0 = nt * 128;
;     f32x4 acc[4][4];
;     gemm_core(P.merged, 2048, P.WoutT, 2048, 2048, m0, n0, 13, 0, smem, acc);
.LBB0_458:
	s_ashr_i32 s0, s6, 3
	s_lshr_b32 s1, s0, 28
	s_add_i32 s1, s0, s1
	s_and_b32 s4, s1, -16
	v_mov_b32_e32 v22, v188
	s_sub_i32 s0, s0, s4
	s_lshl_b32 s4, s6, 1
	ds_read2_b64 v[0:3], v82 offset0:23 offset1:42
	s_and_b32 s4, s4, 14
	v_ashrrev_i32_e32 v24, 6, v22
	s_ashr_i32 s5, s0, 3
	s_lshl_b32 s1, s1, 6
	s_lshl_b32 s0, s0, 7
	v_bfe_u32 v25, v22, 3, 3
	v_lshlrev_b32_e32 v26, 5, v24
	s_add_i32 s15, s5, s4
	s_and_b32 s1, s1, 0xfffffc00
	s_and_b32 s4, s0, 0x380
	v_or_b32_e32 v20, v26, v25
	s_or_b32 s14, s4, s1
	s_lshl_b32 s0, s15, 7
	v_or_b32_e32 v14, 8, v20
	v_or_b32_e32 v18, 16, v20
	v_or_b32_e32 v27, 24, v20
	v_bitop3_b32 v4, v25, v22, 7 bitop3:0x78
	v_add_u32_e32 v8, s14, v20
	v_add_u32_e32 v10, s0, v20
	v_add_u32_e32 v12, s14, v14
	v_add_u32_e32 v16, s14, v18
	v_add_u32_e32 v20, s14, v27
	v_lshlrev_b32_e32 v180, 4, v4
	v_ashrrev_i32_e32 v9, 31, v8
	v_ashrrev_i32_e32 v13, 31, v12
	v_ashrrev_i32_e32 v17, 31, v16
	v_ashrrev_i32_e32 v21, 31, v20
	s_waitcnt lgkmcnt(0)
	v_lshl_add_u64 v[4:5], v[2:3], 0, v[180:181]
	v_lshlrev_b64 v[8:9], 12, v[8:9]
	v_lshlrev_b64 v[12:13], 12, v[12:13]
	v_lshlrev_b64 v[16:17], 12, v[16:17]
	v_lshlrev_b64 v[20:21], 12, v[20:21]
	v_lshl_add_u64 v[8:9], v[4:5], 0, v[8:9]
	v_lshl_add_u64 v[12:13], v[4:5], 0, v[12:13]
	v_add_u32_e32 v14, s0, v14
	v_lshl_add_u64 v[16:17], v[4:5], 0, v[16:17]
	v_add_u32_e32 v18, s0, v18
	v_lshl_add_u64 v[4:5], v[4:5], 0, v[20:21]
	v_add_u32_e32 v20, s0, v27
	v_ashrrev_i32_e32 v11, 31, v10
	v_ashrrev_i32_e32 v15, 31, v14
	v_ashrrev_i32_e32 v19, 31, v18
	v_ashrrev_i32_e32 v21, 31, v20
	v_lshl_add_u64 v[6:7], v[0:1], 0, v[180:181]
	v_lshlrev_b64 v[10:11], 12, v[10:11]
	v_lshlrev_b64 v[14:15], 12, v[14:15]
	v_lshlrev_b64 v[18:19], 12, v[18:19]
	v_lshlrev_b64 v[20:21], 12, v[20:21]
	v_and_b32_e32 v23, 63, v22
	v_lshl_add_u64 v[10:11], v[6:7], 0, v[10:11]
	v_lshl_add_u64 v[14:15], v[6:7], 0, v[14:15]
	v_lshl_add_u64 v[18:19], v[6:7], 0, v[18:19]
	v_lshl_add_u64 v[6:7], v[6:7], 0, v[20:21]
	v_lshlrev_b32_e32 v21, 12, v24
	v_lshl_or_b32 v85, v23, 4, v21
	s_nop 0
	v_readfirstlane_b32 s15, v85
	s_mov_b32 m0, s15
	s_barrier
	global_load_lds_dwordx4 v[8:9], off
	v_add_u32_e32 v8, 0x4000, v85
	v_and_b32_e32 v20, 15, v22
	v_readfirstlane_b32 s15, v8
	v_or_b32_e32 v8, 0x400, v85
	s_mov_b32 m0, s15
	v_readfirstlane_b32 s15, v8
	v_add_u32_e32 v8, 0x4400, v85
	global_load_lds_dwordx4 v[10:11], off
	s_mov_b32 m0, s15
	v_readfirstlane_b32 s15, v8
	v_or_b32_e32 v8, 0x800, v85
	global_load_lds_dwordx4 v[12:13], off
	s_mov_b32 m0, s15
	v_readfirstlane_b32 s15, v8
	v_add_u32_e32 v8, 0x4800, v85
	global_load_lds_dwordx4 v[14:15], off
	s_mov_b32 m0, s15
	v_readfirstlane_b32 s15, v8
	v_or_b32_e32 v8, 0xc00, v85
	global_load_lds_dwordx4 v[16:17], off
	s_mov_b32 m0, s15
	v_readfirstlane_b32 s15, v8
	global_load_lds_dwordx4 v[18:19], off
	s_mov_b32 m0, s15
	s_lshl_b32 s5, s5, 7
	global_load_lds_dwordx4 v[4:5], off
	v_add_u32_e32 v4, 0x4c00, v85
	v_lshrrev_b32_e32 v5, 1, v22
	v_readfirstlane_b32 s15, v4
	s_mov_b32 m0, s15
	v_lshlrev_b32_e32 v4, 4, v22
	global_load_lds_dwordx4 v[6:7], off
	s_mov_b32 s15, 0x1ffffc0
	v_bitop3_b32 v4, v23, s31, v4 bitop3:0x48
	v_and_or_b32 v5, v5, s15, v20
	v_and_or_b32 v6, v26, 32, v20
	s_and_b32 s15, s6, 7
	v_lshl_or_b32 v6, v6, 7, v4
	s_lshl_b32 s15, s15, 8
	v_lshlrev_b32_e32 v5, 7, v5
	v_or_b32_e32 v87, 0x4000, v6
	v_bitop3_b32 v88, v6, 64, v219 bitop3:0x36
	v_or_b32_e32 v6, 24, v25
	s_add_i32 s5, s5, s15
	v_or_b32_e32 v86, v4, v5
	v_bitop3_b32 v89, v4, 64, v5 bitop3:0x36
	v_or_b32_e32 v4, s5, v6
	v_add_u32_e32 v4, v4, v26
	v_ashrrev_i32_e32 v5, 31, v4
	s_mov_b64 s[16:17], 0x80
	v_lshlrev_b64 v[4:5], 12, v[4:5]
	v_lshl_add_u64 v[0:1], v[0:1], 0, s[16:17]
	v_or_b32_e32 v4, v4, v180
	v_lshl_add_u64 v[66:67], v[0:1], 0, v[4:5]
	v_or_b32_e32 v4, s1, v6
	v_or_b32_e32 v4, s4, v4
	v_add_u32_e32 v4, v4, v26
	v_ashrrev_i32_e32 v5, 31, v4
	v_lshlrev_b64 v[4:5], 12, v[4:5]
	v_lshl_add_u64 v[2:3], v[2:3], 0, s[16:17]
	v_or_b32_e32 v4, v4, v180
	v_or_b32_e32 v6, 16, v25
	v_lshl_add_u64 v[68:69], v[2:3], 0, v[4:5]
	v_or_b32_e32 v4, s5, v6
	v_add_u32_e32 v4, v4, v26
	v_ashrrev_i32_e32 v5, 31, v4
	v_lshlrev_b64 v[4:5], 12, v[4:5]
	v_or_b32_e32 v4, v4, v180
	v_lshl_add_u64 v[70:71], v[0:1], 0, v[4:5]
	v_or_b32_e32 v4, s1, v6
	v_or_b32_e32 v4, s4, v4
	v_add_u32_e32 v4, v4, v26
	v_ashrrev_i32_e32 v5, 31, v4
	v_lshlrev_b64 v[4:5], 12, v[4:5]
	v_or_b32_e32 v4, v4, v180
	v_or_b32_e32 v6, 8, v25
	v_lshl_add_u64 v[72:73], v[2:3], 0, v[4:5]
	v_or_b32_e32 v4, s5, v6
	v_add_u32_e32 v4, v4, v26
	v_ashrrev_i32_e32 v5, 31, v4
	v_lshlrev_b64 v[4:5], 12, v[4:5]
	v_or_b32_e32 v4, v4, v180
	v_lshl_add_u64 v[74:75], v[0:1], 0, v[4:5]
	v_or_b32_e32 v4, s1, v6
	v_or_b32_e32 v4, s4, v4
	v_add_u32_e32 v4, v4, v26
	v_ashrrev_i32_e32 v5, 31, v4
	v_lshlrev_b64 v[4:5], 12, v[4:5]
	v_or_b32_e32 v4, v4, v180
	v_lshl_add_u64 v[76:77], v[2:3], 0, v[4:5]
	v_or_b32_e32 v4, s5, v25
	v_add_u32_e32 v4, v4, v26
	v_ashrrev_i32_e32 v5, 31, v4
	v_lshlrev_b64 v[4:5], 12, v[4:5]
	v_or_b32_e32 v4, v4, v180
	v_lshl_add_u64 v[78:79], v[0:1], 0, v[4:5]
	v_or_b32_e32 v0, s1, v25
	v_or_b32_e32 v0, s4, v0
	v_add_u32_e32 v0, v0, v26
	v_ashrrev_i32_e32 v1, 31, v0
	v_lshlrev_b64 v[0:1], 12, v[0:1]
	v_or_b32_e32 v0, v0, v180
	v_lshl_add_u64 v[80:81], v[2:3], 0, v[0:1]
	v_mov_b32_e32 v0, 0
	s_mov_b64 s[4:5], 0
	s_mov_b32 s1, 0x8000
	v_mov_b32_e32 v1, v0
	v_mov_b32_e32 v2, v0
	v_mov_b32_e32 v3, v0
	v_mov_b32_e32 v4, v0
	v_mov_b32_e32 v5, v0
	v_mov_b32_e32 v6, v0
	v_mov_b32_e32 v7, v0
	v_mov_b32_e32 v8, v0
	v_mov_b32_e32 v9, v0
	v_mov_b32_e32 v10, v0
	v_mov_b32_e32 v11, v0
	v_mov_b32_e32 v12, v0
	v_mov_b32_e32 v13, v0
	v_mov_b32_e32 v14, v0
; DEV f32x4 mma_step(bf16x8 a, bf16x8 b, f32x4 c) { return MFMA(a, b, c); }
; template <class FragT, class AccT>
; DEV void gemm_core_t(const char* __restrict__ A, size_t lda_bytes, const char* __restrict__ Bt, size_t ldb_bytes, int kbytes,
;                      int m0, int n0, int Sshift, int dl, char* smem, AccT (&acc)[4][4]) {
;     ...
;   for (int kt = 0; kt < nk; ++kt) {
;     const unsigned so = (unsigned)(kt & 1) * 32768u;
;     char* nxt = smem + ((kt + 1) & 1) * 32768;
;     if (kt + 1 < nk) {
; #pragma unroll
;       for (int u = 0; u < 4; ++u) {
;         __builtin_amdgcn_global_load_lds((const unsigned*)(ap[u] + (size_t)(kt + 1) * 128), (unsigned*)(nxt + (wid * 4 + u) * 1024 + lane * 16), 16, 0, 0);
;         __builtin_amdgcn_global_load_lds((const unsigned*)(bp[u] + (size_t)(kt + 1) * 128), (unsigned*)(nxt + 16384 + (wid * 4 + u) * 1024 + lane * 16), 16, 0, 0);
;       }
;     }
;     FragT xa[2][4], wb[2][4];
;     asm volatile(
;         "ds_read_b128 %0, %16\n\t"
;         "ds_read_b128 %1, %16 offset:2048\n\t"
;         "ds_read_b128 %2, %16 offset:4096\n\t"
;         "ds_read_b128 %3, %16 offset:6144\n\t"
;         "ds_read_b128 %4, %18\n\t"
;         "ds_read_b128 %5, %18 offset:2048\n\t"
;         "ds_read_b128 %6, %18 offset:8192\n\t"
;         "ds_read_b128 %7, %18 offset:10240\n\t"
;         "ds_read_b128 %8, %17\n\t"
;         "ds_read_b128 %9, %17 offset:2048\n\t"
;         "ds_read_b128 %10, %17 offset:4096\n\t"
;         "ds_read_b128 %11, %17 offset:6144\n\t"
;         "ds_read_b128 %12, %19\n\t"
;         "ds_read_b128 %13, %19 offset:2048\n\t"
;         "ds_read_b128 %14, %19 offset:8192\n\t"
;         "ds_read_b128 %15, %19 offset:10240\n\t"
;         "s_waitcnt lgkmcnt(8)"
;         : "=&v"(xa[0][0]), "=&v"(xa[0][1]), "=&v"(xa[0][2]), "=&v"(xa[0][3]), "=&v"(wb[0][0]), "=&v"(wb[0][1]), "=&v"(wb[0][2]),
;           "=&v"(wb[0][3]), "=&v"(xa[1][0]), "=&v"(xa[1][1]), "=&v"(xa[1][2]), "=&v"(xa[1][3]), "=&v"(wb[1][0]), "=&v"(wb[1][1]),
;           "=&v"(wb[1][2]), "=&v"(wb[1][3])
;         : "v"(a0 + so), "v"((a0 ^ 64u) + so), "v"(b0 + so), "v"((b0 ^ 64u) + so)
;         : "memory");
;     __builtin_amdgcn_s_setprio(1);
; #pragma unroll
;     for (int i = 0; i < 4; ++i)
; #pragma unroll
;       for (int j = 0; j < 4; ++j) acc[i][j] = mma_step(wb[0][j], xa[0][i], acc[i][j]);
;     asm volatile("s_waitcnt lgkmcnt(0)"
	v_mov_b32_e32 v15, v0
	v_mov_b32_e32 v16, v0
	v_mov_b32_e32 v17, v0
	v_mov_b32_e32 v18, v0
	v_mov_b32_e32 v19, v0
	v_mov_b32_e32 v20, v0
	v_mov_b32_e32 v21, v0
	v_mov_b32_e32 v22, v0
	v_mov_b32_e32 v23, v0
	v_mov_b32_e32 v24, v0
	v_mov_b32_e32 v25, v0
	v_mov_b32_e32 v26, v0
	v_mov_b32_e32 v27, v0
	v_mov_b32_e32 v28, v0
	v_mov_b32_e32 v29, v0
	v_mov_b32_e32 v30, v0
	v_mov_b32_e32 v31, v0
	v_mov_b32_e32 v32, v0
	v_mov_b32_e32 v33, v0
	v_mov_b32_e32 v34, v0
	v_mov_b32_e32 v35, v0
	v_mov_b32_e32 v36, v0
	v_mov_b32_e32 v37, v0
	v_mov_b32_e32 v38, v0
	v_mov_b32_e32 v39, v0
	v_mov_b32_e32 v40, v0
	v_mov_b32_e32 v41, v0
	v_mov_b32_e32 v42, v0
	v_mov_b32_e32 v43, v0
	v_mov_b32_e32 v44, v0
	v_mov_b32_e32 v45, v0
	v_mov_b32_e32 v46, v0
	v_mov_b32_e32 v47, v0
	v_mov_b32_e32 v48, v0
	v_mov_b32_e32 v49, v0
	v_mov_b32_e32 v50, v0
	v_mov_b32_e32 v51, v0
	v_mov_b32_e32 v52, v0
	v_mov_b32_e32 v53, v0
	v_mov_b32_e32 v54, v0
	v_mov_b32_e32 v55, v0
	v_mov_b32_e32 v56, v0
	v_mov_b32_e32 v57, v0
	v_mov_b32_e32 v58, v0
	v_mov_b32_e32 v59, v0
	v_mov_b32_e32 v60, v0
	v_mov_b32_e32 v61, v0
	v_mov_b32_e32 v62, v0
	v_mov_b32_e32 v63, v0
	v_readfirstlane_b32 s64, v80
	v_readfirstlane_b32 s65, v81
	v_readfirstlane_b32 s66, v78
	v_readfirstlane_b32 s67, v79
	v_readfirstlane_b32 s62, v85
	s_sub_u32 s64, s64, 0x80000000
	s_subb_u32 s65, s65, 0
	s_sub_u32 s66, s66, 0x80000000
	s_subb_u32 s67, s67, 0
	v_subrev_u32_e32 v80, s64, v80
	v_subrev_u32_e32 v78, s66, v78
	v_subrev_u32_e32 v76, s64, v76
	v_subrev_u32_e32 v74, s66, v74
	v_subrev_u32_e32 v72, s64, v72
	v_subrev_u32_e32 v70, s66, v70
	v_subrev_u32_e32 v68, s64, v68
	v_subrev_u32_e32 v66, s66, v66
	s_waitcnt vmcnt(0) lgkmcnt(0)
	s_barrier
.LBB0_459:
	s_add_i32 s15, s1, 0xffff8000
	s_and_b32 s15, s15, 0x8000
	v_add_u32_e32 v154, s15, v86
	v_add_u32_e32 v155, s15, v89
	v_or_b32_e32 v156, s15, v87
	v_or_b32_e32 v157, s15, v88
	s_and_b32 s15, s1, 0x8000
	s_add_i32 s15, s15, s62
	s_mov_b32 m0, s15
	ds_read_b128 v[90:93], v154
	global_load_lds_dwordx4 v80, s[64:65]
	ds_read_b128 v[94:97], v154 offset:2048
	s_add_i32 m0, s15, 0x4000
	ds_read_b128 v[98:101], v154 offset:4096
	global_load_lds_dwordx4 v78, s[66:67]
	ds_read_b128 v[102:105], v154 offset:6144
	s_add_i32 m0, s15, 0x400
	ds_read_b128 v[106:109], v156
	global_load_lds_dwordx4 v76, s[64:65]
	ds_read_b128 v[110:113], v156 offset:2048
	s_add_i32 m0, s15, 0x4400
	ds_read_b128 v[114:117], v156 offset:8192
	global_load_lds_dwordx4 v74, s[66:67]
	ds_read_b128 v[118:121], v156 offset:10240
	ds_read_b128 v[122:125], v155
	ds_read_b128 v[126:129], v155 offset:2048
	ds_read_b128 v[130:133], v155 offset:4096
	ds_read_b128 v[134:137], v155 offset:6144
	ds_read_b128 v[138:141], v157
	ds_read_b128 v[142:145], v157 offset:2048
	ds_read_b128 v[146:149], v157 offset:8192
	ds_read_b128 v[150:153], v157 offset:10240
	s_waitcnt lgkmcnt(8)
	s_setprio 1
	v_mfma_f32_16x16x32_bf16 v[60:63], v[106:109], v[90:93], v[60:63]
	v_mfma_f32_16x16x32_bf16 v[56:59], v[110:113], v[90:93], v[56:59]
	s_add_i32 m0, s15, 0x800
	v_mfma_f32_16x16x32_bf16 v[52:55], v[114:117], v[90:93], v[52:55]
	global_load_lds_dwordx4 v72, s[64:65]
	v_mfma_f32_16x16x32_bf16 v[48:51], v[118:121], v[90:93], v[48:51]
	v_mfma_f32_16x16x32_bf16 v[44:47], v[106:109], v[94:97], v[44:47]
	v_mfma_f32_16x16x32_bf16 v[40:43], v[110:113], v[94:97], v[40:43]
	s_add_i32 m0, s15, 0x4800
	v_mfma_f32_16x16x32_bf16 v[36:39], v[114:117], v[94:97], v[36:39]
	global_load_lds_dwordx4 v70, s[66:67]
	v_mfma_f32_16x16x32_bf16 v[32:35], v[118:121], v[94:97], v[32:35]
	v_mfma_f32_16x16x32_bf16 v[28:31], v[106:109], v[98:101], v[28:31]
	v_mfma_f32_16x16x32_bf16 v[24:27], v[110:113], v[98:101], v[24:27]
	s_add_i32 m0, s15, 0xc00
	v_mfma_f32_16x16x32_bf16 v[20:23], v[114:117], v[98:101], v[20:23]
	global_load_lds_dwordx4 v68, s[64:65]
	v_mfma_f32_16x16x32_bf16 v[16:19], v[118:121], v[98:101], v[16:19]
	v_mfma_f32_16x16x32_bf16 v[12:15], v[106:109], v[102:105], v[12:15]
	v_mfma_f32_16x16x32_bf16 v[8:11], v[110:113], v[102:105], v[8:11]
	s_add_i32 m0, s15, 0x4c00
	v_mfma_f32_16x16x32_bf16 v[4:7], v[114:117], v[102:105], v[4:7]
	global_load_lds_dwordx4 v66, s[66:67]
	v_mfma_f32_16x16x32_bf16 v[0:3], v[118:121], v[102:105], v[0:3]
	s_waitcnt lgkmcnt(0)
	s_nop 0
	v_mfma_f32_16x16x32_bf16 v[60:63], v[138:141], v[122:125], v[60:63]
	v_mfma_f32_16x16x32_bf16 v[56:59], v[142:145], v[122:125], v[56:59]
	v_mfma_f32_16x16x32_bf16 v[52:55], v[146:149], v[122:125], v[52:55]
	v_mfma_f32_16x16x32_bf16 v[48:51], v[150:153], v[122:125], v[48:51]
	v_mfma_f32_16x16x32_bf16 v[44:47], v[138:141], v[126:129], v[44:47]
	v_mfma_f32_16x16x32_bf16 v[40:43], v[142:145], v[126:129], v[40:43]
	v_mfma_f32_16x16x32_bf16 v[36:39], v[146:149], v[126:129], v[36:39]
	v_mfma_f32_16x16x32_bf16 v[32:35], v[150:153], v[126:129], v[32:35]
	v_mfma_f32_16x16x32_bf16 v[28:31], v[138:141], v[130:133], v[28:31]
	v_mfma_f32_16x16x32_bf16 v[24:27], v[142:145], v[130:133], v[24:27]
	v_mfma_f32_16x16x32_bf16 v[20:23], v[146:149], v[130:133], v[20:23]
	v_mfma_f32_16x16x32_bf16 v[16:19], v[150:153], v[130:133], v[16:19]
	v_mfma_f32_16x16x32_bf16 v[12:15], v[138:141], v[134:137], v[12:15]
	v_mfma_f32_16x16x32_bf16 v[8:11], v[142:145], v[134:137], v[8:11]
	v_mfma_f32_16x16x32_bf16 v[4:7], v[146:149], v[134:137], v[4:7]
	v_mfma_f32_16x16x32_bf16 v[0:3], v[150:153], v[134:137], v[0:3]
	s_setprio 0
	s_waitcnt vmcnt(0)
	s_add_u32 s4, s4, 0x80
	s_addc_u32 s5, s5, 0
	s_add_u32 s64, s64, 0x80
	s_addc_u32 s65, s65, 0
	s_add_u32 s66, s66, 0x80
	s_addc_u32 s67, s67, 0
	s_add_i32 s1, s1, 0x8000
	s_cmpk_lg_i32 s4, 0xf80
	s_waitcnt vmcnt(0) lgkmcnt(0)
	s_barrier
	s_cbranch_scc1 .LBB0_459
; DEV f32x4 mma_step(bf16x8 a, bf16x8 b, f32x4 c) { return MFMA(a, b, c); }
; DEV i32x4 mma_step(i32x4 a, i32x4 b, i32x4 c) { return __builtin_amdgcn_mfma_i32_16x16x64_i8(a, b, c, 0, 0, 0); }
; template <class FragT, class AccT>
; DEV void gemm_core_t(const char* __restrict__ A, size_t lda_bytes, const char* __restrict__ Bt, size_t ldb_bytes, int kbytes,
;                      int m0, int n0, int Sshift, int dl, char* smem, AccT (&acc)[4][4]) {
;     ...
;     for (int i = 0; i < 4; ++i)
; #pragma unroll
;       for (int j = 0; j < 4; ++j) acc[i][j] = mma_step(wb[0][j], xa[0][i], acc[i][j]);
;     asm volatile("s_waitcnt lgkmcnt(0)"
;                  : "+v"(xa[1][0]), "+v"(xa[1][1]), "+v"(xa[1][2]), "+v"(xa[1][3]), "+v"(wb[1][0]), "+v"(wb[1][1]), "+v"(wb[1][2]),
;                    "+v"(wb[1][3]), "+v"(acc[0][0]), "+v"(acc[0][1]), "+v"(acc[0][2]), "+v"(acc[0][3]), "+v"(acc[1][0]),
;                    "+v"(acc[1][1]), "+v"(acc[1][2]), "+v"(acc[1][3]), "+v"(acc[2][0]), "+v"(acc[2][1]), "+v"(acc[2][2]),
;                    "+v"(acc[2][3]), "+v"(acc[3][0]), "+v"(acc[3][1]), "+v"(acc[3][2]), "+v"(acc[3][3])
;                  :
;                  : "memory");
; #pragma unroll
;     for (int i = 0; i < 4; ++i)
; #pragma unroll
;       for (int j = 0; j < 4; ++j) acc[i][j] = mma_step(wb[1][j], xa[1][i], acc[i][j]);
; __device__ __forceinline__ void phase_gemm3(PREF P, int slab, char* smem) {
;     ...
; #pragma unroll
;     for (int i = 0; i < 4; ++i)
; #pragma unroll
;       for (int j = 0; j < 4; ++j) {
;         const int row = m0 + wm * 64 + i * 16 + l15, col = n0 + (j & 1) * 16 + wn * 32 + (j >> 1) * 64 + q * 4;
;         float4 xv = *(const float4*)(xs + (size_t)row * 2048 + col);
;         f32x4 o;
;         o[0] = DN_ALPHA * xv.x + acc[i][j][0]; o[1] = DN_ALPHA * xv.y + acc[i][j][1];
;         o[2] = DN_ALPHA * xv.z + acc[i][j][2]; o[3] = DN_ALPHA * xv.w + acc[i][j][3];
;         acc[i][j] = o;
;       }
	v_add_u32_e32 v85, 0x8000, v86
	v_add_u32_e32 v134, 0x8000, v89
	v_or_b32_e32 v135, 0x8000, v87
	v_or_b32_e32 v136, 0x8000, v88
	ds_read_b128 v[66:69], v85
	ds_read_b128 v[70:73], v85 offset:2048
	ds_read_b128 v[74:77], v85 offset:4096
	ds_read_b128 v[78:81], v85 offset:6144
	ds_read_b128 v[86:89], v135
	ds_read_b128 v[90:93], v135 offset:2048
	ds_read_b128 v[94:97], v135 offset:8192
	ds_read_b128 v[98:101], v135 offset:10240
	ds_read_b128 v[102:105], v134
	ds_read_b128 v[106:109], v134 offset:2048
	ds_read_b128 v[110:113], v134 offset:4096
	ds_read_b128 v[114:117], v134 offset:6144
	ds_read_b128 v[118:121], v136
	ds_read_b128 v[122:125], v136 offset:2048
	ds_read_b128 v[126:129], v136 offset:8192
	ds_read_b128 v[130:133], v136 offset:10240
	s_waitcnt lgkmcnt(8)
	s_setprio 1
	v_mfma_f32_16x16x32_bf16 v[60:63], v[86:89], v[66:69], v[60:63]
	v_mfma_f32_16x16x32_bf16 v[56:59], v[90:93], v[66:69], v[56:59]
	v_mfma_f32_16x16x32_bf16 v[52:55], v[94:97], v[66:69], v[52:55]
	v_mfma_f32_16x16x32_bf16 v[48:51], v[98:101], v[66:69], v[48:51]
	v_mfma_f32_16x16x32_bf16 v[44:47], v[86:89], v[70:73], v[44:47]
	v_mfma_f32_16x16x32_bf16 v[40:43], v[90:93], v[70:73], v[40:43]
	v_mfma_f32_16x16x32_bf16 v[36:39], v[94:97], v[70:73], v[36:39]
	v_mfma_f32_16x16x32_bf16 v[32:35], v[98:101], v[70:73], v[32:35]
	v_mfma_f32_16x16x32_bf16 v[28:31], v[86:89], v[74:77], v[28:31]
	v_mfma_f32_16x16x32_bf16 v[24:27], v[90:93], v[74:77], v[24:27]
	v_mfma_f32_16x16x32_bf16 v[20:23], v[94:97], v[74:77], v[20:23]
	v_mfma_f32_16x16x32_bf16 v[16:19], v[98:101], v[74:77], v[16:19]
	v_mfma_f32_16x16x32_bf16 v[12:15], v[86:89], v[78:81], v[12:15]
	v_mfma_f32_16x16x32_bf16 v[8:11], v[90:93], v[78:81], v[8:11]
	v_mfma_f32_16x16x32_bf16 v[4:7], v[94:97], v[78:81], v[4:7]
	v_mfma_f32_16x16x32_bf16 v[0:3], v[98:101], v[78:81], v[0:3]
	s_waitcnt lgkmcnt(0)
	s_nop 0
	v_mfma_f32_16x16x32_bf16 v[60:63], v[118:121], v[102:105], v[60:63]
	v_mfma_f32_16x16x32_bf16 v[56:59], v[122:125], v[102:105], v[56:59]
	v_mfma_f32_16x16x32_bf16 v[52:55], v[126:129], v[102:105], v[52:55]
	v_mfma_f32_16x16x32_bf16 v[48:51], v[130:133], v[102:105], v[48:51]
	v_mfma_f32_16x16x32_bf16 v[44:47], v[118:121], v[106:109], v[44:47]
	v_mfma_f32_16x16x32_bf16 v[40:43], v[122:125], v[106:109], v[40:43]
	v_mfma_f32_16x16x32_bf16 v[36:39], v[126:129], v[106:109], v[36:39]
	v_mfma_f32_16x16x32_bf16 v[32:35], v[130:133], v[106:109], v[32:35]
	v_mfma_f32_16x16x32_bf16 v[66:69], v[118:121], v[110:113], v[28:31]
	v_mfma_f32_16x16x32_bf16 v[70:73], v[122:125], v[110:113], v[24:27]
	v_mfma_f32_16x16x32_bf16 v[74:77], v[126:129], v[110:113], v[20:23]
	v_mfma_f32_16x16x32_bf16 v[78:81], v[130:133], v[110:113], v[16:19]
	v_mfma_f32_16x16x32_bf16 v[86:89], v[118:121], v[114:117], v[12:15]
	v_mfma_f32_16x16x32_bf16 v[90:93], v[122:125], v[114:117], v[8:11]
	v_mfma_f32_16x16x32_bf16 v[94:97], v[126:129], v[114:117], v[4:7]
	v_mfma_f32_16x16x32_bf16 v[0:3], v[130:133], v[114:117], v[0:3]
	s_setprio 0
	v_add_u32_e32 v98, s14, v83
	v_or_b32_e32 v4, s0, v84
	v_ashrrev_i32_e32 v99, 31, v98
	v_ashrrev_i32_e32 v5, 31, v4
	v_lshlrev_b64 v[6:7], 13, v[98:99]
	v_lshl_add_u64 v[6:7], v[64:65], 0, v[6:7]
	v_lshlrev_b64 v[100:101], 2, v[4:5]
	v_lshl_add_u64 v[12:13], v[6:7], 0, v[100:101]
	s_waitcnt vmcnt(0)
	s_barrier
	flat_load_dwordx4 v[4:7], v[12:13]
	flat_load_dwordx4 v[8:11], v[12:13] offset:256
	v_or_b32_e32 v16, 16, v98
	v_ashrrev_i32_e32 v17, 31, v16
	v_lshlrev_b64 v[16:17], 13, v[16:17]
	v_lshl_add_u64 v[16:17], v[64:65], 0, v[16:17]
	v_lshl_add_u64 v[28:29], v[16:17], 0, v[100:101]
	flat_load_dwordx4 v[24:27], v[28:29] offset:256
	s_mov_b32 s1, 0xfffffc0
	flat_load_dwordx4 v[16:19], v[28:29]
	flat_load_dwordx4 v[20:23], v[28:29] offset:64
	s_waitcnt vmcnt(0) lgkmcnt(0)
	v_pk_fma_f32 v[60:61], v[4:5], s[28:29], v[60:61] op_sel_hi:[1,0,1]
	v_pk_fma_f32 v[62:63], v[6:7], s[28:29], v[62:63] op_sel_hi:[1,0,1]
	flat_load_dwordx4 v[4:7], v[12:13] offset:64
	v_pk_fma_f32 v[8:9], v[8:9], s[28:29], v[52:53] op_sel_hi:[1,0,1]
	flat_load_dwordx4 v[12:15], v[12:13] offset:320
	v_pk_fma_f32 v[10:11], v[10:11], s[28:29], v[54:55] op_sel_hi:[1,0,1]
	flat_load_dwordx4 v[28:31], v[28:29] offset:320
	v_pk_fma_f32 v[24:25], v[24:25], s[28:29], v[36:37] op_sel_hi:[1,0,1]
	v_pk_fma_f32 v[26:27], v[26:27], s[28:29], v[38:39] op_sel_hi:[1,0,1]
	v_pk_fma_f32 v[16:17], v[16:17], s[28:29], v[44:45] op_sel_hi:[1,0,1]
	v_pk_fma_f32 v[18:19], v[18:19], s[28:29], v[46:47] op_sel_hi:[1,0,1]
	v_pk_fma_f32 v[20:21], v[20:21], s[28:29], v[40:41] op_sel_hi:[1,0,1]
	v_pk_fma_f32 v[22:23], v[22:23], s[28:29], v[42:43] op_sel_hi:[1,0,1]
	s_waitcnt vmcnt(0) lgkmcnt(0)
	v_pk_fma_f32 v[4:5], v[4:5], s[28:29], v[56:57] op_sel_hi:[1,0,1]
	v_pk_fma_f32 v[6:7], v[6:7], s[28:29], v[58:59] op_sel_hi:[1,0,1]
	v_pk_fma_f32 v[12:13], v[12:13], s[28:29], v[48:49] op_sel_hi:[1,0,1]
	v_pk_fma_f32 v[14:15], v[14:15], s[28:29], v[50:51] op_sel_hi:[1,0,1]
	v_pk_fma_f32 v[28:29], v[28:29], s[28:29], v[32:33] op_sel_hi:[1,0,1]
	v_or_b32_e32 v32, 32, v98
	v_ashrrev_i32_e32 v33, 31, v32
	v_lshlrev_b64 v[32:33], 13, v[32:33]
	v_lshl_add_u64 v[32:33], v[64:65], 0, v[32:33]
	v_lshl_add_u64 v[44:45], v[32:33], 0, v[100:101]
	v_pk_fma_f32 v[30:31], v[30:31], s[28:29], v[34:35] op_sel_hi:[1,0,1]
	flat_load_dwordx4 v[32:35], v[44:45]
	flat_load_dwordx4 v[36:39], v[44:45] offset:64
	flat_load_dwordx4 v[40:43], v[44:45] offset:256
	v_cvt_pk_bf16_f32 v4, v4, v5
	flat_load_dwordx4 v[44:47], v[44:45] offset:320
	v_cvt_pk_bf16_f32 v5, v6, v7
	v_cvt_pk_bf16_f32 v6, v12, v13
	v_cvt_pk_bf16_f32 v7, v14, v15
	s_waitcnt vmcnt(0) lgkmcnt(0)
; DEV int tid_() { int t = threadIdx.x; asm volatile("" : "+v"(t)); return t; }
; #define P (*launderP(lp))
; DEV void stage_tile_bf16(char* smem, const f32x4 (&v)[4][4], u16* buf, int ld, int m0, int col0) {
;   const int tid = tid_(), lane = tid & 63, wid = tid >> 6, wm = wid >> 1, wn = wid & 1, l15 = lane & 15, q = lane >> 4;
; #pragma unroll
;   for (int i = 0; i < 4; ++i)
; #pragma unroll
;     for (int j = 0; j < 4; ++j) {
;       const int rl = wm * 64 + i * 16 + l15, cl = (j & 1) * 16 + wn * 32 + (j >> 1) * 64 + q * 4;
;       u32x2 o; o.x = pack2(v[i][j][0], v[i][j][1]); o.y = pack2(v[i][j][2], v[i][j][3]);
;       *(u32x2*)(smem + rl * 272 + cl * 2) = o;
;     }
;   __syncthreads();
; #pragma unroll
;   for (int k = 0; k < 8; ++k) {
;     const int chunk = tid + 256 * k, rl = chunk >> 4, c16 = chunk & 15;
;     u32x4 d = *(const u32x4*)(smem + rl * 272 + c16 * 16);
;     *(u32x4*)(buf + (size_t)(m0 + rl) * ld + col0 + c16 * 8) = d;
;   }
; __device__ __forceinline__ void phase_gemm3(PREF P, int slab, char* smem) {
;     ...
; #pragma unroll
;     for (int i = 0; i < 4; ++i)
; #pragma unroll
;       for (int j = 0; j < 4; ++j) {
;         const int row = m0 + wm * 64 + i * 16 + l15, col = n0 + (j & 1) * 16 + wn * 32 + (j >> 1) * 64 + q * 4;
;         float4 xv = *(const float4*)(xs + (size_t)row * 2048 + col);
;         f32x4 o;
;         o[0] = DN_ALPHA * xv.x + acc[i][j][0]; o[1] = DN_ALPHA * xv.y + acc[i][j][1];
;         o[2] = DN_ALPHA * xv.z + acc[i][j][2]; o[3] = DN_ALPHA * xv.w + acc[i][j][3];
;         acc[i][j] = o;
;       }
;     stage_tile_bf16(smem, acc, (u16*)P.y, 2048, m0, n0);
	v_pk_fma_f32 v[32:33], v[32:33], s[28:29], v[66:67] op_sel_hi:[1,0,1]
	v_pk_fma_f32 v[34:35], v[34:35], s[28:29], v[68:69] op_sel_hi:[1,0,1]
	v_pk_fma_f32 v[36:37], v[36:37], s[28:29], v[70:71] op_sel_hi:[1,0,1]
	v_pk_fma_f32 v[38:39], v[38:39], s[28:29], v[72:73] op_sel_hi:[1,0,1]
	v_pk_fma_f32 v[48:49], v[44:45], s[28:29], v[78:79] op_sel_hi:[1,0,1]
	v_or_b32_e32 v44, 48, v98
	v_ashrrev_i32_e32 v45, 31, v44
	v_lshlrev_b64 v[44:45], 13, v[44:45]
	v_lshl_add_u64 v[44:45], v[64:65], 0, v[44:45]
	v_lshl_add_u64 v[52:53], v[44:45], 0, v[100:101]
	v_pk_fma_f32 v[50:51], v[46:47], s[28:29], v[80:81] op_sel_hi:[1,0,1]
	flat_load_dwordx4 v[44:47], v[52:53]
	v_mov_b32_e32 v72, v188
	v_pk_fma_f32 v[40:41], v[40:41], s[28:29], v[74:75] op_sel_hi:[1,0,1]
	v_pk_fma_f32 v[42:43], v[42:43], s[28:29], v[76:77] op_sel_hi:[1,0,1]
	s_waitcnt vmcnt(0) lgkmcnt(0)
	v_pk_fma_f32 v[54:55], v[44:45], s[28:29], v[86:87] op_sel_hi:[1,0,1]
	v_pk_fma_f32 v[56:57], v[46:47], s[28:29], v[88:89] op_sel_hi:[1,0,1]
	flat_load_dwordx4 v[44:47], v[52:53] offset:64
	s_waitcnt vmcnt(0) lgkmcnt(0)
	v_pk_fma_f32 v[58:59], v[44:45], s[28:29], v[90:91] op_sel_hi:[1,0,1]
	v_pk_fma_f32 v[66:67], v[46:47], s[28:29], v[92:93] op_sel_hi:[1,0,1]
	flat_load_dwordx4 v[44:47], v[52:53] offset:256
	s_waitcnt vmcnt(0) lgkmcnt(0)
	v_pk_fma_f32 v[68:69], v[44:45], s[28:29], v[94:95] op_sel_hi:[1,0,1]
	v_pk_fma_f32 v[70:71], v[46:47], s[28:29], v[96:97] op_sel_hi:[1,0,1]
	flat_load_dwordx4 v[44:47], v[52:53] offset:320
	s_waitcnt vmcnt(0) lgkmcnt(0)
	v_pk_fma_f32 v[0:1], v[44:45], s[28:29], v[0:1] op_sel_hi:[1,0,1]
	v_pk_fma_f32 v[2:3], v[46:47], s[28:29], v[2:3] op_sel_hi:[1,0,1]
	ds_read_b64 v[44:45], v82 offset:376
	v_cvt_pk_bf16_f32 v46, v60, v61
	v_and_b32_e32 v73, 15, v72
	v_lshrrev_b32_e32 v52, 1, v72
	v_and_b32_e32 v60, 64, v72
	v_and_or_b32 v53, v52, s1, v73
	v_and_or_b32 v52, v52, 24, v60
	v_cvt_pk_bf16_f32 v47, v62, v63
	v_mad_u64_u32 v[52:53], s[4:5], v53, s11, v[52:53]
	ds_write2_b64 v52, v[46:47], v[4:5] offset1:4
	v_cvt_pk_bf16_f32 v4, v8, v9
	v_cvt_pk_bf16_f32 v5, v10, v11
	ds_write2_b64 v52, v[4:5], v[6:7] offset0:16 offset1:20
	v_cvt_pk_bf16_f32 v4, v16, v17
	v_cvt_pk_bf16_f32 v5, v18, v19
	v_cvt_pk_bf16_f32 v6, v20, v21
	v_cvt_pk_bf16_f32 v7, v22, v23
	v_add_u32_e32 v8, 0x1000, v52
	ds_write2_b64 v8, v[4:5], v[6:7] offset0:32 offset1:36
	v_cvt_pk_bf16_f32 v4, v24, v25
	v_cvt_pk_bf16_f32 v5, v26, v27
	v_cvt_pk_bf16_f32 v6, v28, v29
	v_cvt_pk_bf16_f32 v7, v30, v31
	ds_write2_b64 v8, v[4:5], v[6:7] offset0:48 offset1:52
	v_cvt_pk_bf16_f32 v4, v32, v33
	v_cvt_pk_bf16_f32 v5, v34, v35
	v_cvt_pk_bf16_f32 v6, v36, v37
	v_cvt_pk_bf16_f32 v7, v38, v39
	v_add_u32_e32 v8, 0x2000, v52
	ds_write2_b64 v8, v[4:5], v[6:7] offset0:64 offset1:68
	v_cvt_pk_bf16_f32 v4, v40, v41
	v_cvt_pk_bf16_f32 v5, v42, v43
	v_cvt_pk_bf16_f32 v6, v48, v49
	v_cvt_pk_bf16_f32 v7, v50, v51
	ds_write2_b64 v8, v[4:5], v[6:7] offset0:80 offset1:84
	v_cvt_pk_bf16_f32 v4, v54, v55
	v_cvt_pk_bf16_f32 v5, v56, v57
	v_cvt_pk_bf16_f32 v6, v58, v59
	v_cvt_pk_bf16_f32 v7, v66, v67
	v_add_u32_e32 v8, 0x3000, v52
	ds_write2_b64 v8, v[4:5], v[6:7] offset0:96 offset1:100
	v_cvt_pk_bf16_f32 v4, v68, v69
	v_cvt_pk_bf16_f32 v5, v70, v71
	v_cvt_pk_bf16_f32 v0, v0, v1
	v_cvt_pk_bf16_f32 v1, v2, v3
	s_ashr_i32 s1, s0, 31
	ds_write2_b64 v8, v[4:5], v[0:1] offset0:112 offset1:116
	v_lshlrev_b32_e32 v180, 4, v73
	s_waitcnt lgkmcnt(8)
	v_lshl_add_u64 v[0:1], s[0:1], 1, v[44:45]
	v_ashrrev_i32_e32 v6, 4, v72
	v_lshl_add_u64 v[4:5], v[0:1], 0, v[180:181]
	v_mad_u64_u32 v[0:1], s[0:1], v6, s11, v[180:181]
	s_waitcnt lgkmcnt(0)
	s_barrier
	ds_read_b128 v[0:3], v0
	v_add_u32_e32 v6, s14, v6
	v_ashrrev_i32_e32 v7, 31, v6
	v_lshlrev_b64 v[6:7], 12, v[6:7]
	v_lshl_add_u64 v[6:7], v[4:5], 0, v[6:7]
	s_waitcnt lgkmcnt(0)
	flat_store_dwordx4 v[6:7], v[0:3]
	s_nop 1
	v_add_u32_e32 v0, 0x100, v72
	v_ashrrev_i32_e32 v6, 4, v0
	v_mad_u64_u32 v[0:1], s[0:1], v6, s11, v[180:181]
	ds_read_b128 v[0:3], v0
	v_add_u32_e32 v6, s14, v6
	v_ashrrev_i32_e32 v7, 31, v6
	v_lshlrev_b64 v[6:7], 12, v[6:7]
	v_lshl_add_u64 v[6:7], v[4:5], 0, v[6:7]
	s_waitcnt lgkmcnt(0)
	flat_store_dwordx4 v[6:7], v[0:3]
	s_nop 1
	v_add_u32_e32 v0, 0x200, v72
	v_ashrrev_i32_e32 v6, 4, v0
	v_mad_u64_u32 v[0:1], s[0:1], v6, s11, v[180:181]
	ds_read_b128 v[0:3], v0
	v_add_u32_e32 v6, s14, v6
	v_ashrrev_i32_e32 v7, 31, v6
	v_lshlrev_b64 v[6:7], 12, v[6:7]
	v_lshl_add_u64 v[6:7], v[4:5], 0, v[6:7]
	s_waitcnt lgkmcnt(0)
	flat_store_dwordx4 v[6:7], v[0:3]
	s_nop 1
	v_add_u32_e32 v0, 0x300, v72
	v_ashrrev_i32_e32 v6, 4, v0
	v_mad_u64_u32 v[0:1], s[0:1], v6, s11, v[180:181]
	ds_read_b128 v[0:3], v0
	v_add_u32_e32 v6, s14, v6
	v_ashrrev_i32_e32 v7, 31, v6
	v_lshlrev_b64 v[6:7], 12, v[6:7]
	v_lshl_add_u64 v[6:7], v[4:5], 0, v[6:7]
	s_waitcnt lgkmcnt(0)
	flat_store_dwordx4 v[6:7], v[0:3]
	s_nop 1
	v_add_u32_e32 v0, 0x400, v72
	v_ashrrev_i32_e32 v6, 4, v0
	v_mad_u64_u32 v[0:1], s[0:1], v6, s11, v[180:181]
	ds_read_b128 v[0:3], v0
	v_add_u32_e32 v6, s14, v6
	v_ashrrev_i32_e32 v7, 31, v6
	v_lshlrev_b64 v[6:7], 12, v[6:7]
	v_lshl_add_u64 v[6:7], v[4:5], 0, v[6:7]
	s_waitcnt lgkmcnt(0)
	flat_store_dwordx4 v[6:7], v[0:3]
	s_nop 1
	v_add_u32_e32 v0, 0x500, v72
	v_ashrrev_i32_e32 v6, 4, v0
	v_mad_u64_u32 v[0:1], s[0:1], v6, s11, v[180:181]
	ds_read_b128 v[0:3], v0
	v_add_u32_e32 v6, s14, v6
	v_ashrrev_i32_e32 v7, 31, v6
	v_lshlrev_b64 v[6:7], 12, v[6:7]
	v_lshl_add_u64 v[6:7], v[4:5], 0, v[6:7]
	s_waitcnt lgkmcnt(0)
	flat_store_dwordx4 v[6:7], v[0:3]
	s_nop 1
	v_add_u32_e32 v0, 0x600, v72
	v_ashrrev_i32_e32 v6, 4, v0
	v_mad_u64_u32 v[0:1], s[0:1], v6, s11, v[180:181]
	ds_read_b128 v[0:3], v0
	v_add_u32_e32 v6, s14, v6
	v_ashrrev_i32_e32 v7, 31, v6
	v_lshlrev_b64 v[6:7], 12, v[6:7]
	v_lshl_add_u64 v[6:7], v[4:5], 0, v[6:7]
	s_waitcnt lgkmcnt(0)
	flat_store_dwordx4 v[6:7], v[0:3]
	s_nop 1
	v_add_u32_e32 v0, 0x700, v72
	v_ashrrev_i32_e32 v6, 4, v0
	v_mad_u64_u32 v[0:1], s[0:1], v6, s11, v[180:181]
	ds_read_b128 v[0:3], v0
	v_add_u32_e32 v6, s14, v6
	v_ashrrev_i32_e32 v7, 31, v6
	v_lshlrev_b64 v[6:7], 12, v[6:7]
	v_lshl_add_u64 v[4:5], v[4:5], 0, v[6:7]
	v_readlane_b32 s0, v251, 6
	s_waitcnt lgkmcnt(0)
	flat_store_dwordx4 v[4:5], v[0:3]
	s_add_i32 s6, s0, s6
	s_cmpk_lt_i32 s6, 0x400
	v_readlane_b32 s1, v251, 7
	s_cbranch_scc1 .LBB0_458

; DEV int tid_() { int t = threadIdx.x; asm volatile("" : "+v"(t)); return t; }
; DEV int bid_() { int t = blockIdx.x; asm volatile("" : "+s"(t)); return t; }
; DEV int gdim_() { int t = gridDim.x; asm volatile("" : "+s"(t)); return t; }
; #define P (*launderP(lp))
; template <class FragT, class AccT>
; DEV void gemm_core_t(const char* __restrict__ A, size_t lda_bytes, const char* __restrict__ Bt, size_t ldb_bytes, int kbytes,
;                      int m0, int n0, int Sshift, int dl, char* smem, AccT (&acc)[4][4]) {
;   const int tid = tid_(), lane = tid & 63, wid = tid >> 6, wm = wid >> 1, wn = wid & 1;
;   const int l15 = lane & 15, q = lane >> 4;
;   const int srow = lane >> 3, schunk = (lane & 7) ^ (lane >> 3);
;   const char* ap[4];
;   const char* bp[4];
; #pragma unroll
;   for (int u = 0; u < 4; ++u) {
;     int r = (wid * 4 + u) * 8 + srow;
;     int ar = rowmap(m0 + r, Sshift, dl);
;     ap[u] = A + (size_t)ar * lda_bytes + schunk * 16;
;     bp[u] = Bt + (size_t)(n0 + r) * ldb_bytes + schunk * 16;
;   }
; #pragma unroll
;   for (int i = 0; i < 4; ++i)
; #pragma unroll
;     for (int j = 0; j < 4; ++j) acc[i][j] = AccT{0, 0, 0, 0};
;   const int nk = kbytes >> 7;
;   __syncthreads();
; #pragma unroll
;   for (int u = 0; u < 4; ++u) {
;     __builtin_amdgcn_global_load_lds((const unsigned*)ap[u], (unsigned*)(smem + (wid * 4 + u) * 1024 + lane * 16), 16, 0, 0);
;     __builtin_amdgcn_global_load_lds((const unsigned*)bp[u], (unsigned*)(smem + 16384 + (wid * 4 + u) * 1024 + lane * 16), 16, 0, 0);
;   }
;   const unsigned sbase = (unsigned)(unsigned long)((__attribute__((address_space(3))) char*)smem);
;   const unsigned sq0 = (unsigned)((q ^ (l15 & 7)) << 4);
;   const unsigned a0 = sbase + (unsigned)((wm * 64 + l15) * 128) + sq0;
;   const unsigned b0 = sbase + 16384u + (unsigned)((wn * 32 + l15) * 128) + sq0;
;   asm volatile("s_waitcnt vmcnt(0)" ::: "memory");
;   __syncthreads();
; __device__ __forceinline__ void phase_gemm45(PREF P, char* smem, int which) {
;     ...
;   for (int t = bid_(); t < 64 * 16; t += gdim_()) {
;     int mt, nt;
;     tile_map(t, 2, mt, nt);
;     const int m0 = mt * 128, n0 = nt * 128;
;     f32x4 acc[4][4];
;     if (!which) {
;       i32x4 iacc[4][4];
;       gemm_core_i8(P.h8, 2048, P.Wq8, 2048, 2048, m0, n0, 13, 0, smem, iacc);
.LBB0_564:
	s_ashr_i32 s0, s6, 3
	s_lshr_b32 s1, s0, 28
	s_add_i32 s1, s0, s1
	s_and_b32 s4, s1, -16
	v_mov_b32_e32 v22, v188
	s_sub_i32 s0, s0, s4
	s_lshl_b32 s4, s6, 1
	ds_read2_b64 v[0:3], v80 offset0:60 offset1:61
	s_and_b32 s4, s4, 14
	v_ashrrev_i32_e32 v24, 6, v22
	s_ashr_i32 s5, s0, 3
	s_lshl_b32 s1, s1, 6
	s_lshl_b32 s0, s0, 7
	v_bfe_u32 v25, v22, 3, 3
	v_lshlrev_b32_e32 v26, 5, v24
	s_add_i32 s15, s5, s4
	s_and_b32 s1, s1, 0xfffffc00
	s_and_b32 s4, s0, 0x380
	v_or_b32_e32 v20, v26, v25
	s_or_b32 s14, s4, s1
	s_lshl_b32 s0, s15, 7
	v_or_b32_e32 v14, 8, v20
	v_or_b32_e32 v18, 16, v20
	v_or_b32_e32 v27, 24, v20
	v_bitop3_b32 v4, v25, v22, 7 bitop3:0x78
	v_add_u32_e32 v8, s14, v20
	v_add_u32_e32 v10, s0, v20
	v_add_u32_e32 v12, s14, v14
	v_add_u32_e32 v16, s14, v18
	v_add_u32_e32 v20, s14, v27
	v_lshlrev_b32_e32 v180, 4, v4
	v_ashrrev_i32_e32 v9, 31, v8
	v_ashrrev_i32_e32 v13, 31, v12
	v_ashrrev_i32_e32 v17, 31, v16
	v_ashrrev_i32_e32 v21, 31, v20
	s_waitcnt lgkmcnt(0)
	v_lshl_add_u64 v[4:5], v[2:3], 0, v[180:181]
	v_lshlrev_b64 v[8:9], 11, v[8:9]
	v_lshlrev_b64 v[12:13], 11, v[12:13]
	v_lshlrev_b64 v[16:17], 11, v[16:17]
	v_lshlrev_b64 v[20:21], 11, v[20:21]
	v_lshl_add_u64 v[8:9], v[4:5], 0, v[8:9]
	v_lshl_add_u64 v[12:13], v[4:5], 0, v[12:13]
	v_add_u32_e32 v14, s0, v14
	v_lshl_add_u64 v[16:17], v[4:5], 0, v[16:17]
	v_add_u32_e32 v18, s0, v18
	v_lshl_add_u64 v[4:5], v[4:5], 0, v[20:21]
	v_add_u32_e32 v20, s0, v27
	v_ashrrev_i32_e32 v11, 31, v10
	v_ashrrev_i32_e32 v15, 31, v14
	v_ashrrev_i32_e32 v19, 31, v18
	v_ashrrev_i32_e32 v21, 31, v20
	v_lshl_add_u64 v[6:7], v[0:1], 0, v[180:181]
	v_lshlrev_b64 v[10:11], 11, v[10:11]
	v_lshlrev_b64 v[14:15], 11, v[14:15]
	v_lshlrev_b64 v[18:19], 11, v[18:19]
	v_lshlrev_b64 v[20:21], 11, v[20:21]
	v_and_b32_e32 v23, 63, v22
	v_lshl_add_u64 v[10:11], v[6:7], 0, v[10:11]
	v_lshl_add_u64 v[14:15], v[6:7], 0, v[14:15]
	v_lshl_add_u64 v[18:19], v[6:7], 0, v[18:19]
	v_lshl_add_u64 v[6:7], v[6:7], 0, v[20:21]
	v_lshlrev_b32_e32 v20, 12, v24
	v_lshl_or_b32 v83, v23, 4, v20
	s_nop 0
	v_readfirstlane_b32 s15, v83
	s_mov_b32 m0, s15
	s_barrier
	global_load_lds_dwordx4 v[8:9], off
	v_add_u32_e32 v8, 0x4000, v83
	s_lshl_b32 s5, s5, 7
	v_readfirstlane_b32 s15, v8
	v_or_b32_e32 v8, 0x400, v83
	s_mov_b32 m0, s15
	v_readfirstlane_b32 s15, v8
	v_add_u32_e32 v8, 0x4400, v83
	global_load_lds_dwordx4 v[10:11], off
	s_mov_b32 m0, s15
	v_readfirstlane_b32 s15, v8
	v_or_b32_e32 v8, 0x800, v83
	global_load_lds_dwordx4 v[12:13], off
	s_mov_b32 m0, s15
	v_readfirstlane_b32 s15, v8
	v_add_u32_e32 v8, 0x4800, v83
	global_load_lds_dwordx4 v[14:15], off
	s_mov_b32 m0, s15
	v_readfirstlane_b32 s15, v8
	v_or_b32_e32 v8, 0xc00, v83
	global_load_lds_dwordx4 v[16:17], off
	s_mov_b32 m0, s15
	v_readfirstlane_b32 s15, v8
	global_load_lds_dwordx4 v[18:19], off
	s_mov_b32 m0, s15
	s_mov_b64 s[16:17], 0x80
	global_load_lds_dwordx4 v[4:5], off
	v_add_u32_e32 v4, 0x4c00, v83
	v_lshlrev_b32_e32 v5, 4, v22
	v_readfirstlane_b32 s15, v4
	s_mov_b32 m0, s15
	v_and_b32_e32 v4, 15, v22
	global_load_lds_dwordx4 v[6:7], off
	v_lshrrev_b32_e32 v6, 1, v22
	s_mov_b32 s15, 0x1ffffc0
	v_and_or_b32 v6, v6, s15, v4
	s_and_b32 s15, s6, 7
	v_bitop3_b32 v5, v23, s31, v5 bitop3:0x48
	v_lshlrev_b32_e32 v6, 7, v6
	v_and_or_b32 v4, v26, 32, v4
	s_lshl_b32 s15, s15, 8
	v_or_b32_e32 v84, v5, v6
	v_lshl_or_b32 v4, v4, 7, v5
	v_bitop3_b32 v87, v5, 64, v6 bitop3:0x36
	v_or_b32_e32 v6, 24, v25
	s_add_i32 s5, s5, s15
	v_or_b32_e32 v85, 0x4000, v4
	v_bitop3_b32 v86, v4, 64, v219 bitop3:0x36
	v_or_b32_e32 v4, s5, v6
	v_add_u32_e32 v4, v4, v26
	v_ashrrev_i32_e32 v5, 31, v4
	v_lshlrev_b64 v[4:5], 11, v[4:5]
	v_lshl_add_u64 v[0:1], v[0:1], 0, s[16:17]
	v_or_b32_e32 v4, v4, v180
	v_lshl_add_u64 v[64:65], v[0:1], 0, v[4:5]
	v_or_b32_e32 v4, s1, v6
	v_or_b32_e32 v4, s4, v4
	v_add_u32_e32 v4, v4, v26
	v_ashrrev_i32_e32 v5, 31, v4
	v_lshlrev_b64 v[4:5], 11, v[4:5]
	v_lshl_add_u64 v[2:3], v[2:3], 0, s[16:17]
	v_or_b32_e32 v4, v4, v180
	v_or_b32_e32 v6, 16, v25
	v_lshl_add_u64 v[66:67], v[2:3], 0, v[4:5]
	v_or_b32_e32 v4, s5, v6
	v_add_u32_e32 v4, v4, v26
	v_ashrrev_i32_e32 v5, 31, v4
	v_lshlrev_b64 v[4:5], 11, v[4:5]
	v_or_b32_e32 v4, v4, v180
	v_lshl_add_u64 v[68:69], v[0:1], 0, v[4:5]
	v_or_b32_e32 v4, s1, v6
	v_or_b32_e32 v4, s4, v4
	v_add_u32_e32 v4, v4, v26
	v_ashrrev_i32_e32 v5, 31, v4
	v_lshlrev_b64 v[4:5], 11, v[4:5]
	v_or_b32_e32 v4, v4, v180
	v_or_b32_e32 v6, 8, v25
	v_lshl_add_u64 v[70:71], v[2:3], 0, v[4:5]
	v_or_b32_e32 v4, s5, v6
	v_add_u32_e32 v4, v4, v26
	v_ashrrev_i32_e32 v5, 31, v4
	v_lshlrev_b64 v[4:5], 11, v[4:5]
	v_or_b32_e32 v4, v4, v180
	v_lshl_add_u64 v[72:73], v[0:1], 0, v[4:5]
	v_or_b32_e32 v4, s1, v6
	v_or_b32_e32 v4, s4, v4
	v_add_u32_e32 v4, v4, v26
	v_ashrrev_i32_e32 v5, 31, v4
	v_lshlrev_b64 v[4:5], 11, v[4:5]
	v_or_b32_e32 v4, v4, v180
	v_lshl_add_u64 v[74:75], v[2:3], 0, v[4:5]
	v_or_b32_e32 v4, s5, v25
	v_add_u32_e32 v4, v4, v26
	v_ashrrev_i32_e32 v5, 31, v4
	v_lshlrev_b64 v[4:5], 11, v[4:5]
	v_or_b32_e32 v4, v4, v180
	v_lshl_add_u64 v[76:77], v[0:1], 0, v[4:5]
	v_or_b32_e32 v0, s1, v25
	v_or_b32_e32 v0, s4, v0
	v_add_u32_e32 v0, v0, v26
	v_ashrrev_i32_e32 v1, 31, v0
	v_lshlrev_b64 v[0:1], 11, v[0:1]
	v_or_b32_e32 v0, v0, v180
	v_lshl_add_u64 v[78:79], v[2:3], 0, v[0:1]
	v_mov_b32_e32 v0, 0
	s_mov_b64 s[4:5], 0
	s_mov_b32 s1, 0x8000
	v_mov_b32_e32 v1, v0
	v_mov_b32_e32 v2, v0
	v_mov_b32_e32 v3, v0
	v_mov_b32_e32 v4, v0
	v_mov_b32_e32 v5, v0
	v_mov_b32_e32 v6, v0
	v_mov_b32_e32 v7, v0
	v_mov_b32_e32 v8, v0
	v_mov_b32_e32 v9, v0
	v_mov_b32_e32 v10, v0
	v_mov_b32_e32 v11, v0
	v_mov_b32_e32 v12, v0
	v_mov_b32_e32 v13, v0
	v_mov_b32_e32 v14, v0
; DEV f32x4 mma_step(bf16x8 a, bf16x8 b, f32x4 c) { return MFMA(a, b, c); }
; template <class FragT, class AccT>
; DEV void gemm_core_t(const char* __restrict__ A, size_t lda_bytes, const char* __restrict__ Bt, size_t ldb_bytes, int kbytes,
;                      int m0, int n0, int Sshift, int dl, char* smem, AccT (&acc)[4][4]) {
;     ...
;   for (int kt = 0; kt < nk; ++kt) {
;     const unsigned so = (unsigned)(kt & 1) * 32768u;
;     char* nxt = smem + ((kt + 1) & 1) * 32768;
;     if (kt + 1 < nk) {
; #pragma unroll
;       for (int u = 0; u < 4; ++u) {
;         __builtin_amdgcn_global_load_lds((const unsigned*)(ap[u] + (size_t)(kt + 1) * 128), (unsigned*)(nxt + (wid * 4 + u) * 1024 + lane * 16), 16, 0, 0);
;         __builtin_amdgcn_global_load_lds((const unsigned*)(bp[u] + (size_t)(kt + 1) * 128), (unsigned*)(nxt + 16384 + (wid * 4 + u) * 1024 + lane * 16), 16, 0, 0);
;       }
;     }
;     FragT xa[2][4], wb[2][4];
;     asm volatile(
;         "ds_read_b128 %0, %16\n\t"
;         "ds_read_b128 %1, %16 offset:2048\n\t"
;         "ds_read_b128 %2, %16 offset:4096\n\t"
;         "ds_read_b128 %3, %16 offset:6144\n\t"
;         "ds_read_b128 %4, %18\n\t"
;         "ds_read_b128 %5, %18 offset:2048\n\t"
;         "ds_read_b128 %6, %18 offset:8192\n\t"
;         "ds_read_b128 %7, %18 offset:10240\n\t"
;         "ds_read_b128 %8, %17\n\t"
;         "ds_read_b128 %9, %17 offset:2048\n\t"
;         "ds_read_b128 %10, %17 offset:4096\n\t"
;         "ds_read_b128 %11, %17 offset:6144\n\t"
;         "ds_read_b128 %12, %19\n\t"
;         "ds_read_b128 %13, %19 offset:2048\n\t"
;         "ds_read_b128 %14, %19 offset:8192\n\t"
;         "ds_read_b128 %15, %19 offset:10240\n\t"
;         "s_waitcnt lgkmcnt(8)"
;         : "=&v"(xa[0][0]), "=&v"(xa[0][1]), "=&v"(xa[0][2]), "=&v"(xa[0][3]), "=&v"(wb[0][0]), "=&v"(wb[0][1]), "=&v"(wb[0][2]),
;           "=&v"(wb[0][3]), "=&v"(xa[1][0]), "=&v"(xa[1][1]), "=&v"(xa[1][2]), "=&v"(xa[1][3]), "=&v"(wb[1][0]), "=&v"(wb[1][1]),
;           "=&v"(wb[1][2]), "=&v"(wb[1][3])
;         : "v"(a0 + so), "v"((a0 ^ 64u) + so), "v"(b0 + so), "v"((b0 ^ 64u) + so)
;         : "memory");
;     __builtin_amdgcn_s_setprio(1);
; #pragma unroll
;     for (int i = 0; i < 4; ++i)
; #pragma unroll
;       for (int j = 0; j < 4; ++j) acc[i][j] = mma_step(wb[0][j], xa[0][i], acc[i][j]);
;     asm volatile("s_waitcnt lgkmcnt(0)"
	v_mov_b32_e32 v15, v0
	v_mov_b32_e32 v16, v0
	v_mov_b32_e32 v17, v0
	v_mov_b32_e32 v18, v0
	v_mov_b32_e32 v19, v0
	v_mov_b32_e32 v20, v0
	v_mov_b32_e32 v21, v0
	v_mov_b32_e32 v22, v0
	v_mov_b32_e32 v23, v0
	v_mov_b32_e32 v24, v0
	v_mov_b32_e32 v25, v0
	v_mov_b32_e32 v26, v0
	v_mov_b32_e32 v27, v0
	v_mov_b32_e32 v28, v0
	v_mov_b32_e32 v29, v0
	v_mov_b32_e32 v30, v0
	v_mov_b32_e32 v31, v0
	v_mov_b32_e32 v32, v0
	v_mov_b32_e32 v33, v0
	v_mov_b32_e32 v34, v0
	v_mov_b32_e32 v35, v0
	v_mov_b32_e32 v36, v0
	v_mov_b32_e32 v37, v0
	v_mov_b32_e32 v38, v0
	v_mov_b32_e32 v39, v0
	v_mov_b32_e32 v40, v0
	v_mov_b32_e32 v41, v0
	v_mov_b32_e32 v42, v0
	v_mov_b32_e32 v43, v0
	v_mov_b32_e32 v44, v0
	v_mov_b32_e32 v45, v0
	v_mov_b32_e32 v46, v0
	v_mov_b32_e32 v47, v0
	v_mov_b32_e32 v48, v0
	v_mov_b32_e32 v49, v0
	v_mov_b32_e32 v50, v0
	v_mov_b32_e32 v51, v0
	v_mov_b32_e32 v52, v0
	v_mov_b32_e32 v53, v0
	v_mov_b32_e32 v54, v0
	v_mov_b32_e32 v55, v0
	v_mov_b32_e32 v56, v0
	v_mov_b32_e32 v57, v0
	v_mov_b32_e32 v58, v0
	v_mov_b32_e32 v59, v0
	v_mov_b32_e32 v60, v0
	v_mov_b32_e32 v61, v0
	v_mov_b32_e32 v62, v0
	v_mov_b32_e32 v63, v0
	v_readfirstlane_b32 s64, v78
	v_readfirstlane_b32 s65, v79
	v_readfirstlane_b32 s66, v76
	v_readfirstlane_b32 s67, v77
	v_readfirstlane_b32 s62, v83
	s_sub_u32 s64, s64, 0x80000000
	s_subb_u32 s65, s65, 0
	s_sub_u32 s66, s66, 0x80000000
	s_subb_u32 s67, s67, 0
	v_subrev_u32_e32 v78, s64, v78
	v_subrev_u32_e32 v76, s66, v76
	v_subrev_u32_e32 v74, s64, v74
	v_subrev_u32_e32 v72, s66, v72
	v_subrev_u32_e32 v70, s64, v70
	v_subrev_u32_e32 v68, s66, v68
	v_subrev_u32_e32 v66, s64, v66
	v_subrev_u32_e32 v64, s66, v64
	s_waitcnt vmcnt(0) lgkmcnt(0)
	s_barrier
.LBB0_565:
	s_add_i32 s15, s1, 0xffff8000
	s_and_b32 s15, s15, 0x8000
	v_add_u32_e32 v152, s15, v84
	v_add_u32_e32 v153, s15, v87
	v_or_b32_e32 v154, s15, v85
	v_or_b32_e32 v155, s15, v86
	s_and_b32 s15, s1, 0x8000
	s_add_i32 s15, s15, s62
	s_mov_b32 m0, s15
	ds_read_b128 v[88:91], v152
	global_load_lds_dwordx4 v78, s[64:65]
	ds_read_b128 v[92:95], v152 offset:2048
	s_add_i32 m0, s15, 0x4000
	ds_read_b128 v[96:99], v152 offset:4096
	global_load_lds_dwordx4 v76, s[66:67]
	ds_read_b128 v[100:103], v152 offset:6144
	s_add_i32 m0, s15, 0x400
	ds_read_b128 v[104:107], v154
	global_load_lds_dwordx4 v74, s[64:65]
	ds_read_b128 v[108:111], v154 offset:2048
	s_add_i32 m0, s15, 0x4400
	ds_read_b128 v[112:115], v154 offset:8192
	global_load_lds_dwordx4 v72, s[66:67]
	ds_read_b128 v[116:119], v154 offset:10240
	ds_read_b128 v[120:123], v153
	ds_read_b128 v[124:127], v153 offset:2048
	ds_read_b128 v[128:131], v153 offset:4096
	ds_read_b128 v[132:135], v153 offset:6144
	ds_read_b128 v[136:139], v155
	ds_read_b128 v[140:143], v155 offset:2048
	ds_read_b128 v[144:147], v155 offset:8192
	ds_read_b128 v[148:151], v155 offset:10240
	s_waitcnt lgkmcnt(8)
	s_setprio 1
	v_mfma_i32_16x16x64_i8 v[60:63], v[104:107], v[88:91], v[60:63]
	v_mfma_i32_16x16x64_i8 v[56:59], v[108:111], v[88:91], v[56:59]
	s_add_i32 m0, s15, 0x800
	v_mfma_i32_16x16x64_i8 v[52:55], v[112:115], v[88:91], v[52:55]
	global_load_lds_dwordx4 v70, s[64:65]
	v_mfma_i32_16x16x64_i8 v[48:51], v[116:119], v[88:91], v[48:51]
	v_mfma_i32_16x16x64_i8 v[44:47], v[104:107], v[92:95], v[44:47]
	v_mfma_i32_16x16x64_i8 v[40:43], v[108:111], v[92:95], v[40:43]
	s_add_i32 m0, s15, 0x4800
	v_mfma_i32_16x16x64_i8 v[36:39], v[112:115], v[92:95], v[36:39]
	global_load_lds_dwordx4 v68, s[66:67]
	v_mfma_i32_16x16x64_i8 v[32:35], v[116:119], v[92:95], v[32:35]
	v_mfma_i32_16x16x64_i8 v[28:31], v[104:107], v[96:99], v[28:31]
	v_mfma_i32_16x16x64_i8 v[24:27], v[108:111], v[96:99], v[24:27]
	s_add_i32 m0, s15, 0xc00
	v_mfma_i32_16x16x64_i8 v[20:23], v[112:115], v[96:99], v[20:23]
	global_load_lds_dwordx4 v66, s[64:65]
	v_mfma_i32_16x16x64_i8 v[16:19], v[116:119], v[96:99], v[16:19]
	v_mfma_i32_16x16x64_i8 v[12:15], v[104:107], v[100:103], v[12:15]
	v_mfma_i32_16x16x64_i8 v[8:11], v[108:111], v[100:103], v[8:11]
	s_add_i32 m0, s15, 0x4c00
	v_mfma_i32_16x16x64_i8 v[4:7], v[112:115], v[100:103], v[4:7]
	global_load_lds_dwordx4 v64, s[66:67]
	v_mfma_i32_16x16x64_i8 v[0:3], v[116:119], v[100:103], v[0:3]
	s_waitcnt lgkmcnt(0)
	s_nop 0
	v_mfma_i32_16x16x64_i8 v[60:63], v[136:139], v[120:123], v[60:63]
	v_mfma_i32_16x16x64_i8 v[56:59], v[140:143], v[120:123], v[56:59]
	v_mfma_i32_16x16x64_i8 v[52:55], v[144:147], v[120:123], v[52:55]
	v_mfma_i32_16x16x64_i8 v[48:51], v[148:151], v[120:123], v[48:51]
	v_mfma_i32_16x16x64_i8 v[44:47], v[136:139], v[124:127], v[44:47]
	v_mfma_i32_16x16x64_i8 v[40:43], v[140:143], v[124:127], v[40:43]
	v_mfma_i32_16x16x64_i8 v[36:39], v[144:147], v[124:127], v[36:39]
	v_mfma_i32_16x16x64_i8 v[32:35], v[148:151], v[124:127], v[32:35]
	v_mfma_i32_16x16x64_i8 v[28:31], v[136:139], v[128:131], v[28:31]
	v_mfma_i32_16x16x64_i8 v[24:27], v[140:143], v[128:131], v[24:27]
	v_mfma_i32_16x16x64_i8 v[20:23], v[144:147], v[128:131], v[20:23]
	v_mfma_i32_16x16x64_i8 v[16:19], v[148:151], v[128:131], v[16:19]
	v_mfma_i32_16x16x64_i8 v[12:15], v[136:139], v[132:135], v[12:15]
	v_mfma_i32_16x16x64_i8 v[8:11], v[140:143], v[132:135], v[8:11]
	v_mfma_i32_16x16x64_i8 v[4:7], v[144:147], v[132:135], v[4:7]
	v_mfma_i32_16x16x64_i8 v[0:3], v[148:151], v[132:135], v[0:3]
	s_setprio 0
	s_waitcnt vmcnt(0)
	s_add_u32 s4, s4, 0x80
	s_addc_u32 s5, s5, 0
	s_add_u32 s64, s64, 0x80
	s_addc_u32 s65, s65, 0
	s_add_u32 s66, s66, 0x80
	s_addc_u32 s67, s67, 0
	s_add_i32 s1, s1, 0x8000
	s_cmpk_lg_i32 s4, 0x780
	s_waitcnt vmcnt(0) lgkmcnt(0)
	s_barrier
	s_cbranch_scc1 .LBB0_565
; DEV f32x4 mma_step(bf16x8 a, bf16x8 b, f32x4 c) { return MFMA(a, b, c); }
; DEV i32x4 mma_step(i32x4 a, i32x4 b, i32x4 c) { return __builtin_amdgcn_mfma_i32_16x16x64_i8(a, b, c, 0, 0, 0); }
; #define P (*launderP(lp))
; template <class FragT, class AccT>
; DEV void gemm_core_t(const char* __restrict__ A, size_t lda_bytes, const char* __restrict__ Bt, size_t ldb_bytes, int kbytes,
;                      int m0, int n0, int Sshift, int dl, char* smem, AccT (&acc)[4][4]) {
;     ...
;     for (int i = 0; i < 4; ++i)
; #pragma unroll
;       for (int j = 0; j < 4; ++j) acc[i][j] = mma_step(wb[0][j], xa[0][i], acc[i][j]);
;     asm volatile("s_waitcnt lgkmcnt(0)"
;                  : "+v"(xa[1][0]), "+v"(xa[1][1]), "+v"(xa[1][2]), "+v"(xa[1][3]), "+v"(wb[1][0]), "+v"(wb[1][1]), "+v"(wb[1][2]),
;                    "+v"(wb[1][3]), "+v"(acc[0][0]), "+v"(acc[0][1]), "+v"(acc[0][2]), "+v"(acc[0][3]), "+v"(acc[1][0]),
;                    "+v"(acc[1][1]), "+v"(acc[1][2]), "+v"(acc[1][3]), "+v"(acc[2][0]), "+v"(acc[2][1]), "+v"(acc[2][2]),
;                    "+v"(acc[2][3]), "+v"(acc[3][0]), "+v"(acc[3][1]), "+v"(acc[3][2]), "+v"(acc[3][3])
;                  :
;                  : "memory");
; #pragma unroll
;     for (int i = 0; i < 4; ++i)
; #pragma unroll
;       for (int j = 0; j < 4; ++j) acc[i][j] = mma_step(wb[1][j], xa[1][i], acc[i][j]);
; __device__ __forceinline__ void phase_gemm45(PREF P, char* smem, int which) {
;     ...
; #pragma unroll
;       for (int i = 0; i < 4; ++i) {
;         const int row = m0 + wm * 64 + i * 16 + l15;
;     ...
; #pragma unroll
;         for (int j = 0; j < 4; ++j) {
;           const int col = n0 + (j & 1) * 16 + wn * 32 + (j >> 1) * 64 + q * 4;
;           const float4 swc = *(const float4*)(P.swq + col);
;           f32x4 v;
;           v[0] = (float)iacc[i][j][0] * shr * swc.x; v[1] = (float)iacc[i][j][1] * shr * swc.y;
;           v[2] = (float)iacc[i][j][2] * shr * swc.z; v[3] = (float)iacc[i][j][3] * shr * swc.w;
;           acc[i][j] = v;
;         }
;       }
	v_add_u32_e32 v83, 0x8000, v84
	v_add_u32_e32 v132, 0x8000, v87
	v_or_b32_e32 v133, 0x8000, v85
	v_or_b32_e32 v134, 0x8000, v86
	ds_read_b128 v[64:67], v83
	ds_read_b128 v[68:71], v83 offset:2048
	ds_read_b128 v[72:75], v83 offset:4096
	ds_read_b128 v[76:79], v83 offset:6144
	ds_read_b128 v[84:87], v133
	ds_read_b128 v[88:91], v133 offset:2048
	ds_read_b128 v[92:95], v133 offset:8192
	ds_read_b128 v[96:99], v133 offset:10240
	ds_read_b128 v[100:103], v132
	ds_read_b128 v[104:107], v132 offset:2048
	ds_read_b128 v[108:111], v132 offset:4096
	ds_read_b128 v[112:115], v132 offset:6144
	ds_read_b128 v[116:119], v134
	ds_read_b128 v[120:123], v134 offset:2048
	ds_read_b128 v[124:127], v134 offset:8192
	ds_read_b128 v[128:131], v134 offset:10240
	s_waitcnt lgkmcnt(8)
	s_setprio 1
	v_mfma_i32_16x16x64_i8 v[60:63], v[84:87], v[64:67], v[60:63]
	v_mfma_i32_16x16x64_i8 v[56:59], v[88:91], v[64:67], v[56:59]
	v_mfma_i32_16x16x64_i8 v[52:55], v[92:95], v[64:67], v[52:55]
	v_mfma_i32_16x16x64_i8 v[48:51], v[96:99], v[64:67], v[48:51]
	v_mfma_i32_16x16x64_i8 v[44:47], v[84:87], v[68:71], v[44:47]
	v_mfma_i32_16x16x64_i8 v[40:43], v[88:91], v[68:71], v[40:43]
	v_mfma_i32_16x16x64_i8 v[36:39], v[92:95], v[68:71], v[36:39]
	v_mfma_i32_16x16x64_i8 v[32:35], v[96:99], v[68:71], v[32:35]
	v_mfma_i32_16x16x64_i8 v[28:31], v[84:87], v[72:75], v[28:31]
	v_mfma_i32_16x16x64_i8 v[24:27], v[88:91], v[72:75], v[24:27]
	v_mfma_i32_16x16x64_i8 v[20:23], v[92:95], v[72:75], v[20:23]
	v_mfma_i32_16x16x64_i8 v[16:19], v[96:99], v[72:75], v[16:19]
	v_mfma_i32_16x16x64_i8 v[12:15], v[84:87], v[76:79], v[12:15]
	v_mfma_i32_16x16x64_i8 v[8:11], v[88:91], v[76:79], v[8:11]
	v_mfma_i32_16x16x64_i8 v[4:7], v[92:95], v[76:79], v[4:7]
	v_mfma_i32_16x16x64_i8 v[0:3], v[96:99], v[76:79], v[0:3]
	s_waitcnt lgkmcnt(0)
	s_nop 0
	v_mfma_i32_16x16x64_i8 v[60:63], v[116:119], v[100:103], v[60:63]
	v_mfma_i32_16x16x64_i8 v[56:59], v[120:123], v[100:103], v[56:59]
	v_mfma_i32_16x16x64_i8 v[52:55], v[124:127], v[100:103], v[52:55]
	v_mfma_i32_16x16x64_i8 v[64:67], v[128:131], v[100:103], v[48:51]
	v_mfma_i32_16x16x64_i8 v[44:47], v[116:119], v[104:107], v[44:47]
	v_mfma_i32_16x16x64_i8 v[48:51], v[120:123], v[104:107], v[40:43]
	v_mfma_i32_16x16x64_i8 v[38:41], v[124:127], v[104:107], v[36:39]
	v_mfma_i32_16x16x64_i8 v[68:71], v[128:131], v[104:107], v[32:35]
	v_mfma_i32_16x16x64_i8 v[28:31], v[116:119], v[108:111], v[28:31]
	v_mfma_i32_16x16x64_i8 v[34:37], v[120:123], v[108:111], v[24:27]
	v_mfma_i32_16x16x64_i8 v[72:75], v[124:127], v[108:111], v[20:23]
	v_mfma_i32_16x16x64_i8 v[76:79], v[128:131], v[108:111], v[16:19]
	v_mfma_i32_16x16x64_i8 v[12:15], v[116:119], v[112:115], v[12:15]
	v_mfma_i32_16x16x64_i8 v[84:87], v[120:123], v[112:115], v[8:11]
	v_mfma_i32_16x16x64_i8 v[88:91], v[124:127], v[112:115], v[4:7]
	v_mfma_i32_16x16x64_i8 v[92:95], v[128:131], v[112:115], v[0:3]
	s_setprio 0
	s_waitcnt vmcnt(0)
	s_barrier
	s_nop 0
	ds_read2_b64 v[0:3], v80 offset0:55 offset1:56
	v_add_u32_e32 v4, s14, v81
	v_or_b32_e32 v6, s0, v82
	v_ashrrev_i32_e32 v7, 31, v6
	v_ashrrev_i32_e32 v5, 31, v4
	s_waitcnt lgkmcnt(0)
	v_lshl_add_u64 v[96:97], v[6:7], 2, v[0:1]
	v_lshl_add_u64 v[0:1], v[4:5], 2, v[2:3]
	flat_load_dword v98, v[0:1]
	flat_load_dword v100, v[0:1] offset:64
	flat_load_dword v102, v[0:1] offset:128
	flat_load_dword v104, v[0:1] offset:192
	flat_load_dwordx4 v[4:7], v[96:97]
	v_cvt_f32_i32_e32 v1, v61
	v_cvt_f32_i32_e32 v0, v60
	v_cvt_f32_i32_e32 v21, v53
	v_cvt_f32_i32_e32 v20, v52
	s_mov_b32 s1, 0xfffffc0
	s_waitcnt vmcnt(0) lgkmcnt(0)
	v_pk_mul_f32 v[0:1], v[98:99], v[0:1] op_sel_hi:[0,1]
	v_pk_mul_f32 v[20:21], v[98:99], v[20:21] op_sel_hi:[0,1]
	v_pk_mul_f32 v[18:19], v[4:5], v[0:1]
	v_cvt_f32_i32_e32 v1, v45
	v_cvt_f32_i32_e32 v0, v44
	v_cvt_pk_bf16_f32 v18, v18, v19
	v_pk_mul_f32 v[0:1], v[100:101], v[0:1] op_sel_hi:[0,1]
	v_pk_mul_f32 v[8:9], v[4:5], v[0:1]
	v_cvt_f32_i32_e32 v1, v29
	v_cvt_f32_i32_e32 v0, v28
	v_cvt_pk_bf16_f32 v8, v8, v9
	v_pk_mul_f32 v[0:1], v[102:103], v[0:1] op_sel_hi:[0,1]
	v_pk_mul_f32 v[2:3], v[4:5], v[0:1]
	v_cvt_f32_i32_e32 v1, v13
	v_cvt_f32_i32_e32 v0, v12
	v_cvt_pk_bf16_f32 v2, v2, v3
	v_pk_mul_f32 v[0:1], v[104:105], v[0:1] op_sel_hi:[0,1]
	v_pk_mul_f32 v[0:1], v[4:5], v[0:1]
	v_cvt_f32_i32_e32 v5, v63
	v_cvt_f32_i32_e32 v4, v62
	v_cvt_pk_bf16_f32 v0, v0, v1
	v_pk_mul_f32 v[4:5], v[98:99], v[4:5] op_sel_hi:[0,1]
	v_pk_mul_f32 v[26:27], v[4:5], v[6:7]
	v_cvt_f32_i32_e32 v5, v47
	v_cvt_f32_i32_e32 v4, v46
	flat_load_dwordx4 v[44:47], v[96:97] offset:256
	v_cvt_pk_bf16_f32 v19, v26, v27
	v_pk_mul_f32 v[4:5], v[100:101], v[4:5] op_sel_hi:[0,1]
	v_pk_mul_f32 v[16:17], v[6:7], v[4:5]
	v_cvt_f32_i32_e32 v5, v31
	v_cvt_f32_i32_e32 v4, v30
	flat_load_dwordx4 v[28:31], v[96:97] offset:64
	v_cvt_pk_bf16_f32 v9, v16, v17
	v_pk_mul_f32 v[4:5], v[102:103], v[4:5] op_sel_hi:[0,1]
	v_pk_mul_f32 v[10:11], v[6:7], v[4:5]
	v_cvt_f32_i32_e32 v5, v15
	v_cvt_f32_i32_e32 v4, v14
	v_cvt_f32_i32_e32 v15, v59
	v_cvt_f32_i32_e32 v14, v58
	v_cvt_pk_bf16_f32 v3, v10, v11
	v_pk_mul_f32 v[4:5], v[104:105], v[4:5] op_sel_hi:[0,1]
	v_pk_mul_f32 v[4:5], v[6:7], v[4:5]
	v_cvt_f32_i32_e32 v7, v57
	v_cvt_f32_i32_e32 v6, v56
	v_pk_mul_f32 v[14:15], v[98:99], v[14:15] op_sel_hi:[0,1]
	v_cvt_pk_bf16_f32 v1, v4, v5
	v_pk_mul_f32 v[6:7], v[98:99], v[6:7] op_sel_hi:[0,1]
	s_waitcnt vmcnt(0) lgkmcnt(0)
; DEV int tid_() { int t = threadIdx.x; asm volatile("" : "+v"(t)); return t; }
; #define P (*launderP(lp))
; DEV void stage_tile_bf16(char* smem, const f32x4 (&v)[4][4], u16* buf, int ld, int m0, int col0) {
;   const int tid = tid_(), lane = tid & 63, wid = tid >> 6, wm = wid >> 1, wn = wid & 1, l15 = lane & 15, q = lane >> 4;
; #pragma unroll
;   for (int i = 0; i < 4; ++i)
; #pragma unroll
;     for (int j = 0; j < 4; ++j) {
;       const int rl = wm * 64 + i * 16 + l15, cl = (j & 1) * 16 + wn * 32 + (j >> 1) * 64 + q * 4;
;       u32x2 o; o.x = pack2(v[i][j][0], v[i][j][1]); o.y = pack2(v[i][j][2], v[i][j][3]);
;       *(u32x2*)(smem + rl * 272 + cl * 2) = o;
;     }
;   __syncthreads();
; __device__ __forceinline__ void phase_gemm45(PREF P, char* smem, int which) {
;     ...
; #pragma unroll
;       for (int i = 0; i < 4; ++i) {
;         const int row = m0 + wm * 64 + i * 16 + l15;
;     ...
; #pragma unroll
;         for (int j = 0; j < 4; ++j) {
;           const int col = n0 + (j & 1) * 16 + wn * 32 + (j >> 1) * 64 + q * 4;
;           const float4 swc = *(const float4*)(P.swq + col);
;           f32x4 v;
;           v[0] = (float)iacc[i][j][0] * shr * swc.x; v[1] = (float)iacc[i][j][1] * shr * swc.y;
;           v[2] = (float)iacc[i][j][2] * shr * swc.z; v[3] = (float)iacc[i][j][3] * shr * swc.w;
;           acc[i][j] = v;
;         }
;       }
;       stage_tile_bf16(smem, acc, P.qb, 2048, m0, n0);
	v_pk_mul_f32 v[32:33], v[6:7], v[28:29]
	v_cvt_f32_i32_e32 v7, v49
	v_cvt_f32_i32_e32 v6, v48
	v_pk_mul_f32 v[42:43], v[14:15], v[30:31]
	v_cvt_f32_i32_e32 v15, v51
	v_cvt_f32_i32_e32 v14, v50
	v_pk_mul_f32 v[6:7], v[100:101], v[6:7] op_sel_hi:[0,1]
	v_pk_mul_f32 v[22:23], v[28:29], v[6:7]
	v_cvt_f32_i32_e32 v7, v35
	v_pk_mul_f32 v[14:15], v[100:101], v[14:15] op_sel_hi:[0,1]
	v_cvt_f32_i32_e32 v6, v34
	v_pk_mul_f32 v[34:35], v[30:31], v[14:15]
	v_cvt_f32_i32_e32 v15, v37
	v_cvt_f32_i32_e32 v14, v36
	v_pk_mul_f32 v[48:49], v[20:21], v[44:45]
	v_cvt_f32_i32_e32 v21, v39
	v_cvt_f32_i32_e32 v20, v38
	v_pk_mul_f32 v[14:15], v[102:103], v[14:15] op_sel_hi:[0,1]
	v_pk_mul_f32 v[24:25], v[30:31], v[14:15]
	v_cvt_f32_i32_e32 v15, v87
	v_cvt_f32_i32_e32 v14, v86
	v_pk_mul_f32 v[20:21], v[100:101], v[20:21] op_sel_hi:[0,1]
	v_pk_mul_f32 v[38:39], v[44:45], v[20:21]
	v_cvt_f32_i32_e32 v21, v73
	v_pk_mul_f32 v[14:15], v[104:105], v[14:15] op_sel_hi:[0,1]
	v_pk_mul_f32 v[14:15], v[30:31], v[14:15]
	v_cvt_f32_i32_e32 v31, v55
	v_cvt_f32_i32_e32 v30, v54
	v_cvt_f32_i32_e32 v20, v72
	v_cvt_f32_i32_e32 v37, v65
	v_cvt_f32_i32_e32 v36, v64
	v_pk_mul_f32 v[30:31], v[98:99], v[30:31] op_sel_hi:[0,1]
	v_pk_mul_f32 v[56:57], v[30:31], v[46:47]
	v_cvt_f32_i32_e32 v31, v41
	v_cvt_f32_i32_e32 v30, v40
	v_pk_mul_f32 v[6:7], v[102:103], v[6:7] op_sel_hi:[0,1]
	v_pk_mul_f32 v[36:37], v[98:99], v[36:37] op_sel_hi:[0,1]
	v_pk_mul_f32 v[12:13], v[28:29], v[6:7]
	v_pk_mul_f32 v[30:31], v[100:101], v[30:31] op_sel_hi:[0,1]
	v_pk_mul_f32 v[50:51], v[46:47], v[30:31]
	v_cvt_f32_i32_e32 v31, v75
	v_cvt_f32_i32_e32 v30, v74
	flat_load_dwordx4 v[72:75], v[96:97] offset:320
	v_cvt_f32_i32_e32 v7, v85
	v_cvt_f32_i32_e32 v6, v84
	v_pk_mul_f32 v[30:31], v[102:103], v[30:31] op_sel_hi:[0,1]
	v_pk_mul_f32 v[40:41], v[46:47], v[30:31]
	v_cvt_f32_i32_e32 v31, v91
	v_cvt_f32_i32_e32 v30, v90
	v_pk_mul_f32 v[6:7], v[104:105], v[6:7] op_sel_hi:[0,1]
	v_pk_mul_f32 v[20:21], v[102:103], v[20:21] op_sel_hi:[0,1]
	v_pk_mul_f32 v[6:7], v[28:29], v[6:7]
	v_pk_mul_f32 v[30:31], v[104:105], v[30:31] op_sel_hi:[0,1]
	v_pk_mul_f32 v[30:31], v[46:47], v[30:31]
	v_cvt_f32_i32_e32 v47, v67
	v_cvt_f32_i32_e32 v46, v66
	v_pk_mul_f32 v[28:29], v[44:45], v[20:21]
	v_cvt_f32_i32_e32 v21, v89
	v_cvt_f32_i32_e32 v20, v88
	v_pk_mul_f32 v[46:47], v[98:99], v[46:47] op_sel_hi:[0,1]
	v_mov_b32_e32 v66, v188
	ds_read_b64 v[64:65], v80 offset:352
	v_pk_mul_f32 v[20:21], v[104:105], v[20:21] op_sel_hi:[0,1]
	v_and_b32_e32 v67, 15, v66
	v_and_b32_e32 v26, 64, v66
	v_cvt_pk_bf16_f32 v32, v32, v33
	v_cvt_pk_bf16_f32 v33, v42, v43
	v_pk_mul_f32 v[20:21], v[44:45], v[20:21]
	v_cvt_pk_bf16_f32 v16, v22, v23
	v_cvt_pk_bf16_f32 v17, v34, v35
	v_lshlrev_b32_e32 v180, 4, v67
	s_waitcnt vmcnt(0) lgkmcnt(0)
	v_pk_mul_f32 v[58:59], v[36:37], v[72:73]
	v_cvt_f32_i32_e32 v37, v69
	v_cvt_f32_i32_e32 v36, v68
	v_pk_mul_f32 v[62:63], v[46:47], v[74:75]
	v_cvt_f32_i32_e32 v47, v71
	v_cvt_f32_i32_e32 v46, v70
	v_pk_mul_f32 v[36:37], v[100:101], v[36:37] op_sel_hi:[0,1]
	v_pk_mul_f32 v[52:53], v[72:73], v[36:37]
	v_cvt_f32_i32_e32 v37, v77
	v_pk_mul_f32 v[46:47], v[100:101], v[46:47] op_sel_hi:[0,1]
	v_cvt_f32_i32_e32 v36, v76
	v_pk_mul_f32 v[60:61], v[74:75], v[46:47]
	v_cvt_f32_i32_e32 v47, v79
	v_cvt_f32_i32_e32 v46, v78
	v_lshrrev_b32_e32 v68, 1, v66
	v_and_or_b32 v69, v68, s1, v67
	v_and_or_b32 v26, v68, 24, v26
	v_pk_mul_f32 v[36:37], v[102:103], v[36:37] op_sel_hi:[0,1]
	v_pk_mul_f32 v[46:47], v[102:103], v[46:47] op_sel_hi:[0,1]
	v_mad_u64_u32 v[26:27], s[4:5], v69, s11, v[26:27]
	v_pk_mul_f32 v[44:45], v[72:73], v[36:37]
	v_cvt_f32_i32_e32 v37, v93
	v_cvt_f32_i32_e32 v36, v92
	v_pk_mul_f32 v[54:55], v[74:75], v[46:47]
	v_cvt_f32_i32_e32 v47, v95
	v_cvt_f32_i32_e32 v46, v94
	ds_write2_b64 v26, v[18:19], v[32:33] offset1:4
	v_cvt_pk_bf16_f32 v18, v48, v49
	v_cvt_pk_bf16_f32 v19, v56, v57
	v_cvt_pk_bf16_f32 v32, v58, v59
	v_cvt_pk_bf16_f32 v33, v62, v63
	ds_write2_b64 v26, v[18:19], v[32:33] offset0:16 offset1:20
	v_add_u32_e32 v18, 0x1000, v26
	ds_write2_b64 v18, v[8:9], v[16:17] offset0:32 offset1:36
	v_cvt_pk_bf16_f32 v8, v38, v39
	v_cvt_pk_bf16_f32 v9, v50, v51
	v_cvt_pk_bf16_f32 v16, v52, v53
	v_cvt_pk_bf16_f32 v17, v60, v61
	ds_write2_b64 v18, v[8:9], v[16:17] offset0:48 offset1:52
	v_cvt_pk_bf16_f32 v8, v12, v13
	v_cvt_pk_bf16_f32 v9, v24, v25
	v_add_u32_e32 v10, 0x2000, v26
	v_pk_mul_f32 v[36:37], v[104:105], v[36:37] op_sel_hi:[0,1]
	v_pk_mul_f32 v[46:47], v[104:105], v[46:47] op_sel_hi:[0,1]
	ds_write2_b64 v10, v[2:3], v[8:9] offset0:64 offset1:68
	v_cvt_pk_bf16_f32 v2, v28, v29
	v_cvt_pk_bf16_f32 v3, v40, v41
	v_cvt_pk_bf16_f32 v8, v44, v45
	v_cvt_pk_bf16_f32 v9, v54, v55
	v_pk_mul_f32 v[36:37], v[72:73], v[36:37]
	v_pk_mul_f32 v[46:47], v[74:75], v[46:47]
	ds_write2_b64 v10, v[2:3], v[8:9] offset0:80 offset1:84
	v_cvt_pk_bf16_f32 v2, v6, v7
	v_cvt_pk_bf16_f32 v3, v14, v15
	v_add_u32_e32 v4, 0x3000, v26
	ds_write2_b64 v4, v[0:1], v[2:3] offset0:96 offset1:100
	v_cvt_pk_bf16_f32 v0, v20, v21
	v_cvt_pk_bf16_f32 v1, v30, v31
	v_cvt_pk_bf16_f32 v2, v36, v37
	v_cvt_pk_bf16_f32 v3, v46, v47
	s_ashr_i32 s1, s0, 31
	ds_write2_b64 v4, v[0:1], v[2:3] offset0:112 offset1:116
	v_lshl_add_u64 v[0:1], s[0:1], 1, v[64:65]
	v_ashrrev_i32_e32 v6, 4, v66
	v_lshl_add_u64 v[4:5], v[0:1], 0, v[180:181]
	v_mad_u64_u32 v[0:1], s[0:1], v6, s11, v[180:181]
	s_waitcnt lgkmcnt(0)
	s_barrier
; DEV void stage_tile_bf16(char* smem, const f32x4 (&v)[4][4], u16* buf, int ld, int m0, int col0) {
;     ...
; #pragma unroll
;   for (int k = 0; k < 8; ++k) {
;     const int chunk = tid + 256 * k, rl = chunk >> 4, c16 = chunk & 15;
;     u32x4 d = *(const u32x4*)(smem + rl * 272 + c16 * 16);
;     *(u32x4*)(buf + (size_t)(m0 + rl) * ld + col0 + c16 * 8) = d;
;   }
	ds_read_b128 v[0:3], v0
	v_add_u32_e32 v6, s14, v6
	v_ashrrev_i32_e32 v7, 31, v6
	v_lshlrev_b64 v[6:7], 12, v[6:7]
	v_lshl_add_u64 v[6:7], v[4:5], 0, v[6:7]
	s_waitcnt lgkmcnt(0)
	flat_store_dwordx4 v[6:7], v[0:3]
	s_nop 1
	v_add_u32_e32 v0, 0x100, v66
	v_ashrrev_i32_e32 v6, 4, v0
	v_mad_u64_u32 v[0:1], s[0:1], v6, s11, v[180:181]
	ds_read_b128 v[0:3], v0
	v_add_u32_e32 v6, s14, v6
	v_ashrrev_i32_e32 v7, 31, v6
	v_lshlrev_b64 v[6:7], 12, v[6:7]
	v_lshl_add_u64 v[6:7], v[4:5], 0, v[6:7]
	s_waitcnt lgkmcnt(0)
	flat_store_dwordx4 v[6:7], v[0:3]
	s_nop 1
	v_add_u32_e32 v0, 0x200, v66
	v_ashrrev_i32_e32 v6, 4, v0
	v_mad_u64_u32 v[0:1], s[0:1], v6, s11, v[180:181]
	ds_read_b128 v[0:3], v0
	v_add_u32_e32 v6, s14, v6
	v_ashrrev_i32_e32 v7, 31, v6
	v_lshlrev_b64 v[6:7], 12, v[6:7]
	v_lshl_add_u64 v[6:7], v[4:5], 0, v[6:7]
	s_waitcnt lgkmcnt(0)
	flat_store_dwordx4 v[6:7], v[0:3]
	s_nop 1
	v_add_u32_e32 v0, 0x300, v66
	v_ashrrev_i32_e32 v6, 4, v0
	v_mad_u64_u32 v[0:1], s[0:1], v6, s11, v[180:181]
	ds_read_b128 v[0:3], v0
	v_add_u32_e32 v6, s14, v6
	v_ashrrev_i32_e32 v7, 31, v6
	v_lshlrev_b64 v[6:7], 12, v[6:7]
	v_lshl_add_u64 v[6:7], v[4:5], 0, v[6:7]
	s_waitcnt lgkmcnt(0)
	flat_store_dwordx4 v[6:7], v[0:3]
	s_nop 1
	v_add_u32_e32 v0, 0x400, v66
	v_ashrrev_i32_e32 v6, 4, v0
	v_mad_u64_u32 v[0:1], s[0:1], v6, s11, v[180:181]
	ds_read_b128 v[0:3], v0
	v_add_u32_e32 v6, s14, v6
	v_ashrrev_i32_e32 v7, 31, v6
	v_lshlrev_b64 v[6:7], 12, v[6:7]
	v_lshl_add_u64 v[6:7], v[4:5], 0, v[6:7]
	s_waitcnt lgkmcnt(0)
	flat_store_dwordx4 v[6:7], v[0:3]
	s_nop 1
	v_add_u32_e32 v0, 0x500, v66
	v_ashrrev_i32_e32 v6, 4, v0
	v_mad_u64_u32 v[0:1], s[0:1], v6, s11, v[180:181]
	ds_read_b128 v[0:3], v0
	v_add_u32_e32 v6, s14, v6
	v_ashrrev_i32_e32 v7, 31, v6
	v_lshlrev_b64 v[6:7], 12, v[6:7]
	v_lshl_add_u64 v[6:7], v[4:5], 0, v[6:7]
	s_waitcnt lgkmcnt(0)
	flat_store_dwordx4 v[6:7], v[0:3]
	s_nop 1
	v_add_u32_e32 v0, 0x600, v66
	v_ashrrev_i32_e32 v6, 4, v0
	v_mad_u64_u32 v[0:1], s[0:1], v6, s11, v[180:181]
	ds_read_b128 v[0:3], v0
	v_add_u32_e32 v6, s14, v6
	v_ashrrev_i32_e32 v7, 31, v6
	v_lshlrev_b64 v[6:7], 12, v[6:7]
	v_lshl_add_u64 v[6:7], v[4:5], 0, v[6:7]
	s_waitcnt lgkmcnt(0)
	flat_store_dwordx4 v[6:7], v[0:3]
	s_nop 1
	v_add_u32_e32 v0, 0x700, v66
	v_ashrrev_i32_e32 v6, 4, v0
	v_mad_u64_u32 v[0:1], s[0:1], v6, s11, v[180:181]
	ds_read_b128 v[0:3], v0
	v_add_u32_e32 v6, s14, v6
	v_ashrrev_i32_e32 v7, 31, v6
	v_lshlrev_b64 v[6:7], 12, v[6:7]
	v_lshl_add_u64 v[4:5], v[4:5], 0, v[6:7]
	v_readlane_b32 s0, v251, 6
	s_waitcnt lgkmcnt(0)
	flat_store_dwordx4 v[4:5], v[0:3]
	s_add_i32 s6, s0, s6
	s_cmpk_lt_i32 s6, 0x400
	v_readlane_b32 s1, v251, 7
	s_cbranch_scc1 .LBB0_564

; DEV int tid_() { int t = threadIdx.x; asm volatile("" : "+v"(t)); return t; }
; template <class FragT, class AccT>
; DEV void gemm_core_t(const char* __restrict__ A, size_t lda_bytes, const char* __restrict__ Bt, size_t ldb_bytes, int kbytes,
;                      int m0, int n0, int Sshift, int dl, char* smem, AccT (&acc)[4][4]) {
;   const int tid = tid_(), lane = tid & 63, wid = tid >> 6, wm = wid >> 1, wn = wid & 1;
;   const int l15 = lane & 15, q = lane >> 4;
;   const int srow = lane >> 3, schunk = (lane & 7) ^ (lane >> 3);
;   const char* ap[4];
;   const char* bp[4];
; #pragma unroll
;   for (int u = 0; u < 4; ++u) {
;     int r = (wid * 4 + u) * 8 + srow;
;     int ar = rowmap(m0 + r, Sshift, dl);
;     ap[u] = A + (size_t)ar * lda_bytes + schunk * 16;
;     bp[u] = Bt + (size_t)(n0 + r) * ldb_bytes + schunk * 16;
;   }
; #pragma unroll
;   for (int i = 0; i < 4; ++i)
; #pragma unroll
;     for (int j = 0; j < 4; ++j) acc[i][j] = AccT{0, 0, 0, 0};
;   const int nk = kbytes >> 7;
;   __syncthreads();
; #pragma unroll
;   for (int u = 0; u < 4; ++u) {
;     __builtin_amdgcn_global_load_lds((const unsigned*)ap[u], (unsigned*)(smem + (wid * 4 + u) * 1024 + lane * 16), 16, 0, 0);
;     __builtin_amdgcn_global_load_lds((const unsigned*)bp[u], (unsigned*)(smem + 16384 + (wid * 4 + u) * 1024 + lane * 16), 16, 0, 0);
;   }
;   const unsigned sbase = (unsigned)(unsigned long)((__attribute__((address_space(3))) char*)smem);
;   const unsigned sq0 = (unsigned)((q ^ (l15 & 7)) << 4);
;   const unsigned a0 = sbase + (unsigned)((wm * 64 + l15) * 128) + sq0;
;   const unsigned b0 = sbase + 16384u + (unsigned)((wn * 32 + l15) * 128) + sq0;
;   asm volatile("s_waitcnt vmcnt(0)" ::: "memory");
;   __syncthreads();
.LBB0_623:
	s_ashr_i32 s4, s16, 3
	s_lshr_b32 s5, s4, 28
	s_add_i32 s5, s4, s5
	s_and_b32 s6, s5, -16
	v_mov_b32_e32 v22, v188
	s_sub_i32 s4, s4, s6
	s_lshl_b32 s6, s16, 1
	ds_read2_b64 v[0:3], v80 offset0:59 offset1:61
	s_and_b32 s6, s6, 14
	v_ashrrev_i32_e32 v24, 6, v22
	s_ashr_i32 s14, s4, 3
	s_lshl_b32 s5, s5, 6
	s_lshl_b32 s4, s4, 7
	v_bfe_u32 v25, v22, 3, 3
	v_lshlrev_b32_e32 v26, 5, v24
	s_add_i32 s15, s14, s6
	s_and_b32 s5, s5, 0xfffffc00
	s_and_b32 s6, s4, 0x380
	v_or_b32_e32 v20, v26, v25
	s_or_b32 s17, s6, s5
	s_lshl_b32 s4, s15, 7
	v_or_b32_e32 v14, 8, v20
	v_or_b32_e32 v18, 16, v20
	v_or_b32_e32 v27, 24, v20
	v_bitop3_b32 v4, v25, v22, 7 bitop3:0x78
	v_add_u32_e32 v8, s17, v20
	v_add_u32_e32 v10, s4, v20
	v_add_u32_e32 v12, s17, v14
	v_add_u32_e32 v16, s17, v18
	v_add_u32_e32 v20, s17, v27
	v_lshlrev_b32_e32 v180, 4, v4
	v_ashrrev_i32_e32 v9, 31, v8
	v_ashrrev_i32_e32 v13, 31, v12
	v_ashrrev_i32_e32 v17, 31, v16
	v_ashrrev_i32_e32 v21, 31, v20
	s_waitcnt lgkmcnt(0)
	v_lshl_add_u64 v[4:5], v[2:3], 0, v[180:181]
	v_lshlrev_b64 v[8:9], 11, v[8:9]
	v_lshlrev_b64 v[12:13], 11, v[12:13]
	v_lshlrev_b64 v[16:17], 11, v[16:17]
	v_lshlrev_b64 v[20:21], 11, v[20:21]
	v_lshl_add_u64 v[8:9], v[4:5], 0, v[8:9]
	v_lshl_add_u64 v[12:13], v[4:5], 0, v[12:13]
	v_add_u32_e32 v14, s4, v14
	v_lshl_add_u64 v[16:17], v[4:5], 0, v[16:17]
	v_add_u32_e32 v18, s4, v18
	v_lshl_add_u64 v[4:5], v[4:5], 0, v[20:21]
	v_add_u32_e32 v20, s4, v27
	v_ashrrev_i32_e32 v11, 31, v10
	v_ashrrev_i32_e32 v15, 31, v14
	v_ashrrev_i32_e32 v19, 31, v18
	v_ashrrev_i32_e32 v21, 31, v20
	v_lshl_add_u64 v[6:7], v[0:1], 0, v[180:181]
	v_lshlrev_b64 v[10:11], 11, v[10:11]
	v_lshlrev_b64 v[14:15], 11, v[14:15]
	v_lshlrev_b64 v[18:19], 11, v[18:19]
	v_lshlrev_b64 v[20:21], 11, v[20:21]
	v_and_b32_e32 v23, 63, v22
	v_lshl_add_u64 v[10:11], v[6:7], 0, v[10:11]
	v_lshl_add_u64 v[14:15], v[6:7], 0, v[14:15]
	v_lshl_add_u64 v[18:19], v[6:7], 0, v[18:19]
	v_lshl_add_u64 v[6:7], v[6:7], 0, v[20:21]
	v_lshlrev_b32_e32 v20, 12, v24
	v_lshl_or_b32 v83, v23, 4, v20
	s_nop 0
	v_readfirstlane_b32 s15, v83
	s_mov_b32 m0, s15
	s_barrier
	global_load_lds_dwordx4 v[8:9], off
	v_add_u32_e32 v8, 0x4000, v83
	s_lshl_b32 s14, s14, 7
	v_readfirstlane_b32 s15, v8
	v_or_b32_e32 v8, 0x400, v83
	s_mov_b32 m0, s15
	v_readfirstlane_b32 s15, v8
	v_add_u32_e32 v8, 0x4400, v83
	global_load_lds_dwordx4 v[10:11], off
	s_mov_b32 m0, s15
	v_readfirstlane_b32 s15, v8
	v_or_b32_e32 v8, 0x800, v83
	global_load_lds_dwordx4 v[12:13], off
	s_mov_b32 m0, s15
	v_readfirstlane_b32 s15, v8
	v_add_u32_e32 v8, 0x4800, v83
	global_load_lds_dwordx4 v[14:15], off
	s_mov_b32 m0, s15
	v_readfirstlane_b32 s15, v8
	v_or_b32_e32 v8, 0xc00, v83
	global_load_lds_dwordx4 v[16:17], off
	s_mov_b32 m0, s15
	v_readfirstlane_b32 s15, v8
	global_load_lds_dwordx4 v[18:19], off
	s_mov_b32 m0, s15
	v_lshl_add_u64 v[0:1], v[0:1], 0, s[46:47]
	global_load_lds_dwordx4 v[4:5], off
	v_add_u32_e32 v4, 0x4c00, v83
	v_lshlrev_b32_e32 v5, 4, v22
	v_readfirstlane_b32 s15, v4
	s_mov_b32 m0, s15
	v_and_b32_e32 v4, 15, v22
	global_load_lds_dwordx4 v[6:7], off
	v_lshrrev_b32_e32 v6, 1, v22
	v_and_or_b32 v6, v6, s44, v4
	s_and_b32 s15, s16, 7
	v_bitop3_b32 v5, v23, s31, v5 bitop3:0x48
	v_lshlrev_b32_e32 v6, 7, v6
	v_and_or_b32 v4, v26, 32, v4
	s_lshl_b32 s15, s15, 8
	v_or_b32_e32 v84, v5, v6
	v_lshl_or_b32 v4, v4, 7, v5
	v_bitop3_b32 v87, v5, 64, v6 bitop3:0x36
	v_or_b32_e32 v6, 24, v25
	s_add_i32 s14, s14, s15
	v_or_b32_e32 v85, 0x4000, v4
	v_bitop3_b32 v86, v4, 64, v219 bitop3:0x36
	v_or_b32_e32 v4, s14, v6
	v_add_u32_e32 v4, v4, v26
	v_ashrrev_i32_e32 v5, 31, v4
	v_lshlrev_b64 v[4:5], 11, v[4:5]
	v_or_b32_e32 v4, v4, v180
	v_lshl_add_u64 v[64:65], v[0:1], 0, v[4:5]
	v_or_b32_e32 v4, s5, v6
	v_or_b32_e32 v4, s6, v4
	v_add_u32_e32 v4, v4, v26
	v_ashrrev_i32_e32 v5, 31, v4
	v_lshlrev_b64 v[4:5], 11, v[4:5]
	v_lshl_add_u64 v[2:3], v[2:3], 0, s[46:47]
	v_or_b32_e32 v4, v4, v180
	v_or_b32_e32 v6, 16, v25
	v_lshl_add_u64 v[66:67], v[2:3], 0, v[4:5]
	v_or_b32_e32 v4, s14, v6
	v_add_u32_e32 v4, v4, v26
	v_ashrrev_i32_e32 v5, 31, v4
	v_lshlrev_b64 v[4:5], 11, v[4:5]
	v_or_b32_e32 v4, v4, v180
	v_lshl_add_u64 v[68:69], v[0:1], 0, v[4:5]
	v_or_b32_e32 v4, s5, v6
	v_or_b32_e32 v4, s6, v4
	v_add_u32_e32 v4, v4, v26
	v_ashrrev_i32_e32 v5, 31, v4
	v_lshlrev_b64 v[4:5], 11, v[4:5]
	v_or_b32_e32 v4, v4, v180
	v_or_b32_e32 v6, 8, v25
	v_lshl_add_u64 v[70:71], v[2:3], 0, v[4:5]
	v_or_b32_e32 v4, s14, v6
	v_add_u32_e32 v4, v4, v26
	v_ashrrev_i32_e32 v5, 31, v4
	v_lshlrev_b64 v[4:5], 11, v[4:5]
	v_or_b32_e32 v4, v4, v180
	v_lshl_add_u64 v[72:73], v[0:1], 0, v[4:5]
	v_or_b32_e32 v4, s5, v6
	v_or_b32_e32 v4, s6, v4
	v_add_u32_e32 v4, v4, v26
	v_ashrrev_i32_e32 v5, 31, v4
	v_lshlrev_b64 v[4:5], 11, v[4:5]
	v_or_b32_e32 v4, v4, v180
	v_lshl_add_u64 v[74:75], v[2:3], 0, v[4:5]
	v_or_b32_e32 v4, s14, v25
	v_add_u32_e32 v4, v4, v26
	v_ashrrev_i32_e32 v5, 31, v4
	v_lshlrev_b64 v[4:5], 11, v[4:5]
	v_or_b32_e32 v4, v4, v180
	v_lshl_add_u64 v[76:77], v[0:1], 0, v[4:5]
	v_or_b32_e32 v0, s5, v25
	v_or_b32_e32 v0, s6, v0
	v_add_u32_e32 v0, v0, v26
	v_ashrrev_i32_e32 v1, 31, v0
	v_lshlrev_b64 v[0:1], 11, v[0:1]
	v_or_b32_e32 v0, v0, v180
	v_lshl_add_u64 v[78:79], v[2:3], 0, v[0:1]
	v_mov_b32_e32 v0, 0
	s_mov_b64 s[14:15], 0
	s_mov_b32 s5, 0x8000
	v_mov_b32_e32 v1, v0
	v_mov_b32_e32 v2, v0
	v_mov_b32_e32 v3, v0
	v_mov_b32_e32 v4, v0
	v_mov_b32_e32 v5, v0
	v_mov_b32_e32 v6, v0
	v_mov_b32_e32 v7, v0
	v_mov_b32_e32 v8, v0
	v_mov_b32_e32 v9, v0
	v_mov_b32_e32 v10, v0
	v_mov_b32_e32 v11, v0
	v_mov_b32_e32 v12, v0
	v_mov_b32_e32 v13, v0
	v_mov_b32_e32 v14, v0
	v_mov_b32_e32 v15, v0
	v_mov_b32_e32 v16, v0
; DEV f32x4 mma_step(bf16x8 a, bf16x8 b, f32x4 c) { return MFMA(a, b, c); }
; template <class FragT, class AccT>
; DEV void gemm_core_t(const char* __restrict__ A, size_t lda_bytes, const char* __restrict__ Bt, size_t ldb_bytes, int kbytes,
;                      int m0, int n0, int Sshift, int dl, char* smem, AccT (&acc)[4][4]) {
;     ...
;   for (int kt = 0; kt < nk; ++kt) {
;     const unsigned so = (unsigned)(kt & 1) * 32768u;
;     char* nxt = smem + ((kt + 1) & 1) * 32768;
;     if (kt + 1 < nk) {
; #pragma unroll
;       for (int u = 0; u < 4; ++u) {
;         __builtin_amdgcn_global_load_lds((const unsigned*)(ap[u] + (size_t)(kt + 1) * 128), (unsigned*)(nxt + (wid * 4 + u) * 1024 + lane * 16), 16, 0, 0);
;         __builtin_amdgcn_global_load_lds((const unsigned*)(bp[u] + (size_t)(kt + 1) * 128), (unsigned*)(nxt + 16384 + (wid * 4 + u) * 1024 + lane * 16), 16, 0, 0);
;       }
;     }
;     FragT xa[2][4], wb[2][4];
;     asm volatile(
;         "ds_read_b128 %0, %16\n\t"
;         "ds_read_b128 %1, %16 offset:2048\n\t"
;         "ds_read_b128 %2, %16 offset:4096\n\t"
;         "ds_read_b128 %3, %16 offset:6144\n\t"
;         "ds_read_b128 %4, %18\n\t"
;         "ds_read_b128 %5, %18 offset:2048\n\t"
;         "ds_read_b128 %6, %18 offset:8192\n\t"
;         "ds_read_b128 %7, %18 offset:10240\n\t"
;         "ds_read_b128 %8, %17\n\t"
;         "ds_read_b128 %9, %17 offset:2048\n\t"
;         "ds_read_b128 %10, %17 offset:4096\n\t"
;         "ds_read_b128 %11, %17 offset:6144\n\t"
;         "ds_read_b128 %12, %19\n\t"
;         "ds_read_b128 %13, %19 offset:2048\n\t"
;         "ds_read_b128 %14, %19 offset:8192\n\t"
;         "ds_read_b128 %15, %19 offset:10240\n\t"
;         "s_waitcnt lgkmcnt(8)"
;         : "=&v"(xa[0][0]), "=&v"(xa[0][1]), "=&v"(xa[0][2]), "=&v"(xa[0][3]), "=&v"(wb[0][0]), "=&v"(wb[0][1]), "=&v"(wb[0][2]),
;           "=&v"(wb[0][3]), "=&v"(xa[1][0]), "=&v"(xa[1][1]), "=&v"(xa[1][2]), "=&v"(xa[1][3]), "=&v"(wb[1][0]), "=&v"(wb[1][1]),
;           "=&v"(wb[1][2]), "=&v"(wb[1][3])
;         : "v"(a0 + so), "v"((a0 ^ 64u) + so), "v"(b0 + so), "v"((b0 ^ 64u) + so)
;         : "memory");
;     __builtin_amdgcn_s_setprio(1);
; #pragma unroll
;     for (int i = 0; i < 4; ++i)
; #pragma unroll
;       for (int j = 0; j < 4; ++j) acc[i][j] = mma_step(wb[0][j], xa[0][i], acc[i][j]);
;     asm volatile("s_waitcnt lgkmcnt(0)"
	v_mov_b32_e32 v17, v0
	v_mov_b32_e32 v18, v0
	v_mov_b32_e32 v19, v0
	v_mov_b32_e32 v20, v0
	v_mov_b32_e32 v21, v0
	v_mov_b32_e32 v22, v0
	v_mov_b32_e32 v23, v0
	v_mov_b32_e32 v24, v0
	v_mov_b32_e32 v25, v0
	v_mov_b32_e32 v26, v0
	v_mov_b32_e32 v27, v0
	v_mov_b32_e32 v28, v0
	v_mov_b32_e32 v29, v0
	v_mov_b32_e32 v30, v0
	v_mov_b32_e32 v31, v0
	v_mov_b32_e32 v32, v0
	v_mov_b32_e32 v33, v0
	v_mov_b32_e32 v34, v0
	v_mov_b32_e32 v35, v0
	v_mov_b32_e32 v36, v0
	v_mov_b32_e32 v37, v0
	v_mov_b32_e32 v38, v0
	v_mov_b32_e32 v39, v0
	v_mov_b32_e32 v40, v0
	v_mov_b32_e32 v41, v0
	v_mov_b32_e32 v42, v0
	v_mov_b32_e32 v43, v0
	v_mov_b32_e32 v44, v0
	v_mov_b32_e32 v45, v0
	v_mov_b32_e32 v46, v0
	v_mov_b32_e32 v47, v0
	v_mov_b32_e32 v48, v0
	v_mov_b32_e32 v49, v0
	v_mov_b32_e32 v50, v0
	v_mov_b32_e32 v51, v0
	v_mov_b32_e32 v52, v0
	v_mov_b32_e32 v53, v0
	v_mov_b32_e32 v54, v0
	v_mov_b32_e32 v55, v0
	v_mov_b32_e32 v56, v0
	v_mov_b32_e32 v57, v0
	v_mov_b32_e32 v58, v0
	v_mov_b32_e32 v59, v0
	v_mov_b32_e32 v60, v0
	v_mov_b32_e32 v61, v0
	v_mov_b32_e32 v62, v0
	v_mov_b32_e32 v63, v0
	v_readfirstlane_b32 s64, v78
	v_readfirstlane_b32 s65, v79
	v_readfirstlane_b32 s66, v76
	v_readfirstlane_b32 s67, v77
	v_readfirstlane_b32 s62, v83
	s_sub_u32 s64, s64, 0x80000000
	s_subb_u32 s65, s65, 0
	s_sub_u32 s66, s66, 0x80000000
	s_subb_u32 s67, s67, 0
	v_subrev_u32_e32 v78, s64, v78
	v_subrev_u32_e32 v76, s66, v76
	v_subrev_u32_e32 v74, s64, v74
	v_subrev_u32_e32 v72, s66, v72
	v_subrev_u32_e32 v70, s64, v70
	v_subrev_u32_e32 v68, s66, v68
	v_subrev_u32_e32 v66, s64, v66
	v_subrev_u32_e32 v64, s66, v64
	s_waitcnt vmcnt(0) lgkmcnt(0)
	s_barrier
.LBB0_624:
	s_add_i32 s6, s5, 0xffff8000
	s_and_b32 s6, s6, 0x8000
	v_add_u32_e32 v152, s6, v84
	v_add_u32_e32 v153, s6, v87
	v_or_b32_e32 v154, s6, v85
	v_or_b32_e32 v155, s6, v86
	s_and_b32 s6, s5, 0x8000
	s_add_i32 s6, s6, s62
	s_mov_b32 m0, s6
	ds_read_b128 v[88:91], v152
	global_load_lds_dwordx4 v78, s[64:65]
	ds_read_b128 v[92:95], v152 offset:2048
	s_add_i32 m0, s6, 0x4000
	ds_read_b128 v[96:99], v152 offset:4096
	global_load_lds_dwordx4 v76, s[66:67]
	ds_read_b128 v[100:103], v152 offset:6144
	s_add_i32 m0, s6, 0x400
	ds_read_b128 v[104:107], v154
	global_load_lds_dwordx4 v74, s[64:65]
	ds_read_b128 v[108:111], v154 offset:2048
	s_add_i32 m0, s6, 0x4400
	ds_read_b128 v[112:115], v154 offset:8192
	global_load_lds_dwordx4 v72, s[66:67]
	ds_read_b128 v[116:119], v154 offset:10240
	ds_read_b128 v[120:123], v153
	ds_read_b128 v[124:127], v153 offset:2048
	ds_read_b128 v[128:131], v153 offset:4096
	ds_read_b128 v[132:135], v153 offset:6144
	ds_read_b128 v[136:139], v155
	ds_read_b128 v[140:143], v155 offset:2048
	ds_read_b128 v[144:147], v155 offset:8192
	ds_read_b128 v[148:151], v155 offset:10240
	s_waitcnt lgkmcnt(8)
	s_setprio 1
	v_mfma_i32_16x16x64_i8 v[60:63], v[104:107], v[88:91], v[60:63]
	v_mfma_i32_16x16x64_i8 v[56:59], v[108:111], v[88:91], v[56:59]
	s_add_i32 m0, s6, 0x800
	v_mfma_i32_16x16x64_i8 v[52:55], v[112:115], v[88:91], v[52:55]
	global_load_lds_dwordx4 v70, s[64:65]
	v_mfma_i32_16x16x64_i8 v[48:51], v[116:119], v[88:91], v[48:51]
	v_mfma_i32_16x16x64_i8 v[44:47], v[104:107], v[92:95], v[44:47]
	v_mfma_i32_16x16x64_i8 v[40:43], v[108:111], v[92:95], v[40:43]
	s_add_i32 m0, s6, 0x4800
	v_mfma_i32_16x16x64_i8 v[36:39], v[112:115], v[92:95], v[36:39]
	global_load_lds_dwordx4 v68, s[66:67]
	v_mfma_i32_16x16x64_i8 v[32:35], v[116:119], v[92:95], v[32:35]
	v_mfma_i32_16x16x64_i8 v[28:31], v[104:107], v[96:99], v[28:31]
	v_mfma_i32_16x16x64_i8 v[24:27], v[108:111], v[96:99], v[24:27]
	s_add_i32 m0, s6, 0xc00
	v_mfma_i32_16x16x64_i8 v[20:23], v[112:115], v[96:99], v[20:23]
	global_load_lds_dwordx4 v66, s[64:65]
	v_mfma_i32_16x16x64_i8 v[16:19], v[116:119], v[96:99], v[16:19]
	v_mfma_i32_16x16x64_i8 v[12:15], v[104:107], v[100:103], v[12:15]
	v_mfma_i32_16x16x64_i8 v[8:11], v[108:111], v[100:103], v[8:11]
	s_add_i32 m0, s6, 0x4c00
	v_mfma_i32_16x16x64_i8 v[4:7], v[112:115], v[100:103], v[4:7]
	global_load_lds_dwordx4 v64, s[66:67]
	v_mfma_i32_16x16x64_i8 v[0:3], v[116:119], v[100:103], v[0:3]
	s_waitcnt lgkmcnt(0)
	s_nop 0
	v_mfma_i32_16x16x64_i8 v[60:63], v[136:139], v[120:123], v[60:63]
	v_mfma_i32_16x16x64_i8 v[56:59], v[140:143], v[120:123], v[56:59]
	v_mfma_i32_16x16x64_i8 v[52:55], v[144:147], v[120:123], v[52:55]
	v_mfma_i32_16x16x64_i8 v[48:51], v[148:151], v[120:123], v[48:51]
	v_mfma_i32_16x16x64_i8 v[44:47], v[136:139], v[124:127], v[44:47]
	v_mfma_i32_16x16x64_i8 v[40:43], v[140:143], v[124:127], v[40:43]
	v_mfma_i32_16x16x64_i8 v[36:39], v[144:147], v[124:127], v[36:39]
	v_mfma_i32_16x16x64_i8 v[32:35], v[148:151], v[124:127], v[32:35]
	v_mfma_i32_16x16x64_i8 v[28:31], v[136:139], v[128:131], v[28:31]
	v_mfma_i32_16x16x64_i8 v[24:27], v[140:143], v[128:131], v[24:27]
	v_mfma_i32_16x16x64_i8 v[20:23], v[144:147], v[128:131], v[20:23]
	v_mfma_i32_16x16x64_i8 v[16:19], v[148:151], v[128:131], v[16:19]
	v_mfma_i32_16x16x64_i8 v[12:15], v[136:139], v[132:135], v[12:15]
	v_mfma_i32_16x16x64_i8 v[8:11], v[140:143], v[132:135], v[8:11]
	v_mfma_i32_16x16x64_i8 v[4:7], v[144:147], v[132:135], v[4:7]
	v_mfma_i32_16x16x64_i8 v[0:3], v[148:151], v[132:135], v[0:3]
	s_setprio 0
	s_waitcnt vmcnt(0)
	s_add_u32 s14, s14, 0x80
	s_addc_u32 s15, s15, 0
	s_add_u32 s64, s64, 0x80
	s_addc_u32 s65, s65, 0
	s_add_u32 s66, s66, 0x80
	s_addc_u32 s67, s67, 0
	s_add_i32 s5, s5, 0x8000
	s_cmpk_lg_i32 s14, 0x780
	s_waitcnt vmcnt(0) lgkmcnt(0)
	s_barrier
	s_cbranch_scc1 .LBB0_624
; template <class FragT, class AccT>
; DEV void gemm_core_t(const char* __restrict__ A, size_t lda_bytes, const char* __restrict__ Bt, size_t ldb_bytes, int kbytes,
;                      int m0, int n0, int Sshift, int dl, char* smem, AccT (&acc)[4][4]) {
;     ...
;     asm volatile(
;         "ds_read_b128 %0, %16\n\t"
;         "ds_read_b128 %1, %16 offset:2048\n\t"
;         "ds_read_b128 %2, %16 offset:4096\n\t"
;         "ds_read_b128 %3, %16 offset:6144\n\t"
;         "ds_read_b128 %4, %18\n\t"
;         "ds_read_b128 %5, %18 offset:2048\n\t"
;         "ds_read_b128 %6, %18 offset:8192\n\t"
;         "ds_read_b128 %7, %18 offset:10240\n\t"
;         "ds_read_b128 %8, %17\n\t"
;         "ds_read_b128 %9, %17 offset:2048\n\t"
;         "ds_read_b128 %10, %17 offset:4096\n\t"
;         "ds_read_b128 %11, %17 offset:6144\n\t"
;         "ds_read_b128 %12, %19\n\t"
;         "ds_read_b128 %13, %19 offset:2048\n\t"
;         "ds_read_b128 %14, %19 offset:8192\n\t"
;         "ds_read_b128 %15, %19 offset:10240\n\t"
;         "s_waitcnt lgkmcnt(8)"
;         : "=&v"(xa[0][0]), "=&v"(xa[0][1]), "=&v"(xa[0][2]), "=&v"(xa[0][3]), "=&v"(wb[0][0]), "=&v"(wb[0][1]), "=&v"(wb[0][2]),
;           "=&v"(wb[0][3]), "=&v"(xa[1][0]), "=&v"(xa[1][1]), "=&v"(xa[1][2]), "=&v"(xa[1][3]), "=&v"(wb[1][0]), "=&v"(wb[1][1]),
;           "=&v"(wb[1][2]), "=&v"(wb[1][3])
;         : "v"(a0 + so), "v"((a0 ^ 64u) + so), "v"(b0 + so), "v"((b0 ^ 64u) + so)
;         : "memory");
;     __builtin_amdgcn_s_setprio(1);
; #pragma unroll
;     for (int i = 0; i < 4; ++i)
; #pragma unroll
;       for (int j = 0; j < 4; ++j) acc[i][j] = mma_step(wb[0][j], xa[0][i], acc[i][j]);
;     asm volatile("s_waitcnt lgkmcnt(0)"
;                  : "+v"(xa[1][0]), "+v"(xa[1][1]), "+v"(xa[1][2]), "+v"(xa[1][3]), "+v"(wb[1][0]), "+v"(wb[1][1]), "+v"(wb[1][2]),
;                    "+v"(wb[1][3]), "+v"(acc[0][0]), "+v"(acc[0][1]), "+v"(acc[0][2]), "+v"(acc[0][3]), "+v"(acc[1][0]),
;                    "+v"(acc[1][1]), "+v"(acc[1][2]), "+v"(acc[1][3]), "+v"(acc[2][0]), "+v"(acc[2][1]), "+v"(acc[2][2]),
;                    "+v"(acc[2][3]), "+v"(acc[3][0]), "+v"(acc[3][1]), "+v"(acc[3][2]), "+v"(acc[3][3])
;                  :
;                  : "memory");
; #pragma unroll
;     for (int i = 0; i < 4; ++i)
; #pragma unroll
;       for (int j = 0; j < 4; ++j) acc[i][j] = mma_step(wb[1][j], xa[1][i], acc[i][j]);
	v_add_u32_e32 v83, 0x8000, v84
	v_add_u32_e32 v132, 0x8000, v87
	v_or_b32_e32 v133, 0x8000, v85
	v_or_b32_e32 v134, 0x8000, v86
	ds_read_b128 v[64:67], v83
	ds_read_b128 v[68:71], v83 offset:2048
	ds_read_b128 v[72:75], v83 offset:4096
	ds_read_b128 v[76:79], v83 offset:6144
	ds_read_b128 v[84:87], v133
	ds_read_b128 v[88:91], v133 offset:2048
	ds_read_b128 v[92:95], v133 offset:8192
	ds_read_b128 v[96:99], v133 offset:10240
	ds_read_b128 v[100:103], v132
	ds_read_b128 v[104:107], v132 offset:2048
	ds_read_b128 v[108:111], v132 offset:4096
	ds_read_b128 v[112:115], v132 offset:6144
	ds_read_b128 v[116:119], v134
	ds_read_b128 v[120:123], v134 offset:2048
	ds_read_b128 v[124:127], v134 offset:8192
	ds_read_b128 v[128:131], v134 offset:10240
	s_waitcnt lgkmcnt(8)
	s_setprio 1
	v_mfma_i32_16x16x64_i8 v[60:63], v[84:87], v[64:67], v[60:63]
	v_mfma_i32_16x16x64_i8 v[56:59], v[88:91], v[64:67], v[56:59]
	v_mfma_i32_16x16x64_i8 v[52:55], v[92:95], v[64:67], v[52:55]
	v_mfma_i32_16x16x64_i8 v[48:51], v[96:99], v[64:67], v[48:51]
	v_mfma_i32_16x16x64_i8 v[44:47], v[84:87], v[68:71], v[44:47]
	v_mfma_i32_16x16x64_i8 v[40:43], v[88:91], v[68:71], v[40:43]
	v_mfma_i32_16x16x64_i8 v[36:39], v[92:95], v[68:71], v[36:39]
	v_mfma_i32_16x16x64_i8 v[32:35], v[96:99], v[68:71], v[32:35]
	v_mfma_i32_16x16x64_i8 v[28:31], v[84:87], v[72:75], v[28:31]
	v_mfma_i32_16x16x64_i8 v[24:27], v[88:91], v[72:75], v[24:27]
	v_mfma_i32_16x16x64_i8 v[20:23], v[92:95], v[72:75], v[20:23]
	v_mfma_i32_16x16x64_i8 v[68:71], v[96:99], v[72:75], v[16:19]
	v_mfma_i32_16x16x64_i8 v[72:75], v[84:87], v[76:79], v[12:15]
	v_mfma_i32_16x16x64_i8 v[8:11], v[88:91], v[76:79], v[8:11]
	v_mfma_i32_16x16x64_i8 v[4:7], v[92:95], v[76:79], v[4:7]
	v_mfma_i32_16x16x64_i8 v[0:3], v[96:99], v[76:79], v[0:3]
	s_waitcnt lgkmcnt(0)
	s_nop 0
	v_mfma_i32_16x16x64_i8 v[84:87], v[116:119], v[100:103], v[60:63]
	v_mfma_i32_16x16x64_i8 v[16:19], v[120:123], v[100:103], v[56:59]
	v_mfma_i32_16x16x64_i8 v[12:15], v[124:127], v[100:103], v[52:55]
	v_mfma_i32_16x16x64_i8 v[64:67], v[128:131], v[100:103], v[48:51]
	v_mfma_i32_16x16x64_i8 v[60:63], v[116:119], v[104:107], v[44:47]
	v_mfma_i32_16x16x64_i8 v[56:59], v[120:123], v[104:107], v[40:43]
	v_mfma_i32_16x16x64_i8 v[52:55], v[124:127], v[104:107], v[36:39]
	v_mfma_i32_16x16x64_i8 v[48:51], v[128:131], v[104:107], v[32:35]
	v_mfma_i32_16x16x64_i8 v[44:47], v[116:119], v[108:111], v[28:31]
	v_mfma_i32_16x16x64_i8 v[40:43], v[120:123], v[108:111], v[24:27]
	v_mfma_i32_16x16x64_i8 v[36:39], v[124:127], v[108:111], v[20:23]
	v_mfma_i32_16x16x64_i8 v[32:35], v[128:131], v[108:111], v[68:71]
	v_mfma_i32_16x16x64_i8 v[20:23], v[116:119], v[112:115], v[72:75]
	v_mfma_i32_16x16x64_i8 v[8:11], v[120:123], v[112:115], v[8:11]
	v_mfma_i32_16x16x64_i8 v[4:7], v[124:127], v[112:115], v[4:7]
	v_mfma_i32_16x16x64_i8 v[0:3], v[128:131], v[112:115], v[0:3]
	s_setprio 0
	s_waitcnt vmcnt(0)
	s_barrier
	ds_read2_b64 v[24:27], v80 offset0:54 offset1:56
	v_add_u32_e32 v28, s17, v81
	v_or_b32_e32 v30, s4, v82
	v_ashrrev_i32_e32 v29, 31, v28
	v_ashrrev_i32_e32 v31, 31, v30
	s_waitcnt lgkmcnt(0)
	v_lshl_add_u64 v[68:69], v[28:29], 2, v[26:27]
	v_lshl_add_u64 v[70:71], v[30:31], 2, v[24:25]
	flat_load_dword v78, v[68:69]
	flat_load_dwordx4 v[24:27], v[70:71]
	v_cvt_f32_i32_e32 v28, v84
	v_cvt_f32_i32_e32 v29, v85
	v_cvt_f32_i32_e32 v16, v16
	v_cvt_f32_i32_e32 v17, v17
	v_cvt_f32_i32_e32 v12, v12
	v_cvt_f32_i32_e32 v13, v13
	v_cvt_f32_i32_e32 v64, v64
	v_cvt_f32_i32_e32 v65, v65
	v_cvt_f32_i32_e32 v60, v60
	v_cvt_f32_i32_e32 v61, v61
	v_cvt_f32_i32_e32 v56, v56
	v_cvt_f32_i32_e32 v57, v57
	v_cvt_f32_i32_e32 v52, v52
	v_cvt_f32_i32_e32 v53, v53
	v_cvt_f32_i32_e32 v48, v48
	v_cvt_f32_i32_e32 v49, v49
	v_cvt_f32_i32_e32 v44, v44
	v_cvt_f32_i32_e32 v45, v45
	v_cvt_f32_i32_e32 v40, v40
	v_cvt_f32_i32_e32 v41, v41
	v_cvt_f32_i32_e32 v36, v36
	v_cvt_f32_i32_e32 v37, v37
	v_cvt_f32_i32_e32 v32, v32
	v_cvt_f32_i32_e32 v33, v33
	v_cvt_f32_i32_e32 v20, v20
	v_cvt_f32_i32_e32 v21, v21
	v_cvt_f32_i32_e32 v8, v8
	v_cvt_f32_i32_e32 v9, v9
	v_cvt_f32_i32_e32 v4, v4
	v_cvt_f32_i32_e32 v5, v5
	v_cvt_f32_i32_e32 v0, v0
	v_cvt_f32_i32_e32 v1, v1
	s_mov_b32 s44, 0x1ffffc0
	s_mov_b64 s[46:47], 0x80
	s_waitcnt vmcnt(0) lgkmcnt(0)
	v_mul_f32_e32 v28, v78, v28
	v_mul_f32_e32 v29, v78, v29
	v_mul_f32_e32 v28, v24, v28
	v_mul_f32_e32 v29, v29, v25
	v_mul_f32_e32 v28, 0xbfb8aa3b, v28
	v_mul_f32_e32 v29, 0xbfb8aa3b, v29
	v_exp_f32_e32 v28, v28
	v_exp_f32_e32 v29, v29
	v_mul_f32_e32 v16, v78, v16
	v_mul_f32_e32 v17, v78, v17
	v_mul_f32_e32 v12, v78, v12
	v_pk_add_f32 v[28:29], v[28:29], 1.0 op_sel_hi:[1,0]
	v_mul_f32_e32 v13, v78, v13
	v_div_scale_f32 v30, s[14:15], v29, v29, 1.0
	v_rcp_f32_e32 v31, v30
	v_mul_f32_e32 v64, v78, v64
	v_mul_f32_e32 v65, v78, v65
	v_fma_f32 v72, -v30, v31, 1.0
	v_fmac_f32_e32 v31, v72, v31
	v_div_scale_f32 v72, vcc, 1.0, v29, 1.0
	v_mul_f32_e32 v73, v72, v31
	v_fma_f32 v74, -v30, v73, v72
	v_fmac_f32_e32 v73, v74, v31
	v_fma_f32 v30, -v30, v73, v72
	v_div_fmas_f32 v30, v30, v31, v73
	v_div_fixup_f32 v29, v30, v29, 1.0
	v_div_scale_f32 v30, s[14:15], v28, v28, 1.0
	v_rcp_f32_e32 v31, v30
	s_nop 0
	v_fma_f32 v72, -v30, v31, 1.0
	v_fmac_f32_e32 v31, v72, v31
	v_div_scale_f32 v72, vcc, 1.0, v28, 1.0
	v_mul_f32_e32 v73, v72, v31
	v_fma_f32 v74, -v30, v73, v72
	v_fmac_f32_e32 v73, v74, v31
	v_fma_f32 v30, -v30, v73, v72
	v_div_fmas_f32 v30, v30, v31, v73
	v_div_fixup_f32 v28, v30, v28, 1.0
	v_cvt_pk_bf16_f32 v72, v28, v29
	v_cvt_f32_i32_e32 v28, v86
	v_cvt_f32_i32_e32 v29, v87
	v_mul_f32_e32 v28, v78, v28
	v_mul_f32_e32 v29, v78, v29
	v_mul_f32_e32 v28, v28, v26
	v_mul_f32_e32 v29, v29, v27
	v_mul_f32_e32 v28, 0xbfb8aa3b, v28
	v_mul_f32_e32 v29, 0xbfb8aa3b, v29
	v_exp_f32_e32 v28, v28
	v_exp_f32_e32 v29, v29
	s_nop 0
	v_pk_add_f32 v[28:29], v[28:29], 1.0 op_sel_hi:[1,0]
	s_nop 0
	v_div_scale_f32 v30, s[14:15], v29, v29, 1.0
	v_rcp_f32_e32 v31, v30
	s_nop 0
	v_fma_f32 v73, -v30, v31, 1.0
	v_fmac_f32_e32 v31, v73, v31
	v_div_scale_f32 v73, vcc, 1.0, v29, 1.0
	v_mul_f32_e32 v74, v73, v31
	v_fma_f32 v75, -v30, v74, v73
	v_fmac_f32_e32 v74, v75, v31
	v_fma_f32 v30, -v30, v74, v73
	v_div_fmas_f32 v30, v30, v31, v74
	v_div_fixup_f32 v29, v30, v29, 1.0
	v_div_scale_f32 v30, s[14:15], v28, v28, 1.0
	v_rcp_f32_e32 v31, v30
	s_nop 0
	v_fma_f32 v73, -v30, v31, 1.0
	v_fmac_f32_e32 v31, v73, v31
	v_div_scale_f32 v73, vcc, 1.0, v28, 1.0
	v_mul_f32_e32 v74, v73, v31
	v_fma_f32 v75, -v30, v74, v73
	v_fmac_f32_e32 v74, v75, v31
	v_fma_f32 v30, -v30, v74, v73
	v_div_fmas_f32 v30, v30, v31, v74
	v_div_fixup_f32 v28, v30, v28, 1.0
	v_cvt_pk_bf16_f32 v73, v28, v29
	flat_load_dwordx4 v[28:31], v[70:71] offset:64
	s_waitcnt vmcnt(0) lgkmcnt(0)
; DEV float sigm(float x) { return 1.f / (1.f + __expf(-x)); }
; #define P (*launderP(lp))
; __device__ __forceinline__ void phase_gemm45(PREF P, char* smem, int which) {
;     ...
; #pragma unroll
;         for (int i = 0; i < 4; ++i) {
;           const int row = m0 + wm * 64 + i * 16 + l15;
;     ...
; #pragma unroll
;           for (int j = 0; j < 4; ++j) {
;             const int col = n0 + (j & 1) * 16 + wn * 32 + (j >> 1) * 64 + q * 4;
;             const float4 swc = *(const float4*)(P.swpg + col);
;             part[i][j][0] = pack2(sigm((float)iacc[i][j][0] * shr * swc.x), sigm((float)iacc[i][j][1] * shr * swc.y));
;             part[i][j][1] = pack2(sigm((float)iacc[i][j][2] * shr * swc.z), sigm((float)iacc[i][j][3] * shr * swc.w));
;           }
;         }
	v_mul_f32_e32 v16, v16, v28
	v_mul_f32_e32 v17, v17, v29
	v_mul_f32_e32 v16, 0xbfb8aa3b, v16
	v_mul_f32_e32 v17, 0xbfb8aa3b, v17
	v_exp_f32_e32 v16, v16
	v_exp_f32_e32 v17, v17
	s_nop 0
	v_pk_add_f32 v[16:17], v[16:17], 1.0 op_sel_hi:[1,0]
	s_nop 0
	v_div_scale_f32 v74, s[14:15], v17, v17, 1.0
	v_rcp_f32_e32 v75, v74
	s_nop 0
	v_fma_f32 v76, -v74, v75, 1.0
	v_fmac_f32_e32 v75, v76, v75
	v_div_scale_f32 v76, vcc, 1.0, v17, 1.0
	v_mul_f32_e32 v77, v76, v75
	v_fma_f32 v79, -v74, v77, v76
	v_fmac_f32_e32 v77, v79, v75
	v_fma_f32 v74, -v74, v77, v76
	v_div_fmas_f32 v74, v74, v75, v77
	v_div_fixup_f32 v17, v74, v17, 1.0
	v_div_scale_f32 v74, s[14:15], v16, v16, 1.0
	v_rcp_f32_e32 v75, v74
	s_nop 0
	v_fma_f32 v76, -v74, v75, 1.0
	v_fmac_f32_e32 v75, v76, v75
	v_div_scale_f32 v76, vcc, 1.0, v16, 1.0
	v_mul_f32_e32 v77, v76, v75
	v_fma_f32 v79, -v74, v77, v76
	v_fmac_f32_e32 v77, v79, v75
	v_fma_f32 v74, -v74, v77, v76
	v_div_fmas_f32 v74, v74, v75, v77
	v_div_fixup_f32 v16, v74, v16, 1.0
	v_cvt_pk_bf16_f32 v74, v16, v17
	v_cvt_f32_i32_e32 v16, v18
	v_cvt_f32_i32_e32 v17, v19
	v_mul_f32_e32 v16, v78, v16
	v_mul_f32_e32 v17, v78, v17
	v_mul_f32_e32 v16, v16, v30
	v_mul_f32_e32 v17, v17, v31
	v_mul_f32_e32 v16, 0xbfb8aa3b, v16
	v_mul_f32_e32 v17, 0xbfb8aa3b, v17
	v_exp_f32_e32 v16, v16
	v_exp_f32_e32 v17, v17
	s_nop 0
	v_pk_add_f32 v[16:17], v[16:17], 1.0 op_sel_hi:[1,0]
	s_nop 0
	v_div_scale_f32 v18, s[14:15], v17, v17, 1.0
	v_rcp_f32_e32 v19, v18
	s_nop 0
	v_fma_f32 v75, -v18, v19, 1.0
	v_fmac_f32_e32 v19, v75, v19
	v_div_scale_f32 v75, vcc, 1.0, v17, 1.0
	v_mul_f32_e32 v76, v75, v19
	v_fma_f32 v77, -v18, v76, v75
	v_fmac_f32_e32 v76, v77, v19
	v_fma_f32 v18, -v18, v76, v75
	v_div_fmas_f32 v18, v18, v19, v76
	v_div_fixup_f32 v17, v18, v17, 1.0
	v_div_scale_f32 v18, s[14:15], v16, v16, 1.0
	v_rcp_f32_e32 v19, v18
	s_nop 0
	v_fma_f32 v75, -v18, v19, 1.0
	v_fmac_f32_e32 v19, v75, v19
	v_div_scale_f32 v75, vcc, 1.0, v16, 1.0
	v_mul_f32_e32 v76, v75, v19
	v_fma_f32 v77, -v18, v76, v75
	v_fmac_f32_e32 v76, v77, v19
	v_fma_f32 v18, -v18, v76, v75
	v_div_fmas_f32 v18, v18, v19, v76
	v_div_fixup_f32 v16, v18, v16, 1.0
	v_cvt_pk_bf16_f32 v75, v16, v17
	flat_load_dwordx4 v[16:19], v[70:71] offset:256
	s_waitcnt vmcnt(0) lgkmcnt(0)
	v_mul_f32_e32 v12, v12, v16
	v_mul_f32_e32 v13, v13, v17
	v_mul_f32_e32 v12, 0xbfb8aa3b, v12
	v_mul_f32_e32 v13, 0xbfb8aa3b, v13
	v_exp_f32_e32 v12, v12
	v_exp_f32_e32 v13, v13
	s_nop 0
	v_pk_add_f32 v[12:13], v[12:13], 1.0 op_sel_hi:[1,0]
	s_nop 0
	v_div_scale_f32 v76, s[14:15], v13, v13, 1.0
	v_rcp_f32_e32 v77, v76
	s_nop 0
	v_fma_f32 v79, -v76, v77, 1.0
	v_fmac_f32_e32 v77, v79, v77
	v_div_scale_f32 v79, vcc, 1.0, v13, 1.0
	v_mul_f32_e32 v83, v79, v77
	v_fma_f32 v84, -v76, v83, v79
	v_fmac_f32_e32 v83, v84, v77
	v_fma_f32 v76, -v76, v83, v79
	v_div_fmas_f32 v76, v76, v77, v83
	v_div_fixup_f32 v13, v76, v13, 1.0
	v_div_scale_f32 v76, s[14:15], v12, v12, 1.0
	v_rcp_f32_e32 v77, v76
	s_nop 0
	v_fma_f32 v79, -v76, v77, 1.0
	v_fmac_f32_e32 v77, v79, v77
	v_div_scale_f32 v79, vcc, 1.0, v12, 1.0
	v_mul_f32_e32 v83, v79, v77
	v_fma_f32 v84, -v76, v83, v79
	v_fmac_f32_e32 v83, v84, v77
	v_fma_f32 v76, -v76, v83, v79
	v_div_fmas_f32 v76, v76, v77, v83
	v_div_fixup_f32 v12, v76, v12, 1.0
	v_cvt_pk_bf16_f32 v76, v12, v13
	v_cvt_f32_i32_e32 v12, v14
	v_cvt_f32_i32_e32 v13, v15
	v_mul_f32_e32 v12, v78, v12
	v_mul_f32_e32 v13, v78, v13
	v_mul_f32_e32 v12, v12, v18
	v_mul_f32_e32 v13, v13, v19
	v_mul_f32_e32 v12, 0xbfb8aa3b, v12
	v_mul_f32_e32 v13, 0xbfb8aa3b, v13
	v_exp_f32_e32 v12, v12
	v_exp_f32_e32 v13, v13
	s_nop 0
	v_pk_add_f32 v[12:13], v[12:13], 1.0 op_sel_hi:[1,0]
	s_nop 0
	v_div_scale_f32 v14, s[14:15], v13, v13, 1.0
	v_rcp_f32_e32 v15, v14
	s_nop 0
	v_fma_f32 v77, -v14, v15, 1.0
	v_fmac_f32_e32 v15, v77, v15
	v_div_scale_f32 v77, vcc, 1.0, v13, 1.0
	v_mul_f32_e32 v79, v77, v15
	v_fma_f32 v83, -v14, v79, v77
	v_fmac_f32_e32 v79, v83, v15
	v_fma_f32 v14, -v14, v79, v77
	v_div_fmas_f32 v14, v14, v15, v79
	v_div_fixup_f32 v13, v14, v13, 1.0
	v_div_scale_f32 v14, s[14:15], v12, v12, 1.0
	v_rcp_f32_e32 v15, v14
	s_nop 0
	v_fma_f32 v77, -v14, v15, 1.0
	v_fmac_f32_e32 v15, v77, v15
	v_div_scale_f32 v77, vcc, 1.0, v12, 1.0
	v_mul_f32_e32 v79, v77, v15
	v_fma_f32 v83, -v14, v79, v77
	v_fmac_f32_e32 v79, v83, v15
	v_fma_f32 v14, -v14, v79, v77
	v_div_fmas_f32 v14, v14, v15, v79
	v_div_fixup_f32 v12, v14, v12, 1.0
	v_cvt_pk_bf16_f32 v77, v12, v13
	flat_load_dwordx4 v[12:15], v[70:71] offset:320
	s_waitcnt vmcnt(0) lgkmcnt(0)
	v_mul_f32_e32 v64, v64, v12
	v_mul_f32_e32 v65, v65, v13
	v_mul_f32_e32 v64, 0xbfb8aa3b, v64
	v_mul_f32_e32 v65, 0xbfb8aa3b, v65
	v_exp_f32_e32 v64, v64
	v_exp_f32_e32 v65, v65
	s_nop 0
	v_pk_add_f32 v[64:65], v[64:65], 1.0 op_sel_hi:[1,0]
	s_nop 0
	v_div_scale_f32 v70, s[14:15], v65, v65, 1.0
	v_rcp_f32_e32 v71, v70
	s_nop 0
	v_fma_f32 v79, -v70, v71, 1.0
	v_fmac_f32_e32 v71, v79, v71
	v_div_scale_f32 v79, vcc, 1.0, v65, 1.0
	v_mul_f32_e32 v83, v79, v71
	v_fma_f32 v84, -v70, v83, v79
	v_fmac_f32_e32 v83, v84, v71
	v_fma_f32 v70, -v70, v83, v79
	v_div_fmas_f32 v70, v70, v71, v83
	v_div_fixup_f32 v65, v70, v65, 1.0
	v_div_scale_f32 v70, s[14:15], v64, v64, 1.0
	v_rcp_f32_e32 v71, v70
	s_nop 0
	v_fma_f32 v79, -v70, v71, 1.0
	v_fmac_f32_e32 v71, v79, v71
	v_div_scale_f32 v79, vcc, 1.0, v64, 1.0
	v_mul_f32_e32 v83, v79, v71
	v_fma_f32 v84, -v70, v83, v79
	v_fmac_f32_e32 v83, v84, v71
	v_fma_f32 v70, -v70, v83, v79
	v_div_fmas_f32 v70, v70, v71, v83
	v_div_fixup_f32 v64, v70, v64, 1.0
	v_cvt_pk_bf16_f32 v64, v64, v65
	v_cvt_f32_i32_e32 v65, v66
	v_mul_f32_e32 v65, v78, v65
	v_mul_f32_e32 v65, v65, v14
	v_mul_f32_e32 v65, 0xbfb8aa3b, v65
	v_exp_f32_e32 v66, v65
	v_cvt_f32_i32_e32 v65, v67
	v_mul_f32_e32 v65, v78, v65
	v_mul_f32_e32 v65, v65, v15
	v_mul_f32_e32 v65, 0xbfb8aa3b, v65
	v_exp_f32_e32 v67, v65
	s_nop 0
	v_pk_add_f32 v[66:67], v[66:67], 1.0 op_sel_hi:[1,0]
	s_nop 0
	v_div_scale_f32 v65, s[14:15], v67, v67, 1.0
	v_rcp_f32_e32 v70, v65
	s_nop 0
	v_fma_f32 v71, -v65, v70, 1.0
	v_fmac_f32_e32 v70, v71, v70
	v_div_scale_f32 v71, vcc, 1.0, v67, 1.0
	v_mul_f32_e32 v78, v71, v70
	v_fma_f32 v79, -v65, v78, v71
	v_fmac_f32_e32 v78, v79, v70
	v_fma_f32 v65, -v65, v78, v71
	v_div_fmas_f32 v65, v65, v70, v78
	v_div_fixup_f32 v65, v65, v67, 1.0
	v_div_scale_f32 v67, s[14:15], v66, v66, 1.0
	v_rcp_f32_e32 v70, v67
	s_nop 0
	v_fma_f32 v71, -v67, v70, 1.0
	v_fmac_f32_e32 v70, v71, v70
	v_div_scale_f32 v71, vcc, 1.0, v66, 1.0
	v_mul_f32_e32 v78, v71, v70
	v_fma_f32 v79, -v67, v78, v71
	v_fmac_f32_e32 v78, v79, v70
	v_fma_f32 v67, -v67, v78, v71
	v_div_fmas_f32 v67, v67, v70, v78
	v_div_fixup_f32 v66, v67, v66, 1.0
	v_cvt_pk_bf16_f32 v65, v66, v65
	flat_load_dword v66, v[68:69] offset:64
	s_waitcnt vmcnt(0) lgkmcnt(0)
; DEV float sigm(float x) { return 1.f / (1.f + __expf(-x)); }
; #define P (*launderP(lp))
; __device__ __forceinline__ void phase_gemm45(PREF P, char* smem, int which) {
;     ...
; #pragma unroll
;         for (int i = 0; i < 4; ++i) {
;           const int row = m0 + wm * 64 + i * 16 + l15;
;     ...
; #pragma unroll
;           for (int j = 0; j < 4; ++j) {
;             const int col = n0 + (j & 1) * 16 + wn * 32 + (j >> 1) * 64 + q * 4;
;             const float4 swc = *(const float4*)(P.swpg + col);
;             part[i][j][0] = pack2(sigm((float)iacc[i][j][0] * shr * swc.x), sigm((float)iacc[i][j][1] * shr * swc.y));
;             part[i][j][1] = pack2(sigm((float)iacc[i][j][2] * shr * swc.z), sigm((float)iacc[i][j][3] * shr * swc.w));
;           }
;         }
	v_mul_f32_e32 v60, v66, v60
	v_mul_f32_e32 v61, v66, v61
	v_mul_f32_e32 v60, v24, v60
	v_mul_f32_e32 v61, v25, v61
	v_mul_f32_e32 v60, 0xbfb8aa3b, v60
	v_mul_f32_e32 v61, 0xbfb8aa3b, v61
	v_exp_f32_e32 v60, v60
	v_exp_f32_e32 v61, v61
	v_mul_f32_e32 v56, v66, v56
	v_mul_f32_e32 v57, v66, v57
	v_mul_f32_e32 v56, v28, v56
	v_pk_add_f32 v[60:61], v[60:61], 1.0 op_sel_hi:[1,0]
	v_mul_f32_e32 v57, v29, v57
	v_div_scale_f32 v67, s[14:15], v61, v61, 1.0
	v_rcp_f32_e32 v70, v67
	v_mul_f32_e32 v56, 0xbfb8aa3b, v56
	v_mul_f32_e32 v57, 0xbfb8aa3b, v57
	v_exp_f32_e32 v56, v56
	v_fma_f32 v71, -v67, v70, 1.0
	v_fmac_f32_e32 v70, v71, v70
	v_div_scale_f32 v71, vcc, 1.0, v61, 1.0
	v_mul_f32_e32 v78, v71, v70
	v_fma_f32 v79, -v67, v78, v71
	v_fmac_f32_e32 v78, v79, v70
	v_fma_f32 v67, -v67, v78, v71
	v_div_fmas_f32 v67, v67, v70, v78
	v_div_fixup_f32 v61, v67, v61, 1.0
	v_div_scale_f32 v67, s[14:15], v60, v60, 1.0
	v_rcp_f32_e32 v70, v67
	v_exp_f32_e32 v57, v57
	v_mul_f32_e32 v52, v66, v52
	v_mul_f32_e32 v53, v66, v53
	v_fma_f32 v71, -v67, v70, 1.0
	v_fmac_f32_e32 v70, v71, v70
	v_div_scale_f32 v71, vcc, 1.0, v60, 1.0
	v_mul_f32_e32 v78, v71, v70
	v_fma_f32 v79, -v67, v78, v71
	v_fmac_f32_e32 v78, v79, v70
	v_fma_f32 v67, -v67, v78, v71
	v_div_fmas_f32 v67, v67, v70, v78
	v_div_fixup_f32 v60, v67, v60, 1.0
	v_cvt_pk_bf16_f32 v60, v60, v61
	v_cvt_f32_i32_e32 v61, v62
	v_pk_add_f32 v[56:57], v[56:57], 1.0 op_sel_hi:[1,0]
	v_mul_f32_e32 v52, v16, v52
	v_mul_f32_e32 v53, v17, v53
	v_mul_f32_e32 v61, v66, v61
	v_mul_f32_e32 v61, v26, v61
	v_mul_f32_e32 v61, 0xbfb8aa3b, v61
	v_exp_f32_e32 v62, v61
	v_cvt_f32_i32_e32 v61, v63
	v_mul_f32_e32 v52, 0xbfb8aa3b, v52
	v_mul_f32_e32 v53, 0xbfb8aa3b, v53
	v_exp_f32_e32 v52, v52
	v_mul_f32_e32 v61, v66, v61
	v_mul_f32_e32 v61, v27, v61
	v_mul_f32_e32 v61, 0xbfb8aa3b, v61
	v_exp_f32_e32 v63, v61
	v_exp_f32_e32 v53, v53
	v_mul_f32_e32 v48, v66, v48
	v_mul_f32_e32 v49, v66, v49
	v_pk_add_f32 v[62:63], v[62:63], 1.0 op_sel_hi:[1,0]
	v_pk_add_f32 v[52:53], v[52:53], 1.0 op_sel_hi:[1,0]
	v_div_scale_f32 v61, s[14:15], v63, v63, 1.0
	v_rcp_f32_e32 v67, v61
	v_mul_f32_e32 v48, v12, v48
	v_mul_f32_e32 v49, v13, v49
	v_mul_f32_e32 v48, 0xbfb8aa3b, v48
	v_fma_f32 v70, -v61, v67, 1.0
	v_fmac_f32_e32 v67, v70, v67
	v_div_scale_f32 v70, vcc, 1.0, v63, 1.0
	v_mul_f32_e32 v71, v70, v67
	v_fma_f32 v78, -v61, v71, v70
	v_fmac_f32_e32 v71, v78, v67
	v_fma_f32 v61, -v61, v71, v70
	v_div_fmas_f32 v61, v61, v67, v71
	v_div_fixup_f32 v61, v61, v63, 1.0
	v_div_scale_f32 v63, s[14:15], v62, v62, 1.0
	v_rcp_f32_e32 v67, v63
	v_mul_f32_e32 v49, 0xbfb8aa3b, v49
	v_exp_f32_e32 v48, v48
	v_exp_f32_e32 v49, v49
	v_fma_f32 v70, -v63, v67, 1.0
	v_fmac_f32_e32 v67, v70, v67
	v_div_scale_f32 v70, vcc, 1.0, v62, 1.0
	v_mul_f32_e32 v71, v70, v67
	v_fma_f32 v78, -v63, v71, v70
	v_fmac_f32_e32 v71, v78, v67
	v_fma_f32 v63, -v63, v71, v70
	v_div_fmas_f32 v63, v63, v67, v71
	v_div_fixup_f32 v62, v63, v62, 1.0
	v_cvt_pk_bf16_f32 v61, v62, v61
	v_div_scale_f32 v62, s[14:15], v57, v57, 1.0
	v_rcp_f32_e32 v63, v62
	v_pk_add_f32 v[48:49], v[48:49], 1.0 op_sel_hi:[1,0]
	v_fma_f32 v67, -v62, v63, 1.0
	v_fmac_f32_e32 v63, v67, v63
	v_div_scale_f32 v67, vcc, 1.0, v57, 1.0
	v_mul_f32_e32 v70, v67, v63
	v_fma_f32 v71, -v62, v70, v67
	v_fmac_f32_e32 v70, v71, v63
	v_fma_f32 v62, -v62, v70, v67
	v_div_fmas_f32 v62, v62, v63, v70
	v_div_fixup_f32 v57, v62, v57, 1.0
	v_div_scale_f32 v62, s[14:15], v56, v56, 1.0
	v_rcp_f32_e32 v63, v62
	s_nop 0
	v_fma_f32 v67, -v62, v63, 1.0
	v_fmac_f32_e32 v63, v67, v63
	v_div_scale_f32 v67, vcc, 1.0, v56, 1.0
	v_mul_f32_e32 v70, v67, v63
	v_fma_f32 v71, -v62, v70, v67
	v_fmac_f32_e32 v70, v71, v63
	v_fma_f32 v62, -v62, v70, v67
	v_div_fmas_f32 v62, v62, v63, v70
	v_div_fixup_f32 v56, v62, v56, 1.0
	v_cvt_pk_bf16_f32 v56, v56, v57
	v_cvt_f32_i32_e32 v57, v58
	v_mul_f32_e32 v57, v66, v57
	v_mul_f32_e32 v57, v30, v57
	v_mul_f32_e32 v57, 0xbfb8aa3b, v57
	v_exp_f32_e32 v58, v57
	v_cvt_f32_i32_e32 v57, v59
	v_mul_f32_e32 v57, v66, v57
	v_mul_f32_e32 v57, v31, v57
	v_mul_f32_e32 v57, 0xbfb8aa3b, v57
	v_exp_f32_e32 v59, v57
	s_nop 0
	v_pk_add_f32 v[58:59], v[58:59], 1.0 op_sel_hi:[1,0]
	s_nop 0
	v_div_scale_f32 v57, s[14:15], v59, v59, 1.0
	v_rcp_f32_e32 v62, v57
	s_nop 0
	v_fma_f32 v63, -v57, v62, 1.0
	v_fmac_f32_e32 v62, v63, v62
	v_div_scale_f32 v63, vcc, 1.0, v59, 1.0
	v_mul_f32_e32 v67, v63, v62
	v_fma_f32 v70, -v57, v67, v63
	v_fmac_f32_e32 v67, v70, v62
	v_fma_f32 v57, -v57, v67, v63
	v_div_fmas_f32 v57, v57, v62, v67
	v_div_fixup_f32 v57, v57, v59, 1.0
	v_div_scale_f32 v59, s[14:15], v58, v58, 1.0
	v_rcp_f32_e32 v62, v59
	s_nop 0
	v_fma_f32 v63, -v59, v62, 1.0
	v_fmac_f32_e32 v62, v63, v62
	v_div_scale_f32 v63, vcc, 1.0, v58, 1.0
	v_mul_f32_e32 v67, v63, v62
	v_fma_f32 v70, -v59, v67, v63
	v_fmac_f32_e32 v67, v70, v62
	v_fma_f32 v59, -v59, v67, v63
	v_div_fmas_f32 v59, v59, v62, v67
	v_div_fixup_f32 v58, v59, v58, 1.0
	v_cvt_pk_bf16_f32 v57, v58, v57
	v_div_scale_f32 v58, s[14:15], v53, v53, 1.0
	v_rcp_f32_e32 v59, v58
	s_nop 0
	v_fma_f32 v62, -v58, v59, 1.0
	v_fmac_f32_e32 v59, v62, v59
	v_div_scale_f32 v62, vcc, 1.0, v53, 1.0
	v_mul_f32_e32 v63, v62, v59
	v_fma_f32 v67, -v58, v63, v62
	v_fmac_f32_e32 v63, v67, v59
	v_fma_f32 v58, -v58, v63, v62
	v_div_fmas_f32 v58, v58, v59, v63
	v_div_fixup_f32 v53, v58, v53, 1.0
	v_div_scale_f32 v58, s[14:15], v52, v52, 1.0
	v_rcp_f32_e32 v59, v58
	s_nop 0
	v_fma_f32 v62, -v58, v59, 1.0
	v_fmac_f32_e32 v59, v62, v59
	v_div_scale_f32 v62, vcc, 1.0, v52, 1.0
	v_mul_f32_e32 v63, v62, v59
	v_fma_f32 v67, -v58, v63, v62
	v_fmac_f32_e32 v63, v67, v59
	v_fma_f32 v58, -v58, v63, v62
	v_div_fmas_f32 v58, v58, v59, v63
; DEV float sigm(float x) { return 1.f / (1.f + __expf(-x)); }
; #define P (*launderP(lp))
; __device__ __forceinline__ void phase_gemm45(PREF P, char* smem, int which) {
;     ...
; #pragma unroll
;         for (int i = 0; i < 4; ++i) {
;           const int row = m0 + wm * 64 + i * 16 + l15;
;     ...
; #pragma unroll
;           for (int j = 0; j < 4; ++j) {
;             const int col = n0 + (j & 1) * 16 + wn * 32 + (j >> 1) * 64 + q * 4;
;             const float4 swc = *(const float4*)(P.swpg + col);
;             part[i][j][0] = pack2(sigm((float)iacc[i][j][0] * shr * swc.x), sigm((float)iacc[i][j][1] * shr * swc.y));
;             part[i][j][1] = pack2(sigm((float)iacc[i][j][2] * shr * swc.z), sigm((float)iacc[i][j][3] * shr * swc.w));
;           }
;         }
	v_div_fixup_f32 v52, v58, v52, 1.0
	v_cvt_pk_bf16_f32 v52, v52, v53
	v_cvt_f32_i32_e32 v53, v54
	v_mul_f32_e32 v53, v66, v53
	v_mul_f32_e32 v53, v18, v53
	v_mul_f32_e32 v53, 0xbfb8aa3b, v53
	v_exp_f32_e32 v54, v53
	v_cvt_f32_i32_e32 v53, v55
	v_mul_f32_e32 v53, v66, v53
	v_mul_f32_e32 v53, v19, v53
	v_mul_f32_e32 v53, 0xbfb8aa3b, v53
	v_exp_f32_e32 v55, v53
	s_nop 0
	v_pk_add_f32 v[54:55], v[54:55], 1.0 op_sel_hi:[1,0]
	s_nop 0
	v_div_scale_f32 v53, s[14:15], v55, v55, 1.0
	v_rcp_f32_e32 v58, v53
	s_nop 0
	v_fma_f32 v59, -v53, v58, 1.0
	v_fmac_f32_e32 v58, v59, v58
	v_div_scale_f32 v59, vcc, 1.0, v55, 1.0
	v_mul_f32_e32 v62, v59, v58
	v_fma_f32 v63, -v53, v62, v59
	v_fmac_f32_e32 v62, v63, v58
	v_fma_f32 v53, -v53, v62, v59
	v_div_fmas_f32 v53, v53, v58, v62
	v_div_fixup_f32 v53, v53, v55, 1.0
	v_div_scale_f32 v55, s[14:15], v54, v54, 1.0
	v_rcp_f32_e32 v58, v55
	s_nop 0
	v_fma_f32 v59, -v55, v58, 1.0
	v_fmac_f32_e32 v58, v59, v58
	v_div_scale_f32 v59, vcc, 1.0, v54, 1.0
	v_mul_f32_e32 v62, v59, v58
	v_fma_f32 v63, -v55, v62, v59
	v_fmac_f32_e32 v62, v63, v58
	v_fma_f32 v55, -v55, v62, v59
	v_div_fmas_f32 v55, v55, v58, v62
	v_div_fixup_f32 v54, v55, v54, 1.0
	v_cvt_pk_bf16_f32 v53, v54, v53
	v_div_scale_f32 v54, s[14:15], v49, v49, 1.0
	v_rcp_f32_e32 v55, v54
	s_nop 0
	v_fma_f32 v58, -v54, v55, 1.0
	v_fmac_f32_e32 v55, v58, v55
	v_div_scale_f32 v58, vcc, 1.0, v49, 1.0
	v_mul_f32_e32 v59, v58, v55
	v_fma_f32 v62, -v54, v59, v58
	v_fmac_f32_e32 v59, v62, v55
	v_fma_f32 v54, -v54, v59, v58
	v_div_fmas_f32 v54, v54, v55, v59
	v_div_fixup_f32 v49, v54, v49, 1.0
	v_div_scale_f32 v54, s[14:15], v48, v48, 1.0
	v_rcp_f32_e32 v55, v54
	s_nop 0
	v_fma_f32 v58, -v54, v55, 1.0
	v_fmac_f32_e32 v55, v58, v55
	v_div_scale_f32 v58, vcc, 1.0, v48, 1.0
	v_mul_f32_e32 v59, v58, v55
	v_fma_f32 v62, -v54, v59, v58
	v_fmac_f32_e32 v59, v62, v55
	v_fma_f32 v54, -v54, v59, v58
	v_div_fmas_f32 v54, v54, v55, v59
	v_div_fixup_f32 v48, v54, v48, 1.0
	v_cvt_pk_bf16_f32 v48, v48, v49
	v_cvt_f32_i32_e32 v49, v50
	v_mul_f32_e32 v49, v66, v49
	v_mul_f32_e32 v49, v14, v49
	v_mul_f32_e32 v49, 0xbfb8aa3b, v49
	v_exp_f32_e32 v50, v49
	v_cvt_f32_i32_e32 v49, v51
	v_mul_f32_e32 v49, v66, v49
	v_mul_f32_e32 v49, v15, v49
	v_mul_f32_e32 v49, 0xbfb8aa3b, v49
	v_exp_f32_e32 v51, v49
	s_nop 0
	v_pk_add_f32 v[50:51], v[50:51], 1.0 op_sel_hi:[1,0]
	s_nop 0
	v_div_scale_f32 v49, s[14:15], v51, v51, 1.0
	v_rcp_f32_e32 v54, v49
	s_nop 0
	v_fma_f32 v55, -v49, v54, 1.0
	v_fmac_f32_e32 v54, v55, v54
	v_div_scale_f32 v55, vcc, 1.0, v51, 1.0
	v_mul_f32_e32 v58, v55, v54
	v_fma_f32 v59, -v49, v58, v55
	v_fmac_f32_e32 v58, v59, v54
	v_fma_f32 v49, -v49, v58, v55
	v_div_fmas_f32 v49, v49, v54, v58
	v_div_fixup_f32 v49, v49, v51, 1.0
	v_div_scale_f32 v51, s[14:15], v50, v50, 1.0
	v_rcp_f32_e32 v54, v51
	s_nop 0
	v_fma_f32 v55, -v51, v54, 1.0
	v_fmac_f32_e32 v54, v55, v54
	v_div_scale_f32 v55, vcc, 1.0, v50, 1.0
	v_mul_f32_e32 v58, v55, v54
	v_fma_f32 v59, -v51, v58, v55
	v_fmac_f32_e32 v58, v59, v54
	v_fma_f32 v51, -v51, v58, v55
	v_div_fmas_f32 v51, v51, v54, v58
	v_div_fixup_f32 v50, v51, v50, 1.0
	v_cvt_pk_bf16_f32 v49, v50, v49
	flat_load_dword v50, v[68:69] offset:128
	s_waitcnt vmcnt(0) lgkmcnt(0)
	v_mul_f32_e32 v44, v50, v44
	v_mul_f32_e32 v45, v50, v45
	v_mul_f32_e32 v44, v24, v44
	v_mul_f32_e32 v45, v25, v45
	v_mul_f32_e32 v44, 0xbfb8aa3b, v44
	v_mul_f32_e32 v45, 0xbfb8aa3b, v45
	v_exp_f32_e32 v44, v44
	v_exp_f32_e32 v45, v45
	v_mul_f32_e32 v40, v50, v40
	v_mul_f32_e32 v41, v50, v41
	v_mul_f32_e32 v40, v28, v40
	v_pk_add_f32 v[44:45], v[44:45], 1.0 op_sel_hi:[1,0]
	v_mul_f32_e32 v41, v29, v41
	v_div_scale_f32 v51, s[14:15], v45, v45, 1.0
	v_rcp_f32_e32 v54, v51
	v_mul_f32_e32 v40, 0xbfb8aa3b, v40
	v_mul_f32_e32 v41, 0xbfb8aa3b, v41
	v_exp_f32_e32 v40, v40
	v_fma_f32 v55, -v51, v54, 1.0
	v_fmac_f32_e32 v54, v55, v54
	v_div_scale_f32 v55, vcc, 1.0, v45, 1.0
	v_mul_f32_e32 v58, v55, v54
	v_fma_f32 v59, -v51, v58, v55
	v_fmac_f32_e32 v58, v59, v54
	v_fma_f32 v51, -v51, v58, v55
	v_div_fmas_f32 v51, v51, v54, v58
	v_div_fixup_f32 v45, v51, v45, 1.0
	v_div_scale_f32 v51, s[14:15], v44, v44, 1.0
	v_rcp_f32_e32 v54, v51
	v_exp_f32_e32 v41, v41
	v_mul_f32_e32 v36, v50, v36
	v_mul_f32_e32 v37, v50, v37
	v_fma_f32 v55, -v51, v54, 1.0
	v_fmac_f32_e32 v54, v55, v54
	v_div_scale_f32 v55, vcc, 1.0, v44, 1.0
	v_mul_f32_e32 v58, v55, v54
	v_fma_f32 v59, -v51, v58, v55
	v_fmac_f32_e32 v58, v59, v54
	v_fma_f32 v51, -v51, v58, v55
	v_div_fmas_f32 v51, v51, v54, v58
	v_div_fixup_f32 v44, v51, v44, 1.0
	v_cvt_pk_bf16_f32 v44, v44, v45
	v_cvt_f32_i32_e32 v45, v46
	v_pk_add_f32 v[40:41], v[40:41], 1.0 op_sel_hi:[1,0]
	v_mul_f32_e32 v36, v16, v36
	v_mul_f32_e32 v37, v17, v37
	v_mul_f32_e32 v45, v50, v45
	v_mul_f32_e32 v45, v26, v45
	v_mul_f32_e32 v45, 0xbfb8aa3b, v45
	v_exp_f32_e32 v46, v45
	v_cvt_f32_i32_e32 v45, v47
	v_mul_f32_e32 v36, 0xbfb8aa3b, v36
	v_mul_f32_e32 v37, 0xbfb8aa3b, v37
	v_exp_f32_e32 v36, v36
	v_mul_f32_e32 v45, v50, v45
	v_mul_f32_e32 v45, v27, v45
	v_mul_f32_e32 v45, 0xbfb8aa3b, v45
	v_exp_f32_e32 v47, v45
	v_exp_f32_e32 v37, v37
	v_mul_f32_e32 v32, v50, v32
	v_mul_f32_e32 v33, v50, v33
	v_pk_add_f32 v[46:47], v[46:47], 1.0 op_sel_hi:[1,0]
	v_pk_add_f32 v[36:37], v[36:37], 1.0 op_sel_hi:[1,0]
	v_div_scale_f32 v45, s[14:15], v47, v47, 1.0
	v_rcp_f32_e32 v51, v45
	v_mul_f32_e32 v32, v12, v32
	v_mul_f32_e32 v33, v13, v33
	v_mul_f32_e32 v32, 0xbfb8aa3b, v32
	v_fma_f32 v54, -v45, v51, 1.0
	v_fmac_f32_e32 v51, v54, v51
	v_div_scale_f32 v54, vcc, 1.0, v47, 1.0
	v_mul_f32_e32 v55, v54, v51
	v_fma_f32 v58, -v45, v55, v54
	v_fmac_f32_e32 v55, v58, v51
	v_fma_f32 v45, -v45, v55, v54
; DEV float sigm(float x) { return 1.f / (1.f + __expf(-x)); }
; #define P (*launderP(lp))
; __device__ __forceinline__ void phase_gemm45(PREF P, char* smem, int which) {
;     ...
; #pragma unroll
;         for (int i = 0; i < 4; ++i) {
;           const int row = m0 + wm * 64 + i * 16 + l15;
;     ...
; #pragma unroll
;           for (int j = 0; j < 4; ++j) {
;             const int col = n0 + (j & 1) * 16 + wn * 32 + (j >> 1) * 64 + q * 4;
;             const float4 swc = *(const float4*)(P.swpg + col);
;             part[i][j][0] = pack2(sigm((float)iacc[i][j][0] * shr * swc.x), sigm((float)iacc[i][j][1] * shr * swc.y));
;             part[i][j][1] = pack2(sigm((float)iacc[i][j][2] * shr * swc.z), sigm((float)iacc[i][j][3] * shr * swc.w));
;           }
;         }
	v_div_fmas_f32 v45, v45, v51, v55
	v_div_fixup_f32 v45, v45, v47, 1.0
	v_div_scale_f32 v47, s[14:15], v46, v46, 1.0
	v_rcp_f32_e32 v51, v47
	v_mul_f32_e32 v33, 0xbfb8aa3b, v33
	v_exp_f32_e32 v32, v32
	v_exp_f32_e32 v33, v33
	v_fma_f32 v54, -v47, v51, 1.0
	v_fmac_f32_e32 v51, v54, v51
	v_div_scale_f32 v54, vcc, 1.0, v46, 1.0
	v_mul_f32_e32 v55, v54, v51
	v_fma_f32 v58, -v47, v55, v54
	v_fmac_f32_e32 v55, v58, v51
	v_fma_f32 v47, -v47, v55, v54
	v_div_fmas_f32 v47, v47, v51, v55
	v_div_fixup_f32 v46, v47, v46, 1.0
	v_cvt_pk_bf16_f32 v45, v46, v45
	v_div_scale_f32 v46, s[14:15], v41, v41, 1.0
	v_rcp_f32_e32 v47, v46
	v_pk_add_f32 v[32:33], v[32:33], 1.0 op_sel_hi:[1,0]
	v_fma_f32 v51, -v46, v47, 1.0
	v_fmac_f32_e32 v47, v51, v47
	v_div_scale_f32 v51, vcc, 1.0, v41, 1.0
	v_mul_f32_e32 v54, v51, v47
	v_fma_f32 v55, -v46, v54, v51
	v_fmac_f32_e32 v54, v55, v47
	v_fma_f32 v46, -v46, v54, v51
	v_div_fmas_f32 v46, v46, v47, v54
	v_div_fixup_f32 v41, v46, v41, 1.0
	v_div_scale_f32 v46, s[14:15], v40, v40, 1.0
	v_rcp_f32_e32 v47, v46
	s_nop 0
	v_fma_f32 v51, -v46, v47, 1.0
	v_fmac_f32_e32 v47, v51, v47
	v_div_scale_f32 v51, vcc, 1.0, v40, 1.0
	v_mul_f32_e32 v54, v51, v47
	v_fma_f32 v55, -v46, v54, v51
	v_fmac_f32_e32 v54, v55, v47
	v_fma_f32 v46, -v46, v54, v51
	v_div_fmas_f32 v46, v46, v47, v54
	v_div_fixup_f32 v40, v46, v40, 1.0
	v_cvt_pk_bf16_f32 v40, v40, v41
	v_cvt_f32_i32_e32 v41, v42
	v_mul_f32_e32 v41, v50, v41
	v_mul_f32_e32 v41, v30, v41
	v_mul_f32_e32 v41, 0xbfb8aa3b, v41
	v_exp_f32_e32 v42, v41
	v_cvt_f32_i32_e32 v41, v43
	v_mul_f32_e32 v41, v50, v41
	v_mul_f32_e32 v41, v31, v41
	v_mul_f32_e32 v41, 0xbfb8aa3b, v41
	v_exp_f32_e32 v43, v41
	s_nop 0
	v_pk_add_f32 v[42:43], v[42:43], 1.0 op_sel_hi:[1,0]
	s_nop 0
	v_div_scale_f32 v41, s[14:15], v43, v43, 1.0
	v_rcp_f32_e32 v46, v41
	s_nop 0
	v_fma_f32 v47, -v41, v46, 1.0
	v_fmac_f32_e32 v46, v47, v46
	v_div_scale_f32 v47, vcc, 1.0, v43, 1.0
	v_mul_f32_e32 v51, v47, v46
	v_fma_f32 v54, -v41, v51, v47
	v_fmac_f32_e32 v51, v54, v46
	v_fma_f32 v41, -v41, v51, v47
	v_div_fmas_f32 v41, v41, v46, v51
	v_div_fixup_f32 v41, v41, v43, 1.0
	v_div_scale_f32 v43, s[14:15], v42, v42, 1.0
	v_rcp_f32_e32 v46, v43
	s_nop 0
	v_fma_f32 v47, -v43, v46, 1.0
	v_fmac_f32_e32 v46, v47, v46
	v_div_scale_f32 v47, vcc, 1.0, v42, 1.0
	v_mul_f32_e32 v51, v47, v46
	v_fma_f32 v54, -v43, v51, v47
	v_fmac_f32_e32 v51, v54, v46
	v_fma_f32 v43, -v43, v51, v47
	v_div_fmas_f32 v43, v43, v46, v51
	v_div_fixup_f32 v42, v43, v42, 1.0
	v_cvt_pk_bf16_f32 v41, v42, v41
	v_div_scale_f32 v42, s[14:15], v37, v37, 1.0
	v_rcp_f32_e32 v43, v42
	s_nop 0
	v_fma_f32 v46, -v42, v43, 1.0
	v_fmac_f32_e32 v43, v46, v43
	v_div_scale_f32 v46, vcc, 1.0, v37, 1.0
	v_mul_f32_e32 v47, v46, v43
	v_fma_f32 v51, -v42, v47, v46
	v_fmac_f32_e32 v47, v51, v43
	v_fma_f32 v42, -v42, v47, v46
	v_div_fmas_f32 v42, v42, v43, v47
	v_div_fixup_f32 v37, v42, v37, 1.0
	v_div_scale_f32 v42, s[14:15], v36, v36, 1.0
	v_rcp_f32_e32 v43, v42
	s_nop 0
	v_fma_f32 v46, -v42, v43, 1.0
	v_fmac_f32_e32 v43, v46, v43
	v_div_scale_f32 v46, vcc, 1.0, v36, 1.0
	v_mul_f32_e32 v47, v46, v43
	v_fma_f32 v51, -v42, v47, v46
	v_fmac_f32_e32 v47, v51, v43
	v_fma_f32 v42, -v42, v47, v46
	v_div_fmas_f32 v42, v42, v43, v47
	v_div_fixup_f32 v36, v42, v36, 1.0
	v_cvt_pk_bf16_f32 v36, v36, v37
	v_cvt_f32_i32_e32 v37, v38
	v_mul_f32_e32 v37, v50, v37
	v_mul_f32_e32 v37, v18, v37
	v_mul_f32_e32 v37, 0xbfb8aa3b, v37
	v_exp_f32_e32 v38, v37
	v_cvt_f32_i32_e32 v37, v39
	v_mul_f32_e32 v37, v50, v37
	v_mul_f32_e32 v37, v19, v37
	v_mul_f32_e32 v37, 0xbfb8aa3b, v37
	v_exp_f32_e32 v39, v37
	s_nop 0
	v_pk_add_f32 v[38:39], v[38:39], 1.0 op_sel_hi:[1,0]
	s_nop 0
	v_div_scale_f32 v37, s[14:15], v39, v39, 1.0
	v_rcp_f32_e32 v42, v37
	s_nop 0
	v_fma_f32 v43, -v37, v42, 1.0
	v_fmac_f32_e32 v42, v43, v42
	v_div_scale_f32 v43, vcc, 1.0, v39, 1.0
	v_mul_f32_e32 v46, v43, v42
	v_fma_f32 v47, -v37, v46, v43
	v_fmac_f32_e32 v46, v47, v42
	v_fma_f32 v37, -v37, v46, v43
	v_div_fmas_f32 v37, v37, v42, v46
	v_div_fixup_f32 v37, v37, v39, 1.0
	v_div_scale_f32 v39, s[14:15], v38, v38, 1.0
	v_rcp_f32_e32 v42, v39
	s_nop 0
	v_fma_f32 v43, -v39, v42, 1.0
	v_fmac_f32_e32 v42, v43, v42
	v_div_scale_f32 v43, vcc, 1.0, v38, 1.0
	v_mul_f32_e32 v46, v43, v42
	v_fma_f32 v47, -v39, v46, v43
	v_fmac_f32_e32 v46, v47, v42
	v_fma_f32 v39, -v39, v46, v43
	v_div_fmas_f32 v39, v39, v42, v46
	v_div_fixup_f32 v38, v39, v38, 1.0
	v_cvt_pk_bf16_f32 v37, v38, v37
	v_div_scale_f32 v38, s[14:15], v33, v33, 1.0
	v_rcp_f32_e32 v39, v38
	s_nop 0
	v_fma_f32 v42, -v38, v39, 1.0
	v_fmac_f32_e32 v39, v42, v39
	v_div_scale_f32 v42, vcc, 1.0, v33, 1.0
	v_mul_f32_e32 v43, v42, v39
	v_fma_f32 v46, -v38, v43, v42
	v_fmac_f32_e32 v43, v46, v39
	v_fma_f32 v38, -v38, v43, v42
	v_div_fmas_f32 v38, v38, v39, v43
	v_div_fixup_f32 v33, v38, v33, 1.0
	v_div_scale_f32 v38, s[14:15], v32, v32, 1.0
	v_rcp_f32_e32 v39, v38
	s_nop 0
	v_fma_f32 v42, -v38, v39, 1.0
	v_fmac_f32_e32 v39, v42, v39
	v_div_scale_f32 v42, vcc, 1.0, v32, 1.0
	v_mul_f32_e32 v43, v42, v39
	v_fma_f32 v46, -v38, v43, v42
	v_fmac_f32_e32 v43, v46, v39
	v_fma_f32 v38, -v38, v43, v42
	v_div_fmas_f32 v38, v38, v39, v43
	v_div_fixup_f32 v32, v38, v32, 1.0
	v_cvt_pk_bf16_f32 v32, v32, v33
	v_cvt_f32_i32_e32 v33, v34
	v_mul_f32_e32 v33, v50, v33
	v_mul_f32_e32 v33, v14, v33
	v_mul_f32_e32 v33, 0xbfb8aa3b, v33
	v_exp_f32_e32 v34, v33
	v_cvt_f32_i32_e32 v33, v35
	v_mul_f32_e32 v33, v50, v33
	v_mul_f32_e32 v33, v15, v33
	v_mul_f32_e32 v33, 0xbfb8aa3b, v33
	v_exp_f32_e32 v35, v33
	s_nop 0
	v_pk_add_f32 v[34:35], v[34:35], 1.0 op_sel_hi:[1,0]
	s_nop 0
	v_div_scale_f32 v33, s[14:15], v35, v35, 1.0
	v_rcp_f32_e32 v38, v33
	s_nop 0
	v_fma_f32 v39, -v33, v38, 1.0
	v_fmac_f32_e32 v38, v39, v38
	v_div_scale_f32 v39, vcc, 1.0, v35, 1.0
	v_mul_f32_e32 v42, v39, v38
	v_fma_f32 v43, -v33, v42, v39
	v_fmac_f32_e32 v42, v43, v38
	v_fma_f32 v33, -v33, v42, v39
	v_div_fmas_f32 v33, v33, v38, v42
	v_div_fixup_f32 v33, v33, v35, 1.0
	v_div_scale_f32 v35, s[14:15], v34, v34, 1.0
	v_rcp_f32_e32 v38, v35
	s_nop 0
	v_fma_f32 v39, -v35, v38, 1.0
	v_fmac_f32_e32 v38, v39, v38
	v_div_scale_f32 v39, vcc, 1.0, v34, 1.0
	v_mul_f32_e32 v42, v39, v38
	v_fma_f32 v43, -v35, v42, v39
	v_fmac_f32_e32 v42, v43, v38
	v_fma_f32 v35, -v35, v42, v39
	v_div_fmas_f32 v35, v35, v38, v42
	v_div_fixup_f32 v34, v35, v34, 1.0
	v_cvt_pk_bf16_f32 v33, v34, v33
	flat_load_dword v34, v[68:69] offset:192
	s_waitcnt vmcnt(0) lgkmcnt(0)
; DEV float sigm(float x) { return 1.f / (1.f + __expf(-x)); }
; #define P (*launderP(lp))
; __device__ __forceinline__ void phase_gemm45(PREF P, char* smem, int which) {
;     ...
; #pragma unroll
;         for (int i = 0; i < 4; ++i) {
;           const int row = m0 + wm * 64 + i * 16 + l15;
;     ...
; #pragma unroll
;           for (int j = 0; j < 4; ++j) {
;             const int col = n0 + (j & 1) * 16 + wn * 32 + (j >> 1) * 64 + q * 4;
;             const float4 swc = *(const float4*)(P.swpg + col);
;             part[i][j][0] = pack2(sigm((float)iacc[i][j][0] * shr * swc.x), sigm((float)iacc[i][j][1] * shr * swc.y));
;             part[i][j][1] = pack2(sigm((float)iacc[i][j][2] * shr * swc.z), sigm((float)iacc[i][j][3] * shr * swc.w));
;           }
;         }
	v_mul_f32_e32 v20, v34, v20
	v_mul_f32_e32 v21, v34, v21
	v_mul_f32_e32 v20, v24, v20
	v_mul_f32_e32 v21, v25, v21
	v_mul_f32_e32 v20, 0xbfb8aa3b, v20
	v_mul_f32_e32 v21, 0xbfb8aa3b, v21
	v_exp_f32_e32 v20, v20
	v_exp_f32_e32 v21, v21
	v_mul_f32_e32 v8, v34, v8
	v_mul_f32_e32 v9, v34, v9
	v_mul_f32_e32 v8, v28, v8
	v_pk_add_f32 v[20:21], v[20:21], 1.0 op_sel_hi:[1,0]
	v_mul_f32_e32 v9, v29, v9
	v_div_scale_f32 v24, s[14:15], v21, v21, 1.0
	v_rcp_f32_e32 v25, v24
	v_mul_f32_e32 v8, 0xbfb8aa3b, v8
	v_mul_f32_e32 v9, 0xbfb8aa3b, v9
	v_exp_f32_e32 v8, v8
	v_fma_f32 v35, -v24, v25, 1.0
	v_fmac_f32_e32 v25, v35, v25
	v_div_scale_f32 v35, vcc, 1.0, v21, 1.0
	v_mul_f32_e32 v38, v35, v25
	v_fma_f32 v39, -v24, v38, v35
	v_fmac_f32_e32 v38, v39, v25
	v_fma_f32 v24, -v24, v38, v35
	v_div_fmas_f32 v24, v24, v25, v38
	v_div_fixup_f32 v21, v24, v21, 1.0
	v_div_scale_f32 v24, s[14:15], v20, v20, 1.0
	v_rcp_f32_e32 v25, v24
	v_exp_f32_e32 v9, v9
	v_mul_f32_e32 v4, v34, v4
	v_mul_f32_e32 v5, v34, v5
	v_fma_f32 v35, -v24, v25, 1.0
	v_fmac_f32_e32 v25, v35, v25
	v_div_scale_f32 v35, vcc, 1.0, v20, 1.0
	v_mul_f32_e32 v38, v35, v25
	v_fma_f32 v39, -v24, v38, v35
	v_fmac_f32_e32 v38, v39, v25
	v_fma_f32 v24, -v24, v38, v35
	v_div_fmas_f32 v24, v24, v25, v38
	v_div_fixup_f32 v20, v24, v20, 1.0
	v_cvt_pk_bf16_f32 v20, v20, v21
	v_cvt_f32_i32_e32 v21, v22
	v_pk_add_f32 v[8:9], v[8:9], 1.0 op_sel_hi:[1,0]
	v_mul_f32_e32 v4, v16, v4
	v_mul_f32_e32 v5, v17, v5
	v_mul_f32_e32 v21, v34, v21
	v_mul_f32_e32 v21, v26, v21
	v_mul_f32_e32 v21, 0xbfb8aa3b, v21
	v_exp_f32_e32 v22, v21
	v_cvt_f32_i32_e32 v21, v23
	v_mul_f32_e32 v4, 0xbfb8aa3b, v4
	v_mul_f32_e32 v5, 0xbfb8aa3b, v5
	v_exp_f32_e32 v4, v4
	v_mul_f32_e32 v21, v34, v21
	v_mul_f32_e32 v21, v27, v21
	v_mul_f32_e32 v21, 0xbfb8aa3b, v21
	v_exp_f32_e32 v23, v21
	v_exp_f32_e32 v5, v5
	v_mul_f32_e32 v0, v34, v0
	v_mul_f32_e32 v1, v34, v1
	v_pk_add_f32 v[22:23], v[22:23], 1.0 op_sel_hi:[1,0]
	v_pk_add_f32 v[4:5], v[4:5], 1.0 op_sel_hi:[1,0]
	v_div_scale_f32 v21, s[14:15], v23, v23, 1.0
	v_rcp_f32_e32 v24, v21
	v_mul_f32_e32 v0, v12, v0
	v_mul_f32_e32 v1, v13, v1
	v_mul_f32_e32 v0, 0xbfb8aa3b, v0
	v_fma_f32 v25, -v21, v24, 1.0
	v_fmac_f32_e32 v24, v25, v24
	v_div_scale_f32 v25, vcc, 1.0, v23, 1.0
	v_mul_f32_e32 v26, v25, v24
	v_fma_f32 v27, -v21, v26, v25
	v_fmac_f32_e32 v26, v27, v24
	v_fma_f32 v21, -v21, v26, v25
	v_div_fmas_f32 v21, v21, v24, v26
	v_div_fixup_f32 v21, v21, v23, 1.0
	v_div_scale_f32 v23, s[14:15], v22, v22, 1.0
	v_rcp_f32_e32 v24, v23
	v_mul_f32_e32 v1, 0xbfb8aa3b, v1
	v_exp_f32_e32 v0, v0
	v_exp_f32_e32 v1, v1
	v_fma_f32 v25, -v23, v24, 1.0
	v_fmac_f32_e32 v24, v25, v24
	v_div_scale_f32 v25, vcc, 1.0, v22, 1.0
	v_mul_f32_e32 v26, v25, v24
	v_fma_f32 v27, -v23, v26, v25
	v_fmac_f32_e32 v26, v27, v24
	v_fma_f32 v23, -v23, v26, v25
	v_div_fmas_f32 v23, v23, v24, v26
	v_div_fixup_f32 v22, v23, v22, 1.0
	v_cvt_pk_bf16_f32 v21, v22, v21
	v_div_scale_f32 v22, s[14:15], v9, v9, 1.0
	v_rcp_f32_e32 v23, v22
	v_pk_add_f32 v[0:1], v[0:1], 1.0 op_sel_hi:[1,0]
	v_fma_f32 v24, -v22, v23, 1.0
	v_fmac_f32_e32 v23, v24, v23
	v_div_scale_f32 v24, vcc, 1.0, v9, 1.0
	v_mul_f32_e32 v25, v24, v23
	v_fma_f32 v26, -v22, v25, v24
	v_fmac_f32_e32 v25, v26, v23
	v_fma_f32 v22, -v22, v25, v24
	v_div_fmas_f32 v22, v22, v23, v25
	v_div_fixup_f32 v9, v22, v9, 1.0
	v_div_scale_f32 v22, s[14:15], v8, v8, 1.0
	v_rcp_f32_e32 v23, v22
	s_nop 0
	v_fma_f32 v24, -v22, v23, 1.0
	v_fmac_f32_e32 v23, v24, v23
	v_div_scale_f32 v24, vcc, 1.0, v8, 1.0
	v_mul_f32_e32 v25, v24, v23
	v_fma_f32 v26, -v22, v25, v24
	v_fmac_f32_e32 v25, v26, v23
	v_fma_f32 v22, -v22, v25, v24
	v_div_fmas_f32 v22, v22, v23, v25
	v_div_fixup_f32 v8, v22, v8, 1.0
	v_cvt_pk_bf16_f32 v22, v8, v9
	v_cvt_f32_i32_e32 v8, v10
	v_cvt_f32_i32_e32 v9, v11
	v_mov_b32_e32 v26, v188
	v_mul_f32_e32 v8, v34, v8
	v_mul_f32_e32 v9, v34, v9
	v_mul_f32_e32 v8, v30, v8
	v_mul_f32_e32 v9, v31, v9
	v_mul_f32_e32 v8, 0xbfb8aa3b, v8
	v_mul_f32_e32 v9, 0xbfb8aa3b, v9
	v_exp_f32_e32 v8, v8
	v_exp_f32_e32 v9, v9
	s_nop 0
	v_pk_add_f32 v[8:9], v[8:9], 1.0 op_sel_hi:[1,0]
	s_nop 0
	v_div_scale_f32 v10, s[14:15], v9, v9, 1.0
	v_rcp_f32_e32 v11, v10
	s_nop 0
	v_fma_f32 v23, -v10, v11, 1.0
	v_fmac_f32_e32 v11, v23, v11
	v_div_scale_f32 v23, vcc, 1.0, v9, 1.0
	v_mul_f32_e32 v24, v23, v11
	v_fma_f32 v25, -v10, v24, v23
	v_fmac_f32_e32 v24, v25, v11
	v_fma_f32 v10, -v10, v24, v23
	v_div_fmas_f32 v10, v10, v11, v24
	v_div_fixup_f32 v9, v10, v9, 1.0
	v_div_scale_f32 v10, s[14:15], v8, v8, 1.0
	v_rcp_f32_e32 v11, v10
	s_nop 0
	v_fma_f32 v23, -v10, v11, 1.0
	v_fmac_f32_e32 v11, v23, v11
	v_div_scale_f32 v23, vcc, 1.0, v8, 1.0
	v_mul_f32_e32 v24, v23, v11
	v_fma_f32 v25, -v10, v24, v23
	v_fmac_f32_e32 v24, v25, v11
	v_fma_f32 v10, -v10, v24, v23
	v_div_fmas_f32 v10, v10, v11, v24
	v_div_fixup_f32 v8, v10, v8, 1.0
	v_cvt_pk_bf16_f32 v23, v8, v9
	v_div_scale_f32 v8, s[14:15], v5, v5, 1.0
	v_rcp_f32_e32 v9, v8
	s_nop 0
	v_fma_f32 v10, -v8, v9, 1.0
	v_fmac_f32_e32 v9, v10, v9
	v_div_scale_f32 v10, vcc, 1.0, v5, 1.0
	v_mul_f32_e32 v11, v10, v9
	v_fma_f32 v16, -v8, v11, v10
	v_fmac_f32_e32 v11, v16, v9
	v_fma_f32 v8, -v8, v11, v10
	v_div_fmas_f32 v8, v8, v9, v11
	v_div_fixup_f32 v5, v8, v5, 1.0
	v_div_scale_f32 v8, s[14:15], v4, v4, 1.0
	v_rcp_f32_e32 v9, v8
	s_nop 0
	v_fma_f32 v10, -v8, v9, 1.0
	v_fmac_f32_e32 v9, v10, v9
	v_div_scale_f32 v10, vcc, 1.0, v4, 1.0
	v_mul_f32_e32 v11, v10, v9
	v_fma_f32 v16, -v8, v11, v10
	v_fmac_f32_e32 v11, v16, v9
	v_fma_f32 v8, -v8, v11, v10
	v_div_fmas_f32 v8, v8, v9, v11
	v_div_fixup_f32 v4, v8, v4, 1.0
	v_cvt_pk_bf16_f32 v16, v4, v5
	v_cvt_f32_i32_e32 v4, v6
	v_cvt_f32_i32_e32 v5, v7
; DEV int tid_() { int t = threadIdx.x; asm volatile("" : "+v"(t)); return t; }
; DEV float sigm(float x) { return 1.f / (1.f + __expf(-x)); }
; #define P (*launderP(lp))
; template <class FragT, class AccT>
; DEV void gemm_core_t(const char* __restrict__ A, size_t lda_bytes, const char* __restrict__ Bt, size_t ldb_bytes, int kbytes,
;                      int m0, int n0, int Sshift, int dl, char* smem, AccT (&acc)[4][4]) {
;   const int tid = tid_(), lane = tid & 63, wid = tid >> 6, wm = wid >> 1, wn = wid & 1;
;   const int l15 = lane & 15, q = lane >> 4;
;   const int srow = lane >> 3, schunk = (lane & 7) ^ (lane >> 3);
;   const char* ap[4];
;   const char* bp[4];
; #pragma unroll
;   for (int u = 0; u < 4; ++u) {
;     int r = (wid * 4 + u) * 8 + srow;
;     int ar = rowmap(m0 + r, Sshift, dl);
;     ap[u] = A + (size_t)ar * lda_bytes + schunk * 16;
;     bp[u] = Bt + (size_t)(n0 + r) * ldb_bytes + schunk * 16;
;   }
; #pragma unroll
;   for (int i = 0; i < 4; ++i)
; #pragma unroll
;     for (int j = 0; j < 4; ++j) acc[i][j] = AccT{0, 0, 0, 0};
;   const int nk = kbytes >> 7;
;   __syncthreads();
; #pragma unroll
;   for (int u = 0; u < 4; ++u) {
;     __builtin_amdgcn_global_load_lds((const unsigned*)ap[u], (unsigned*)(smem + (wid * 4 + u) * 1024 + lane * 16), 16, 0, 0);
;     __builtin_amdgcn_global_load_lds((const unsigned*)bp[u], (unsigned*)(smem + 16384 + (wid * 4 + u) * 1024 + lane * 16), 16, 0, 0);
;   }
;   const unsigned sbase = (unsigned)(unsigned long)((__attribute__((address_space(3))) char*)smem);
;   const unsigned sq0 = (unsigned)((q ^ (l15 & 7)) << 4);
;   const unsigned a0 = sbase + (unsigned)((wm * 64 + l15) * 128) + sq0;
;   const unsigned b0 = sbase + 16384u + (unsigned)((wn * 32 + l15) * 128) + sq0;
;   asm volatile("s_waitcnt vmcnt(0)" ::: "memory");
;   __syncthreads();
; __device__ __forceinline__ void phase_gemm45(PREF P, char* smem, int which) {
;     ...
;           for (int j = 0; j < 4; ++j) {
;             const int col = n0 + (j & 1) * 16 + wn * 32 + (j >> 1) * 64 + q * 4;
;             const float4 swc = *(const float4*)(P.swpg + col);
;             part[i][j][0] = pack2(sigm((float)iacc[i][j][0] * shr * swc.x), sigm((float)iacc[i][j][1] * shr * swc.y));
;             part[i][j][1] = pack2(sigm((float)iacc[i][j][2] * shr * swc.z), sigm((float)iacc[i][j][3] * shr * swc.w));
	v_mul_f32_e32 v4, v34, v4
	v_mul_f32_e32 v5, v34, v5
	v_mul_f32_e32 v4, v18, v4
	v_mul_f32_e32 v5, v19, v5
	v_mul_f32_e32 v4, 0xbfb8aa3b, v4
	v_mul_f32_e32 v5, 0xbfb8aa3b, v5
	v_exp_f32_e32 v4, v4
	v_exp_f32_e32 v5, v5
	s_nop 0
	v_pk_add_f32 v[4:5], v[4:5], 1.0 op_sel_hi:[1,0]
	s_nop 0
	v_div_scale_f32 v6, s[14:15], v5, v5, 1.0
	v_rcp_f32_e32 v7, v6
	s_nop 0
	v_fma_f32 v8, -v6, v7, 1.0
	v_fmac_f32_e32 v7, v8, v7
	v_div_scale_f32 v8, vcc, 1.0, v5, 1.0
	v_mul_f32_e32 v9, v8, v7
	v_fma_f32 v10, -v6, v9, v8
	v_fmac_f32_e32 v9, v10, v7
	v_fma_f32 v6, -v6, v9, v8
	v_div_fmas_f32 v6, v6, v7, v9
	v_div_fixup_f32 v5, v6, v5, 1.0
	v_div_scale_f32 v6, s[14:15], v4, v4, 1.0
	v_rcp_f32_e32 v7, v6
	s_nop 0
	v_fma_f32 v8, -v6, v7, 1.0
	v_fmac_f32_e32 v7, v8, v7
	v_div_scale_f32 v8, vcc, 1.0, v4, 1.0
	v_mul_f32_e32 v9, v8, v7
	v_fma_f32 v10, -v6, v9, v8
	v_fmac_f32_e32 v9, v10, v7
	v_fma_f32 v6, -v6, v9, v8
	v_div_fmas_f32 v6, v6, v7, v9
	v_div_fixup_f32 v4, v6, v4, 1.0
	v_cvt_pk_bf16_f32 v17, v4, v5
	v_div_scale_f32 v4, s[14:15], v1, v1, 1.0
	v_rcp_f32_e32 v5, v4
	s_nop 0
	v_fma_f32 v6, -v4, v5, 1.0
	v_fmac_f32_e32 v5, v6, v5
	v_div_scale_f32 v6, vcc, 1.0, v1, 1.0
	v_mul_f32_e32 v7, v6, v5
	v_fma_f32 v8, -v4, v7, v6
	v_fmac_f32_e32 v7, v8, v5
	v_fma_f32 v4, -v4, v7, v6
	v_div_fmas_f32 v4, v4, v5, v7
	v_div_fixup_f32 v1, v4, v1, 1.0
	v_div_scale_f32 v4, s[14:15], v0, v0, 1.0
	v_rcp_f32_e32 v5, v4
	s_nop 0
	v_fma_f32 v6, -v4, v5, 1.0
	v_fmac_f32_e32 v5, v6, v5
	v_div_scale_f32 v6, vcc, 1.0, v0, 1.0
	v_mul_f32_e32 v7, v6, v5
	v_fma_f32 v8, -v4, v7, v6
	v_fmac_f32_e32 v7, v8, v5
	v_fma_f32 v4, -v4, v7, v6
	v_div_fmas_f32 v4, v4, v5, v7
	v_div_fixup_f32 v0, v4, v0, 1.0
	v_cvt_pk_bf16_f32 v18, v0, v1
	v_cvt_f32_i32_e32 v0, v2
	v_cvt_f32_i32_e32 v1, v3
	v_mul_f32_e32 v0, v34, v0
	v_mul_f32_e32 v1, v34, v1
	v_mul_f32_e32 v0, v14, v0
	v_mul_f32_e32 v1, v15, v1
	v_mul_f32_e32 v0, 0xbfb8aa3b, v0
	v_mul_f32_e32 v1, 0xbfb8aa3b, v1
	v_exp_f32_e32 v0, v0
	v_exp_f32_e32 v1, v1
	s_nop 0
	v_pk_add_f32 v[0:1], v[0:1], 1.0 op_sel_hi:[1,0]
	s_nop 0
	v_div_scale_f32 v2, s[14:15], v1, v1, 1.0
	v_rcp_f32_e32 v3, v2
	s_nop 0
	v_fma_f32 v4, -v2, v3, 1.0
	v_fmac_f32_e32 v3, v4, v3
	v_div_scale_f32 v4, vcc, 1.0, v1, 1.0
	v_mul_f32_e32 v5, v4, v3
	v_fma_f32 v6, -v2, v5, v4
	v_fmac_f32_e32 v5, v6, v3
	v_fma_f32 v2, -v2, v5, v4
	v_div_fmas_f32 v2, v2, v3, v5
	v_div_fixup_f32 v1, v2, v1, 1.0
	v_div_scale_f32 v2, s[14:15], v0, v0, 1.0
	v_rcp_f32_e32 v3, v2
	s_nop 0
	v_fma_f32 v4, -v2, v3, 1.0
	v_fmac_f32_e32 v3, v4, v3
	v_div_scale_f32 v4, vcc, 1.0, v0, 1.0
	v_mul_f32_e32 v5, v4, v3
	v_fma_f32 v6, -v2, v5, v4
	v_fmac_f32_e32 v5, v6, v3
	v_fma_f32 v2, -v2, v5, v4
	v_div_fmas_f32 v2, v2, v3, v5
	v_div_fixup_f32 v0, v2, v0, 1.0
	v_cvt_pk_bf16_f32 v19, v0, v1
	ds_read2_b64 v[0:3], v80 offset0:24 offset1:28
	s_waitcnt lgkmcnt(0)
	v_ashrrev_i32_e32 v28, 6, v26
	v_bfe_u32 v4, v26, 3, 3
	v_lshlrev_b32_e32 v29, 5, v28
	v_bitop3_b32 v5, v4, v26, 7 bitop3:0x78
	v_or_b32_e32 v24, v29, v4
	v_lshlrev_b32_e32 v180, 4, v5
	v_or_b32_e32 v6, 8, v24
	v_or_b32_e32 v10, 16, v24
	v_or_b32_e32 v30, 24, v24
	v_lshl_add_u64 v[12:13], v[2:3], 0, v[180:181]
	v_lshl_add_u64 v[14:15], v[0:1], 0, v[180:181]
	v_add_u32_e32 v0, s17, v24
	v_add_u32_e32 v2, s4, v24
	v_add_u32_e32 v4, s17, v6
	v_add_u32_e32 v8, s17, v10
	v_add_u32_e32 v24, s17, v30
	v_ashrrev_i32_e32 v1, 31, v0
	v_ashrrev_i32_e32 v5, 31, v4
	v_ashrrev_i32_e32 v9, 31, v8
	v_ashrrev_i32_e32 v25, 31, v24
	v_lshlrev_b64 v[0:1], 9, v[0:1]
	v_lshlrev_b64 v[4:5], 9, v[4:5]
	v_lshlrev_b64 v[8:9], 9, v[8:9]
	v_lshlrev_b64 v[24:25], 9, v[24:25]
	v_lshl_add_u64 v[0:1], v[12:13], 0, v[0:1]
	v_lshl_add_u64 v[4:5], v[12:13], 0, v[4:5]
	v_add_u32_e32 v6, s4, v6
	v_lshl_add_u64 v[8:9], v[12:13], 0, v[8:9]
	v_add_u32_e32 v10, s4, v10
	v_lshl_add_u64 v[12:13], v[12:13], 0, v[24:25]
	v_add_u32_e32 v24, s4, v30
	v_ashrrev_i32_e32 v3, 31, v2
	v_ashrrev_i32_e32 v7, 31, v6
	v_ashrrev_i32_e32 v11, 31, v10
	v_ashrrev_i32_e32 v25, 31, v24
	v_lshlrev_b64 v[2:3], 9, v[2:3]
	v_lshlrev_b64 v[6:7], 9, v[6:7]
	v_lshlrev_b64 v[10:11], 9, v[10:11]
	v_lshlrev_b64 v[24:25], 9, v[24:25]
	v_and_b32_e32 v27, 63, v26
	v_lshl_add_u64 v[2:3], v[14:15], 0, v[2:3]
	v_lshl_add_u64 v[6:7], v[14:15], 0, v[6:7]
	v_lshl_add_u64 v[10:11], v[14:15], 0, v[10:11]
	v_lshl_add_u64 v[14:15], v[14:15], 0, v[24:25]
	v_lshlrev_b32_e32 v24, 12, v28
	v_lshl_or_b32 v28, v27, 4, v24
	v_add_u32_e32 v24, 0x4000, v28
	v_readfirstlane_b32 s43, v28
	v_readfirstlane_b32 s36, v24
	v_or_b32_e32 v24, 0x400, v28
	s_mov_b32 m0, s43
	v_readfirstlane_b32 s37, v24
	v_add_u32_e32 v24, 0x4400, v28
	s_barrier
	v_readfirstlane_b32 s38, v24
	v_or_b32_e32 v24, 0x800, v28
	global_load_lds_dwordx4 v[0:1], off
	s_mov_b32 m0, s36
	v_readfirstlane_b32 s39, v24
	v_add_u32_e32 v24, 0x4800, v28
	global_load_lds_dwordx4 v[2:3], off
	s_mov_b32 m0, s37
	v_readfirstlane_b32 s40, v24
	v_or_b32_e32 v24, 0xc00, v28
	global_load_lds_dwordx4 v[4:5], off
	s_mov_b32 m0, s38
	v_readfirstlane_b32 s41, v24
	v_add_u32_e32 v24, 0x4c00, v28
	global_load_lds_dwordx4 v[6:7], off
	s_mov_b32 m0, s39
	v_readfirstlane_b32 s42, v24
	v_lshlrev_b32_e32 v24, 4, v26
	v_and_b32_e32 v25, 15, v26
	global_load_lds_dwordx4 v[8:9], off
	s_mov_b32 m0, s40
	v_bitop3_b32 v27, v27, s31, v24 bitop3:0x48
	v_lshrrev_b32_e32 v24, 1, v26
	global_load_lds_dwordx4 v[10:11], off
	s_mov_b32 m0, s41
	v_and_or_b32 v24, v24, s44, v25
	v_and_or_b32 v25, v29, 32, v25
	v_add_u32_e32 v29, 0x8000, v28
	global_load_lds_dwordx4 v[12:13], off
	s_mov_b32 m0, s42
	v_lshlrev_b32_e32 v26, 7, v24
	v_readfirstlane_b32 s31, v29
	v_add_u32_e32 v29, 0xc000, v28
	global_load_lds_dwordx4 v[14:15], off
	v_or_b32_e32 v24, v27, v26
	v_lshl_or_b32 v34, v25, 7, v27
	v_bitop3_b32 v35, v27, 64, v26 bitop3:0x36
	v_lshl_add_u64 v[26:27], v[0:1], 0, s[46:47]
	s_mov_b32 m0, s31
	v_readfirstlane_b32 s5, v29
	v_add_u32_e32 v29, 0x8400, v28
	s_waitcnt vmcnt(0)
	s_waitcnt vmcnt(0) lgkmcnt(0)
	s_barrier
; DEV f32x4 mma_step(bf16x8 a, bf16x8 b, f32x4 c) { return MFMA(a, b, c); }
; template <class FragT, class AccT>
; DEV void gemm_core_t(const char* __restrict__ A, size_t lda_bytes, const char* __restrict__ Bt, size_t ldb_bytes, int kbytes,
;                      int m0, int n0, int Sshift, int dl, char* smem, AccT (&acc)[4][4]) {
;     ...
;   for (int kt = 0; kt < nk; ++kt) {
;     const unsigned so = (unsigned)(kt & 1) * 32768u;
;     char* nxt = smem + ((kt + 1) & 1) * 32768;
;     if (kt + 1 < nk) {
; #pragma unroll
;       for (int u = 0; u < 4; ++u) {
;         __builtin_amdgcn_global_load_lds((const unsigned*)(ap[u] + (size_t)(kt + 1) * 128), (unsigned*)(nxt + (wid * 4 + u) * 1024 + lane * 16), 16, 0, 0);
;         __builtin_amdgcn_global_load_lds((const unsigned*)(bp[u] + (size_t)(kt + 1) * 128), (unsigned*)(nxt + 16384 + (wid * 4 + u) * 1024 + lane * 16), 16, 0, 0);
;       }
;     }
;     FragT xa[2][4], wb[2][4];
;     asm volatile(
;         "ds_read_b128 %0, %16\n\t"
;         "ds_read_b128 %1, %16 offset:2048\n\t"
;         "ds_read_b128 %2, %16 offset:4096\n\t"
;         "ds_read_b128 %3, %16 offset:6144\n\t"
;         "ds_read_b128 %4, %18\n\t"
;         "ds_read_b128 %5, %18 offset:2048\n\t"
;         "ds_read_b128 %6, %18 offset:8192\n\t"
;         "ds_read_b128 %7, %18 offset:10240\n\t"
;         "ds_read_b128 %8, %17\n\t"
;         "ds_read_b128 %9, %17 offset:2048\n\t"
;         "ds_read_b128 %10, %17 offset:4096\n\t"
;         "ds_read_b128 %11, %17 offset:6144\n\t"
;         "ds_read_b128 %12, %19\n\t"
;         "ds_read_b128 %13, %19 offset:2048\n\t"
;         "ds_read_b128 %14, %19 offset:8192\n\t"
;         "ds_read_b128 %15, %19 offset:10240\n\t"
;         "s_waitcnt lgkmcnt(8)"
;         : "=&v"(xa[0][0]), "=&v"(xa[0][1]), "=&v"(xa[0][2]), "=&v"(xa[0][3]), "=&v"(wb[0][0]), "=&v"(wb[0][1]), "=&v"(wb[0][2]),
;           "=&v"(wb[0][3]), "=&v"(xa[1][0]), "=&v"(xa[1][1]), "=&v"(xa[1][2]), "=&v"(xa[1][3]), "=&v"(wb[1][0]), "=&v"(wb[1][1]),
;           "=&v"(wb[1][2]), "=&v"(wb[1][3])
;         : "v"(a0 + so), "v"((a0 ^ 64u) + so), "v"(b0 + so), "v"((b0 ^ 64u) + so)
;         : "memory");
;     __builtin_amdgcn_s_setprio(1);
; #pragma unroll
;     for (int i = 0; i < 4; ++i)
; #pragma unroll
;       for (int j = 0; j < 4; ++j) acc[i][j] = mma_step(wb[0][j], xa[0][i], acc[i][j]);
;     asm volatile("s_waitcnt lgkmcnt(0)"
	global_load_lds_dwordx4 v[26:27], off
	v_lshl_add_u64 v[26:27], v[2:3], 0, s[46:47]
	s_mov_b32 m0, s5
	v_readfirstlane_b32 s6, v29
	v_add_u32_e32 v29, 0xc400, v28
	global_load_lds_dwordx4 v[26:27], off
	v_lshl_add_u64 v[26:27], v[4:5], 0, s[46:47]
	s_mov_b32 m0, s6
	v_readfirstlane_b32 s14, v29
	v_add_u32_e32 v29, 0x8800, v28
	global_load_lds_dwordx4 v[26:27], off
	v_lshl_add_u64 v[26:27], v[6:7], 0, s[46:47]
	s_mov_b32 m0, s14
	v_readfirstlane_b32 s15, v29
	v_add_u32_e32 v29, 0xc800, v28
	global_load_lds_dwordx4 v[26:27], off
	v_lshl_add_u64 v[26:27], v[8:9], 0, s[46:47]
	s_mov_b32 m0, s15
	v_readfirstlane_b32 s18, v29
	v_add_u32_e32 v29, 0x8c00, v28
	global_load_lds_dwordx4 v[26:27], off
	v_lshl_add_u64 v[26:27], v[10:11], 0, s[46:47]
	s_mov_b32 m0, s18
	v_readfirstlane_b32 s19, v29
	v_add_u32_e32 v28, 0xcc00, v28
	global_load_lds_dwordx4 v[26:27], off
	v_lshl_add_u64 v[26:27], v[12:13], 0, s[46:47]
	s_mov_b32 m0, s19
	v_readfirstlane_b32 s24, v28
	global_load_lds_dwordx4 v[26:27], off
	v_lshl_add_u64 v[26:27], v[14:15], 0, s[46:47]
	s_mov_b32 m0, s24
	v_or_b32_e32 v25, 0x4000, v34
	global_load_lds_dwordx4 v[26:27], off
	v_bitop3_b32 v38, v34, 64, v219 bitop3:0x36
	ds_read_b128 v[26:29], v24
	ds_read_b128 v[66:69], v24 offset:2048
	ds_read_b128 v[84:87], v24 offset:4096
	ds_read_b128 v[88:91], v24 offset:6144
	ds_read_b128 v[92:95], v25
	ds_read_b128 v[96:99], v25 offset:2048
	ds_read_b128 v[100:103], v25 offset:8192
	ds_read_b128 v[104:107], v25 offset:10240
	ds_read_b128 v[108:111], v35
	ds_read_b128 v[112:115], v35 offset:2048
	ds_read_b128 v[116:119], v35 offset:4096
	ds_read_b128 v[120:123], v35 offset:6144
	ds_read_b128 v[124:127], v38
	ds_read_b128 v[128:131], v38 offset:2048
	ds_read_b128 v[132:135], v38 offset:8192
	ds_read_b128 v[136:139], v38 offset:10240
	s_waitcnt lgkmcnt(8)
	s_setprio 1
	v_mfma_f32_16x16x32_bf16 v[140:143], v[92:95], v[26:29], 0
	v_mfma_f32_16x16x32_bf16 v[144:147], v[96:99], v[26:29], 0
	v_mfma_f32_16x16x32_bf16 v[148:151], v[100:103], v[26:29], 0
	v_mfma_f32_16x16x32_bf16 v[26:29], v[104:107], v[26:29], 0
	v_mfma_f32_16x16x32_bf16 v[152:155], v[92:95], v[66:69], 0
	v_mfma_f32_16x16x32_bf16 v[156:159], v[96:99], v[66:69], 0
	v_mfma_f32_16x16x32_bf16 v[160:163], v[100:103], v[66:69], 0
	v_mfma_f32_16x16x32_bf16 v[66:69], v[104:107], v[66:69], 0
	v_mfma_f32_16x16x32_bf16 v[164:167], v[92:95], v[84:87], 0
	v_mfma_f32_16x16x32_bf16 v[168:171], v[96:99], v[84:87], 0
	v_mfma_f32_16x16x32_bf16 v[172:175], v[100:103], v[84:87], 0
	v_mfma_f32_16x16x32_bf16 v[84:87], v[104:107], v[84:87], 0
	v_mfma_f32_16x16x32_bf16 v[92:95], v[92:95], v[88:91], 0
	v_mfma_f32_16x16x32_bf16 v[96:99], v[96:99], v[88:91], 0
	v_mfma_f32_16x16x32_bf16 v[100:103], v[100:103], v[88:91], 0
	v_mfma_f32_16x16x32_bf16 v[88:91], v[104:107], v[88:91], 0
	s_waitcnt lgkmcnt(0)
	s_nop 0
	v_mfma_f32_16x16x32_bf16 v[104:107], v[124:127], v[108:111], v[140:143]
	v_mfma_f32_16x16x32_bf16 v[140:143], v[128:131], v[108:111], v[144:147]
	v_mfma_f32_16x16x32_bf16 v[144:147], v[132:135], v[108:111], v[148:151]
	v_mfma_f32_16x16x32_bf16 v[26:29], v[136:139], v[108:111], v[26:29]
	v_mfma_f32_16x16x32_bf16 v[108:111], v[124:127], v[112:115], v[152:155]
	v_mfma_f32_16x16x32_bf16 v[148:151], v[128:131], v[112:115], v[156:159]
	v_mfma_f32_16x16x32_bf16 v[152:155], v[132:135], v[112:115], v[160:163]
	v_mfma_f32_16x16x32_bf16 v[66:69], v[136:139], v[112:115], v[66:69]
	v_mfma_f32_16x16x32_bf16 v[112:115], v[124:127], v[116:119], v[164:167]
	v_mfma_f32_16x16x32_bf16 v[156:159], v[128:131], v[116:119], v[168:171]
	v_mfma_f32_16x16x32_bf16 v[160:163], v[132:135], v[116:119], v[172:175]
	v_mfma_f32_16x16x32_bf16 v[84:87], v[136:139], v[116:119], v[84:87]
	v_mfma_f32_16x16x32_bf16 v[92:95], v[124:127], v[120:123], v[92:95]
	v_mfma_f32_16x16x32_bf16 v[96:99], v[128:131], v[120:123], v[96:99]
	v_mfma_f32_16x16x32_bf16 v[100:103], v[132:135], v[120:123], v[100:103]
	v_mfma_f32_16x16x32_bf16 v[88:91], v[136:139], v[120:123], v[88:91]
	s_setprio 0
	s_mov_b64 s[48:49], 0x100
	s_mov_b32 m0, s43
	v_lshl_add_u64 v[30:31], v[0:1], 0, s[48:49]
	s_waitcnt vmcnt(0)
	s_waitcnt vmcnt(0) lgkmcnt(0)
	s_barrier
	global_load_lds_dwordx4 v[30:31], off
	v_lshl_add_u64 v[30:31], v[2:3], 0, s[48:49]
	s_mov_b32 m0, s36
	v_add_u32_e32 v39, 0x8000, v24
	global_load_lds_dwordx4 v[30:31], off
	v_lshl_add_u64 v[30:31], v[4:5], 0, s[48:49]
	s_mov_b32 m0, s37
	v_readlane_b32 s36, v251, 55
	global_load_lds_dwordx4 v[30:31], off
	v_lshl_add_u64 v[30:31], v[6:7], 0, s[48:49]
	s_mov_b32 m0, s38
	v_add_u32_e32 v42, 0x8000, v35
	global_load_lds_dwordx4 v[30:31], off
	v_lshl_add_u64 v[30:31], v[8:9], 0, s[48:49]
	s_mov_b32 m0, s39
	v_or_b32_e32 v34, 0xc000, v34
	global_load_lds_dwordx4 v[30:31], off
	v_lshl_add_u64 v[30:31], v[10:11], 0, s[48:49]
	s_mov_b32 m0, s40
	v_bitop3_b32 v43, v25, s36, 64 bitop3:0xde
	global_load_lds_dwordx4 v[30:31], off
	v_lshl_add_u64 v[30:31], v[12:13], 0, s[48:49]
	s_mov_b32 m0, s41
	v_readlane_b32 s37, v251, 56
	global_load_lds_dwordx4 v[30:31], off
	v_lshl_add_u64 v[30:31], v[14:15], 0, s[48:49]
	s_mov_b32 m0, s42
	s_nop 0
	global_load_lds_dwordx4 v[30:31], off
	ds_read_b128 v[116:119], v39
	ds_read_b128 v[120:123], v39 offset:2048
	ds_read_b128 v[124:127], v39 offset:4096
	ds_read_b128 v[128:131], v39 offset:6144
	ds_read_b128 v[132:135], v34
	ds_read_b128 v[136:139], v34 offset:2048
	ds_read_b128 v[164:167], v34 offset:8192
	ds_read_b128 v[168:171], v34 offset:10240
	ds_read_b128 v[172:175], v42
	ds_read_b128 v[184:187], v42 offset:2048
	ds_read_b128 v[222:225], v42 offset:4096
	ds_read_b128 v[226:229], v42 offset:6144
	ds_read_b128 v[230:233], v43
	ds_read_b128 v[234:237], v43 offset:2048
	ds_read_b128 v[238:241], v43 offset:8192
	ds_read_b128 v[242:245], v43 offset:10240
	s_waitcnt lgkmcnt(8)
; DEV f32x4 mma_step(bf16x8 a, bf16x8 b, f32x4 c) { return MFMA(a, b, c); }
; template <class FragT, class AccT>
; DEV void gemm_core_t(const char* __restrict__ A, size_t lda_bytes, const char* __restrict__ Bt, size_t ldb_bytes, int kbytes,
;                      int m0, int n0, int Sshift, int dl, char* smem, AccT (&acc)[4][4]) {
;     ...
;   for (int kt = 0; kt < nk; ++kt) {
;     const unsigned so = (unsigned)(kt & 1) * 32768u;
;     char* nxt = smem + ((kt + 1) & 1) * 32768;
;     if (kt + 1 < nk) {
; #pragma unroll
;       for (int u = 0; u < 4; ++u) {
;         __builtin_amdgcn_global_load_lds((const unsigned*)(ap[u] + (size_t)(kt + 1) * 128), (unsigned*)(nxt + (wid * 4 + u) * 1024 + lane * 16), 16, 0, 0);
;         __builtin_amdgcn_global_load_lds((const unsigned*)(bp[u] + (size_t)(kt + 1) * 128), (unsigned*)(nxt + 16384 + (wid * 4 + u) * 1024 + lane * 16), 16, 0, 0);
;       }
;     }
;     FragT xa[2][4], wb[2][4];
;     asm volatile(
;         "ds_read_b128 %0, %16\n\t"
;         "ds_read_b128 %1, %16 offset:2048\n\t"
;         "ds_read_b128 %2, %16 offset:4096\n\t"
;         "ds_read_b128 %3, %16 offset:6144\n\t"
;         "ds_read_b128 %4, %18\n\t"
;         "ds_read_b128 %5, %18 offset:2048\n\t"
;         "ds_read_b128 %6, %18 offset:8192\n\t"
;         "ds_read_b128 %7, %18 offset:10240\n\t"
;         "ds_read_b128 %8, %17\n\t"
;         "ds_read_b128 %9, %17 offset:2048\n\t"
;         "ds_read_b128 %10, %17 offset:4096\n\t"
;         "ds_read_b128 %11, %17 offset:6144\n\t"
;         "ds_read_b128 %12, %19\n\t"
;         "ds_read_b128 %13, %19 offset:2048\n\t"
;         "ds_read_b128 %14, %19 offset:8192\n\t"
;         "ds_read_b128 %15, %19 offset:10240\n\t"
;         "s_waitcnt lgkmcnt(8)"
;         : "=&v"(xa[0][0]), "=&v"(xa[0][1]), "=&v"(xa[0][2]), "=&v"(xa[0][3]), "=&v"(wb[0][0]), "=&v"(wb[0][1]), "=&v"(wb[0][2]),
;           "=&v"(wb[0][3]), "=&v"(xa[1][0]), "=&v"(xa[1][1]), "=&v"(xa[1][2]), "=&v"(xa[1][3]), "=&v"(wb[1][0]), "=&v"(wb[1][1]),
;           "=&v"(wb[1][2]), "=&v"(wb[1][3])
;         : "v"(a0 + so), "v"((a0 ^ 64u) + so), "v"(b0 + so), "v"((b0 ^ 64u) + so)
;         : "memory");
;     __builtin_amdgcn_s_setprio(1);
; #pragma unroll
;     for (int i = 0; i < 4; ++i)
; #pragma unroll
;       for (int j = 0; j < 4; ++j) acc[i][j] = mma_step(wb[0][j], xa[0][i], acc[i][j]);
;     asm volatile("s_waitcnt lgkmcnt(0)"
	s_setprio 1
	v_mfma_f32_16x16x32_bf16 v[104:107], v[132:135], v[116:119], v[104:107]
	v_mfma_f32_16x16x32_bf16 v[140:143], v[136:139], v[116:119], v[140:143]
	v_mfma_f32_16x16x32_bf16 v[144:147], v[164:167], v[116:119], v[144:147]
	v_mfma_f32_16x16x32_bf16 v[26:29], v[168:171], v[116:119], v[26:29]
	v_mfma_f32_16x16x32_bf16 v[108:111], v[132:135], v[120:123], v[108:111]
	v_mfma_f32_16x16x32_bf16 v[116:119], v[136:139], v[120:123], v[148:151]
	v_mfma_f32_16x16x32_bf16 v[148:151], v[164:167], v[120:123], v[152:155]
	v_mfma_f32_16x16x32_bf16 v[66:69], v[168:171], v[120:123], v[66:69]
	v_mfma_f32_16x16x32_bf16 v[112:115], v[132:135], v[124:127], v[112:115]
	v_mfma_f32_16x16x32_bf16 v[120:123], v[136:139], v[124:127], v[156:159]
	v_mfma_f32_16x16x32_bf16 v[152:155], v[164:167], v[124:127], v[160:163]
	v_mfma_f32_16x16x32_bf16 v[84:87], v[168:171], v[124:127], v[84:87]
	v_mfma_f32_16x16x32_bf16 v[92:95], v[132:135], v[128:131], v[92:95]
	v_mfma_f32_16x16x32_bf16 v[96:99], v[136:139], v[128:131], v[96:99]
	v_mfma_f32_16x16x32_bf16 v[100:103], v[164:167], v[128:131], v[100:103]
	v_mfma_f32_16x16x32_bf16 v[88:91], v[168:171], v[128:131], v[88:91]
	s_waitcnt lgkmcnt(0)
	s_nop 0
	v_mfma_f32_16x16x32_bf16 v[104:107], v[230:233], v[172:175], v[104:107]
	v_mfma_f32_16x16x32_bf16 v[124:127], v[234:237], v[172:175], v[140:143]
	v_mfma_f32_16x16x32_bf16 v[128:131], v[238:241], v[172:175], v[144:147]
	v_mfma_f32_16x16x32_bf16 v[26:29], v[242:245], v[172:175], v[26:29]
	v_mfma_f32_16x16x32_bf16 v[108:111], v[230:233], v[184:187], v[108:111]
	v_mfma_f32_16x16x32_bf16 v[116:119], v[234:237], v[184:187], v[116:119]
	v_mfma_f32_16x16x32_bf16 v[132:135], v[238:241], v[184:187], v[148:151]
	v_mfma_f32_16x16x32_bf16 v[66:69], v[242:245], v[184:187], v[66:69]
	v_mfma_f32_16x16x32_bf16 v[112:115], v[230:233], v[222:225], v[112:115]
	v_mfma_f32_16x16x32_bf16 v[120:123], v[234:237], v[222:225], v[120:123]
	v_mfma_f32_16x16x32_bf16 v[136:139], v[238:241], v[222:225], v[152:155]
	v_mfma_f32_16x16x32_bf16 v[84:87], v[242:245], v[222:225], v[84:87]
	v_mfma_f32_16x16x32_bf16 v[92:95], v[230:233], v[226:229], v[92:95]
	v_mfma_f32_16x16x32_bf16 v[96:99], v[234:237], v[226:229], v[96:99]
	v_mfma_f32_16x16x32_bf16 v[100:103], v[238:241], v[226:229], v[100:103]
	v_mfma_f32_16x16x32_bf16 v[88:91], v[242:245], v[226:229], v[88:91]
	s_setprio 0
	s_mov_b64 s[36:37], 0x180
	s_mov_b32 m0, s31
	v_lshl_add_u64 v[0:1], v[0:1], 0, s[36:37]
	s_waitcnt vmcnt(0)
	s_waitcnt vmcnt(0) lgkmcnt(0)
	s_barrier
	global_load_lds_dwordx4 v[0:1], off
	v_lshl_add_u64 v[0:1], v[2:3], 0, s[36:37]
	s_mov_b32 m0, s5
	s_movk_i32 s31, 0x70
	global_load_lds_dwordx4 v[0:1], off
	v_lshl_add_u64 v[0:1], v[4:5], 0, s[36:37]
	s_mov_b32 m0, s6
	s_nop 0
	global_load_lds_dwordx4 v[0:1], off
	v_lshl_add_u64 v[0:1], v[6:7], 0, s[36:37]
	s_mov_b32 m0, s14
	s_nop 0
	global_load_lds_dwordx4 v[0:1], off
	v_lshl_add_u64 v[0:1], v[8:9], 0, s[36:37]
	s_mov_b32 m0, s15
	s_nop 0
	global_load_lds_dwordx4 v[0:1], off
	v_lshl_add_u64 v[0:1], v[10:11], 0, s[36:37]
	s_mov_b32 m0, s18
	s_nop 0
	global_load_lds_dwordx4 v[0:1], off
	v_lshl_add_u64 v[0:1], v[12:13], 0, s[36:37]
	s_mov_b32 m0, s19
	s_nop 0
	global_load_lds_dwordx4 v[0:1], off
	v_lshl_add_u64 v[0:1], v[14:15], 0, s[36:37]
	s_mov_b32 m0, s24
	s_nop 0
	global_load_lds_dwordx4 v[0:1], off
	ds_read_b128 v[0:3], v24
	ds_read_b128 v[4:7], v24 offset:2048
	ds_read_b128 v[8:11], v24 offset:4096
	ds_read_b128 v[12:15], v24 offset:6144
	ds_read_b128 v[140:143], v25
	ds_read_b128 v[144:147], v25 offset:2048
	ds_read_b128 v[148:151], v25 offset:8192
	ds_read_b128 v[152:155], v25 offset:10240
	ds_read_b128 v[156:159], v35
	ds_read_b128 v[160:163], v35 offset:2048
	ds_read_b128 v[164:167], v35 offset:4096
	ds_read_b128 v[168:171], v35 offset:6144
	ds_read_b128 v[172:175], v38
	ds_read_b128 v[184:187], v38 offset:2048
	ds_read_b128 v[222:225], v38 offset:8192
	ds_read_b128 v[226:229], v38 offset:10240
	s_waitcnt lgkmcnt(8)
	s_setprio 1
	v_mfma_f32_16x16x32_bf16 v[104:107], v[140:143], v[0:3], v[104:107]
	v_mfma_f32_16x16x32_bf16 v[124:127], v[144:147], v[0:3], v[124:127]
	v_mfma_f32_16x16x32_bf16 v[128:131], v[148:151], v[0:3], v[128:131]
	v_mfma_f32_16x16x32_bf16 v[0:3], v[152:155], v[0:3], v[26:29]
	v_mfma_f32_16x16x32_bf16 v[24:27], v[140:143], v[4:7], v[108:111]
	v_mfma_f32_16x16x32_bf16 v[28:31], v[144:147], v[4:7], v[116:119]
	v_mfma_f32_16x16x32_bf16 v[108:111], v[148:151], v[4:7], v[132:135]
	v_mfma_f32_16x16x32_bf16 v[4:7], v[152:155], v[4:7], v[66:69]
	v_mfma_f32_16x16x32_bf16 v[66:69], v[140:143], v[8:11], v[112:115]
	v_mfma_f32_16x16x32_bf16 v[112:115], v[144:147], v[8:11], v[120:123]
	v_mfma_f32_16x16x32_bf16 v[116:119], v[148:151], v[8:11], v[136:139]
	v_mfma_f32_16x16x32_bf16 v[8:11], v[152:155], v[8:11], v[84:87]
	v_mfma_f32_16x16x32_bf16 v[84:87], v[140:143], v[12:15], v[92:95]
	v_mfma_f32_16x16x32_bf16 v[92:95], v[144:147], v[12:15], v[96:99]
	v_mfma_f32_16x16x32_bf16 v[96:99], v[148:151], v[12:15], v[100:103]
	v_mfma_f32_16x16x32_bf16 v[12:15], v[152:155], v[12:15], v[88:91]
	s_waitcnt lgkmcnt(0)
	s_nop 0
	v_mfma_f32_16x16x32_bf16 v[88:91], v[172:175], v[156:159], v[104:107]
	v_mfma_f32_16x16x32_bf16 v[100:103], v[184:187], v[156:159], v[124:127]
	v_mfma_f32_16x16x32_bf16 v[104:107], v[222:225], v[156:159], v[128:131]
	v_mfma_f32_16x16x32_bf16 v[0:3], v[226:229], v[156:159], v[0:3]
	v_mfma_f32_16x16x32_bf16 v[24:27], v[172:175], v[160:163], v[24:27]
	v_mfma_f32_16x16x32_bf16 v[28:31], v[184:187], v[160:163], v[28:31]
	v_mfma_f32_16x16x32_bf16 v[108:111], v[222:225], v[160:163], v[108:111]
	v_mfma_f32_16x16x32_bf16 v[4:7], v[226:229], v[160:163], v[4:7]
	v_mfma_f32_16x16x32_bf16 v[66:69], v[172:175], v[164:167], v[66:69]
	v_mfma_f32_16x16x32_bf16 v[112:115], v[184:187], v[164:167], v[112:115]
	v_mfma_f32_16x16x32_bf16 v[116:119], v[222:225], v[164:167], v[116:119]
	v_mfma_f32_16x16x32_bf16 v[8:11], v[226:229], v[164:167], v[8:11]
	v_mfma_f32_16x16x32_bf16 v[84:87], v[172:175], v[168:171], v[84:87]
	v_mfma_f32_16x16x32_bf16 v[92:95], v[184:187], v[168:171], v[92:95]
	v_mfma_f32_16x16x32_bf16 v[96:99], v[222:225], v[168:171], v[96:99]
	v_mfma_f32_16x16x32_bf16 v[12:15], v[226:229], v[168:171], v[12:15]
	s_setprio 0
	s_waitcnt vmcnt(0)
	s_waitcnt vmcnt(0) lgkmcnt(0)
	s_barrier
; DEV float bflo(unsigned u) { return __uint_as_float(u << 16); }
; DEV float bfhi(unsigned u) { return __uint_as_float(u & 0xffff0000u); }
; DEV f32x4 mma_step(bf16x8 a, bf16x8 b, f32x4 c) { return MFMA(a, b, c); }
; DEV i32x4 mma_step(i32x4 a, i32x4 b, i32x4 c) { return __builtin_amdgcn_mfma_i32_16x16x64_i8(a, b, c, 0, 0, 0); }
; template <class FragT, class AccT>
; DEV void gemm_core_t(const char* __restrict__ A, size_t lda_bytes, const char* __restrict__ Bt, size_t ldb_bytes, int kbytes,
;                      int m0, int n0, int Sshift, int dl, char* smem, AccT (&acc)[4][4]) {
;     ...
;     for (int i = 0; i < 4; ++i)
; #pragma unroll
;       for (int j = 0; j < 4; ++j) acc[i][j] = mma_step(wb[0][j], xa[0][i], acc[i][j]);
;     asm volatile("s_waitcnt lgkmcnt(0)"
;                  : "+v"(xa[1][0]), "+v"(xa[1][1]), "+v"(xa[1][2]), "+v"(xa[1][3]), "+v"(wb[1][0]), "+v"(wb[1][1]), "+v"(wb[1][2]),
;                    "+v"(wb[1][3]), "+v"(acc[0][0]), "+v"(acc[0][1]), "+v"(acc[0][2]), "+v"(acc[0][3]), "+v"(acc[1][0]),
;                    "+v"(acc[1][1]), "+v"(acc[1][2]), "+v"(acc[1][3]), "+v"(acc[2][0]), "+v"(acc[2][1]), "+v"(acc[2][2]),
;                    "+v"(acc[2][3]), "+v"(acc[3][0]), "+v"(acc[3][1]), "+v"(acc[3][2]), "+v"(acc[3][3])
;                  :
;                  : "memory");
; #pragma unroll
;     for (int i = 0; i < 4; ++i)
; #pragma unroll
;       for (int j = 0; j < 4; ++j) acc[i][j] = mma_step(wb[1][j], xa[1][i], acc[i][j]);
; __device__ __forceinline__ void phase_gemm45(PREF P, char* smem, int which) {
;     ...
; #pragma unroll
;       for (int i = 0; i < 4; ++i)
; #pragma unroll
;         for (int j = 0; j < 4; ++j) {
;           const int row = m0 + wm * 64 + i * 16 + l15, col = n0 + (j & 1) * 16 + wn * 32 + (j >> 1) * 64 + q * 4;
;           f32x4 v;
;           v[0] = bflo(part[i][j][0]) * acc[i][j][0]; v[1] = bfhi(part[i][j][0]) * acc[i][j][1];
;           v[2] = bflo(part[i][j][1]) * acc[i][j][2]; v[3] = bfhi(part[i][j][1]) * acc[i][j][3];
;           acc[i][j] = v;
;         }
	ds_read_b128 v[120:123], v39
	ds_read_b128 v[124:127], v39 offset:2048
	ds_read_b128 v[128:131], v39 offset:4096
	ds_read_b128 v[132:135], v39 offset:6144
	ds_read_b128 v[136:139], v34
	ds_read_b128 v[140:143], v34 offset:2048
	ds_read_b128 v[144:147], v34 offset:8192
	ds_read_b128 v[148:151], v34 offset:10240
	ds_read_b128 v[152:155], v42
	ds_read_b128 v[156:159], v42 offset:2048
	ds_read_b128 v[160:163], v42 offset:4096
	ds_read_b128 v[164:167], v42 offset:6144
	ds_read_b128 v[168:171], v43
	ds_read_b128 v[172:175], v43 offset:2048
	ds_read_b128 v[184:187], v43 offset:8192
	ds_read_b128 v[222:225], v43 offset:10240
	s_waitcnt lgkmcnt(8)
	s_setprio 1
	v_mfma_f32_16x16x32_bf16 v[88:91], v[136:139], v[120:123], v[88:91]
	v_mfma_f32_16x16x32_bf16 v[100:103], v[140:143], v[120:123], v[100:103]
	v_mfma_f32_16x16x32_bf16 v[104:107], v[144:147], v[120:123], v[104:107]
	v_mfma_f32_16x16x32_bf16 v[0:3], v[148:151], v[120:123], v[0:3]
	v_mfma_f32_16x16x32_bf16 v[24:27], v[136:139], v[124:127], v[24:27]
	v_mfma_f32_16x16x32_bf16 v[28:31], v[140:143], v[124:127], v[28:31]
	v_mfma_f32_16x16x32_bf16 v[108:111], v[144:147], v[124:127], v[108:111]
	v_mfma_f32_16x16x32_bf16 v[4:7], v[148:151], v[124:127], v[4:7]
	v_mfma_f32_16x16x32_bf16 v[66:69], v[136:139], v[128:131], v[66:69]
	v_mfma_f32_16x16x32_bf16 v[112:115], v[140:143], v[128:131], v[112:115]
	v_mfma_f32_16x16x32_bf16 v[116:119], v[144:147], v[128:131], v[116:119]
	v_mfma_f32_16x16x32_bf16 v[8:11], v[148:151], v[128:131], v[8:11]
	v_mfma_f32_16x16x32_bf16 v[84:87], v[136:139], v[132:135], v[84:87]
	v_mfma_f32_16x16x32_bf16 v[92:95], v[140:143], v[132:135], v[92:95]
	v_mfma_f32_16x16x32_bf16 v[96:99], v[144:147], v[132:135], v[96:99]
	v_mfma_f32_16x16x32_bf16 v[12:15], v[148:151], v[132:135], v[12:15]
	s_waitcnt lgkmcnt(0)
	s_nop 0
	v_mfma_f32_16x16x32_bf16 v[88:91], v[168:171], v[152:155], v[88:91]
	v_mfma_f32_16x16x32_bf16 v[100:103], v[172:175], v[152:155], v[100:103]
	v_mfma_f32_16x16x32_bf16 v[104:107], v[184:187], v[152:155], v[104:107]
	v_mfma_f32_16x16x32_bf16 v[0:3], v[222:225], v[152:155], v[0:3]
	v_mfma_f32_16x16x32_bf16 v[24:27], v[168:171], v[156:159], v[24:27]
	v_mfma_f32_16x16x32_bf16 v[28:31], v[172:175], v[156:159], v[28:31]
	v_mfma_f32_16x16x32_bf16 v[108:111], v[184:187], v[156:159], v[108:111]
	v_mfma_f32_16x16x32_bf16 v[4:7], v[222:225], v[156:159], v[4:7]
	v_mfma_f32_16x16x32_bf16 v[66:69], v[168:171], v[160:163], v[66:69]
	v_mfma_f32_16x16x32_bf16 v[112:115], v[172:175], v[160:163], v[112:115]
	v_mfma_f32_16x16x32_bf16 v[116:119], v[184:187], v[160:163], v[116:119]
	v_mfma_f32_16x16x32_bf16 v[8:11], v[222:225], v[160:163], v[8:11]
	v_mfma_f32_16x16x32_bf16 v[84:87], v[168:171], v[164:167], v[84:87]
	v_mfma_f32_16x16x32_bf16 v[92:95], v[172:175], v[164:167], v[92:95]
	v_mfma_f32_16x16x32_bf16 v[96:99], v[184:187], v[164:167], v[96:99]
	v_mfma_f32_16x16x32_bf16 v[12:15], v[222:225], v[164:167], v[12:15]
	s_setprio 0
	s_waitcnt vmcnt(0)
	v_lshlrev_b32_e32 v58, 16, v64
	v_and_b32_e32 v59, 0xffff0000, v64
	v_pk_mul_f32 v[0:1], v[0:1], v[58:59]
	v_lshlrev_b32_e32 v58, 16, v65
	v_and_b32_e32 v59, 0xffff0000, v65
	v_pk_mul_f32 v[2:3], v[2:3], v[58:59]
	v_lshlrev_b32_e32 v58, 16, v60
	v_and_b32_e32 v59, 0xffff0000, v60
	v_pk_mul_f32 v[24:25], v[24:25], v[58:59]
	v_lshlrev_b32_e32 v58, 16, v61
	v_and_b32_e32 v59, 0xffff0000, v61
	v_pk_mul_f32 v[26:27], v[26:27], v[58:59]
	v_lshlrev_b32_e32 v58, 16, v56
	v_and_b32_e32 v59, 0xffff0000, v56
	v_pk_mul_f32 v[28:29], v[28:29], v[58:59]
	v_lshlrev_b32_e32 v58, 16, v48
	v_and_b32_e32 v59, 0xffff0000, v48
	v_lshlrev_b32_e32 v48, 16, v49
	v_and_b32_e32 v49, 0xffff0000, v49
	v_pk_mul_f32 v[6:7], v[6:7], v[48:49]
	v_lshlrev_b32_e32 v48, 16, v44
	v_and_b32_e32 v49, 0xffff0000, v44
	v_lshlrev_b32_e32 v34, 16, v72
	v_and_b32_e32 v35, 0xffff0000, v72
	v_lshlrev_b32_e32 v38, 16, v73
	v_and_b32_e32 v39, 0xffff0000, v73
	v_pk_mul_f32 v[48:49], v[66:67], v[48:49]
	v_lshlrev_b32_e32 v66, 16, v18
	v_and_b32_e32 v67, 0xffff0000, v18
	v_pk_mul_f32 v[34:35], v[88:89], v[34:35]
	v_pk_mul_f32 v[38:39], v[90:91], v[38:39]
	v_lshlrev_b32_e32 v44, 16, v45
	v_and_b32_e32 v45, 0xffff0000, v45
	v_pk_mul_f32 v[12:13], v[12:13], v[66:67]
	v_lshlrev_b32_e32 v18, 16, v19
	v_and_b32_e32 v19, 0xffff0000, v19
	v_mov_b32_e32 v66, v188
	s_barrier
; DEV int tid_() { int t = threadIdx.x; asm volatile("" : "+v"(t)); return t; }
; DEV float bflo(unsigned u) { return __uint_as_float(u << 16); }
; DEV float bfhi(unsigned u) { return __uint_as_float(u & 0xffff0000u); }
; #define P (*launderP(lp))
; DEV void stage_tile_bf16(char* smem, const f32x4 (&v)[4][4], u16* buf, int ld, int m0, int col0) {
;   const int tid = tid_(), lane = tid & 63, wid = tid >> 6, wm = wid >> 1, wn = wid & 1, l15 = lane & 15, q = lane >> 4;
; #pragma unroll
;   for (int i = 0; i < 4; ++i)
; #pragma unroll
;     for (int j = 0; j < 4; ++j) {
;       const int rl = wm * 64 + i * 16 + l15, cl = (j & 1) * 16 + wn * 32 + (j >> 1) * 64 + q * 4;
;       u32x2 o; o.x = pack2(v[i][j][0], v[i][j][1]); o.y = pack2(v[i][j][2], v[i][j][3]);
;       *(u32x2*)(smem + rl * 272 + cl * 2) = o;
;     }
;   __syncthreads();
; __device__ __forceinline__ void phase_gemm45(PREF P, char* smem, int which) {
;     ...
; #pragma unroll
;       for (int i = 0; i < 4; ++i)
; #pragma unroll
;         for (int j = 0; j < 4; ++j) {
;           const int row = m0 + wm * 64 + i * 16 + l15, col = n0 + (j & 1) * 16 + wn * 32 + (j >> 1) * 64 + q * 4;
;           f32x4 v;
;           v[0] = bflo(part[i][j][0]) * acc[i][j][0]; v[1] = bfhi(part[i][j][0]) * acc[i][j][1];
;           v[2] = bflo(part[i][j][1]) * acc[i][j][2]; v[3] = bfhi(part[i][j][1]) * acc[i][j][3];
;           acc[i][j] = v;
;         }
;       stage_tile_bf16(smem, acc, P.peb, 2048, m0, n0);
	v_lshlrev_b32_e32 v42, 16, v74
	v_and_b32_e32 v43, 0xffff0000, v74
	v_lshlrev_b32_e32 v46, 16, v75
	v_and_b32_e32 v47, 0xffff0000, v75
	v_pk_mul_f32 v[44:45], v[68:69], v[44:45]
	v_pk_mul_f32 v[14:15], v[14:15], v[18:19]
	ds_read_b64 v[18:19], v80 offset:360
	s_mov_b32 s5, 0xfffffc0
	v_and_b32_e32 v67, 15, v66
	v_lshrrev_b32_e32 v68, 1, v66
	v_cvt_pk_bf16_f32 v34, v34, v35
	v_cvt_pk_bf16_f32 v35, v38, v39
	v_and_b32_e32 v38, 64, v66
	v_pk_mul_f32 v[42:43], v[100:101], v[42:43]
	v_pk_mul_f32 v[46:47], v[102:103], v[46:47]
	v_lshlrev_b32_e32 v50, 16, v76
	v_and_b32_e32 v51, 0xffff0000, v76
	v_lshlrev_b32_e32 v54, 16, v77
	v_and_b32_e32 v55, 0xffff0000, v77
	v_and_or_b32 v69, v68, s5, v67
	v_and_or_b32 v38, v68, 24, v38
	v_pk_mul_f32 v[50:51], v[104:105], v[50:51]
	v_pk_mul_f32 v[54:55], v[106:107], v[54:55]
	v_lshlrev_b32_e32 v56, 16, v57
	v_and_b32_e32 v57, 0xffff0000, v57
	v_mad_u64_u32 v[38:39], s[14:15], v69, s11, v[38:39]
	v_cvt_pk_bf16_f32 v42, v42, v43
	v_cvt_pk_bf16_f32 v43, v46, v47
	v_pk_mul_f32 v[30:31], v[30:31], v[56:57]
	v_lshlrev_b32_e32 v56, 16, v52
	v_and_b32_e32 v57, 0xffff0000, v52
	v_lshlrev_b32_e32 v52, 16, v53
	v_and_b32_e32 v53, 0xffff0000, v53
	ds_write2_b64 v38, v[34:35], v[42:43] offset1:4
	v_cvt_pk_bf16_f32 v34, v50, v51
	v_cvt_pk_bf16_f32 v35, v54, v55
	v_cvt_pk_bf16_f32 v0, v0, v1
	v_cvt_pk_bf16_f32 v1, v2, v3
	v_pk_mul_f32 v[56:57], v[108:109], v[56:57]
	v_pk_mul_f32 v[52:53], v[110:111], v[52:53]
	v_pk_mul_f32 v[4:5], v[4:5], v[58:59]
	v_lshlrev_b32_e32 v58, 16, v40
	v_and_b32_e32 v59, 0xffff0000, v40
	v_lshlrev_b32_e32 v40, 16, v41
	v_and_b32_e32 v41, 0xffff0000, v41
	ds_write2_b64 v38, v[34:35], v[0:1] offset0:16 offset1:20
	v_cvt_pk_bf16_f32 v0, v24, v25
	v_cvt_pk_bf16_f32 v1, v26, v27
	v_cvt_pk_bf16_f32 v2, v28, v29
	v_cvt_pk_bf16_f32 v3, v30, v31
	v_add_u32_e32 v24, 0x1000, v38
	v_pk_mul_f32 v[58:59], v[112:113], v[58:59]
	v_pk_mul_f32 v[40:41], v[114:115], v[40:41]
	v_lshlrev_b32_e32 v60, 16, v36
	v_and_b32_e32 v61, 0xffff0000, v36
	v_lshlrev_b32_e32 v36, 16, v37
	v_and_b32_e32 v37, 0xffff0000, v37
	v_lshlrev_b32_e32 v62, 16, v32
	v_and_b32_e32 v63, 0xffff0000, v32
	v_lshlrev_b32_e32 v32, 16, v33
	v_and_b32_e32 v33, 0xffff0000, v33
	ds_write2_b64 v24, v[0:1], v[2:3] offset0:32 offset1:36
	v_cvt_pk_bf16_f32 v0, v56, v57
	v_cvt_pk_bf16_f32 v1, v52, v53
	v_cvt_pk_bf16_f32 v2, v4, v5
	v_cvt_pk_bf16_f32 v3, v6, v7
	v_pk_mul_f32 v[60:61], v[116:117], v[60:61]
	v_pk_mul_f32 v[36:37], v[118:119], v[36:37]
	v_pk_mul_f32 v[8:9], v[8:9], v[62:63]
	v_pk_mul_f32 v[10:11], v[10:11], v[32:33]
	v_lshlrev_b32_e32 v32, 16, v20
	v_and_b32_e32 v33, 0xffff0000, v20
	v_lshlrev_b32_e32 v20, 16, v21
	v_and_b32_e32 v21, 0xffff0000, v21
	v_lshlrev_b32_e32 v62, 16, v22
	v_and_b32_e32 v63, 0xffff0000, v22
	v_lshlrev_b32_e32 v22, 16, v23
	v_and_b32_e32 v23, 0xffff0000, v23
	ds_write2_b64 v24, v[0:1], v[2:3] offset0:48 offset1:52
	v_cvt_pk_bf16_f32 v0, v48, v49
	v_cvt_pk_bf16_f32 v1, v44, v45
	v_cvt_pk_bf16_f32 v2, v58, v59
	v_cvt_pk_bf16_f32 v3, v40, v41
	v_add_u32_e32 v4, 0x2000, v38
	v_pk_mul_f32 v[32:33], v[84:85], v[32:33]
	v_pk_mul_f32 v[20:21], v[86:87], v[20:21]
	v_pk_mul_f32 v[62:63], v[92:93], v[62:63]
	v_pk_mul_f32 v[22:23], v[94:95], v[22:23]
	v_lshlrev_b32_e32 v64, 16, v16
	v_and_b32_e32 v65, 0xffff0000, v16
	v_lshlrev_b32_e32 v16, 16, v17
	v_and_b32_e32 v17, 0xffff0000, v17
	ds_write2_b64 v4, v[0:1], v[2:3] offset0:64 offset1:68
	v_cvt_pk_bf16_f32 v0, v60, v61
	v_cvt_pk_bf16_f32 v1, v36, v37
	v_cvt_pk_bf16_f32 v2, v8, v9
	v_cvt_pk_bf16_f32 v3, v10, v11
	v_pk_mul_f32 v[64:65], v[96:97], v[64:65]
	v_pk_mul_f32 v[16:17], v[98:99], v[16:17]
	ds_write2_b64 v4, v[0:1], v[2:3] offset0:80 offset1:84
	v_cvt_pk_bf16_f32 v0, v32, v33
	v_cvt_pk_bf16_f32 v1, v20, v21
	v_cvt_pk_bf16_f32 v2, v62, v63
	v_cvt_pk_bf16_f32 v3, v22, v23
	v_add_u32_e32 v4, 0x3000, v38
	ds_write2_b64 v4, v[0:1], v[2:3] offset0:96 offset1:100
	v_cvt_pk_bf16_f32 v0, v64, v65
	v_cvt_pk_bf16_f32 v1, v16, v17
	v_cvt_pk_bf16_f32 v2, v12, v13
	v_cvt_pk_bf16_f32 v3, v14, v15
	s_ashr_i32 s5, s4, 31
	ds_write2_b64 v4, v[0:1], v[2:3] offset0:112 offset1:116
	v_lshlrev_b32_e32 v180, 4, v67
	s_waitcnt lgkmcnt(8)
	v_lshl_add_u64 v[0:1], s[4:5], 1, v[18:19]
	v_ashrrev_i32_e32 v6, 4, v66
	v_lshl_add_u64 v[4:5], v[0:1], 0, v[180:181]
	v_mad_u64_u32 v[0:1], s[4:5], v6, s11, v[180:181]
	s_waitcnt lgkmcnt(0)
	s_barrier
; DEV int bid_() { int t = blockIdx.x; asm volatile("" : "+s"(t)); return t; }
; DEV int gdim_() { int t = gridDim.x; asm volatile("" : "+s"(t)); return t; }
; DEV void stage_tile_bf16(char* smem, const f32x4 (&v)[4][4], u16* buf, int ld, int m0, int col0) {
;     ...
; #pragma unroll
;   for (int k = 0; k < 8; ++k) {
;     const int chunk = tid + 256 * k, rl = chunk >> 4, c16 = chunk & 15;
;     u32x4 d = *(const u32x4*)(smem + rl * 272 + c16 * 16);
;     *(u32x4*)(buf + (size_t)(m0 + rl) * ld + col0 + c16 * 8) = d;
;   }
; __device__ __forceinline__ void phase_gemm45(PREF P, char* smem, int which) {
;     ...
;   for (int t = bid_(); t < 64 * 16; t += gdim_()) {
	ds_read_b128 v[0:3], v0
	v_add_u32_e32 v6, s17, v6
	v_ashrrev_i32_e32 v7, 31, v6
	v_lshlrev_b64 v[6:7], 12, v[6:7]
	v_lshl_add_u64 v[6:7], v[4:5], 0, v[6:7]
	s_waitcnt lgkmcnt(0)
	flat_store_dwordx4 v[6:7], v[0:3]
	s_nop 1
	v_add_u32_e32 v0, 0x100, v66
	v_ashrrev_i32_e32 v6, 4, v0
	v_mad_u64_u32 v[0:1], s[4:5], v6, s11, v[180:181]
	ds_read_b128 v[0:3], v0
	v_add_u32_e32 v6, s17, v6
	v_ashrrev_i32_e32 v7, 31, v6
	v_lshlrev_b64 v[6:7], 12, v[6:7]
	v_lshl_add_u64 v[6:7], v[4:5], 0, v[6:7]
	s_waitcnt lgkmcnt(0)
	flat_store_dwordx4 v[6:7], v[0:3]
	s_nop 1
	v_add_u32_e32 v0, 0x200, v66
	v_ashrrev_i32_e32 v6, 4, v0
	v_mad_u64_u32 v[0:1], s[4:5], v6, s11, v[180:181]
	ds_read_b128 v[0:3], v0
	v_add_u32_e32 v6, s17, v6
	v_ashrrev_i32_e32 v7, 31, v6
	v_lshlrev_b64 v[6:7], 12, v[6:7]
	v_lshl_add_u64 v[6:7], v[4:5], 0, v[6:7]
	s_waitcnt lgkmcnt(0)
	flat_store_dwordx4 v[6:7], v[0:3]
	s_nop 1
	v_add_u32_e32 v0, 0x300, v66
	v_ashrrev_i32_e32 v6, 4, v0
	v_mad_u64_u32 v[0:1], s[4:5], v6, s11, v[180:181]
	ds_read_b128 v[0:3], v0
	v_add_u32_e32 v6, s17, v6
	v_ashrrev_i32_e32 v7, 31, v6
	v_lshlrev_b64 v[6:7], 12, v[6:7]
	v_lshl_add_u64 v[6:7], v[4:5], 0, v[6:7]
	s_waitcnt lgkmcnt(0)
	flat_store_dwordx4 v[6:7], v[0:3]
	s_nop 1
	v_add_u32_e32 v0, 0x400, v66
	v_ashrrev_i32_e32 v6, 4, v0
	v_mad_u64_u32 v[0:1], s[4:5], v6, s11, v[180:181]
	ds_read_b128 v[0:3], v0
	v_add_u32_e32 v6, s17, v6
	v_ashrrev_i32_e32 v7, 31, v6
	v_lshlrev_b64 v[6:7], 12, v[6:7]
	v_lshl_add_u64 v[6:7], v[4:5], 0, v[6:7]
	s_waitcnt lgkmcnt(0)
	flat_store_dwordx4 v[6:7], v[0:3]
	s_nop 1
	v_add_u32_e32 v0, 0x500, v66
	v_ashrrev_i32_e32 v6, 4, v0
	v_mad_u64_u32 v[0:1], s[4:5], v6, s11, v[180:181]
	ds_read_b128 v[0:3], v0
	v_add_u32_e32 v6, s17, v6
	v_ashrrev_i32_e32 v7, 31, v6
	v_lshlrev_b64 v[6:7], 12, v[6:7]
	v_lshl_add_u64 v[6:7], v[4:5], 0, v[6:7]
	s_waitcnt lgkmcnt(0)
	flat_store_dwordx4 v[6:7], v[0:3]
	s_nop 1
	v_add_u32_e32 v0, 0x600, v66
	v_ashrrev_i32_e32 v6, 4, v0
	v_mad_u64_u32 v[0:1], s[4:5], v6, s11, v[180:181]
	ds_read_b128 v[0:3], v0
	v_add_u32_e32 v6, s17, v6
	v_ashrrev_i32_e32 v7, 31, v6
	v_lshlrev_b64 v[6:7], 12, v[6:7]
	v_lshl_add_u64 v[6:7], v[4:5], 0, v[6:7]
	s_waitcnt lgkmcnt(0)
	flat_store_dwordx4 v[6:7], v[0:3]
	s_nop 1
	v_add_u32_e32 v0, 0x700, v66
	v_ashrrev_i32_e32 v6, 4, v0
	v_mad_u64_u32 v[0:1], s[4:5], v6, s11, v[180:181]
	ds_read_b128 v[0:3], v0
	v_add_u32_e32 v6, s17, v6
	v_ashrrev_i32_e32 v7, 31, v6
	v_lshlrev_b64 v[6:7], 12, v[6:7]
	v_lshl_add_u64 v[4:5], v[4:5], 0, v[6:7]
	v_readlane_b32 s4, v251, 6
	s_waitcnt lgkmcnt(0)
	flat_store_dwordx4 v[4:5], v[0:3]
	s_add_i32 s16, s4, s16
	s_cmpk_gt_i32 s16, 0x3ff
	v_readlane_b32 s5, v251, 7
	s_cbranch_scc0 .LBB0_623
	s_branch .LBB0_616

; DEV int tid_() { int t = threadIdx.x; asm volatile("" : "+v"(t)); return t; }
; DEV int rowmap(int p, int Sshift, int dl) {
;   int seq = p >> Sshift, pp = p & ((1 << Sshift) - 1);
;   int Lshift = Sshift - dl;
;   int r = pp >> Lshift, l = pp & ((1 << Lshift) - 1);
;   return (seq << Sshift) + (l << dl) + r;
; }
; template <class FragT, class AccT>
; DEV void gemm_core_t(const char* __restrict__ A, size_t lda_bytes, const char* __restrict__ Bt, size_t ldb_bytes, int kbytes,
;                      int m0, int n0, int Sshift, int dl, char* smem, AccT (&acc)[4][4]) {
;   const int tid = tid_(), lane = tid & 63, wid = tid >> 6, wm = wid >> 1, wn = wid & 1;
;   const int l15 = lane & 15, q = lane >> 4;
;   const int srow = lane >> 3, schunk = (lane & 7) ^ (lane >> 3);
;   const char* ap[4];
;   const char* bp[4];
; #pragma unroll
;   for (int u = 0; u < 4; ++u) {
;     int r = (wid * 4 + u) * 8 + srow;
;     int ar = rowmap(m0 + r, Sshift, dl);
;     ap[u] = A + (size_t)ar * lda_bytes + schunk * 16;
;     bp[u] = Bt + (size_t)(n0 + r) * ldb_bytes + schunk * 16;
;   }
; #pragma unroll
;   for (int i = 0; i < 4; ++i)
; #pragma unroll
;     for (int j = 0; j < 4; ++j) acc[i][j] = AccT{0, 0, 0, 0};
;   const int nk = kbytes >> 7;
;   __syncthreads();
; #pragma unroll
;   for (int u = 0; u < 4; ++u) {
;     __builtin_amdgcn_global_load_lds((const unsigned*)ap[u], (unsigned*)(smem + (wid * 4 + u) * 1024 + lane * 16), 16, 0, 0);
;     __builtin_amdgcn_global_load_lds((const unsigned*)bp[u], (unsigned*)(smem + 16384 + (wid * 4 + u) * 1024 + lane * 16), 16, 0, 0);
;   }
;   const unsigned sbase = (unsigned)(unsigned long)((__attribute__((address_space(3))) char*)smem);
;   const unsigned sq0 = (unsigned)((q ^ (l15 & 7)) << 4);
;   const unsigned a0 = sbase + (unsigned)((wm * 64 + l15) * 128) + sq0;
;   const unsigned b0 = sbase + 16384u + (unsigned)((wn * 32 + l15) * 128) + sq0;
;   asm volatile("s_waitcnt vmcnt(0)" ::: "memory");
;   __syncthreads();
.LBB0_733:
	v_mov_b32_e32 v30, v188
	ds_read2_b64 v[0:3], v79 offset0:57 offset1:58
	s_lshl_b32 s18, s18, 7
	v_ashrrev_i32_e32 v32, 6, v30
	v_bfe_u32 v33, v30, 3, 3
	v_lshlrev_b32_e32 v34, 5, v32
	s_lshl_b32 s17, s17, 10
	s_and_b32 s18, s18, 0x380
	v_or_b32_e32 v26, v34, v33
	s_or_b32 s36, s18, s17
	s_sub_i32 s17, s31, s6
	v_or_b32_e32 v18, 8, v26
	v_or_b32_e32 v24, 16, v26
	v_or_b32_e32 v28, 24, v26
	s_lshl_b32 s37, -1, s17
	v_add_u32_e32 v8, s36, v26
	v_mov_b32_e32 v27, s51
	v_add_u32_e32 v12, s40, v26
	v_add_u32_e32 v14, s36, v18
	v_add_u32_e32 v20, s36, v24
	v_add_u32_e32 v26, s36, v28
	v_bitop3_b32 v10, v8, s37, v27 bitop3:0x20
	v_bitop3_b32 v16, v14, s37, v27 bitop3:0x20
	v_bitop3_b32 v22, v20, s37, v27 bitop3:0x20
	v_and_b32_e32 v29, s51, v26
	v_bitop3_b32 v27, v26, s37, v27 bitop3:0x20
	v_bitop3_b32 v4, v33, v30, 7 bitop3:0x78
	v_add_u32_e32 v18, s40, v18
	v_add_u32_e32 v24, s40, v24
	v_lshrrev_b32_e32 v29, s17, v29
	v_and_b32_e32 v26, s50, v26
	v_lshlrev_b32_e32 v27, s6, v27
	v_add_u32_e32 v28, s40, v28
	v_lshlrev_b32_e32 v180, 4, v4
	v_and_b32_e32 v9, s51, v8
	v_ashrrev_i32_e32 v13, 31, v12
	v_ashrrev_i32_e32 v19, 31, v18
	v_ashrrev_i32_e32 v25, 31, v24
	v_add3_u32 v26, v29, v26, v27
	v_ashrrev_i32_e32 v29, 31, v28
	s_waitcnt lgkmcnt(0)
	v_lshl_add_u64 v[6:7], v[2:3], 0, v[180:181]
	v_lshrrev_b32_e32 v9, s17, v9
	v_and_b32_e32 v8, s50, v8
	v_lshlrev_b32_e32 v10, s6, v10
	v_lshlrev_b64 v[12:13], 11, v[12:13]
	v_lshlrev_b64 v[18:19], 11, v[18:19]
	v_lshlrev_b64 v[24:25], 11, v[24:25]
	v_lshlrev_b64 v[28:29], 11, v[28:29]
	v_and_b32_e32 v31, 63, v30
	v_add3_u32 v8, v9, v8, v10
	v_lshl_add_u64 v[12:13], v[6:7], 0, v[12:13]
	v_lshl_add_u64 v[18:19], v[6:7], 0, v[18:19]
	v_lshl_add_u64 v[24:25], v[6:7], 0, v[24:25]
	v_lshl_add_u64 v[6:7], v[6:7], 0, v[28:29]
	v_lshlrev_b32_e32 v28, 12, v32
	v_ashrrev_i32_e32 v9, 31, v8
	v_lshl_or_b32 v81, v31, 4, v28
	s_not_b32 s18, s37
	v_lshl_add_u64 v[4:5], v[0:1], 0, v[180:181]
	v_lshlrev_b64 v[8:9], 11, v[8:9]
	v_and_b32_e32 v15, s51, v14
	v_readfirstlane_b32 s37, v81
	v_lshl_add_u64 v[10:11], v[4:5], 0, v[8:9]
	v_lshrrev_b32_e32 v15, s17, v15
	v_and_b32_e32 v14, s50, v14
	v_lshlrev_b32_e32 v16, s6, v16
	s_mov_b32 m0, s37
	v_add3_u32 v14, v15, v14, v16
	v_and_b32_e32 v21, s51, v20
	s_barrier
	global_load_lds_dwordx4 v[10:11], off
	v_add_u32_e32 v10, 0x4000, v81
	v_ashrrev_i32_e32 v15, 31, v14
	v_lshrrev_b32_e32 v21, s17, v21
	v_and_b32_e32 v20, s50, v20
	v_lshlrev_b32_e32 v22, s6, v22
	v_readfirstlane_b32 s37, v10
	v_or_b32_e32 v10, 0x400, v81
	v_lshlrev_b64 v[14:15], 11, v[14:15]
	v_add3_u32 v20, v21, v20, v22
	s_mov_b32 m0, s37
	v_readfirstlane_b32 s37, v10
	v_add_u32_e32 v10, 0x4400, v81
	v_lshl_add_u64 v[16:17], v[4:5], 0, v[14:15]
	v_ashrrev_i32_e32 v21, 31, v20
	global_load_lds_dwordx4 v[12:13], off
	s_mov_b32 m0, s37
	v_readfirstlane_b32 s37, v10
	v_or_b32_e32 v10, 0x800, v81
	v_lshlrev_b64 v[20:21], 11, v[20:21]
	global_load_lds_dwordx4 v[16:17], off
	s_mov_b32 m0, s37
	v_readfirstlane_b32 s37, v10
	v_add_u32_e32 v10, 0x4800, v81
	v_lshl_add_u64 v[22:23], v[4:5], 0, v[20:21]
	v_ashrrev_i32_e32 v27, 31, v26
	global_load_lds_dwordx4 v[18:19], off
	s_mov_b32 m0, s37
	v_readfirstlane_b32 s37, v10
	v_or_b32_e32 v10, 0xc00, v81
	v_lshlrev_b64 v[26:27], 11, v[26:27]
	global_load_lds_dwordx4 v[22:23], off
	s_mov_b32 m0, s37
	v_readfirstlane_b32 s37, v10
	v_lshl_add_u64 v[4:5], v[4:5], 0, v[26:27]
	global_load_lds_dwordx4 v[24:25], off
	s_mov_b32 m0, s37
	s_mulk_i32 s19, 0x980
	global_load_lds_dwordx4 v[4:5], off
	v_add_u32_e32 v4, 0x4c00, v81
	v_lshlrev_b32_e32 v5, 4, v30
	v_readfirstlane_b32 s37, v4
	s_mov_b32 m0, s37
	v_and_b32_e32 v4, 15, v30
	global_load_lds_dwordx4 v[6:7], off
	v_lshrrev_b32_e32 v6, 1, v30
	s_mov_b32 s37, 0x1ffffc0
	v_bitop3_b32 v5, v31, s56, v5 bitop3:0x48
	v_and_or_b32 v6, v6, s37, v4
	v_and_or_b32 v4, v34, 32, v4
	s_lshl_b32 s37, s41, 7
	v_lshl_or_b32 v4, v4, 7, v5
	s_add_i32 s37, s37, s19
	v_or_b32_e32 v85, 0x4000, v4
	v_bitop3_b32 v86, v4, 64, v219 bitop3:0x36
	v_or_b32_e32 v4, s37, v33
	v_lshlrev_b32_e32 v6, 7, v6
	v_add_u32_e32 v4, v4, v34
	v_or_b32_e32 v84, v5, v6
	v_bitop3_b32 v87, v5, 64, v6 bitop3:0x36
	v_or_b32_e32 v6, 24, v4
	v_ashrrev_i32_e32 v7, 31, v6
	s_mov_b64 s[44:45], 0x80
	v_lshlrev_b64 v[6:7], 11, v[6:7]
	v_lshl_add_u64 v[2:3], v[2:3], 0, s[44:45]
	v_or_b32_e32 v6, v6, v180
	v_lshl_add_u64 v[64:65], v[2:3], 0, v[6:7]
	v_or_b32_e32 v6, 16, v4
	v_ashrrev_i32_e32 v7, 31, v6
	v_lshlrev_b64 v[6:7], 11, v[6:7]
	v_or_b32_e32 v6, v6, v180
	v_lshl_add_u64 v[68:69], v[2:3], 0, v[6:7]
	v_or_b32_e32 v6, 8, v4
	v_ashrrev_i32_e32 v7, 31, v6
	v_ashrrev_i32_e32 v5, 31, v4
	v_lshl_add_u64 v[0:1], v[0:1], 0, s[44:45]
	v_or_b32_e32 v26, v26, v180
	v_or_b32_e32 v20, v20, v180
	v_lshlrev_b64 v[6:7], 11, v[6:7]
	v_or_b32_e32 v14, v14, v180
	v_lshlrev_b64 v[4:5], 11, v[4:5]
	v_or_b32_e32 v8, v8, v180
	v_lshl_add_u64 v[66:67], v[0:1], 0, v[26:27]
	v_lshl_add_u64 v[70:71], v[0:1], 0, v[20:21]
	v_or_b32_e32 v6, v6, v180
	v_lshl_add_u64 v[74:75], v[0:1], 0, v[14:15]
	v_or_b32_e32 v4, v4, v180
	v_lshl_add_u64 v[82:83], v[0:1], 0, v[8:9]
	v_mov_b32_e32 v0, 0
	v_lshl_add_u64 v[72:73], v[2:3], 0, v[6:7]
	v_lshl_add_u64 v[76:77], v[2:3], 0, v[4:5]
	s_mov_b64 s[44:45], 0
	s_mov_b32 s19, 0x8000
	v_mov_b32_e32 v1, v0
	v_mov_b32_e32 v2, v0
	v_mov_b32_e32 v3, v0
	v_mov_b32_e32 v4, v0
	v_mov_b32_e32 v5, v0
	v_mov_b32_e32 v6, v0
	v_mov_b32_e32 v7, v0
	v_mov_b32_e32 v8, v0
	v_mov_b32_e32 v9, v0
	v_mov_b32_e32 v10, v0
	v_mov_b32_e32 v11, v0
	v_mov_b32_e32 v12, v0
	v_mov_b32_e32 v13, v0
	v_mov_b32_e32 v14, v0
	v_mov_b32_e32 v15, v0
	v_mov_b32_e32 v16, v0
	v_mov_b32_e32 v17, v0
	v_mov_b32_e32 v18, v0
; DEV f32x4 mma_step(bf16x8 a, bf16x8 b, f32x4 c) { return MFMA(a, b, c); }
; template <class FragT, class AccT>
; DEV void gemm_core_t(const char* __restrict__ A, size_t lda_bytes, const char* __restrict__ Bt, size_t ldb_bytes, int kbytes,
;                      int m0, int n0, int Sshift, int dl, char* smem, AccT (&acc)[4][4]) {
;     ...
;   for (int kt = 0; kt < nk; ++kt) {
;     const unsigned so = (unsigned)(kt & 1) * 32768u;
;     char* nxt = smem + ((kt + 1) & 1) * 32768;
;     if (kt + 1 < nk) {
; #pragma unroll
;       for (int u = 0; u < 4; ++u) {
;         __builtin_amdgcn_global_load_lds((const unsigned*)(ap[u] + (size_t)(kt + 1) * 128), (unsigned*)(nxt + (wid * 4 + u) * 1024 + lane * 16), 16, 0, 0);
;         __builtin_amdgcn_global_load_lds((const unsigned*)(bp[u] + (size_t)(kt + 1) * 128), (unsigned*)(nxt + 16384 + (wid * 4 + u) * 1024 + lane * 16), 16, 0, 0);
;       }
;     }
;     FragT xa[2][4], wb[2][4];
;     asm volatile(
;         "ds_read_b128 %0, %16\n\t"
;         "ds_read_b128 %1, %16 offset:2048\n\t"
;         "ds_read_b128 %2, %16 offset:4096\n\t"
;         "ds_read_b128 %3, %16 offset:6144\n\t"
;         "ds_read_b128 %4, %18\n\t"
;         "ds_read_b128 %5, %18 offset:2048\n\t"
;         "ds_read_b128 %6, %18 offset:8192\n\t"
;         "ds_read_b128 %7, %18 offset:10240\n\t"
;         "ds_read_b128 %8, %17\n\t"
;         "ds_read_b128 %9, %17 offset:2048\n\t"
;         "ds_read_b128 %10, %17 offset:4096\n\t"
;         "ds_read_b128 %11, %17 offset:6144\n\t"
;         "ds_read_b128 %12, %19\n\t"
;         "ds_read_b128 %13, %19 offset:2048\n\t"
;         "ds_read_b128 %14, %19 offset:8192\n\t"
;         "ds_read_b128 %15, %19 offset:10240\n\t"
;         "s_waitcnt lgkmcnt(8)"
;         : "=&v"(xa[0][0]), "=&v"(xa[0][1]), "=&v"(xa[0][2]), "=&v"(xa[0][3]), "=&v"(wb[0][0]), "=&v"(wb[0][1]), "=&v"(wb[0][2]),
;           "=&v"(wb[0][3]), "=&v"(xa[1][0]), "=&v"(xa[1][1]), "=&v"(xa[1][2]), "=&v"(xa[1][3]), "=&v"(wb[1][0]), "=&v"(wb[1][1]),
;           "=&v"(wb[1][2]), "=&v"(wb[1][3])
;         : "v"(a0 + so), "v"((a0 ^ 64u) + so), "v"(b0 + so), "v"((b0 ^ 64u) + so)
;         : "memory");
;     __builtin_amdgcn_s_setprio(1);
; #pragma unroll
;     for (int i = 0; i < 4; ++i)
; #pragma unroll
;       for (int j = 0; j < 4; ++j) acc[i][j] = mma_step(wb[0][j], xa[0][i], acc[i][j]);
;     asm volatile("s_waitcnt lgkmcnt(0)"
	v_mov_b32_e32 v19, v0
	v_mov_b32_e32 v20, v0
	v_mov_b32_e32 v21, v0
	v_mov_b32_e32 v22, v0
	v_mov_b32_e32 v23, v0
	v_mov_b32_e32 v24, v0
	v_mov_b32_e32 v25, v0
	v_mov_b32_e32 v26, v0
	v_mov_b32_e32 v27, v0
	v_mov_b32_e32 v28, v0
	v_mov_b32_e32 v29, v0
	v_mov_b32_e32 v30, v0
	v_mov_b32_e32 v31, v0
	v_mov_b32_e32 v32, v0
	v_mov_b32_e32 v33, v0
	v_mov_b32_e32 v34, v0
	v_mov_b32_e32 v35, v0
	v_mov_b32_e32 v36, v0
	v_mov_b32_e32 v37, v0
	v_mov_b32_e32 v38, v0
	v_mov_b32_e32 v39, v0
	v_mov_b32_e32 v40, v0
	v_mov_b32_e32 v41, v0
	v_mov_b32_e32 v42, v0
	v_mov_b32_e32 v43, v0
	v_mov_b32_e32 v44, v0
	v_mov_b32_e32 v45, v0
	v_mov_b32_e32 v46, v0
	v_mov_b32_e32 v47, v0
	v_mov_b32_e32 v48, v0
	v_mov_b32_e32 v49, v0
	v_mov_b32_e32 v50, v0
	v_mov_b32_e32 v51, v0
	v_mov_b32_e32 v52, v0
	v_mov_b32_e32 v53, v0
	v_mov_b32_e32 v54, v0
	v_mov_b32_e32 v55, v0
	v_mov_b32_e32 v56, v0
	v_mov_b32_e32 v57, v0
	v_mov_b32_e32 v58, v0
	v_mov_b32_e32 v59, v0
	v_mov_b32_e32 v60, v0
	v_mov_b32_e32 v61, v0
	v_mov_b32_e32 v62, v0
	v_mov_b32_e32 v63, v0
	v_readfirstlane_b32 s64, v82
	v_readfirstlane_b32 s65, v83
	v_readfirstlane_b32 s66, v76
	v_readfirstlane_b32 s67, v77
	v_readfirstlane_b32 s62, v81
	s_sub_u32 s64, s64, 0x80000000
	s_subb_u32 s65, s65, 0
	s_sub_u32 s66, s66, 0x80000000
	s_subb_u32 s67, s67, 0
	v_subrev_u32_e32 v82, s64, v82
	v_subrev_u32_e32 v76, s66, v76
	v_subrev_u32_e32 v74, s64, v74
	v_subrev_u32_e32 v72, s66, v72
	v_subrev_u32_e32 v70, s64, v70
	v_subrev_u32_e32 v68, s66, v68
	v_subrev_u32_e32 v66, s64, v66
	v_subrev_u32_e32 v64, s66, v64
	s_waitcnt vmcnt(0) lgkmcnt(0)
	s_barrier
.LBB0_734:
	s_add_i32 s37, s19, 0xffff8000
	s_and_b32 s37, s37, 0x8000
	v_add_u32_e32 v92, s37, v84
	v_add_u32_e32 v93, s37, v87
	v_or_b32_e32 v99, s37, v85
	v_or_b32_e32 v160, s37, v86
	s_and_b32 s37, s19, 0x8000
	s_add_i32 s37, s37, s62
	s_mov_b32 m0, s37
	ds_read_b128 v[88:91], v92
	global_load_lds_dwordx4 v82, s[64:65]
	ds_read_b128 v[100:103], v92 offset:2048
	s_add_i32 m0, s37, 0x4000
	ds_read_b128 v[104:107], v92 offset:4096
	global_load_lds_dwordx4 v76, s[66:67]
	ds_read_b128 v[108:111], v92 offset:6144
	s_add_i32 m0, s37, 0x400
	ds_read_b128 v[112:115], v99
	global_load_lds_dwordx4 v74, s[64:65]
	ds_read_b128 v[116:119], v99 offset:2048
	s_add_i32 m0, s37, 0x4400
	ds_read_b128 v[120:123], v99 offset:8192
	global_load_lds_dwordx4 v72, s[66:67]
	ds_read_b128 v[124:127], v99 offset:10240
	ds_read_b128 v[128:131], v93
	ds_read_b128 v[132:135], v93 offset:2048
	ds_read_b128 v[136:139], v93 offset:4096
	ds_read_b128 v[140:143], v93 offset:6144
	ds_read_b128 v[144:147], v160
	ds_read_b128 v[148:151], v160 offset:2048
	ds_read_b128 v[152:155], v160 offset:8192
	ds_read_b128 v[156:159], v160 offset:10240
	s_waitcnt lgkmcnt(8)
	s_setprio 1
	v_mfma_i32_16x16x64_i8 v[60:63], v[112:115], v[88:91], v[60:63]
	v_mfma_i32_16x16x64_i8 v[56:59], v[116:119], v[88:91], v[56:59]
	s_add_i32 m0, s37, 0x800
	v_mfma_i32_16x16x64_i8 v[52:55], v[120:123], v[88:91], v[52:55]
	global_load_lds_dwordx4 v70, s[64:65]
	v_mfma_i32_16x16x64_i8 v[48:51], v[124:127], v[88:91], v[48:51]
	v_mfma_i32_16x16x64_i8 v[44:47], v[112:115], v[100:103], v[44:47]
	v_mfma_i32_16x16x64_i8 v[40:43], v[116:119], v[100:103], v[40:43]
	s_add_i32 m0, s37, 0x4800
	v_mfma_i32_16x16x64_i8 v[36:39], v[120:123], v[100:103], v[36:39]
	global_load_lds_dwordx4 v68, s[66:67]
	v_mfma_i32_16x16x64_i8 v[32:35], v[124:127], v[100:103], v[32:35]
	v_mfma_i32_16x16x64_i8 v[28:31], v[112:115], v[104:107], v[28:31]
	v_mfma_i32_16x16x64_i8 v[24:27], v[116:119], v[104:107], v[24:27]
	s_add_i32 m0, s37, 0xc00
	v_mfma_i32_16x16x64_i8 v[20:23], v[120:123], v[104:107], v[20:23]
	global_load_lds_dwordx4 v66, s[64:65]
	v_mfma_i32_16x16x64_i8 v[16:19], v[124:127], v[104:107], v[16:19]
	v_mfma_i32_16x16x64_i8 v[12:15], v[112:115], v[108:111], v[12:15]
	v_mfma_i32_16x16x64_i8 v[8:11], v[116:119], v[108:111], v[8:11]
	s_add_i32 m0, s37, 0x4c00
	v_mfma_i32_16x16x64_i8 v[4:7], v[120:123], v[108:111], v[4:7]
	global_load_lds_dwordx4 v64, s[66:67]
	v_mfma_i32_16x16x64_i8 v[0:3], v[124:127], v[108:111], v[0:3]
	s_waitcnt lgkmcnt(0)
	s_nop 0
	v_mfma_i32_16x16x64_i8 v[60:63], v[144:147], v[128:131], v[60:63]
	v_mfma_i32_16x16x64_i8 v[56:59], v[148:151], v[128:131], v[56:59]
	v_mfma_i32_16x16x64_i8 v[52:55], v[152:155], v[128:131], v[52:55]
	v_mfma_i32_16x16x64_i8 v[48:51], v[156:159], v[128:131], v[48:51]
	v_mfma_i32_16x16x64_i8 v[44:47], v[144:147], v[132:135], v[44:47]
	v_mfma_i32_16x16x64_i8 v[40:43], v[148:151], v[132:135], v[40:43]
	v_mfma_i32_16x16x64_i8 v[36:39], v[152:155], v[132:135], v[36:39]
	v_mfma_i32_16x16x64_i8 v[32:35], v[156:159], v[132:135], v[32:35]
	v_mfma_i32_16x16x64_i8 v[28:31], v[144:147], v[136:139], v[28:31]
	v_mfma_i32_16x16x64_i8 v[24:27], v[148:151], v[136:139], v[24:27]
	v_mfma_i32_16x16x64_i8 v[20:23], v[152:155], v[136:139], v[20:23]
	v_mfma_i32_16x16x64_i8 v[16:19], v[156:159], v[136:139], v[16:19]
	v_mfma_i32_16x16x64_i8 v[12:15], v[144:147], v[140:143], v[12:15]
	v_mfma_i32_16x16x64_i8 v[8:11], v[148:151], v[140:143], v[8:11]
	v_mfma_i32_16x16x64_i8 v[4:7], v[152:155], v[140:143], v[4:7]
	v_mfma_i32_16x16x64_i8 v[0:3], v[156:159], v[140:143], v[0:3]
	s_setprio 0
	s_waitcnt vmcnt(0)
	s_add_u32 s44, s44, 0x80
	s_addc_u32 s45, s45, 0
	s_add_u32 s64, s64, 0x80
	s_addc_u32 s65, s65, 0
	s_add_u32 s66, s66, 0x80
	s_addc_u32 s67, s67, 0
	s_add_i32 s19, s19, 0x8000
	s_cmpk_lg_i32 s44, 0x780
	s_waitcnt vmcnt(0) lgkmcnt(0)
	s_barrier
	s_cbranch_scc1 .LBB0_734
; template <class FragT, class AccT>
; DEV void gemm_core_t(const char* __restrict__ A, size_t lda_bytes, const char* __restrict__ Bt, size_t ldb_bytes, int kbytes,
;                      int m0, int n0, int Sshift, int dl, char* smem, AccT (&acc)[4][4]) {
;     ...
;     asm volatile(
;         "ds_read_b128 %0, %16\n\t"
;         "ds_read_b128 %1, %16 offset:2048\n\t"
;         "ds_read_b128 %2, %16 offset:4096\n\t"
;         "ds_read_b128 %3, %16 offset:6144\n\t"
;         "ds_read_b128 %4, %18\n\t"
;         "ds_read_b128 %5, %18 offset:2048\n\t"
;         "ds_read_b128 %6, %18 offset:8192\n\t"
;         "ds_read_b128 %7, %18 offset:10240\n\t"
;         "ds_read_b128 %8, %17\n\t"
;         "ds_read_b128 %9, %17 offset:2048\n\t"
;         "ds_read_b128 %10, %17 offset:4096\n\t"
;         "ds_read_b128 %11, %17 offset:6144\n\t"
;         "ds_read_b128 %12, %19\n\t"
;         "ds_read_b128 %13, %19 offset:2048\n\t"
;         "ds_read_b128 %14, %19 offset:8192\n\t"
;         "ds_read_b128 %15, %19 offset:10240\n\t"
;         "s_waitcnt lgkmcnt(8)"
;         : "=&v"(xa[0][0]), "=&v"(xa[0][1]), "=&v"(xa[0][2]), "=&v"(xa[0][3]), "=&v"(wb[0][0]), "=&v"(wb[0][1]), "=&v"(wb[0][2]),
;           "=&v"(wb[0][3]), "=&v"(xa[1][0]), "=&v"(xa[1][1]), "=&v"(xa[1][2]), "=&v"(xa[1][3]), "=&v"(wb[1][0]), "=&v"(wb[1][1]),
;           "=&v"(wb[1][2]), "=&v"(wb[1][3])
;         : "v"(a0 + so), "v"((a0 ^ 64u) + so), "v"(b0 + so), "v"((b0 ^ 64u) + so)
;         : "memory");
;     __builtin_amdgcn_s_setprio(1);
; #pragma unroll
;     for (int i = 0; i < 4; ++i)
; #pragma unroll
;       for (int j = 0; j < 4; ++j) acc[i][j] = mma_step(wb[0][j], xa[0][i], acc[i][j]);
;     asm volatile("s_waitcnt lgkmcnt(0)"
;                  : "+v"(xa[1][0]), "+v"(xa[1][1]), "+v"(xa[1][2]), "+v"(xa[1][3]), "+v"(wb[1][0]), "+v"(wb[1][1]), "+v"(wb[1][2]),
;                    "+v"(wb[1][3]), "+v"(acc[0][0]), "+v"(acc[0][1]), "+v"(acc[0][2]), "+v"(acc[0][3]), "+v"(acc[1][0]),
;                    "+v"(acc[1][1]), "+v"(acc[1][2]), "+v"(acc[1][3]), "+v"(acc[2][0]), "+v"(acc[2][1]), "+v"(acc[2][2]),
;                    "+v"(acc[2][3]), "+v"(acc[3][0]), "+v"(acc[3][1]), "+v"(acc[3][2]), "+v"(acc[3][3])
;                  :
;                  : "memory");
; #pragma unroll
;     for (int i = 0; i < 4; ++i)
; #pragma unroll
;       for (int j = 0; j < 4; ++j) acc[i][j] = mma_step(wb[1][j], xa[1][i], acc[i][j]);
	v_add_u32_e32 v76, 0x8000, v84
	v_add_u32_e32 v77, 0x8000, v87
	v_or_b32_e32 v81, 0x8000, v85
	v_or_b32_e32 v99, 0x8000, v86
	ds_read_b128 v[64:67], v76
	ds_read_b128 v[68:71], v76 offset:2048
	ds_read_b128 v[72:75], v76 offset:4096
	ds_read_b128 v[82:85], v76 offset:6144
	ds_read_b128 v[86:89], v81
	ds_read_b128 v[90:93], v81 offset:2048
	ds_read_b128 v[100:103], v81 offset:8192
	ds_read_b128 v[104:107], v81 offset:10240
	ds_read_b128 v[108:111], v77
	ds_read_b128 v[112:115], v77 offset:2048
	ds_read_b128 v[116:119], v77 offset:4096
	ds_read_b128 v[120:123], v77 offset:6144
	ds_read_b128 v[124:127], v99
	ds_read_b128 v[128:131], v99 offset:2048
	ds_read_b128 v[132:135], v99 offset:8192
	ds_read_b128 v[136:139], v99 offset:10240
	s_waitcnt lgkmcnt(8)
	s_setprio 1
	v_mfma_i32_16x16x64_i8 v[60:63], v[86:89], v[64:67], v[60:63]
	v_mfma_i32_16x16x64_i8 v[56:59], v[90:93], v[64:67], v[56:59]
	v_mfma_i32_16x16x64_i8 v[52:55], v[100:103], v[64:67], v[52:55]
	v_mfma_i32_16x16x64_i8 v[48:51], v[104:107], v[64:67], v[48:51]
	v_mfma_i32_16x16x64_i8 v[64:67], v[86:89], v[68:71], v[44:47]
	v_mfma_i32_16x16x64_i8 v[40:43], v[90:93], v[68:71], v[40:43]
	v_mfma_i32_16x16x64_i8 v[36:39], v[100:103], v[68:71], v[36:39]
	v_mfma_i32_16x16x64_i8 v[32:35], v[104:107], v[68:71], v[32:35]
	v_mfma_i32_16x16x64_i8 v[68:71], v[86:89], v[72:75], v[28:31]
	v_mfma_i32_16x16x64_i8 v[24:27], v[90:93], v[72:75], v[24:27]
	v_mfma_i32_16x16x64_i8 v[20:23], v[100:103], v[72:75], v[20:23]
	v_mfma_i32_16x16x64_i8 v[16:19], v[104:107], v[72:75], v[16:19]
	v_mfma_i32_16x16x64_i8 v[74:77], v[86:89], v[82:85], v[12:15]
	v_mfma_i32_16x16x64_i8 v[8:11], v[90:93], v[82:85], v[8:11]
	v_mfma_i32_16x16x64_i8 v[86:89], v[100:103], v[82:85], v[4:7]
	v_mfma_i32_16x16x64_i8 v[82:85], v[104:107], v[82:85], v[0:3]
	s_waitcnt lgkmcnt(0)
	s_nop 0
	v_mfma_i32_16x16x64_i8 v[56:59], v[128:131], v[108:111], v[56:59]
	v_mfma_i32_16x16x64_i8 v[140:143], v[132:135], v[108:111], v[52:55]
	v_mfma_i32_16x16x64_i8 v[46:49], v[136:139], v[108:111], v[48:51]
	v_mfma_i32_16x16x64_i8 v[52:55], v[124:127], v[112:115], v[64:67]
	v_mfma_i32_16x16x64_i8 v[40:43], v[128:131], v[112:115], v[40:43]
	v_mfma_i32_16x16x64_i8 v[36:39], v[132:135], v[112:115], v[36:39]
	v_mfma_i32_16x16x64_i8 v[30:33], v[136:139], v[112:115], v[32:35]
	v_mfma_i32_16x16x64_i8 v[24:27], v[128:131], v[116:119], v[24:27]
	v_mfma_i32_16x16x64_i8 v[20:23], v[132:135], v[116:119], v[20:23]
	v_mfma_i32_16x16x64_i8 v[14:17], v[136:139], v[116:119], v[16:19]
	v_mfma_i32_16x16x64_i8 v[4:7], v[124:127], v[120:123], v[74:77]
	v_mfma_i32_16x16x64_i8 v[0:3], v[128:131], v[120:123], v[8:11]
	v_mfma_i32_16x16x64_i8 v[8:11], v[136:139], v[120:123], v[82:85]
	v_mfma_i32_16x16x64_i8 v[102:105], v[124:127], v[108:111], v[60:63]
	v_mfma_i32_16x16x64_i8 v[70:73], v[124:127], v[116:119], v[68:71]
	v_mfma_i32_16x16x64_i8 v[62:65], v[132:135], v[120:123], v[86:89]
	s_setprio 0
	s_waitcnt vmcnt(0)
	s_barrier
	s_nop 0
	ds_read2_b64 v[84:87], v79 offset0:52 offset1:53
	v_add_u32_e32 v28, s36, v94
	v_mov_b32_e32 v29, s51
	v_and_b32_e32 v101, s51, v28
	v_bitop3_b32 v19, v28, s18, v29 bitop3:0x80
	v_lshrrev_b32_e32 v18, s17, v101
	v_and_b32_e32 v34, s50, v28
	v_lshlrev_b32_e32 v19, s6, v19
	v_add3_u32 v18, v18, v34, v19
	v_ashrrev_i32_e32 v19, 31, v18
	s_waitcnt lgkmcnt(0)
	v_lshl_add_u64 v[18:19], v[18:19], 2, v[84:85]
	flat_load_dword v82, v[18:19]
	v_or_b32_e32 v18, 16, v28
	v_bitop3_b32 v100, v28, s51, 16 bitop3:0xc8
	v_bitop3_b32 v18, v18, s18, v29 bitop3:0x80
	s_ashr_i32 s41, s40, 31
	v_lshrrev_b32_e32 v19, s17, v100
	v_lshlrev_b32_e32 v18, s6, v18
	v_lshl_add_u64 v[12:13], s[40:41], 2, v[86:87]
	v_mov_b32_e32 v81, v181
	v_add3_u32 v18, v19, v34, v18
	v_lshl_add_u64 v[12:13], v[12:13], 0, v[80:81]
	v_ashrrev_i32_e32 v19, 31, v18
	v_lshlrev_b32_e32 v180, 2, v78
	v_lshl_add_u64 v[18:19], v[18:19], 2, v[84:85]
	v_lshl_add_u64 v[12:13], v[12:13], 0, v[180:181]
	flat_load_dword v114, v[18:19]
	flat_load_dwordx4 v[106:109], v[12:13]
	flat_load_dwordx4 v[110:113], v[12:13] offset:256
	flat_load_dwordx4 v[74:77], v[12:13] offset:64
	flat_load_dwordx4 v[66:69], v[12:13] offset:320
	v_or_b32_e32 v12, 32, v28
	v_bitop3_b32 v99, v28, s51, 32 bitop3:0xc8
	v_bitop3_b32 v12, v12, s18, v29 bitop3:0x80
	v_lshrrev_b32_e32 v13, s17, v99
	v_lshlrev_b32_e32 v12, s6, v12
	v_add3_u32 v12, v13, v34, v12
	v_ashrrev_i32_e32 v13, 31, v12
	v_lshl_add_u64 v[12:13], v[12:13], 2, v[84:85]
	flat_load_dword v116, v[12:13]
	v_or_b32_e32 v12, 48, v28
	v_bitop3_b32 v81, v28, s51, 48 bitop3:0xc8
	v_bitop3_b32 v12, v12, s18, v29 bitop3:0x80
	v_lshrrev_b32_e32 v18, s17, v81
	v_lshlrev_b32_e32 v12, s6, v12
	v_add3_u32 v18, v18, v34, v12
	v_ashrrev_i32_e32 v19, 31, v18
	v_lshl_add_u64 v[18:19], v[18:19], 2, v[84:85]
	flat_load_dword v118, v[18:19]
	v_cvt_f32_i32_e32 v19, v143
	v_cvt_f32_i32_e32 v18, v105
	v_cvt_f32_i32_e32 v29, v48
	v_cvt_f32_i32_e32 v28, v58
	v_cvt_f32_i32_e32 v13, v142
	v_cvt_f32_i32_e32 v12, v104
	v_cvt_f32_i32_e32 v35, v49
	v_cvt_f32_i32_e32 v34, v59
	v_cvt_f32_i32_e32 v49, v32
	v_cvt_f32_i32_e32 v33, v33
	v_cvt_f32_i32_e32 v32, v43
	v_cvt_f32_i32_e32 v59, v22
	v_cvt_f32_i32_e32 v58, v72
	v_cvt_f32_i32_e32 v45, v38
	v_cvt_f32_i32_e32 v44, v54
	v_cvt_f32_i32_e32 v38, v55
	v_cvt_f32_i32_e32 v48, v42
	v_cvt_f32_i32_e32 v5, v5
	v_cvt_f32_i32_e32 v4, v4
	v_cvt_f32_i32_e32 v25, v25
	v_cvt_f32_i32_e32 v24, v24
	v_cvt_f32_i32_e32 v15, v15
	v_cvt_f32_i32_e32 v14, v14
	v_cvt_f32_i32_e32 v31, v31
	v_cvt_f32_i32_e32 v30, v30
	v_cvt_f32_i32_e32 v1, v1
	v_cvt_f32_i32_e32 v0, v0
	v_cvt_f32_i32_e32 v39, v39
	v_cvt_f32_i32_e32 v11, v11
	s_andn2_b64 vcc, exec, s[14:15]
	s_waitcnt vmcnt(0) lgkmcnt(0)
; #define P (*launderP(lp))
; __device__ __forceinline__ void phase_gemm1(PREF P, int slab, char* smem) {
;     ...
;       gemm_core_i8(P.xq8, DM, P.Win8, DM, DM, m0, n0, Sshift, dl, smem, iacc);
; #pragma unroll
;       for (int i = 0; i < 4; ++i) {
;         const float sxr = P.sx[rowmap(m0 + wm * 64 + i * 16 + l15, Sshift, dl)];
; #pragma unroll
;         for (int j = 0; j < 4; ++j) {
;           const float4 swc = *(const float4*)(P.sw + n0 + (j & 1) * 16 + wn * 32 + (j >> 1) * 64 + q * 4);
;           acc[i][j][0] = (float)iacc[i][j][0] * sxr * swc.x; acc[i][j][1] = (float)iacc[i][j][1] * sxr * swc.y;
;           acc[i][j][2] = (float)iacc[i][j][2] * sxr * swc.z; acc[i][j][3] = (float)iacc[i][j][3] * sxr * swc.w;
;         }
;       }
	v_pk_mul_f32 v[18:19], v[82:83], v[18:19] op_sel_hi:[0,1]
	v_pk_mul_f32 v[28:29], v[82:83], v[28:29] op_sel_hi:[0,1]
	v_pk_mul_f32 v[12:13], v[82:83], v[12:13] op_sel_hi:[0,1]
	v_pk_mul_f32 v[34:35], v[82:83], v[34:35] op_sel_hi:[0,1]
	v_mov_b32_e32 v84, v108
	v_mov_b32_e32 v85, v112
	v_mov_b32_e32 v112, v109
	v_mov_b32_e32 v104, v76
	v_mov_b32_e32 v105, v68
	v_pk_mul_f32 v[54:55], v[18:19], v[112:113]
	v_cvt_f32_i32_e32 v19, v23
	v_cvt_f32_i32_e32 v18, v73
	v_pk_mul_f32 v[42:43], v[28:29], v[104:105]
	v_cvt_f32_i32_e32 v29, v16
	v_cvt_f32_i32_e32 v28, v26
	v_mov_b32_e32 v68, v77
	v_pk_mul_f32 v[88:89], v[12:13], v[84:85]
	v_pk_mul_f32 v[12:13], v[114:115], v[32:33] op_sel_hi:[0,1]
	v_pk_mul_f32 v[50:51], v[34:35], v[68:69]
	v_pk_mul_f32 v[34:35], v[68:69], v[12:13]
	v_pk_mul_f32 v[12:13], v[116:117], v[58:59] op_sel_hi:[0,1]
	v_pk_mul_f32 v[86:87], v[84:85], v[12:13]
	v_pk_mul_f32 v[12:13], v[116:117], v[18:19] op_sel_hi:[0,1]
	v_pk_mul_f32 v[22:23], v[112:113], v[12:13]
	v_pk_mul_f32 v[12:13], v[116:117], v[28:29] op_sel_hi:[0,1]
	v_pk_mul_f32 v[76:77], v[104:105], v[12:13]
	v_cvt_f32_i32_e32 v13, v17
	v_cvt_f32_i32_e32 v12, v27
	v_cvt_f32_i32_e32 v17, v103
	v_cvt_f32_i32_e32 v16, v102
	v_cvt_f32_i32_e32 v27, v141
	v_cvt_f32_i32_e32 v26, v140
	v_cvt_f32_i32_e32 v29, v37
	v_cvt_f32_i32_e32 v28, v36
	v_pk_mul_f32 v[12:13], v[116:117], v[12:13] op_sel_hi:[0,1]
	v_pk_mul_f32 v[18:19], v[68:69], v[12:13]
	v_pk_mul_f32 v[12:13], v[82:83], v[16:17] op_sel_hi:[0,1]
	v_pk_mul_f32 v[16:17], v[82:83], v[26:27] op_sel_hi:[0,1]
	v_cvt_f32_i32_e32 v27, v53
	v_cvt_f32_i32_e32 v26, v52
	v_pk_mul_f32 v[52:53], v[16:17], v[110:111]
	v_pk_mul_f32 v[16:17], v[114:115], v[28:29] op_sel_hi:[0,1]
	v_pk_mul_f32 v[36:37], v[110:111], v[16:17]
	v_cvt_f32_i32_e32 v17, v21
	v_cvt_f32_i32_e32 v16, v20
	v_pk_mul_f32 v[44:45], v[114:115], v[44:45] op_sel_hi:[0,1]
	v_pk_mul_f32 v[60:61], v[106:107], v[12:13]
	v_pk_mul_f32 v[12:13], v[114:115], v[26:27] op_sel_hi:[0,1]
	v_pk_mul_f32 v[92:93], v[84:85], v[44:45]
	v_pk_mul_f32 v[44:45], v[106:107], v[12:13]
	v_cvt_f32_i32_e32 v13, v71
	v_cvt_f32_i32_e32 v12, v70
	v_pk_mul_f32 v[16:17], v[116:117], v[16:17] op_sel_hi:[0,1]
	v_pk_mul_f32 v[20:21], v[110:111], v[16:17]
	v_cvt_f32_i32_e32 v17, v63
	v_cvt_f32_i32_e32 v16, v62
	v_cvt_f32_i32_e32 v27, v64
	v_cvt_f32_i32_e32 v26, v6
	v_pk_mul_f32 v[12:13], v[116:117], v[12:13] op_sel_hi:[0,1]
	v_pk_mul_f32 v[4:5], v[118:119], v[4:5] op_sel_hi:[0,1]
	v_pk_mul_f32 v[28:29], v[106:107], v[12:13]
	v_pk_mul_f32 v[12:13], v[106:107], v[4:5]
	v_pk_mul_f32 v[4:5], v[118:119], v[16:17] op_sel_hi:[0,1]
	v_pk_mul_f32 v[16:17], v[118:119], v[26:27] op_sel_hi:[0,1]
	v_pk_mul_f32 v[84:85], v[84:85], v[16:17]
	v_cvt_f32_i32_e32 v17, v65
	v_cvt_f32_i32_e32 v16, v7
	v_cvt_f32_i32_e32 v27, v57
	v_cvt_f32_i32_e32 v26, v56
	v_cvt_f32_i32_e32 v33, v47
	v_cvt_f32_i32_e32 v32, v46
	v_pk_mul_f32 v[6:7], v[118:119], v[16:17] op_sel_hi:[0,1]
	v_pk_mul_f32 v[16:17], v[82:83], v[26:27] op_sel_hi:[0,1]
	v_pk_mul_f32 v[56:57], v[16:17], v[74:75]
	v_pk_mul_f32 v[26:27], v[82:83], v[32:33] op_sel_hi:[0,1]
	v_cvt_f32_i32_e32 v33, v41
	v_cvt_f32_i32_e32 v32, v40
	v_pk_mul_f32 v[48:49], v[114:115], v[48:49] op_sel_hi:[0,1]
	v_pk_mul_f32 v[14:15], v[116:117], v[14:15] op_sel_hi:[0,1]
	v_pk_mul_f32 v[90:91], v[104:105], v[48:49]
	v_pk_mul_f32 v[16:17], v[114:115], v[32:33] op_sel_hi:[0,1]
	v_pk_mul_f32 v[40:41], v[74:75], v[16:17]
	v_pk_mul_f32 v[16:17], v[116:117], v[24:25] op_sel_hi:[0,1]
	v_pk_mul_f32 v[48:49], v[26:27], v[66:67]
	v_pk_mul_f32 v[26:27], v[114:115], v[30:31] op_sel_hi:[0,1]
	v_pk_mul_f32 v[24:25], v[74:75], v[16:17]
	v_pk_mul_f32 v[16:17], v[66:67], v[14:15]
	v_cvt_f32_i32_e32 v15, v10
	v_cvt_f32_i32_e32 v14, v2
	v_pk_mul_f32 v[32:33], v[66:67], v[26:27]
	v_cvt_f32_i32_e32 v27, v9
	v_cvt_f32_i32_e32 v26, v8
	v_cvt_f32_i32_e32 v10, v3
	v_pk_mul_f32 v[0:1], v[118:119], v[0:1] op_sel_hi:[0,1]
	v_pk_mul_f32 v[2:3], v[118:119], v[14:15] op_sel_hi:[0,1]
	v_pk_mul_f32 v[38:39], v[114:115], v[38:39] op_sel_hi:[0,1]
	v_pk_mul_f32 v[8:9], v[74:75], v[0:1]
	v_pk_mul_f32 v[0:1], v[118:119], v[26:27] op_sel_hi:[0,1]
	v_pk_mul_f32 v[82:83], v[104:105], v[2:3]
	v_pk_mul_f32 v[2:3], v[118:119], v[10:11] op_sel_hi:[0,1]
	v_pk_mul_f32 v[38:39], v[112:113], v[38:39]
	v_pk_mul_f32 v[4:5], v[110:111], v[4:5]
	v_pk_mul_f32 v[6:7], v[112:113], v[6:7]
	v_pk_mul_f32 v[0:1], v[66:67], v[0:1]
	v_pk_mul_f32 v[2:3], v[68:69], v[2:3]
	s_cbranch_vccnz .LBB0_737
; #define P (*launderP(lp))
; __device__ __forceinline__ void phase_gemm1(PREF P, int slab, char* smem) {
;     ...
;     if (region <= 1) {
; #pragma unroll
;       for (int i = 0; i < 4; ++i) {
;         const int row = m0 + wm * 64 + i * 16 + l15;
;         const float s = (float)(row & ((1 << Sshift) - 1));
; #pragma unroll
;         for (int jj = 0; jj < 2; ++jj)
; #pragma unroll
;           for (int r = 0; r < 4; ++r) {
;             const int d = jj * 16 + wn * 32 + q * 4 + r;
;             float fr = __builtin_amdgcn_fractf(s * P.ropec[d]);
;             float cs = __builtin_amdgcn_cosf(fr), sn = __builtin_amdgcn_sinf(fr);
;             float t1 = acc[i][jj][r], t2 = acc[i][jj + 2][r];
;             float o1 = t1 * cs - t2 * sn, o2 = t1 * sn + t2 * cs;
;             if (region == 1) { o1 *= QK_SCALE; o2 *= QK_SCALE; }
;             acc[i][jj][r] = o1;
;             acc[i][jj + 2][r] = o2;
;           }
;       }
;     }
	ds_read2_b32 v[10:11], v96 offset0:134 offset1:135
	v_cvt_f32_u32_e32 v26, v101
	v_mov_b32_e32 v30, v60
	v_mov_b32_e32 v31, v52
	v_mov_b32_e32 v46, v61
	s_waitcnt lgkmcnt(0)
	v_mul_f32_e32 v14, v10, v26
	v_fract_f32_e32 v15, v14
	v_cos_f32_e32 v14, v15
	v_sin_f32_e32 v15, v15
	v_mov_b32_e32 v47, v53
	v_pk_mul_f32 v[30:31], v[30:31], v[14:15]
	s_nop 0
	v_sub_f32_e32 v27, v30, v31
	v_mul_f32_e32 v30, 0x3db504f3, v27
	v_cndmask_b32_e64 v62, v27, v30, s[42:43]
	v_mul_f32_e32 v27, v11, v26
	v_fract_f32_e32 v27, v27
	v_cos_f32_e32 v30, v27
	v_sin_f32_e32 v31, v27
	s_nop 0
	v_pk_mul_f32 v[46:47], v[46:47], v[30:31]
	s_nop 0
	v_sub_f32_e32 v27, v46, v47
	v_mov_b32_e32 v46, v15
	v_mov_b32_e32 v15, v30
	v_mov_b32_e32 v47, v31
	v_pk_mul_f32 v[14:15], v[52:53], v[14:15]
	v_mul_f32_e32 v63, 0x3db504f3, v27
	v_pk_fma_f32 v[14:15], v[60:61], v[46:47], v[14:15]
	v_cndmask_b32_e64 v63, v27, v63, s[42:43]
	v_pk_mul_f32 v[30:31], v[14:15], s[12:13] op_sel_hi:[1,0]
	v_mov_b32_e32 v52, v57
	v_cndmask_b32_e64 v59, v15, v31, s[42:43]
	v_cndmask_b32_e64 v58, v14, v30, s[42:43]
	ds_read2_b32 v[14:15], v96 offset0:136 offset1:137
	v_mov_b32_e32 v53, v49
	s_waitcnt lgkmcnt(0)
	v_mul_f32_e32 v27, v14, v26
	v_fract_f32_e32 v27, v27
	v_cos_f32_e32 v30, v27
	v_sin_f32_e32 v31, v27
	s_nop 0
	v_pk_mul_f32 v[46:47], v[88:89], v[30:31]
	s_nop 0
	v_sub_f32_e32 v27, v46, v47
	v_mov_b32_e32 v46, v31
	v_mov_b32_e32 v47, v30
	v_pk_mul_f32 v[30:31], v[88:89], v[46:47]
	ds_read2_b32 v[88:89], v96 offset0:150 offset1:151
	v_add_f32_e32 v30, v30, v31
	v_mul_f32_e32 v31, 0x3db504f3, v27
	v_cndmask_b32_e64 v64, v27, v31, s[42:43]
	v_mul_f32_e32 v27, v15, v26
	v_mul_f32_e32 v46, 0x3db504f3, v30
	v_fract_f32_e32 v27, v27
	v_cndmask_b32_e64 v60, v30, v46, s[42:43]
	v_cos_f32_e32 v30, v27
	v_sin_f32_e32 v31, v27
	s_nop 0
	v_pk_mul_f32 v[46:47], v[54:55], v[30:31]
	s_nop 0
	v_sub_f32_e32 v27, v46, v47
	v_mov_b32_e32 v46, v31
	v_mov_b32_e32 v47, v30
	v_pk_mul_f32 v[30:31], v[54:55], v[46:47]
	v_mov_b32_e32 v47, v48
	v_add_f32_e32 v30, v30, v31
	v_mul_f32_e32 v31, 0x3db504f3, v27
	v_cndmask_b32_e64 v65, v27, v31, s[42:43]
	s_waitcnt lgkmcnt(0)
	v_mul_f32_e32 v27, v88, v26
	v_mul_f32_e32 v46, 0x3db504f3, v30
	v_fract_f32_e32 v27, v27
	v_cndmask_b32_e64 v61, v30, v46, s[42:43]
	v_cos_f32_e32 v30, v27
	v_sin_f32_e32 v31, v27
	v_mov_b32_e32 v46, v56
	v_pk_mul_f32 v[46:47], v[46:47], v[30:31]
	s_nop 0
	v_sub_f32_e32 v27, v46, v47
	v_mul_f32_e32 v46, 0x3db504f3, v27
	v_cndmask_b32_e64 v66, v27, v46, s[42:43]
	v_mul_f32_e32 v27, v89, v26
	v_fract_f32_e32 v27, v27
	v_cos_f32_e32 v46, v27
	v_sin_f32_e32 v47, v27
	s_nop 0
	v_pk_mul_f32 v[52:53], v[52:53], v[46:47]
	s_nop 0
	v_sub_f32_e32 v27, v52, v53
	v_mov_b32_e32 v52, v31
	v_mov_b32_e32 v31, v46
	v_mov_b32_e32 v53, v47
	v_pk_mul_f32 v[30:31], v[48:49], v[30:31]
	v_mul_f32_e32 v54, 0x3db504f3, v27
	v_pk_fma_f32 v[30:31], v[56:57], v[52:53], v[30:31]
	ds_read2_b32 v[56:57], v96 offset0:152 offset1:153
	v_cndmask_b32_e64 v67, v27, v54, s[42:43]
	v_pk_mul_f32 v[46:47], v[30:31], s[12:13] op_sel_hi:[1,0]
	s_waitcnt lgkmcnt(0)
	v_mul_f32_e32 v27, v56, v26
	v_fract_f32_e32 v27, v27
	v_cndmask_b32_e64 v53, v31, v47, s[42:43]
	v_cndmask_b32_e64 v52, v30, v46, s[42:43]
	v_cos_f32_e32 v30, v27
	v_sin_f32_e32 v31, v27
	v_mul_f32_e32 v26, v57, v26
	v_pk_mul_f32 v[46:47], v[42:43], v[30:31]
	s_nop 0
	v_sub_f32_e32 v27, v46, v47
	v_mov_b32_e32 v46, v31
	v_mov_b32_e32 v47, v30
	v_pk_mul_f32 v[30:31], v[42:43], v[46:47]
	v_mov_b32_e32 v43, v37
	v_add_f32_e32 v30, v30, v31
	v_mul_f32_e32 v31, 0x3db504f3, v27
	v_cndmask_b32_e64 v68, v27, v31, s[42:43]
	v_fract_f32_e32 v27, v26
	v_cos_f32_e32 v26, v27
	v_sin_f32_e32 v27, v27
	v_mul_f32_e32 v42, 0x3db504f3, v30
	v_cndmask_b32_e64 v54, v30, v42, s[42:43]
	v_pk_mul_f32 v[30:31], v[50:51], v[26:27]
	s_nop 0
	v_sub_f32_e32 v42, v30, v31
	v_mov_b32_e32 v30, v27
	v_mov_b32_e32 v31, v26
	v_pk_mul_f32 v[26:27], v[50:51], v[30:31]
	v_cvt_f32_u32_e32 v50, v100
	v_add_f32_e32 v26, v26, v27
	v_mul_f32_e32 v30, 0x3db504f3, v26
	v_mul_f32_e32 v27, 0x3db504f3, v42
	v_cndmask_b32_e64 v55, v26, v30, s[42:43]
	v_mul_f32_e32 v26, v10, v50
	v_cndmask_b32_e64 v69, v42, v27, s[42:43]
	v_fract_f32_e32 v27, v26
	v_cos_f32_e32 v26, v27
	v_sin_f32_e32 v27, v27
	v_mov_b32_e32 v30, v44
	v_mov_b32_e32 v31, v36
	v_mov_b32_e32 v42, v45
	v_pk_mul_f32 v[30:31], v[30:31], v[26:27]
	s_nop 0
	v_sub_f32_e32 v30, v30, v31
	v_mul_f32_e32 v31, 0x3db504f3, v30
	v_cndmask_b32_e64 v46, v30, v31, s[42:43]
	v_mul_f32_e32 v30, v11, v50
	v_fract_f32_e32 v31, v30
	v_cos_f32_e32 v30, v31
	v_sin_f32_e32 v31, v31
	s_nop 0
	v_pk_mul_f32 v[42:43], v[42:43], v[30:31]
	s_nop 0
	v_sub_f32_e32 v47, v42, v43
	v_mov_b32_e32 v42, v27
	v_mov_b32_e32 v27, v30
	v_mov_b32_e32 v43, v31
	v_pk_mul_f32 v[26:27], v[36:37], v[26:27]
	v_mul_f32_e32 v48, 0x3db504f3, v47
	v_pk_fma_f32 v[26:27], v[44:45], v[42:43], v[26:27]
	v_cndmask_b32_e64 v47, v47, v48, s[42:43]
	v_pk_mul_f32 v[30:31], v[26:27], s[12:13] op_sel_hi:[1,0]
	v_mov_b32_e32 v37, v33
	v_cndmask_b32_e64 v42, v26, v30, s[42:43]
	v_mul_f32_e32 v26, v14, v50
	v_cndmask_b32_e64 v43, v27, v31, s[42:43]
	v_fract_f32_e32 v27, v26
	v_cos_f32_e32 v26, v27
	v_sin_f32_e32 v27, v27
	s_nop 0
	v_pk_mul_f32 v[30:31], v[92:93], v[26:27]
	s_nop 0
	v_sub_f32_e32 v36, v30, v31
	v_mov_b32_e32 v30, v27
	v_mov_b32_e32 v31, v26
	v_pk_mul_f32 v[26:27], v[92:93], v[30:31]
	s_nop 0
	v_add_f32_e32 v26, v26, v27
	v_mul_f32_e32 v30, 0x3db504f3, v26
	v_mul_f32_e32 v27, 0x3db504f3, v36
	v_cndmask_b32_e64 v44, v26, v30, s[42:43]
	v_mul_f32_e32 v26, v15, v50
	v_cndmask_b32_e64 v48, v36, v27, s[42:43]
	v_fract_f32_e32 v27, v26
	v_cos_f32_e32 v26, v27
; #define P (*launderP(lp))
; __device__ __forceinline__ void phase_gemm1(PREF P, int slab, char* smem) {
;     ...
;     if (region <= 1) {
; #pragma unroll
;       for (int i = 0; i < 4; ++i) {
;         const int row = m0 + wm * 64 + i * 16 + l15;
;         const float s = (float)(row & ((1 << Sshift) - 1));
; #pragma unroll
;         for (int jj = 0; jj < 2; ++jj)
; #pragma unroll
;           for (int r = 0; r < 4; ++r) {
;             const int d = jj * 16 + wn * 32 + q * 4 + r;
;             float fr = __builtin_amdgcn_fractf(s * P.ropec[d]);
;             float cs = __builtin_amdgcn_cosf(fr), sn = __builtin_amdgcn_sinf(fr);
;             float t1 = acc[i][jj][r], t2 = acc[i][jj + 2][r];
;             float o1 = t1 * cs - t2 * sn, o2 = t1 * sn + t2 * cs;
;             if (region == 1) { o1 *= QK_SCALE; o2 *= QK_SCALE; }
;             acc[i][jj][r] = o1;
;             acc[i][jj + 2][r] = o2;
;           }
;       }
;     }
	v_sin_f32_e32 v27, v27
	s_nop 0
	v_pk_mul_f32 v[30:31], v[38:39], v[26:27]
	s_nop 0
	v_sub_f32_e32 v36, v30, v31
	v_mov_b32_e32 v30, v27
	v_mov_b32_e32 v31, v26
	v_pk_mul_f32 v[26:27], v[38:39], v[30:31]
	v_mov_b32_e32 v31, v32
	v_add_f32_e32 v26, v26, v27
	v_mul_f32_e32 v30, 0x3db504f3, v26
	v_mul_f32_e32 v27, 0x3db504f3, v36
	v_cndmask_b32_e64 v45, v26, v30, s[42:43]
	v_mul_f32_e32 v26, v88, v50
	v_cndmask_b32_e64 v49, v36, v27, s[42:43]
	v_fract_f32_e32 v27, v26
	v_cos_f32_e32 v26, v27
	v_sin_f32_e32 v27, v27
	v_mov_b32_e32 v30, v40
	v_mov_b32_e32 v36, v41
	v_pk_mul_f32 v[30:31], v[30:31], v[26:27]
	s_nop 0
	v_sub_f32_e32 v30, v30, v31
	v_mul_f32_e32 v31, 0x3db504f3, v30
	v_cndmask_b32_e64 v70, v30, v31, s[42:43]
	v_mul_f32_e32 v30, v89, v50
	v_fract_f32_e32 v31, v30
	v_cos_f32_e32 v30, v31
	v_sin_f32_e32 v31, v31
	s_nop 0
	v_pk_mul_f32 v[36:37], v[36:37], v[30:31]
	s_nop 0
	v_sub_f32_e32 v38, v36, v37
	v_mov_b32_e32 v36, v27
	v_mov_b32_e32 v27, v30
	v_mov_b32_e32 v37, v31
	v_pk_mul_f32 v[26:27], v[32:33], v[26:27]
	v_mul_f32_e32 v39, 0x3db504f3, v38
	v_pk_fma_f32 v[26:27], v[40:41], v[36:37], v[26:27]
	v_cndmask_b32_e64 v71, v38, v39, s[42:43]
	v_pk_mul_f32 v[30:31], v[26:27], s[12:13] op_sel_hi:[1,0]
	v_cvt_f32_u32_e32 v40, v99
	v_cndmask_b32_e64 v36, v26, v30, s[42:43]
	v_mul_f32_e32 v26, v56, v50
	v_cndmask_b32_e64 v37, v27, v31, s[42:43]
	v_fract_f32_e32 v27, v26
	v_cos_f32_e32 v26, v27
	v_sin_f32_e32 v27, v27
	s_nop 0
	v_pk_mul_f32 v[30:31], v[90:91], v[26:27]
	s_nop 0
	v_sub_f32_e32 v32, v30, v31
	v_mov_b32_e32 v30, v27
	v_mov_b32_e32 v31, v26
	v_pk_mul_f32 v[26:27], v[90:91], v[30:31]
	s_nop 0
	v_add_f32_e32 v26, v26, v27
	v_mul_f32_e32 v30, 0x3db504f3, v26
	v_mul_f32_e32 v27, 0x3db504f3, v32
	v_cndmask_b32_e64 v38, v26, v30, s[42:43]
	v_mul_f32_e32 v26, v57, v50
	v_cndmask_b32_e64 v72, v32, v27, s[42:43]
	v_fract_f32_e32 v27, v26
	v_cos_f32_e32 v26, v27
	v_sin_f32_e32 v27, v27
	s_nop 0
	v_pk_mul_f32 v[30:31], v[34:35], v[26:27]
	s_nop 0
	v_sub_f32_e32 v32, v30, v31
	v_mov_b32_e32 v30, v27
	v_mov_b32_e32 v31, v26
	v_pk_mul_f32 v[26:27], v[34:35], v[30:31]
	v_mov_b32_e32 v31, v20
	v_add_f32_e32 v26, v26, v27
	v_mul_f32_e32 v30, 0x3db504f3, v26
	v_mul_f32_e32 v27, 0x3db504f3, v32
	v_cndmask_b32_e64 v39, v26, v30, s[42:43]
	v_mul_f32_e32 v26, v10, v40
	v_cndmask_b32_e64 v73, v32, v27, s[42:43]
	v_fract_f32_e32 v27, v26
	v_cos_f32_e32 v26, v27
	v_sin_f32_e32 v27, v27
	v_mov_b32_e32 v30, v28
	v_mov_b32_e32 v34, v29
	v_mov_b32_e32 v35, v21
	v_pk_mul_f32 v[30:31], v[30:31], v[26:27]
	s_nop 0
	v_sub_f32_e32 v30, v30, v31
	v_mul_f32_e32 v31, 0x3db504f3, v30
	v_cndmask_b32_e64 v30, v30, v31, s[42:43]
	v_mul_f32_e32 v31, v11, v40
	v_fract_f32_e32 v31, v31
	v_cos_f32_e32 v32, v31
	v_sin_f32_e32 v33, v31
	s_nop 0
	v_pk_mul_f32 v[34:35], v[34:35], v[32:33]
	s_nop 0
	v_sub_f32_e32 v31, v34, v35
	v_mov_b32_e32 v34, v27
	v_mov_b32_e32 v27, v32
	v_mov_b32_e32 v35, v33
	v_pk_mul_f32 v[20:21], v[20:21], v[26:27]
	v_mul_f32_e32 v41, 0x3db504f3, v31
	v_pk_fma_f32 v[20:21], v[28:29], v[34:35], v[20:21]
	v_cndmask_b32_e64 v31, v31, v41, s[42:43]
	v_pk_mul_f32 v[26:27], v[20:21], s[12:13] op_sel_hi:[1,0]
	s_nop 0
	v_cndmask_b32_e64 v26, v20, v26, s[42:43]
	v_mul_f32_e32 v20, v14, v40
	v_cndmask_b32_e64 v27, v21, v27, s[42:43]
	v_fract_f32_e32 v21, v20
	v_cos_f32_e32 v20, v21
	v_sin_f32_e32 v21, v21
	s_nop 0
	v_pk_mul_f32 v[28:29], v[86:87], v[20:21]
	s_nop 0
	v_sub_f32_e32 v32, v28, v29
	v_mov_b32_e32 v28, v21
	v_mov_b32_e32 v29, v20
	v_pk_mul_f32 v[20:21], v[86:87], v[28:29]
	s_nop 0
	v_add_f32_e32 v20, v20, v21
	v_mul_f32_e32 v28, 0x3db504f3, v20
	v_mul_f32_e32 v21, 0x3db504f3, v32
	v_cndmask_b32_e64 v28, v20, v28, s[42:43]
	v_mul_f32_e32 v20, v15, v40
	v_cndmask_b32_e64 v32, v32, v21, s[42:43]
	v_fract_f32_e32 v21, v20
	v_cos_f32_e32 v20, v21
	v_sin_f32_e32 v21, v21
	s_nop 0
	v_pk_mul_f32 v[34:35], v[22:23], v[20:21]
	s_nop 0
	v_sub_f32_e32 v33, v34, v35
	v_mov_b32_e32 v34, v21
	v_mov_b32_e32 v35, v20
	v_pk_mul_f32 v[20:21], v[22:23], v[34:35]
	v_mov_b32_e32 v23, v16
	v_add_f32_e32 v20, v20, v21
	v_mul_f32_e32 v22, 0x3db504f3, v20
	v_mul_f32_e32 v21, 0x3db504f3, v33
	v_cndmask_b32_e64 v29, v20, v22, s[42:43]
	v_mul_f32_e32 v20, v88, v40
	v_cndmask_b32_e64 v33, v33, v21, s[42:43]
	v_fract_f32_e32 v21, v20
	v_cos_f32_e32 v20, v21
	v_sin_f32_e32 v21, v21
	v_mov_b32_e32 v22, v24
	v_mov_b32_e32 v34, v25
	v_mov_b32_e32 v35, v17
	v_pk_mul_f32 v[22:23], v[22:23], v[20:21]
	s_nop 0
	v_sub_f32_e32 v22, v22, v23
	v_mul_f32_e32 v23, 0x3db504f3, v22
	v_cndmask_b32_e64 v74, v22, v23, s[42:43]
	v_mul_f32_e32 v22, v89, v40
	v_fract_f32_e32 v23, v22
	v_cos_f32_e32 v22, v23
	v_sin_f32_e32 v23, v23
	s_nop 0
	v_pk_mul_f32 v[34:35], v[34:35], v[22:23]
	s_nop 0
	v_sub_f32_e32 v41, v34, v35
	v_mov_b32_e32 v34, v21
	v_mov_b32_e32 v21, v22
	v_mov_b32_e32 v35, v23
	v_pk_mul_f32 v[16:17], v[16:17], v[20:21]
	v_mul_f32_e32 v50, 0x3db504f3, v41
	v_pk_fma_f32 v[16:17], v[24:25], v[34:35], v[16:17]
	v_cndmask_b32_e64 v75, v41, v50, s[42:43]
	v_pk_mul_f32 v[20:21], v[16:17], s[12:13] op_sel_hi:[1,0]
	s_nop 0
	v_cndmask_b32_e64 v20, v16, v20, s[42:43]
	v_mul_f32_e32 v16, v56, v40
	v_cndmask_b32_e64 v21, v17, v21, s[42:43]
	v_fract_f32_e32 v17, v16
	v_cos_f32_e32 v16, v17
	v_sin_f32_e32 v17, v17
	s_nop 0
	v_pk_mul_f32 v[22:23], v[76:77], v[16:17]
	s_nop 0
	v_sub_f32_e32 v24, v22, v23
	v_mov_b32_e32 v22, v17
	v_mov_b32_e32 v23, v16
	v_pk_mul_f32 v[16:17], v[76:77], v[22:23]
	s_nop 0
	v_add_f32_e32 v16, v16, v17
; #define P (*launderP(lp))
; __device__ __forceinline__ void phase_gemm1(PREF P, int slab, char* smem) {
;     ...
;     if (region <= 1) {
; #pragma unroll
;       for (int i = 0; i < 4; ++i) {
;         const int row = m0 + wm * 64 + i * 16 + l15;
;         const float s = (float)(row & ((1 << Sshift) - 1));
; #pragma unroll
;         for (int jj = 0; jj < 2; ++jj)
; #pragma unroll
;           for (int r = 0; r < 4; ++r) {
;             const int d = jj * 16 + wn * 32 + q * 4 + r;
;             float fr = __builtin_amdgcn_fractf(s * P.ropec[d]);
;             float cs = __builtin_amdgcn_cosf(fr), sn = __builtin_amdgcn_sinf(fr);
;             float t1 = acc[i][jj][r], t2 = acc[i][jj + 2][r];
;             float o1 = t1 * cs - t2 * sn, o2 = t1 * sn + t2 * cs;
;             if (region == 1) { o1 *= QK_SCALE; o2 *= QK_SCALE; }
;             acc[i][jj][r] = o1;
;             acc[i][jj + 2][r] = o2;
;           }
;       }
;     }
	v_mul_f32_e32 v22, 0x3db504f3, v16
	v_mul_f32_e32 v17, 0x3db504f3, v24
	v_cndmask_b32_e64 v22, v16, v22, s[42:43]
	v_mul_f32_e32 v16, v57, v40
	v_cndmask_b32_e64 v76, v24, v17, s[42:43]
	v_fract_f32_e32 v17, v16
	v_cos_f32_e32 v16, v17
	v_sin_f32_e32 v17, v17
	s_nop 0
	v_pk_mul_f32 v[24:25], v[18:19], v[16:17]
	s_nop 0
	v_sub_f32_e32 v34, v24, v25
	v_mov_b32_e32 v24, v17
	v_mov_b32_e32 v25, v16
	v_pk_mul_f32 v[16:17], v[18:19], v[24:25]
	v_mov_b32_e32 v24, v13
	v_add_f32_e32 v16, v16, v17
	v_mul_f32_e32 v17, 0x3db504f3, v34
	v_cndmask_b32_e64 v77, v34, v17, s[42:43]
	v_cvt_f32_u32_e32 v34, v81
	v_mul_f32_e32 v18, 0x3db504f3, v16
	v_cndmask_b32_e64 v23, v16, v18, s[42:43]
	v_mov_b32_e32 v16, v12
	v_mul_f32_e32 v10, v10, v34
	v_fract_f32_e32 v10, v10
	v_cos_f32_e32 v18, v10
	v_sin_f32_e32 v19, v10
	v_mov_b32_e32 v17, v4
	v_mov_b32_e32 v25, v5
	v_pk_mul_f32 v[16:17], v[16:17], v[18:19]
	s_nop 0
	v_sub_f32_e32 v10, v16, v17
	v_mul_f32_e32 v16, 0x3db504f3, v10
	v_cndmask_b32_e64 v16, v10, v16, s[42:43]
	v_mul_f32_e32 v10, v11, v34
	v_fract_f32_e32 v11, v10
	v_cos_f32_e32 v10, v11
	v_sin_f32_e32 v11, v11
	s_nop 0
	v_pk_mul_f32 v[24:25], v[24:25], v[10:11]
	s_nop 0
	v_sub_f32_e32 v17, v24, v25
	v_mov_b32_e32 v24, v19
	v_mov_b32_e32 v19, v10
	v_mov_b32_e32 v25, v11
	v_pk_mul_f32 v[4:5], v[4:5], v[18:19]
	v_mul_f32_e32 v35, 0x3db504f3, v17
	v_pk_fma_f32 v[4:5], v[12:13], v[24:25], v[4:5]
	v_cndmask_b32_e64 v17, v17, v35, s[42:43]
	v_pk_mul_f32 v[10:11], v[4:5], s[12:13] op_sel_hi:[1,0]
	s_nop 0
	v_cndmask_b32_e64 v10, v4, v10, s[42:43]
	v_mul_f32_e32 v4, v14, v34
	v_cndmask_b32_e64 v11, v5, v11, s[42:43]
	v_fract_f32_e32 v5, v4
	v_cos_f32_e32 v4, v5
	v_sin_f32_e32 v5, v5
	s_nop 0
	v_pk_mul_f32 v[12:13], v[84:85], v[4:5]
	s_nop 0
	v_sub_f32_e32 v14, v12, v13
	v_mov_b32_e32 v12, v5
	v_mov_b32_e32 v13, v4
	v_pk_mul_f32 v[4:5], v[84:85], v[12:13]
	s_nop 0
	v_add_f32_e32 v4, v4, v5
	v_mul_f32_e32 v12, 0x3db504f3, v4
	v_mul_f32_e32 v5, 0x3db504f3, v14
	v_cndmask_b32_e64 v12, v4, v12, s[42:43]
	v_mul_f32_e32 v4, v15, v34
	v_cndmask_b32_e64 v18, v14, v5, s[42:43]
	v_fract_f32_e32 v5, v4
	v_cos_f32_e32 v4, v5
	v_sin_f32_e32 v5, v5
	s_nop 0
	v_pk_mul_f32 v[14:15], v[6:7], v[4:5]
	s_nop 0
	v_sub_f32_e32 v19, v14, v15
	v_mov_b32_e32 v14, v5
	v_mov_b32_e32 v15, v4
	v_pk_mul_f32 v[4:5], v[6:7], v[14:15]
	v_mov_b32_e32 v7, v0
	v_add_f32_e32 v4, v4, v5
	v_mul_f32_e32 v6, 0x3db504f3, v4
	v_mul_f32_e32 v5, 0x3db504f3, v19
	v_cndmask_b32_e64 v13, v4, v6, s[42:43]
	v_mul_f32_e32 v4, v88, v34
	v_cndmask_b32_e64 v19, v19, v5, s[42:43]
	v_fract_f32_e32 v5, v4
	v_cos_f32_e32 v4, v5
	v_sin_f32_e32 v5, v5
	v_mov_b32_e32 v6, v8
	v_mov_b32_e32 v14, v9
	v_mov_b32_e32 v15, v1
	v_pk_mul_f32 v[6:7], v[6:7], v[4:5]
	s_nop 0
	v_sub_f32_e32 v6, v6, v7
	v_mul_f32_e32 v7, 0x3db504f3, v6
	v_cndmask_b32_e64 v84, v6, v7, s[42:43]
	v_mul_f32_e32 v6, v89, v34
	v_fract_f32_e32 v7, v6
	v_cos_f32_e32 v6, v7
	v_sin_f32_e32 v7, v7
	s_nop 0
	v_pk_mul_f32 v[14:15], v[14:15], v[6:7]
	s_nop 0
	v_sub_f32_e32 v24, v14, v15
	v_mov_b32_e32 v14, v5
	v_mov_b32_e32 v5, v6
	v_mov_b32_e32 v15, v7
	v_pk_mul_f32 v[0:1], v[0:1], v[4:5]
	v_mul_f32_e32 v25, 0x3db504f3, v24
	v_pk_fma_f32 v[0:1], v[8:9], v[14:15], v[0:1]
	v_cndmask_b32_e64 v85, v24, v25, s[42:43]
	v_pk_mul_f32 v[4:5], v[0:1], s[12:13] op_sel_hi:[1,0]
	s_nop 0
	v_cndmask_b32_e64 v4, v0, v4, s[42:43]
	v_mul_f32_e32 v0, v56, v34
	v_cndmask_b32_e64 v5, v1, v5, s[42:43]
	v_fract_f32_e32 v1, v0
	v_cos_f32_e32 v0, v1
	v_sin_f32_e32 v1, v1
	s_nop 0
	v_pk_mul_f32 v[6:7], v[82:83], v[0:1]
	s_nop 0
	v_sub_f32_e32 v8, v6, v7
	v_mov_b32_e32 v6, v1
	v_mov_b32_e32 v7, v0
	v_pk_mul_f32 v[0:1], v[82:83], v[6:7]
	s_nop 0
	v_add_f32_e32 v0, v0, v1
	v_mul_f32_e32 v6, 0x3db504f3, v0
	v_mul_f32_e32 v1, 0x3db504f3, v8
	v_cndmask_b32_e64 v6, v0, v6, s[42:43]
	v_mul_f32_e32 v0, v57, v34
	v_cndmask_b32_e64 v86, v8, v1, s[42:43]
	v_fract_f32_e32 v1, v0
	v_cos_f32_e32 v0, v1
	v_sin_f32_e32 v1, v1
	s_nop 0
	v_pk_mul_f32 v[8:9], v[2:3], v[0:1]
	s_nop 0
	v_sub_f32_e32 v14, v8, v9
	v_mov_b32_e32 v8, v1
	v_mov_b32_e32 v9, v0
	v_pk_mul_f32 v[0:1], v[2:3], v[8:9]
	s_nop 0
	v_add_f32_e32 v0, v0, v1
	v_mul_f32_e32 v1, 0x3db504f3, v14
	v_mul_f32_e32 v2, 0x3db504f3, v0
	v_cndmask_b32_e64 v7, v0, v2, s[42:43]
	v_cndmask_b32_e64 v87, v14, v1, s[42:43]
	v_mov_b64_e32 v[0:1], v[4:5]
	v_mov_b64_e32 v[2:3], v[6:7]
	v_mov_b64_e32 v[4:5], v[10:11]
	v_mov_b64_e32 v[6:7], v[12:13]
	v_mov_b64_e32 v[12:13], v[16:17]
	v_mov_b64_e32 v[14:15], v[18:19]
	v_mov_b64_e32 v[16:17], v[20:21]
	v_mov_b64_e32 v[18:19], v[22:23]
	v_mov_b64_e32 v[20:21], v[26:27]
	v_mov_b64_e32 v[22:23], v[28:29]
	v_mov_b64_e32 v[28:29], v[30:31]
	v_mov_b64_e32 v[30:31], v[32:33]
	v_mov_b64_e32 v[32:33], v[36:37]
	v_mov_b64_e32 v[34:35], v[38:39]
	v_mov_b64_e32 v[36:37], v[42:43]
	v_mov_b64_e32 v[38:39], v[44:45]
	v_mov_b64_e32 v[44:45], v[46:47]
	v_mov_b64_e32 v[46:47], v[48:49]
	v_mov_b64_e32 v[48:49], v[52:53]
	v_mov_b64_e32 v[50:51], v[54:55]
	v_mov_b64_e32 v[52:53], v[58:59]
	v_mov_b64_e32 v[8:9], v[84:85]
	v_mov_b64_e32 v[24:25], v[74:75]
	v_mov_b64_e32 v[40:41], v[70:71]
	v_mov_b64_e32 v[54:55], v[60:61]
	v_mov_b64_e32 v[56:57], v[66:67]
	v_mov_b64_e32 v[60:61], v[62:63]
	v_mov_b64_e32 v[10:11], v[86:87]
	v_mov_b64_e32 v[26:27], v[76:77]
	v_mov_b64_e32 v[42:43], v[72:73]
	v_mov_b64_e32 v[58:59], v[68:69]
	v_mov_b64_e32 v[62:63], v[64:65]
	s_cmp_lt_i32 s16, 3
	s_mov_b64 s[14:15], -1
	s_cbranch_scc1 .LBB0_751
	s_branch .LBB0_738
